# speedup vs baseline: 1.0087x; 1.0012x over previous
.LBB0_109:
	s_lshl_b32 s62, s86, 3
	v_cvt_f32_u32_e32 v2, s62
	s_sub_i32 s65, 0, s62
	s_abs_i32 s63, s85
	s_ashr_i32 s64, s85, 31
	v_rcp_iflag_f32_e32 v2, v2
	v_bfe_i32 v5, v171, 27, 1
	v_lshlrev_b32_e32 v169, 4, v171
	v_lshrrev_b32_e32 v5, 22, v5
	v_mul_f32_e32 v2, 0x4f7ffffe, v2
	v_cvt_u32_f32_e32 v2, v2
	v_add_u32_e32 v5, v169, v5
	v_and_b32_e32 v5, 0xfffffc00, v5
	v_sub_u32_e32 v5, v169, v5
	v_readfirstlane_b32 s68, v2
	s_mul_i32 s65, s65, s68
	s_mul_hi_u32 s65, s68, s65
	s_add_i32 s68, s68, s65
	s_mul_hi_u32 s65, s63, s68
	s_mul_i32 s68, s65, s62
	s_sub_i32 s63, s63, s68
	s_add_i32 s69, s65, 1
	s_sub_i32 s68, s63, s62
	s_cmp_ge_u32 s63, s62
	s_cselect_b32 s65, s69, s65
	s_cselect_b32 s63, s68, s63
	s_add_i32 s68, s65, 1
	s_cmp_ge_u32 s63, s62
	s_cselect_b32 s63, s68, s65
	s_xor_b32 s65, s63, s64
	s_sub_i32 s70, s65, s64
	v_lshrrev_b32_e32 v6, 4, v5
	s_mul_i32 s62, s70, s62
	v_bitop3_b32 v5, v6, v5, 32 bitop3:0x6c
	s_sub_i32 s62, s85, s62
	v_ashrrev_i32_e32 v6, 31, v5
	s_ashr_i32 s89, s62, 3
	s_lshl_b32 s62, s62, 8
	v_lshrrev_b32_e32 v6, 26, v6
	s_and_b32 s71, s62, 0x700
	s_lshl_b32 s62, s89, 8
	v_ashrrev_i32_e32 v2, 31, v171
	v_add_u32_e32 v6, v5, v6
	v_lshrrev_b32_e32 v2, 26, v2
	v_ashrrev_i32_e32 v133, 6, v6
	v_and_b32_e32 v6, 0xc0, v6
	s_ashr_i32 s63, s62, 31
	v_and_b32_e32 v3, 15, v0
	v_and_b32_e32 v4, 48, v0
	v_add_u32_e32 v2, v171, v2
	v_sub_u32_e32 v5, v5, v6
	v_and_b32_e32 v6, 32, v0
	v_lshlrev_b32_e32 v10, 2, v0
	s_lshl_b64 s[72:73], s[62:63], 6
	v_lshlrev_b32_e32 v0, 6, v0
	s_lshl_b32 s63, s65, 11
	v_ashrrev_i32_e32 v131, 6, v2
	v_lshlrev_b32_e32 v3, 6, v3
	v_and_b32_e32 v10, 32, v10
	v_and_b32_e32 v0, 0x3c0, v0
	s_or_b32 s63, s63, s71
	s_lshl_b32 s64, s64, 11
	v_or_b32_e32 v9, v3, v4
	v_bitop3_b32 v3, v3, v10, v4 bitop3:0x36
	v_bitop3_b32 v4, v0, v10, v4 bitop3:0x36
	s_sub_i32 s64, s63, s64
	v_lshlrev_b32_e32 v0, 15, v131
	s_ashr_i32 s65, s64, 31
	v_and_b32_e32 v0, 0xffff0000, v0
	v_ashrrev_i16_sdwa v5, v167, sext(v5) dst_sel:DWORD dst_unused:UNUSED_PAD src0_sel:DWORD src1_sel:BYTE_0
	s_lshl_b64 s[64:65], s[64:65], 12
	v_lshl_add_u32 v0, v133, 12, v0
	v_bfe_i32 v134, v5, 0, 16
	v_and_or_b32 v0, v2, 64, v0
	s_add_u32 s64, s54, s64
	s_waitcnt vmcnt(0)
	v_lshl_add_u32 v164, v134, 1, v0
	s_addc_u32 s65, s55, s65
	v_lshlrev_b32_e32 v14, 13, v1
	v_lshl_add_u64 v[0:1], s[64:65], 0, v[164:165]
	s_mul_i32 s64, s4, 0x1800
	s_mul_hi_u32 s63, s4, 0x1800
	s_add_u32 s64, s64, s72
	s_addc_u32 s63, s63, s73
	s_add_u32 s64, s66, s64
	v_bfe_i32 v7, v171, 6, 1
	s_addc_u32 s65, s67, s63
	s_lshl_b64 s[68:69], s[4:5], 12
	v_and_b32_e32 v7, s4, v7
	v_lshrrev_b32_e32 v8, 7, v171
	s_add_u32 s4, s68, s72
	v_add_lshl_u32 v7, v7, v8, 10
	v_lshlrev_b32_e32 v8, 6, v171
	s_addc_u32 s63, s69, s73
	v_and_b32_e32 v5, 0x3f0, v169
	v_and_b32_e32 v8, 0x3000, v8
	v_bitop3_b32 v11, v9, s77, v10 bitop3:0xde
	v_bitop3_b32 v12, v9, s78, v10 bitop3:0xde
	v_bitop3_b32 v13, v9, s79, v10 bitop3:0xde
	v_bitop3_b32 v9, v9, s80, v10 bitop3:0xde
	v_or_b32_e32 v10, 0x800, v14
	v_or_b32_e32 v15, 0x1000, v14
	s_waitcnt vmcnt(0)
	v_or_b32_e32 v16, 0x1800, v14
	v_lshl_add_u64 v[128:129], v[0:1], 0, s[20:21]
	s_add_u32 s66, s66, s4
	v_mov_b32_e32 v0, 0
	v_bitop3_b32 v164, v5, v7, v6 bitop3:0xde
	s_addc_u32 s67, s67, s63
	s_mov_b32 s4, -2
	v_add_u32_e32 v138, v11, v8
	v_add_u32_e32 v192, v3, v14
	v_add_u32_e32 v191, v4, v10
	v_add_u32_e32 v190, v4, v15
	v_add_u32_e32 v189, v4, v16
	v_add_u32_e32 v137, 0xc000, v169
	v_add_u32_e32 v136, 0xe000, v169
	v_add_u32_e32 v135, v12, v8
	v_add_u32_e32 v188, 0x10000, v169
	v_add_u32_e32 v187, 0x12000, v169
	v_add_u32_e32 v186, 0x2000, v169
	v_add_u32_e32 v185, 0x14000, v169
	v_add_u32_e32 v184, 0x16000, v169
	v_add_u32_e32 v130, v13, v8
	v_add_u32_e32 v183, 0x4000, v169
	v_add_u32_e32 v182, 0x6000, v169
	v_add_u32_e32 v132, v9, v8
	v_add_u32_e32 v181, 0x18000, v169
	v_add_u32_e32 v180, 0x1a000, v169
	v_add_u32_e32 v179, 0x8000, v169
	v_add_u32_e32 v177, 0xa000, v169
	v_add_u32_e32 v175, 0x1c000, v169
	v_add_u32_e32 v173, 0x1e000, v169
	v_mov_b32_e32 v1, v0
	v_mov_b32_e32 v2, v0
	v_mov_b32_e32 v3, v0
	v_mov_b32_e32 v4, v0
	v_mov_b32_e32 v5, v0
	v_mov_b32_e32 v6, v0
	v_mov_b32_e32 v7, v0
	v_mov_b32_e32 v8, v0
	v_mov_b32_e32 v9, v0
	v_mov_b32_e32 v10, v0
	v_mov_b32_e32 v11, v0
	v_mov_b32_e32 v12, v0
	v_mov_b32_e32 v13, v0
	v_mov_b32_e32 v14, v0
	v_mov_b32_e32 v15, v0
	v_mov_b32_e32 v16, v0
	v_mov_b32_e32 v17, v0
	v_mov_b32_e32 v18, v0
	v_mov_b32_e32 v19, v0
	v_mov_b32_e32 v20, v0
	v_mov_b32_e32 v21, v0
	v_mov_b32_e32 v22, v0
	v_mov_b32_e32 v23, v0
	v_mov_b32_e32 v24, v0
	v_mov_b32_e32 v25, v0
	v_mov_b32_e32 v26, v0
	v_mov_b32_e32 v27, v0
	v_mov_b32_e32 v28, v0
	v_mov_b32_e32 v29, v0
	v_mov_b32_e32 v30, v0
	v_mov_b32_e32 v31, v0
	v_mov_b32_e32 v32, v0
	v_mov_b32_e32 v33, v0
	v_mov_b32_e32 v34, v0
	v_mov_b32_e32 v35, v0
	v_mov_b32_e32 v36, v0
	v_mov_b32_e32 v37, v0
	v_mov_b32_e32 v38, v0
	v_mov_b32_e32 v39, v0
	v_mov_b32_e32 v40, v0
	v_mov_b32_e32 v41, v0
	v_mov_b32_e32 v42, v0
	v_mov_b32_e32 v43, v0
	v_mov_b32_e32 v44, v0
	v_mov_b32_e32 v45, v0
	v_mov_b32_e32 v46, v0
	v_mov_b32_e32 v47, v0
	v_mov_b32_e32 v48, v0
	v_mov_b32_e32 v49, v0
	v_mov_b32_e32 v50, v0
	v_mov_b32_e32 v51, v0
	v_mov_b32_e32 v52, v0
	v_mov_b32_e32 v53, v0
	v_mov_b32_e32 v54, v0
	v_mov_b32_e32 v55, v0
	v_mov_b32_e32 v56, v0
	v_mov_b32_e32 v57, v0
	v_mov_b32_e32 v58, v0
	v_mov_b32_e32 v59, v0
	v_mov_b32_e32 v60, v0
	v_mov_b32_e32 v61, v0
	v_mov_b32_e32 v62, v0
	v_mov_b32_e32 v63, v0
	v_mov_b32_e32 v64, v0
	v_mov_b32_e32 v65, v0
	v_mov_b32_e32 v66, v0
	v_mov_b32_e32 v67, v0
	v_mov_b32_e32 v68, v0
	v_mov_b32_e32 v69, v0
	v_mov_b32_e32 v70, v0
	v_mov_b32_e32 v71, v0
	v_mov_b32_e32 v72, v0
	v_mov_b32_e32 v73, v0
	v_mov_b32_e32 v74, v0
	v_mov_b32_e32 v75, v0
	v_mov_b32_e32 v76, v0
	v_mov_b32_e32 v77, v0
	v_mov_b32_e32 v78, v0
	v_mov_b32_e32 v79, v0
	v_mov_b32_e32 v80, v0
	v_mov_b32_e32 v81, v0
	v_mov_b32_e32 v82, v0
	v_mov_b32_e32 v83, v0
	v_mov_b32_e32 v84, v0
	v_mov_b32_e32 v85, v0
	v_mov_b32_e32 v86, v0
	v_mov_b32_e32 v87, v0
	v_mov_b32_e32 v88, v0
	v_mov_b32_e32 v89, v0
	v_mov_b32_e32 v90, v0
	v_mov_b32_e32 v91, v0
	v_mov_b32_e32 v92, v0
	v_mov_b32_e32 v93, v0
	v_mov_b32_e32 v94, v0
	v_mov_b32_e32 v95, v0
	v_mov_b32_e32 v96, v0
	v_mov_b32_e32 v97, v0
	v_mov_b32_e32 v98, v0
	v_mov_b32_e32 v99, v0
	v_mov_b32_e32 v100, v0
	v_mov_b32_e32 v101, v0
	v_mov_b32_e32 v102, v0
	v_mov_b32_e32 v103, v0
	v_mov_b32_e32 v104, v0
	v_mov_b32_e32 v105, v0
	v_mov_b32_e32 v106, v0
	v_mov_b32_e32 v107, v0
	v_mov_b32_e32 v108, v0
	v_mov_b32_e32 v109, v0
	v_mov_b32_e32 v110, v0
	v_mov_b32_e32 v111, v0
	v_mov_b32_e32 v112, v0
	v_mov_b32_e32 v113, v0
	v_mov_b32_e32 v114, v0
	v_mov_b32_e32 v115, v0
	v_mov_b32_e32 v116, v0
	v_mov_b32_e32 v117, v0
	v_mov_b32_e32 v118, v0
	v_mov_b32_e32 v119, v0
	v_mov_b32_e32 v120, v0
	v_mov_b32_e32 v121, v0
	v_mov_b32_e32 v122, v0
	v_mov_b32_e32 v123, v0
	v_mov_b32_e32 v124, v0
	v_mov_b32_e32 v125, v0
	v_mov_b32_e32 v126, v0
	v_mov_b32_e32 v127, v0
	s_barrier
	v_readlane_b32 s98, v242, 1
	s_lshl_b32 s98, s98, 10
	s_add_i32 s63, s98, 0xc000
	v_lshl_add_u64 v[142:143], v[128:129], 0, s[22:23]
	s_mov_b32 m0, s63
	s_add_i32 s63, s98, 0xe000
	global_load_lds_dwordx4 v[142:143], off
	v_lshl_add_u64 v[142:143], v[128:129], 0, s[24:25]
	s_mov_b32 m0, s63
	s_nop 0
	global_load_lds_dwordx4 v[142:143], off
	ds_read_b128 v[140:143], v138
	ds_read_b128 v[144:147], v138 offset:1024
	ds_read_b128 v[148:151], v138 offset:2048
	ds_read_b128 v[152:155], v138 offset:3072
.LBB0_110:
	ds_read_b128 v[156:159], v192
	ds_read_b128 v[160:163], v192 offset:1024
	ds_read_b128 v[194:197], v191
	ds_read_b128 v[198:201], v191 offset:1024
	ds_read_b128 v[202:205], v190
	ds_read_b128 v[206:209], v190 offset:1024
	ds_read_b128 v[210:213], v189
	ds_read_b128 v[214:217], v189 offset:1024
	s_waitcnt lgkmcnt(8)
	s_waitcnt vmcnt(10)
	s_barrier
	s_waitcnt lgkmcnt(0)
	s_waitcnt lgkmcnt(0)
	v_mfma_f32_16x16x32_bf16 v[124:127], v[140:143], v[156:159], v[124:127]
	v_mfma_f32_16x16x32_bf16 v[120:123], v[148:151], v[156:159], v[120:123]
	v_mfma_f32_16x16x32_bf16 v[116:119], v[140:143], v[194:197], v[116:119]
	v_mfma_f32_16x16x32_bf16 v[112:115], v[148:151], v[194:197], v[112:115]
	v_mfma_f32_16x16x32_bf16 v[108:111], v[140:143], v[202:205], v[108:111]
	v_mfma_f32_16x16x32_bf16 v[104:107], v[148:151], v[202:205], v[104:107]
	v_mfma_f32_16x16x32_bf16 v[100:103], v[140:143], v[210:213], v[100:103]
	v_mfma_f32_16x16x32_bf16 v[96:99], v[148:151], v[210:213], v[96:99]
	v_mfma_f32_16x16x32_bf16 v[124:127], v[144:147], v[160:163], v[124:127]
	v_mfma_f32_16x16x32_bf16 v[120:123], v[152:155], v[160:163], v[120:123]
	v_mfma_f32_16x16x32_bf16 v[116:119], v[144:147], v[198:201], v[116:119]
	v_mfma_f32_16x16x32_bf16 v[112:115], v[152:155], v[198:201], v[112:115]
	v_mfma_f32_16x16x32_bf16 v[108:111], v[144:147], v[206:209], v[108:111]
	v_mfma_f32_16x16x32_bf16 v[104:107], v[152:155], v[206:209], v[104:107]
	v_mfma_f32_16x16x32_bf16 v[100:103], v[144:147], v[214:217], v[100:103]
	v_mfma_f32_16x16x32_bf16 v[96:99], v[152:155], v[214:217], v[96:99]
	s_barrier
	s_add_i32 s63, s98, 0x10000
	v_lshl_add_u64 v[234:235], s[66:67], 0, v[164:165]
	s_mov_b32 m0, s63
	s_add_i32 s63, s98, 0x12000
	ds_read_b128 v[218:221], v135
	ds_read_b128 v[222:225], v135 offset:1024
	ds_read_b128 v[226:229], v135 offset:2048
	ds_read_b128 v[230:233], v135 offset:3072
	global_load_lds_dwordx4 v[234:235], off
	v_lshl_add_u64 v[236:237], v[234:235], 0, s[10:11]
	s_mov_b32 m0, s63
	s_nop 0
	global_load_lds_dwordx4 v[236:237], off
	s_mov_b32 s63, s98
	v_lshl_add_u64 v[236:237], v[128:129], 0, s[26:27]
	s_mov_b32 m0, s63
	s_add_i32 s63, s98, 0x2000
	global_load_lds_dwordx4 v[236:237], off
	v_lshl_add_u64 v[236:237], v[128:129], 0, s[28:29]
	s_mov_b32 m0, s63
	s_nop 0
	global_load_lds_dwordx4 v[236:237], off
	s_waitcnt vmcnt(12)
	s_barrier
	s_waitcnt lgkmcnt(0)
	s_waitcnt lgkmcnt(0)
	v_mfma_f32_16x16x32_bf16 v[92:95], v[218:221], v[156:159], v[92:95]
	v_mfma_f32_16x16x32_bf16 v[88:91], v[226:229], v[156:159], v[88:91]
	v_mfma_f32_16x16x32_bf16 v[84:87], v[218:221], v[194:197], v[84:87]
	v_mfma_f32_16x16x32_bf16 v[80:83], v[226:229], v[194:197], v[80:83]
	v_mfma_f32_16x16x32_bf16 v[76:79], v[218:221], v[202:205], v[76:79]
	v_mfma_f32_16x16x32_bf16 v[72:75], v[226:229], v[202:205], v[72:75]
	v_mfma_f32_16x16x32_bf16 v[68:71], v[218:221], v[210:213], v[68:71]
	v_mfma_f32_16x16x32_bf16 v[64:67], v[226:229], v[210:213], v[64:67]
	v_mfma_f32_16x16x32_bf16 v[92:95], v[222:225], v[160:163], v[92:95]
	v_mfma_f32_16x16x32_bf16 v[88:91], v[230:233], v[160:163], v[88:91]
	v_mfma_f32_16x16x32_bf16 v[84:87], v[222:225], v[198:201], v[84:87]
	v_mfma_f32_16x16x32_bf16 v[80:83], v[230:233], v[198:201], v[80:83]
	v_mfma_f32_16x16x32_bf16 v[76:79], v[222:225], v[206:209], v[76:79]
	v_mfma_f32_16x16x32_bf16 v[72:75], v[230:233], v[206:209], v[72:75]
	v_mfma_f32_16x16x32_bf16 v[68:71], v[222:225], v[214:217], v[68:71]
	v_mfma_f32_16x16x32_bf16 v[64:67], v[230:233], v[214:217], v[64:67]
	s_barrier
	ds_read_b128 v[156:159], v192 offset:16384
	ds_read_b128 v[160:163], v192 offset:17408
	ds_read_b128 v[194:197], v191 offset:16384
	ds_read_b128 v[198:201], v191 offset:17408
	ds_read_b128 v[202:205], v190 offset:16384
	ds_read_b128 v[206:209], v190 offset:17408
	ds_read_b128 v[210:213], v189 offset:16384
	ds_read_b128 v[214:217], v189 offset:17408
	s_add_i32 s63, s98, 0x14000
	v_lshl_add_u64 v[236:237], v[234:235], 0, s[30:31]
	s_mov_b32 m0, s63
	s_add_i32 s63, s98, 0x16000
	global_load_lds_dwordx4 v[236:237], off
	v_lshl_add_u64 v[236:237], v[234:235], 0, s[34:35]
	s_mov_b32 m0, s63
	s_nop 0
	global_load_lds_dwordx4 v[236:237], off
	s_waitcnt vmcnt(12)
	s_barrier
	s_waitcnt lgkmcnt(0)
	s_waitcnt lgkmcnt(0)
	v_mfma_f32_16x16x32_bf16 v[60:63], v[140:143], v[156:159], v[60:63]
	v_mfma_f32_16x16x32_bf16 v[56:59], v[148:151], v[156:159], v[56:59]
	v_mfma_f32_16x16x32_bf16 v[52:55], v[140:143], v[194:197], v[52:55]
	v_mfma_f32_16x16x32_bf16 v[48:51], v[148:151], v[194:197], v[48:51]
	v_mfma_f32_16x16x32_bf16 v[44:47], v[140:143], v[202:205], v[44:47]
	v_mfma_f32_16x16x32_bf16 v[40:43], v[148:151], v[202:205], v[40:43]
	v_mfma_f32_16x16x32_bf16 v[36:39], v[140:143], v[210:213], v[36:39]
	v_mfma_f32_16x16x32_bf16 v[32:35], v[148:151], v[210:213], v[32:35]
	v_mfma_f32_16x16x32_bf16 v[60:63], v[144:147], v[160:163], v[60:63]
	v_mfma_f32_16x16x32_bf16 v[56:59], v[152:155], v[160:163], v[56:59]
	v_mfma_f32_16x16x32_bf16 v[52:55], v[144:147], v[198:201], v[52:55]
	v_mfma_f32_16x16x32_bf16 v[48:51], v[152:155], v[198:201], v[48:51]
	v_mfma_f32_16x16x32_bf16 v[44:47], v[144:147], v[206:209], v[44:47]
	v_mfma_f32_16x16x32_bf16 v[40:43], v[152:155], v[206:209], v[40:43]
	v_mfma_f32_16x16x32_bf16 v[36:39], v[144:147], v[214:217], v[36:39]
	v_mfma_f32_16x16x32_bf16 v[32:35], v[152:155], v[214:217], v[32:35]
	s_barrier
	s_add_i32 s63, s98, 0x4000
	v_lshl_add_u64 v[142:143], v[128:129], 0, s[40:41]
	s_mov_b32 m0, s63
	s_add_i32 s63, s98, 0x6000
	global_load_lds_dwordx4 v[142:143], off
	s_mov_b32 m0, s63
	s_nop 0
	global_load_lds_dwordx4 v[128:129], off
	ds_read_b128 v[140:143], v130
	ds_read_b128 v[144:147], v130 offset:1024
	ds_read_b128 v[148:151], v130 offset:2048
	ds_read_b128 v[152:155], v130 offset:3072
	s_waitcnt vmcnt(12)
	s_barrier
	v_mfma_f32_16x16x32_bf16 v[28:31], v[218:221], v[156:159], v[28:31]
	v_mfma_f32_16x16x32_bf16 v[24:27], v[226:229], v[156:159], v[24:27]
	v_mfma_f32_16x16x32_bf16 v[20:23], v[218:221], v[194:197], v[20:23]
	v_mfma_f32_16x16x32_bf16 v[16:19], v[226:229], v[194:197], v[16:19]
	v_mfma_f32_16x16x32_bf16 v[12:15], v[218:221], v[202:205], v[12:15]
	v_mfma_f32_16x16x32_bf16 v[8:11], v[226:229], v[202:205], v[8:11]
	v_mfma_f32_16x16x32_bf16 v[4:7], v[218:221], v[210:213], v[4:7]
	v_mfma_f32_16x16x32_bf16 v[0:3], v[226:229], v[210:213], v[0:3]
	v_mfma_f32_16x16x32_bf16 v[28:31], v[222:225], v[160:163], v[28:31]
	v_mfma_f32_16x16x32_bf16 v[24:27], v[230:233], v[160:163], v[24:27]
	v_mfma_f32_16x16x32_bf16 v[20:23], v[222:225], v[198:201], v[20:23]
	v_mfma_f32_16x16x32_bf16 v[16:19], v[230:233], v[198:201], v[16:19]
	v_mfma_f32_16x16x32_bf16 v[12:15], v[222:225], v[206:209], v[12:15]
	v_mfma_f32_16x16x32_bf16 v[8:11], v[230:233], v[206:209], v[8:11]
	v_mfma_f32_16x16x32_bf16 v[4:7], v[222:225], v[214:217], v[4:7]
	v_mfma_f32_16x16x32_bf16 v[0:3], v[230:233], v[214:217], v[0:3]
	s_barrier
	ds_read_b128 v[156:159], v192 offset:32768
	ds_read_b128 v[160:163], v192 offset:33792
	ds_read_b128 v[194:197], v191 offset:32768
	ds_read_b128 v[198:201], v191 offset:33792
	ds_read_b128 v[202:205], v190 offset:32768
	ds_read_b128 v[206:209], v190 offset:33792
	ds_read_b128 v[210:213], v189 offset:32768
	ds_read_b128 v[214:217], v189 offset:33792
	s_waitcnt lgkmcnt(8)
	s_waitcnt vmcnt(10)
	s_barrier
	s_waitcnt lgkmcnt(0)
	s_waitcnt lgkmcnt(0)
	v_mfma_f32_16x16x32_bf16 v[124:127], v[140:143], v[156:159], v[124:127]
	v_mfma_f32_16x16x32_bf16 v[120:123], v[148:151], v[156:159], v[120:123]
	v_mfma_f32_16x16x32_bf16 v[116:119], v[140:143], v[194:197], v[116:119]
	v_mfma_f32_16x16x32_bf16 v[112:115], v[148:151], v[194:197], v[112:115]
	v_mfma_f32_16x16x32_bf16 v[108:111], v[140:143], v[202:205], v[108:111]
	v_mfma_f32_16x16x32_bf16 v[104:107], v[148:151], v[202:205], v[104:107]
	v_mfma_f32_16x16x32_bf16 v[100:103], v[140:143], v[210:213], v[100:103]
	v_mfma_f32_16x16x32_bf16 v[96:99], v[148:151], v[210:213], v[96:99]
	v_mfma_f32_16x16x32_bf16 v[124:127], v[144:147], v[160:163], v[124:127]
	v_mfma_f32_16x16x32_bf16 v[120:123], v[152:155], v[160:163], v[120:123]
	v_mfma_f32_16x16x32_bf16 v[116:119], v[144:147], v[198:201], v[116:119]
	v_mfma_f32_16x16x32_bf16 v[112:115], v[152:155], v[198:201], v[112:115]
	v_mfma_f32_16x16x32_bf16 v[108:111], v[144:147], v[206:209], v[108:111]
	v_mfma_f32_16x16x32_bf16 v[104:107], v[152:155], v[206:209], v[104:107]
	v_mfma_f32_16x16x32_bf16 v[100:103], v[144:147], v[214:217], v[100:103]
	v_mfma_f32_16x16x32_bf16 v[96:99], v[152:155], v[214:217], v[96:99]
	s_barrier
	s_add_i32 s63, s98, 0x18000
	v_lshl_add_u64 v[234:235], s[64:65], 0, v[164:165]
	s_mov_b32 m0, s63
	s_add_i32 s63, s98, 0x1a000
	ds_read_b128 v[218:221], v132
	ds_read_b128 v[222:225], v132 offset:1024
	ds_read_b128 v[226:229], v132 offset:2048
	ds_read_b128 v[230:233], v132 offset:3072
	global_load_lds_dwordx4 v[234:235], off
	v_lshl_add_u64 v[236:237], v[234:235], 0, s[10:11]
	s_mov_b32 m0, s63
	s_nop 0
	global_load_lds_dwordx4 v[236:237], off
	s_add_i32 s63, s98, 0x8000
	v_lshl_add_u64 v[236:237], v[128:129], 0, s[44:45]
	s_mov_b32 m0, s63
	s_add_i32 s63, s98, 0xa000
	global_load_lds_dwordx4 v[236:237], off
	v_lshl_add_u64 v[236:237], v[128:129], 0, s[46:47]
	s_mov_b32 m0, s63
	s_nop 0
	global_load_lds_dwordx4 v[236:237], off
	s_waitcnt vmcnt(12)
	s_barrier
	s_waitcnt lgkmcnt(0)
	s_waitcnt lgkmcnt(0)
	v_mfma_f32_16x16x32_bf16 v[92:95], v[218:221], v[156:159], v[92:95]
	v_mfma_f32_16x16x32_bf16 v[88:91], v[226:229], v[156:159], v[88:91]
	v_mfma_f32_16x16x32_bf16 v[84:87], v[218:221], v[194:197], v[84:87]
	v_mfma_f32_16x16x32_bf16 v[80:83], v[226:229], v[194:197], v[80:83]
	v_mfma_f32_16x16x32_bf16 v[76:79], v[218:221], v[202:205], v[76:79]
	v_mfma_f32_16x16x32_bf16 v[72:75], v[226:229], v[202:205], v[72:75]
	v_mfma_f32_16x16x32_bf16 v[68:71], v[218:221], v[210:213], v[68:71]
	v_mfma_f32_16x16x32_bf16 v[64:67], v[226:229], v[210:213], v[64:67]
	v_mfma_f32_16x16x32_bf16 v[92:95], v[222:225], v[160:163], v[92:95]
	v_mfma_f32_16x16x32_bf16 v[88:91], v[230:233], v[160:163], v[88:91]
	v_mfma_f32_16x16x32_bf16 v[84:87], v[222:225], v[198:201], v[84:87]
	v_mfma_f32_16x16x32_bf16 v[80:83], v[230:233], v[198:201], v[80:83]
	v_mfma_f32_16x16x32_bf16 v[76:79], v[222:225], v[206:209], v[76:79]
	v_mfma_f32_16x16x32_bf16 v[72:75], v[230:233], v[206:209], v[72:75]
	v_mfma_f32_16x16x32_bf16 v[68:71], v[222:225], v[214:217], v[68:71]
	v_mfma_f32_16x16x32_bf16 v[64:67], v[230:233], v[214:217], v[64:67]
	s_barrier
	ds_read_b128 v[156:159], v192 offset:49152
	ds_read_b128 v[160:163], v192 offset:50176
	ds_read_b128 v[194:197], v191 offset:49152
	ds_read_b128 v[198:201], v191 offset:50176
	ds_read_b128 v[202:205], v190 offset:49152
	ds_read_b128 v[206:209], v190 offset:50176
	ds_read_b128 v[210:213], v189 offset:49152
	ds_read_b128 v[214:217], v189 offset:50176
	s_add_i32 s63, s98, 0x1c000
	v_lshl_add_u64 v[236:237], v[234:235], 0, s[30:31]
	s_mov_b32 m0, s63
	s_add_i32 s63, s98, 0x1e000
	global_load_lds_dwordx4 v[236:237], off
	v_lshl_add_u64 v[236:237], v[234:235], 0, s[34:35]
	s_mov_b32 m0, s63
	s_nop 0
	global_load_lds_dwordx4 v[236:237], off
	s_waitcnt vmcnt(12)
	s_barrier
	s_waitcnt lgkmcnt(0)
	s_waitcnt lgkmcnt(0)
	v_mfma_f32_16x16x32_bf16 v[60:63], v[140:143], v[156:159], v[60:63]
	v_mfma_f32_16x16x32_bf16 v[56:59], v[148:151], v[156:159], v[56:59]
	v_mfma_f32_16x16x32_bf16 v[52:55], v[140:143], v[194:197], v[52:55]
	v_mfma_f32_16x16x32_bf16 v[48:51], v[148:151], v[194:197], v[48:51]
	v_mfma_f32_16x16x32_bf16 v[44:47], v[140:143], v[202:205], v[44:47]
	v_mfma_f32_16x16x32_bf16 v[40:43], v[148:151], v[202:205], v[40:43]
	v_mfma_f32_16x16x32_bf16 v[36:39], v[140:143], v[210:213], v[36:39]
	v_mfma_f32_16x16x32_bf16 v[32:35], v[148:151], v[210:213], v[32:35]
	v_mfma_f32_16x16x32_bf16 v[60:63], v[144:147], v[160:163], v[60:63]
	v_mfma_f32_16x16x32_bf16 v[56:59], v[152:155], v[160:163], v[56:59]
	v_mfma_f32_16x16x32_bf16 v[52:55], v[144:147], v[198:201], v[52:55]
	v_mfma_f32_16x16x32_bf16 v[48:51], v[152:155], v[198:201], v[48:51]
	v_mfma_f32_16x16x32_bf16 v[44:47], v[144:147], v[206:209], v[44:47]
	v_mfma_f32_16x16x32_bf16 v[40:43], v[152:155], v[206:209], v[40:43]
	v_mfma_f32_16x16x32_bf16 v[36:39], v[144:147], v[214:217], v[36:39]
	v_mfma_f32_16x16x32_bf16 v[32:35], v[152:155], v[214:217], v[32:35]
	s_barrier
	v_lshl_add_u64 v[128:129], v[128:129], 0, s[56:57]
	s_add_i32 s63, s98, 0xc000
	v_lshl_add_u64 v[142:143], v[128:129], 0, s[22:23]
	s_mov_b32 m0, s63
	s_add_i32 s63, s98, 0xe000
	global_load_lds_dwordx4 v[142:143], off
	v_lshl_add_u64 v[142:143], v[128:129], 0, s[24:25]
	s_mov_b32 m0, s63
	s_nop 0
	global_load_lds_dwordx4 v[142:143], off
	ds_read_b128 v[140:143], v138
	ds_read_b128 v[144:147], v138 offset:1024
	ds_read_b128 v[148:151], v138 offset:2048
	ds_read_b128 v[152:155], v138 offset:3072
	s_waitcnt vmcnt(12)
	s_barrier
	v_mfma_f32_16x16x32_bf16 v[28:31], v[218:221], v[156:159], v[28:31]
	v_mfma_f32_16x16x32_bf16 v[24:27], v[226:229], v[156:159], v[24:27]
	v_mfma_f32_16x16x32_bf16 v[20:23], v[218:221], v[194:197], v[20:23]
	v_mfma_f32_16x16x32_bf16 v[16:19], v[226:229], v[194:197], v[16:19]
	v_mfma_f32_16x16x32_bf16 v[12:15], v[218:221], v[202:205], v[12:15]
	v_mfma_f32_16x16x32_bf16 v[8:11], v[226:229], v[202:205], v[8:11]
	v_mfma_f32_16x16x32_bf16 v[4:7], v[218:221], v[210:213], v[4:7]
	v_mfma_f32_16x16x32_bf16 v[0:3], v[226:229], v[210:213], v[0:3]
	v_mfma_f32_16x16x32_bf16 v[28:31], v[222:225], v[160:163], v[28:31]
	v_mfma_f32_16x16x32_bf16 v[24:27], v[230:233], v[160:163], v[24:27]
	v_mfma_f32_16x16x32_bf16 v[20:23], v[222:225], v[198:201], v[20:23]
	v_mfma_f32_16x16x32_bf16 v[16:19], v[230:233], v[198:201], v[16:19]
	v_mfma_f32_16x16x32_bf16 v[12:15], v[222:225], v[206:209], v[12:15]
	v_mfma_f32_16x16x32_bf16 v[8:11], v[230:233], v[206:209], v[8:11]
	v_mfma_f32_16x16x32_bf16 v[4:7], v[222:225], v[214:217], v[4:7]
	v_mfma_f32_16x16x32_bf16 v[0:3], v[230:233], v[214:217], v[0:3]
	s_add_i32 s4, s4, 2
	s_add_u32 s64, s64, s68
	s_addc_u32 s65, s65, s69
	s_add_u32 s66, s66, s68
	s_addc_u32 s67, s67, s69
	s_cmp_lt_u32 s4, 28
	s_barrier
	s_cbranch_scc1 .LBB0_110
	s_lshl_b32 s4, s70, 11
	s_or_b32 s64, s71, s4
	s_or_b32 s66, s64, 0x80
	v_lshlrev_b32_e32 v128, 3, v131
	v_lshlrev_b32_e32 v129, 5, v131
	s_ashr_i32 s67, s66, 31
	v_and_b32_e32 v128, 0xffff0, v128
	v_and_b32_e32 v129, 32, v129
	s_lshl_b64 s[66:67], s[66:67], 12
	v_add_u32_e32 v129, v129, v134
	v_add_lshl_u32 v128, v133, v128, 12
	s_add_u32 s66, s54, s66
	v_lshl_add_u32 v164, v129, 1, v128
	s_addc_u32 s67, s55, s67
	v_lshl_add_u64 v[128:129], s[66:67], 0, v[164:165]
	v_readfirstlane_b32 s4, v137
	ds_read_b128 v[140:143], v138
	ds_read_b128 v[144:147], v138 offset:1024
	ds_read_b128 v[148:151], v138 offset:2048
	ds_read_b128 v[152:155], v138 offset:3072
	ds_read_b128 v[156:159], v192
	ds_read_b128 v[160:163], v192 offset:1024
	ds_read_b128 v[194:197], v191
	ds_read_b128 v[198:201], v191 offset:1024
	ds_read_b128 v[202:205], v190
	ds_read_b128 v[206:209], v190 offset:1024
	ds_read_b128 v[210:213], v189
	ds_read_b128 v[214:217], v189 offset:1024
	v_lshl_add_u64 v[138:139], v[128:129], 0, s[58:59]
	s_mov_b32 m0, s4
	v_readfirstlane_b32 s4, v136
	global_load_lds_dwordx4 v[138:139], off
	v_lshl_add_u64 v[128:129], v[128:129], 0, s[60:61]
	s_mov_b32 m0, s4
	s_ashr_i32 s65, s64, 31
	global_load_lds_dwordx4 v[128:129], off
	s_waitcnt vmcnt(10)
	s_barrier
	s_waitcnt lgkmcnt(0)
	s_setprio 1
	s_waitcnt lgkmcnt(0)
	v_mfma_f32_16x16x32_bf16 v[124:127], v[140:143], v[156:159], v[124:127]
	v_mfma_f32_16x16x32_bf16 v[120:123], v[148:151], v[156:159], v[120:123]
	v_mfma_f32_16x16x32_bf16 v[116:119], v[140:143], v[194:197], v[116:119]
	v_mfma_f32_16x16x32_bf16 v[112:115], v[148:151], v[194:197], v[112:115]
	v_mfma_f32_16x16x32_bf16 v[108:111], v[140:143], v[202:205], v[108:111]
	v_mfma_f32_16x16x32_bf16 v[104:107], v[148:151], v[202:205], v[104:107]
	v_mfma_f32_16x16x32_bf16 v[100:103], v[140:143], v[210:213], v[100:103]
	v_mfma_f32_16x16x32_bf16 v[96:99], v[148:151], v[210:213], v[96:99]
	v_mfma_f32_16x16x32_bf16 v[124:127], v[144:147], v[160:163], v[124:127]
	v_mfma_f32_16x16x32_bf16 v[120:123], v[152:155], v[160:163], v[120:123]
	v_mfma_f32_16x16x32_bf16 v[116:119], v[144:147], v[198:201], v[116:119]
	v_mfma_f32_16x16x32_bf16 v[112:115], v[152:155], v[198:201], v[112:115]
	v_mfma_f32_16x16x32_bf16 v[108:111], v[144:147], v[206:209], v[108:111]
	v_mfma_f32_16x16x32_bf16 v[104:107], v[152:155], v[206:209], v[104:107]
	v_mfma_f32_16x16x32_bf16 v[100:103], v[144:147], v[214:217], v[100:103]
	v_mfma_f32_16x16x32_bf16 v[96:99], v[152:155], v[214:217], v[96:99]
	s_setprio 0
	s_barrier
	ds_read_b128 v[136:139], v135
	ds_read_b128 v[218:221], v135 offset:1024
	ds_read_b128 v[222:225], v135 offset:2048
	ds_read_b128 v[226:229], v135 offset:3072
	s_barrier
	s_waitcnt lgkmcnt(0)
	s_setprio 1
	s_waitcnt lgkmcnt(0)
	v_mfma_f32_16x16x32_bf16 v[92:95], v[136:139], v[156:159], v[92:95]
	v_mfma_f32_16x16x32_bf16 v[88:91], v[222:225], v[156:159], v[88:91]
	v_mfma_f32_16x16x32_bf16 v[84:87], v[136:139], v[194:197], v[84:87]
	v_mfma_f32_16x16x32_bf16 v[80:83], v[222:225], v[194:197], v[80:83]
	v_mfma_f32_16x16x32_bf16 v[76:79], v[136:139], v[202:205], v[76:79]
	v_mfma_f32_16x16x32_bf16 v[72:75], v[222:225], v[202:205], v[72:75]
	v_mfma_f32_16x16x32_bf16 v[68:71], v[136:139], v[210:213], v[68:71]
	v_mfma_f32_16x16x32_bf16 v[64:67], v[222:225], v[210:213], v[64:67]
	v_mfma_f32_16x16x32_bf16 v[156:159], v[218:221], v[160:163], v[92:95]
	v_mfma_f32_16x16x32_bf16 v[160:163], v[226:229], v[160:163], v[88:91]
	v_mfma_f32_16x16x32_bf16 v[194:197], v[218:221], v[198:201], v[84:87]
	v_mfma_f32_16x16x32_bf16 v[198:201], v[226:229], v[198:201], v[80:83]
	v_mfma_f32_16x16x32_bf16 v[202:205], v[218:221], v[206:209], v[76:79]
	v_mfma_f32_16x16x32_bf16 v[206:209], v[226:229], v[206:209], v[72:75]
	v_mfma_f32_16x16x32_bf16 v[210:213], v[218:221], v[214:217], v[68:71]
	v_mfma_f32_16x16x32_bf16 v[214:217], v[226:229], v[214:217], v[64:67]
	s_setprio 0
	s_barrier
	s_nop 0
	ds_read_b128 v[64:67], v192 offset:16384
	ds_read_b128 v[68:71], v192 offset:17408
	ds_read_b128 v[72:75], v191 offset:16384
	ds_read_b128 v[76:79], v191 offset:17408
	ds_read_b128 v[80:83], v190 offset:16384
	ds_read_b128 v[84:87], v190 offset:17408
	ds_read_b128 v[88:91], v189 offset:16384
	ds_read_b128 v[92:95], v189 offset:17408
	s_waitcnt vmcnt(4)
	s_barrier
	s_waitcnt lgkmcnt(0)
	s_setprio 1
	s_waitcnt lgkmcnt(0)
	v_mfma_f32_16x16x32_bf16 v[60:63], v[140:143], v[64:67], v[60:63]
	v_mfma_f32_16x16x32_bf16 v[56:59], v[148:151], v[64:67], v[56:59]
	v_mfma_f32_16x16x32_bf16 v[52:55], v[140:143], v[72:75], v[52:55]
	v_mfma_f32_16x16x32_bf16 v[48:51], v[148:151], v[72:75], v[48:51]
	v_mfma_f32_16x16x32_bf16 v[230:233], v[140:143], v[80:83], v[44:47]
	v_mfma_f32_16x16x32_bf16 v[234:237], v[148:151], v[80:83], v[40:43]
	v_mfma_f32_16x16x32_bf16 v[140:143], v[140:143], v[88:91], v[36:39]
	v_mfma_f32_16x16x32_bf16 v[148:151], v[148:151], v[88:91], v[32:35]
	v_mfma_f32_16x16x32_bf16 v[32:35], v[144:147], v[68:71], v[60:63]
	v_mfma_f32_16x16x32_bf16 v[36:39], v[152:155], v[68:71], v[56:59]
	v_mfma_f32_16x16x32_bf16 v[40:43], v[144:147], v[76:79], v[52:55]
	v_mfma_f32_16x16x32_bf16 v[44:47], v[152:155], v[76:79], v[48:51]
	v_mfma_f32_16x16x32_bf16 v[48:51], v[144:147], v[84:87], v[230:233]
	v_mfma_f32_16x16x32_bf16 v[52:55], v[152:155], v[84:87], v[234:237]
	v_mfma_f32_16x16x32_bf16 v[56:59], v[144:147], v[92:95], v[140:143]
	v_mfma_f32_16x16x32_bf16 v[60:63], v[152:155], v[92:95], v[148:151]
	s_setprio 0
	s_setprio 1
	v_mfma_f32_16x16x32_bf16 v[28:31], v[136:139], v[64:67], v[28:31]
	v_mfma_f32_16x16x32_bf16 v[24:27], v[222:225], v[64:67], v[24:27]
	v_mfma_f32_16x16x32_bf16 v[20:23], v[136:139], v[72:75], v[20:23]
	v_mfma_f32_16x16x32_bf16 v[64:67], v[222:225], v[72:75], v[16:19]
	v_mfma_f32_16x16x32_bf16 v[12:15], v[136:139], v[80:83], v[12:15]
	v_mfma_f32_16x16x32_bf16 v[8:11], v[222:225], v[80:83], v[8:11]
	v_mfma_f32_16x16x32_bf16 v[72:75], v[136:139], v[88:91], v[4:7]
	v_mfma_f32_16x16x32_bf16 v[80:83], v[222:225], v[88:91], v[0:3]
	v_mfma_f32_16x16x32_bf16 v[0:3], v[218:221], v[68:71], v[28:31]
	v_mfma_f32_16x16x32_bf16 v[4:7], v[226:229], v[68:71], v[24:27]
	v_mfma_f32_16x16x32_bf16 v[16:19], v[218:221], v[76:79], v[20:23]
	v_mfma_f32_16x16x32_bf16 v[20:23], v[226:229], v[76:79], v[64:67]
	v_mfma_f32_16x16x32_bf16 v[64:67], v[218:221], v[84:87], v[12:15]
	v_mfma_f32_16x16x32_bf16 v[68:71], v[226:229], v[84:87], v[8:11]
	v_mfma_f32_16x16x32_bf16 v[72:75], v[218:221], v[92:95], v[72:75]
	v_mfma_f32_16x16x32_bf16 v[76:79], v[226:229], v[92:95], v[80:83]
	s_setprio 0
	s_barrier
	ds_read_b128 v[12:15], v130
	ds_read_b128 v[8:11], v130 offset:1024
	ds_read_b128 v[24:27], v130 offset:2048
	ds_read_b128 v[80:83], v130 offset:3072
	ds_read_b128 v[140:143], v192 offset:32768
	ds_read_b128 v[148:151], v192 offset:33792
	ds_read_b128 v[218:221], v191 offset:32768
	ds_read_b128 v[222:225], v191 offset:33792
	ds_read_b128 v[226:229], v190 offset:32768
	ds_read_b128 v[230:233], v190 offset:33792
	ds_read_b128 v[234:237], v189 offset:32768
	ds_read_b128 v[238:241], v189 offset:33792
	s_waitcnt vmcnt(2)
	s_barrier
	s_waitcnt lgkmcnt(0)
	s_setprio 1
	s_waitcnt lgkmcnt(0)
	v_mfma_f32_16x16x32_bf16 v[28:31], v[12:15], v[140:143], v[124:127]
	v_mfma_f32_16x16x32_bf16 v[84:87], v[24:27], v[140:143], v[120:123]
	v_mfma_f32_16x16x32_bf16 v[88:91], v[12:15], v[218:221], v[116:119]
	v_mfma_f32_16x16x32_bf16 v[92:95], v[24:27], v[218:221], v[112:115]
	v_mfma_f32_16x16x32_bf16 v[108:111], v[12:15], v[226:229], v[108:111]
	v_mfma_f32_16x16x32_bf16 v[104:107], v[24:27], v[226:229], v[104:107]
	v_mfma_f32_16x16x32_bf16 v[100:103], v[12:15], v[234:237], v[100:103]
	v_mfma_f32_16x16x32_bf16 v[96:99], v[24:27], v[234:237], v[96:99]
	v_mfma_f32_16x16x32_bf16 v[152:155], v[8:11], v[148:151], v[28:31]
	v_mfma_f32_16x16x32_bf16 v[144:147], v[80:83], v[148:151], v[84:87]
	v_mfma_f32_16x16x32_bf16 v[136:139], v[8:11], v[222:225], v[88:91]
	v_mfma_f32_16x16x32_bf16 v[128:131], v[80:83], v[222:225], v[92:95]
	v_mfma_f32_16x16x32_bf16 v[120:123], v[8:11], v[230:233], v[108:111]
	v_mfma_f32_16x16x32_bf16 v[112:115], v[80:83], v[230:233], v[104:107]
	v_mfma_f32_16x16x32_bf16 v[104:107], v[8:11], v[238:241], v[100:103]
	v_mfma_f32_16x16x32_bf16 v[28:31], v[80:83], v[238:241], v[96:99]
	s_setprio 0
	s_barrier
	ds_read_b128 v[92:95], v132
	ds_read_b128 v[84:87], v132 offset:1024
	ds_read_b128 v[96:99], v132 offset:2048
	ds_read_b128 v[88:91], v132 offset:3072
	s_waitcnt vmcnt(0)
	s_barrier
	s_waitcnt lgkmcnt(0)
	s_setprio 1
	s_waitcnt lgkmcnt(0)
	v_mfma_f32_16x16x32_bf16 v[100:103], v[92:95], v[140:143], v[156:159]
	v_mfma_f32_16x16x32_bf16 v[108:111], v[96:99], v[140:143], v[160:163]
	v_mfma_f32_16x16x32_bf16 v[116:119], v[92:95], v[218:221], v[194:197]
	v_mfma_f32_16x16x32_bf16 v[124:127], v[96:99], v[218:221], v[198:201]
	v_mfma_f32_16x16x32_bf16 v[160:163], v[92:95], v[226:229], v[202:205]
	v_mfma_f32_16x16x32_bf16 v[194:197], v[96:99], v[226:229], v[206:209]
	v_mfma_f32_16x16x32_bf16 v[198:201], v[92:95], v[234:237], v[210:213]
	v_mfma_f32_16x16x32_bf16 v[202:205], v[96:99], v[234:237], v[214:217]
	v_mfma_f32_16x16x32_bf16 v[156:159], v[84:87], v[148:151], v[100:103]
	v_mfma_f32_16x16x32_bf16 v[148:151], v[88:91], v[148:151], v[108:111]
	v_mfma_f32_16x16x32_bf16 v[140:143], v[84:87], v[222:225], v[116:119]
	v_mfma_f32_16x16x32_bf16 v[132:135], v[88:91], v[222:225], v[124:127]
	v_mfma_f32_16x16x32_bf16 v[124:127], v[84:87], v[230:233], v[160:163]
	v_mfma_f32_16x16x32_bf16 v[116:119], v[88:91], v[230:233], v[194:197]
	v_mfma_f32_16x16x32_bf16 v[108:111], v[84:87], v[238:241], v[198:201]
	v_mfma_f32_16x16x32_bf16 v[100:103], v[88:91], v[238:241], v[202:205]
	s_setprio 0
	s_lshl_b64 s[66:67], s[64:65], 2
	s_barrier
	v_mbcnt_lo_u32_b32 v162, -1, 0
	v_mbcnt_hi_u32_b32 v162, -1, v162
	s_add_u32 s66, s87, s66
	v_add_u32_e32 v160, s76, v162
	s_addc_u32 s67, s88, s67
	v_and_b32_e32 v164, 0x100, v160
	v_and_b32_e32 v162, 15, v162
	v_lshl_add_u64 v[160:161], s[66:67], 0, v[164:165]
	v_lshlrev_b32_e32 v164, 2, v162
	v_lshl_add_u64 v[160:161], v[160:161], 0, v[164:165]
	global_load_dword v178, v[160:161], off
	global_load_dword v176, v[160:161], off offset:64
	global_load_dword v174, v[160:161], off offset:128
	global_load_dword v164, v[160:161], off offset:192
	global_load_dword v172, v[160:161], off offset:512
	global_load_dword v170, v[160:161], off offset:576
	global_load_dword v168, v[160:161], off offset:640
	global_load_dword v166, v[160:161], off offset:704
	v_mbcnt_lo_u32_b32 v194, -1, 0
	v_mbcnt_hi_u32_b32 v194, -1, v194
	s_mov_b64 s[66:67], -1
	v_add_u32_e32 v160, s76, v194
	v_bfe_u32 v161, v160, 8, 1
	v_ashrrev_i32_e32 v196, 6, v160
	v_bfe_u32 v160, v194, 4, 2
	v_and_b32_e32 v198, 3, v196
	v_and_b32_e32 v195, 15, v194
	s_cmp_gt_i32 s74, 1
	v_lshlrev_b32_e32 v193, 6, v161
	v_lshlrev_b32_e32 v197, 4, v160
	s_cbranch_scc0 .LBB0_113
	v_lshlrev_b32_e32 v161, 6, v198
	v_or3_b32 v160, v193, v195, s64
	v_or3_b32 v161, v161, v197, s62
	v_lshl_add_u32 v199, v160, 12, v161
	s_waitcnt vmcnt(0)
	v_mul_f32_e32 v160, v178, v178
	v_pk_mul_f32 v[200:201], v[152:153], v[160:161] op_sel_hi:[1,0]
	v_pk_mul_f32 v[162:163], v[154:155], v[160:161] op_sel_hi:[1,0]
	v_pk_mul_f32 v[202:203], v[158:159], v[160:161] op_sel_hi:[1,0]
	v_pk_mul_f32 v[204:205], v[156:157], v[160:161] op_sel_hi:[1,0]
	v_mul_f32_e32 v160, v144, v200
	v_mul_f32_e32 v161, v145, v201
	v_cvt_pk_bf16_f32 v160, v160, v161
	v_mul_f32_e32 v161, v146, v162
	v_mul_f32_e32 v162, v147, v163
	v_cvt_pk_bf16_f32 v161, v161, v162
	v_mul_f32_e32 v162, v148, v204
	v_mul_f32_e32 v163, v149, v205
	v_cvt_pk_bf16_f32 v162, v162, v163
	v_mul_f32_e32 v163, v150, v202
	v_mul_f32_e32 v200, v151, v203
	v_cvt_pk_bf16_f32 v163, v163, v200
	global_store_dwordx4 v199, v[160:163], s[6:7]
	v_add_u32_e32 v206, 0x10000, v199
	s_mov_b64 s[66:67], 0
	v_mul_f32_e32 v160, v176, v176
	v_pk_mul_f32 v[200:201], v[136:137], v[160:161] op_sel_hi:[1,0]
	v_pk_mul_f32 v[162:163], v[138:139], v[160:161] op_sel_hi:[1,0]
	v_pk_mul_f32 v[202:203], v[142:143], v[160:161] op_sel_hi:[1,0]
	v_pk_mul_f32 v[204:205], v[140:141], v[160:161] op_sel_hi:[1,0]
	v_mul_f32_e32 v160, v128, v200
	v_mul_f32_e32 v161, v129, v201
	v_cvt_pk_bf16_f32 v160, v160, v161
	v_mul_f32_e32 v161, v130, v162
	v_mul_f32_e32 v162, v131, v163
	v_cvt_pk_bf16_f32 v161, v161, v162
	v_mul_f32_e32 v162, v132, v204
	v_mul_f32_e32 v163, v133, v205
	v_cvt_pk_bf16_f32 v162, v162, v163
	v_mul_f32_e32 v163, v134, v202
	v_mul_f32_e32 v200, v135, v203
	v_cvt_pk_bf16_f32 v163, v163, v200
	global_store_dwordx4 v206, v[160:163], s[6:7]
	v_add_u32_e32 v206, 0x20000, v199
	v_add_u32_e32 v199, 0x30000, v199
	v_mul_f32_e32 v160, v174, v174
	v_pk_mul_f32 v[200:201], v[120:121], v[160:161] op_sel_hi:[1,0]
	v_pk_mul_f32 v[162:163], v[122:123], v[160:161] op_sel_hi:[1,0]
	v_pk_mul_f32 v[202:203], v[126:127], v[160:161] op_sel_hi:[1,0]
	v_pk_mul_f32 v[204:205], v[124:125], v[160:161] op_sel_hi:[1,0]
	v_mul_f32_e32 v160, v112, v200
	v_mul_f32_e32 v161, v113, v201
	v_cvt_pk_bf16_f32 v160, v160, v161
	v_mul_f32_e32 v161, v114, v162
	v_mul_f32_e32 v162, v115, v163
	v_cvt_pk_bf16_f32 v161, v161, v162
	v_mul_f32_e32 v162, v116, v204
	v_mul_f32_e32 v163, v117, v205
	v_cvt_pk_bf16_f32 v162, v162, v163
	v_mul_f32_e32 v163, v118, v202
	v_mul_f32_e32 v200, v119, v203
	v_cvt_pk_bf16_f32 v163, v163, v200
	global_store_dwordx4 v206, v[160:163], s[6:7]
	s_nop 1
	v_mul_f32_e32 v160, v164, v164
	v_pk_mul_f32 v[200:201], v[104:105], v[160:161] op_sel_hi:[1,0]
	v_pk_mul_f32 v[162:163], v[106:107], v[160:161] op_sel_hi:[1,0]
	v_pk_mul_f32 v[202:203], v[110:111], v[160:161] op_sel_hi:[1,0]
	v_pk_mul_f32 v[204:205], v[108:109], v[160:161] op_sel_hi:[1,0]
	v_mul_f32_e32 v160, v28, v200
	v_mul_f32_e32 v161, v29, v201
	v_cvt_pk_bf16_f32 v160, v160, v161
	v_mul_f32_e32 v161, v30, v162
	v_mul_f32_e32 v162, v31, v163
	v_cvt_pk_bf16_f32 v161, v161, v162
	v_mul_f32_e32 v162, v100, v204
	v_mul_f32_e32 v163, v101, v205
	v_cvt_pk_bf16_f32 v162, v162, v163
	v_mul_f32_e32 v163, v102, v202
	v_mul_f32_e32 v200, v103, v203
	v_cvt_pk_bf16_f32 v163, v163, v200

.LBB0_177:
	v_bfe_i32 v5, v136, 27, 1
	v_lshlrev_b32_e32 v135, 4, v136
	v_lshrrev_b32_e32 v5, 22, v5
	v_add_u32_e32 v5, v135, v5
	v_and_b32_e32 v5, 0xfffffc00, v5
	v_sub_u32_e32 v5, v135, v5
	v_lshrrev_b32_e32 v6, 4, v5
	v_bitop3_b32 v5, v6, v5, 32 bitop3:0x6c
	v_ashrrev_i32_e32 v6, 31, v5
	v_lshrrev_b32_e32 v6, 26, v6
	v_add_u32_e32 v6, v5, v6
	v_ashrrev_i32_e32 v157, 6, v6
	v_and_b32_e32 v6, 0xc0, v6
	v_sub_u32_e32 v5, v5, v6
	v_ashrrev_i16_sdwa v5, v134, sext(v5) dst_sel:DWORD dst_unused:UNUSED_PAD src0_sel:DWORD src1_sel:BYTE_0
	v_and_b32_e32 v2, 15, v0
	v_and_b32_e32 v3, 48, v0
	v_bfe_i32 v158, v5, 0, 16
	v_and_b32_e32 v5, 32, v0
	v_lshlrev_b32_e32 v8, 2, v0
	v_lshlrev_b32_e32 v0, 6, v0
	s_movk_i32 s65, 0x3f0
	v_lshlrev_b32_e32 v2, 6, v2
	v_and_b32_e32 v8, 32, v8
	v_and_b32_e32 v0, 0x3c0, v0
	v_ashrrev_i32_e32 v4, 31, v136
	v_bitop3_b32 v5, v135, v5, s65 bitop3:0x6c
	v_or_b32_e32 v7, v2, v3
	v_bitop3_b32 v2, v2, v8, v3 bitop3:0x36
	v_bitop3_b32 v3, v0, v8, v3 bitop3:0x36
	v_lshlrev_b32_e32 v0, 11, v136
	v_lshrrev_b32_e32 v4, 26, v4
	v_and_or_b32 v0, v0, s76, v5
	v_lshlrev_b32_e32 v5, 3, v136
	s_bfe_u32 s64, s85, 0x30003
	v_add_u32_e32 v4, v136, v4
	s_mov_b32 s65, 0x14000
	v_and_b32_e32 v5, 0xfffffc00, v5
	s_lshl_b32 s24, s64, 14
	v_ashrrev_i32_e32 v156, 6, v4
	v_bitop3_b32 v10, v7, s65, v8 bitop3:0xde
	s_mov_b32 s65, 0x1c000
	v_add_u32_e32 v128, v0, v5
	v_bitop3_b32 v9, v7, s74, v8 bitop3:0xde
	v_bitop3_b32 v11, v7, s75, v8 bitop3:0xde
	v_bitop3_b32 v7, v7, s65, v8 bitop3:0xde
	v_lshl_add_u64 v[130:131], s[24:25], 0, v[128:129]
	v_lshlrev_b32_e32 v0, 15, v156
	s_lshl_b32 s24, s85, 17
	s_and_b32 s65, s85, 7
	v_and_b32_e32 v0, 0xffff0000, v0
	s_and_b32 s24, s24, 0x1800000
	s_lshl_b32 s65, s65, 20
	v_lshl_add_u32 v0, v157, 12, v0
	s_or_b32 s24, s24, s65
	v_lshlrev_b32_e32 v6, 6, v136
	v_lshlrev_b32_e32 v1, 13, v1
	v_and_or_b32 v0, v4, 64, v0
	s_add_u32 s66, s24, s90
	v_and_b32_e32 v6, 0x3000, v6
	v_or_b32_e32 v8, 0x800, v1
	v_or_b32_e32 v12, 0x1000, v1
	v_or_b32_e32 v13, 0x1800, v1
	v_lshl_add_u32 v128, v158, 1, v0
	s_addc_u32 s67, 0, 0
	v_mov_b32_e32 v0, 0
	v_lshl_add_u64 v[132:133], s[66:67], 0, v[128:129]
	s_mov_b32 s24, -2
	v_add_u32_e32 v162, v9, v6
	v_add_u32_e32 v153, v2, v1
	v_add_u32_e32 v152, v3, v8
	v_add_u32_e32 v151, v3, v12
	v_add_u32_e32 v150, v3, v13
	v_add_u32_e32 v161, 0xc000, v135
	v_add_u32_e32 v160, 0xe000, v135
	v_add_u32_e32 v159, v10, v6
	v_add_u32_e32 v149, 0x10000, v135
	v_add_u32_e32 v148, 0x12000, v135
	v_add_u32_e32 v147, 0x2000, v135
	v_add_u32_e32 v146, 0x14000, v135
	v_add_u32_e32 v145, 0x16000, v135
	v_add_u32_e32 v155, v11, v6
	v_add_u32_e32 v144, 0x4000, v135
	v_add_u32_e32 v143, 0x6000, v135
	v_add_u32_e32 v154, v7, v6
	v_add_u32_e32 v142, 0x18000, v135
	v_add_u32_e32 v141, 0x1a000, v135
	v_add_u32_e32 v140, 0x8000, v135
	v_add_u32_e32 v139, 0xa000, v135
	v_add_u32_e32 v138, 0x1c000, v135
	v_add_u32_e32 v137, 0x1e000, v135
	v_mov_b32_e32 v1, v0
	v_mov_b32_e32 v2, v0
	v_mov_b32_e32 v3, v0
	v_mov_b32_e32 v4, v0
	v_mov_b32_e32 v5, v0
	v_mov_b32_e32 v6, v0
	v_mov_b32_e32 v7, v0
	v_mov_b32_e32 v8, v0
	v_mov_b32_e32 v9, v0
	v_mov_b32_e32 v10, v0
	v_mov_b32_e32 v11, v0
	v_mov_b32_e32 v12, v0
	v_mov_b32_e32 v13, v0
	v_mov_b32_e32 v14, v0
	v_mov_b32_e32 v15, v0
	v_mov_b32_e32 v16, v0
	v_mov_b32_e32 v17, v0
	v_mov_b32_e32 v18, v0
	v_mov_b32_e32 v19, v0
	v_mov_b32_e32 v20, v0
	v_mov_b32_e32 v21, v0
	v_mov_b32_e32 v22, v0
	v_mov_b32_e32 v23, v0
	v_mov_b32_e32 v24, v0
	v_mov_b32_e32 v25, v0
	v_mov_b32_e32 v26, v0
	v_mov_b32_e32 v27, v0
	v_mov_b32_e32 v28, v0
	v_mov_b32_e32 v29, v0
	v_mov_b32_e32 v30, v0
	v_mov_b32_e32 v31, v0
	v_mov_b32_e32 v32, v0
	v_mov_b32_e32 v33, v0
	v_mov_b32_e32 v34, v0
	v_mov_b32_e32 v35, v0
	v_mov_b32_e32 v36, v0
	v_mov_b32_e32 v37, v0
	v_mov_b32_e32 v38, v0
	v_mov_b32_e32 v39, v0
	v_mov_b32_e32 v40, v0
	v_mov_b32_e32 v41, v0
	v_mov_b32_e32 v42, v0
	v_mov_b32_e32 v43, v0
	v_mov_b32_e32 v44, v0
	v_mov_b32_e32 v45, v0
	v_mov_b32_e32 v46, v0
	v_mov_b32_e32 v47, v0
	v_mov_b32_e32 v48, v0
	v_mov_b32_e32 v49, v0
	v_mov_b32_e32 v50, v0
	v_mov_b32_e32 v51, v0
	v_mov_b32_e32 v52, v0
	v_mov_b32_e32 v53, v0
	v_mov_b32_e32 v54, v0
	v_mov_b32_e32 v55, v0
	v_mov_b32_e32 v56, v0
	v_mov_b32_e32 v57, v0
	v_mov_b32_e32 v58, v0
	v_mov_b32_e32 v59, v0
	v_mov_b32_e32 v60, v0
	v_mov_b32_e32 v61, v0
	v_mov_b32_e32 v62, v0
	v_mov_b32_e32 v63, v0
	v_mov_b32_e32 v64, v0
	v_mov_b32_e32 v65, v0
	v_mov_b32_e32 v66, v0
	v_mov_b32_e32 v67, v0
	v_mov_b32_e32 v68, v0
	v_mov_b32_e32 v69, v0
	v_mov_b32_e32 v70, v0
	v_mov_b32_e32 v71, v0
	v_mov_b32_e32 v72, v0
	v_mov_b32_e32 v73, v0
	v_mov_b32_e32 v74, v0
	v_mov_b32_e32 v75, v0
	v_mov_b32_e32 v76, v0
	v_mov_b32_e32 v77, v0
	v_mov_b32_e32 v78, v0
	v_mov_b32_e32 v79, v0
	v_mov_b32_e32 v80, v0
	v_mov_b32_e32 v81, v0
	v_mov_b32_e32 v82, v0
	v_mov_b32_e32 v83, v0
	v_mov_b32_e32 v84, v0
	v_mov_b32_e32 v85, v0
	v_mov_b32_e32 v86, v0
	v_mov_b32_e32 v87, v0
	v_mov_b32_e32 v88, v0
	v_mov_b32_e32 v89, v0
	v_mov_b32_e32 v90, v0
	v_mov_b32_e32 v91, v0
	v_mov_b32_e32 v92, v0
	v_mov_b32_e32 v93, v0
	v_mov_b32_e32 v94, v0
	v_mov_b32_e32 v95, v0
	v_mov_b32_e32 v96, v0
	v_mov_b32_e32 v97, v0
	v_mov_b32_e32 v98, v0
	v_mov_b32_e32 v99, v0
	v_mov_b32_e32 v100, v0
	v_mov_b32_e32 v101, v0
	v_mov_b32_e32 v102, v0
	v_mov_b32_e32 v103, v0
	v_mov_b32_e32 v104, v0
	v_mov_b32_e32 v105, v0
	v_mov_b32_e32 v106, v0
	v_mov_b32_e32 v107, v0
	v_mov_b32_e32 v108, v0
	v_mov_b32_e32 v109, v0
	v_mov_b32_e32 v110, v0
	v_mov_b32_e32 v111, v0
	v_mov_b32_e32 v112, v0
	v_mov_b32_e32 v113, v0
	v_mov_b32_e32 v114, v0
	v_mov_b32_e32 v115, v0
	v_mov_b32_e32 v116, v0
	v_mov_b32_e32 v117, v0
	v_mov_b32_e32 v118, v0
	v_mov_b32_e32 v119, v0
	v_mov_b32_e32 v120, v0
	v_mov_b32_e32 v121, v0
	v_mov_b32_e32 v122, v0
	v_mov_b32_e32 v123, v0
	v_mov_b32_e32 v124, v0
	v_mov_b32_e32 v125, v0
	v_mov_b32_e32 v126, v0
	v_mov_b32_e32 v127, v0
	s_barrier
	v_readlane_b32 s98, v242, 1
	s_lshl_b32 s98, s98, 10
	v_lshl_add_u64 v[228:229], s[50:51], 0, v[132:133]
	s_mov_b64 s[66:67], 0xe080080
	s_add_i32 s65, s98, 0xc000
	v_lshl_add_u64 v[166:167], v[228:229], 0, s[66:67]
	s_mov_b32 m0, s65
	s_mov_b64 s[66:67], 0xe0c0080
	s_add_i32 s65, s98, 0xe000
	global_load_lds_dwordx4 v[166:167], off
	v_lshl_add_u64 v[166:167], v[228:229], 0, s[66:67]
	s_mov_b32 m0, s65
	s_nop 0
	global_load_lds_dwordx4 v[166:167], off
	ds_read_b128 v[164:167], v162
	ds_read_b128 v[168:171], v162 offset:1024
	ds_read_b128 v[172:175], v162 offset:2048
	ds_read_b128 v[176:179], v162 offset:3072
.LBB0_178:
	ds_read_b128 v[180:183], v153
	ds_read_b128 v[184:187], v153 offset:1024
	ds_read_b128 v[188:191], v152
	ds_read_b128 v[192:195], v152 offset:1024
	ds_read_b128 v[196:199], v151
	ds_read_b128 v[200:203], v151 offset:1024
	ds_read_b128 v[204:207], v150
	ds_read_b128 v[208:211], v150 offset:1024
	s_waitcnt lgkmcnt(8)
	s_waitcnt vmcnt(10)
	s_barrier
	s_waitcnt lgkmcnt(0)
	s_waitcnt lgkmcnt(0)
	v_mfma_f32_16x16x32_bf16 v[124:127], v[164:167], v[180:183], v[124:127]
	v_mfma_f32_16x16x32_bf16 v[120:123], v[172:175], v[180:183], v[120:123]
	v_mfma_f32_16x16x32_bf16 v[116:119], v[164:167], v[188:191], v[116:119]
	v_mfma_f32_16x16x32_bf16 v[112:115], v[172:175], v[188:191], v[112:115]
	v_mfma_f32_16x16x32_bf16 v[108:111], v[164:167], v[196:199], v[108:111]
	v_mfma_f32_16x16x32_bf16 v[104:107], v[172:175], v[196:199], v[104:107]
	v_mfma_f32_16x16x32_bf16 v[100:103], v[164:167], v[204:207], v[100:103]
	v_mfma_f32_16x16x32_bf16 v[96:99], v[172:175], v[204:207], v[96:99]
	v_mfma_f32_16x16x32_bf16 v[124:127], v[168:171], v[184:187], v[124:127]
	v_mfma_f32_16x16x32_bf16 v[120:123], v[176:179], v[184:187], v[120:123]
	v_mfma_f32_16x16x32_bf16 v[116:119], v[168:171], v[192:195], v[116:119]
	v_mfma_f32_16x16x32_bf16 v[112:115], v[176:179], v[192:195], v[112:115]
	v_mfma_f32_16x16x32_bf16 v[108:111], v[168:171], v[200:203], v[108:111]
	v_mfma_f32_16x16x32_bf16 v[104:107], v[176:179], v[200:203], v[104:107]
	v_mfma_f32_16x16x32_bf16 v[100:103], v[168:171], v[208:211], v[100:103]
	v_mfma_f32_16x16x32_bf16 v[96:99], v[176:179], v[208:211], v[96:99]
	s_barrier
	v_lshl_add_u64 v[230:231], s[50:51], 0, v[130:131]
	s_mov_b64 s[66:67], 0x1880000
	s_add_i32 s65, s98, 0x10000
	v_lshl_add_u64 v[232:233], v[230:231], 0, s[66:67]
	s_mov_b32 m0, s65
	s_mov_b64 s[66:67], 0x1881000
	s_add_i32 s65, s98, 0x12000
	ds_read_b128 v[212:215], v159
	ds_read_b128 v[216:219], v159 offset:1024
	ds_read_b128 v[220:223], v159 offset:2048
	ds_read_b128 v[224:227], v159 offset:3072
	global_load_lds_dwordx4 v[232:233], off
	v_lshl_add_u64 v[232:233], v[230:231], 0, s[66:67]
	s_mov_b32 m0, s65
	s_nop 0
	global_load_lds_dwordx4 v[232:233], off
	s_mov_b64 s[66:67], 0xe000100
	s_mov_b32 s65, s98
	v_lshl_add_u64 v[232:233], v[228:229], 0, s[66:67]
	s_mov_b32 m0, s65
	s_mov_b64 s[66:67], 0xe040100
	s_add_i32 s65, s98, 0x2000
	global_load_lds_dwordx4 v[232:233], off
	v_lshl_add_u64 v[232:233], v[228:229], 0, s[66:67]
	s_mov_b32 m0, s65
	s_nop 0
	global_load_lds_dwordx4 v[232:233], off
	s_waitcnt vmcnt(12)
	s_barrier
	s_waitcnt lgkmcnt(0)
	s_waitcnt lgkmcnt(0)
	v_mfma_f32_16x16x32_bf16 v[92:95], v[212:215], v[180:183], v[92:95]
	v_mfma_f32_16x16x32_bf16 v[88:91], v[220:223], v[180:183], v[88:91]
	v_mfma_f32_16x16x32_bf16 v[84:87], v[212:215], v[188:191], v[84:87]
	v_mfma_f32_16x16x32_bf16 v[80:83], v[220:223], v[188:191], v[80:83]
	v_mfma_f32_16x16x32_bf16 v[76:79], v[212:215], v[196:199], v[76:79]
	v_mfma_f32_16x16x32_bf16 v[72:75], v[220:223], v[196:199], v[72:75]
	v_mfma_f32_16x16x32_bf16 v[68:71], v[212:215], v[204:207], v[68:71]
	v_mfma_f32_16x16x32_bf16 v[64:67], v[220:223], v[204:207], v[64:67]
	v_mfma_f32_16x16x32_bf16 v[92:95], v[216:219], v[184:187], v[92:95]
	v_mfma_f32_16x16x32_bf16 v[88:91], v[224:227], v[184:187], v[88:91]
	v_mfma_f32_16x16x32_bf16 v[84:87], v[216:219], v[192:195], v[84:87]
	v_mfma_f32_16x16x32_bf16 v[80:83], v[224:227], v[192:195], v[80:83]
	v_mfma_f32_16x16x32_bf16 v[76:79], v[216:219], v[200:203], v[76:79]
	v_mfma_f32_16x16x32_bf16 v[72:75], v[224:227], v[200:203], v[72:75]
	v_mfma_f32_16x16x32_bf16 v[68:71], v[216:219], v[208:211], v[68:71]
	v_mfma_f32_16x16x32_bf16 v[64:67], v[224:227], v[208:211], v[64:67]
	s_barrier
	ds_read_b128 v[180:183], v153 offset:16384
	ds_read_b128 v[184:187], v153 offset:17408
	ds_read_b128 v[188:191], v152 offset:16384
	ds_read_b128 v[192:195], v152 offset:17408
	ds_read_b128 v[196:199], v151 offset:16384
	ds_read_b128 v[200:203], v151 offset:17408
	ds_read_b128 v[204:207], v150 offset:16384
	ds_read_b128 v[208:211], v150 offset:17408
	s_mov_b64 s[66:67], 0x1882000
	s_add_i32 s65, s98, 0x14000
	v_lshl_add_u64 v[232:233], v[230:231], 0, s[66:67]
	s_mov_b32 m0, s65
	s_mov_b64 s[66:67], 0x1883000
	s_add_i32 s65, s98, 0x16000
	global_load_lds_dwordx4 v[232:233], off
	v_lshl_add_u64 v[232:233], v[230:231], 0, s[66:67]
	s_mov_b32 m0, s65
	s_nop 0
	global_load_lds_dwordx4 v[232:233], off
	s_waitcnt vmcnt(12)
	s_barrier
	s_waitcnt lgkmcnt(0)
	s_waitcnt lgkmcnt(0)
	v_mfma_f32_16x16x32_bf16 v[60:63], v[164:167], v[180:183], v[60:63]
	v_mfma_f32_16x16x32_bf16 v[56:59], v[172:175], v[180:183], v[56:59]
	v_mfma_f32_16x16x32_bf16 v[52:55], v[164:167], v[188:191], v[52:55]
	v_mfma_f32_16x16x32_bf16 v[48:51], v[172:175], v[188:191], v[48:51]
	v_mfma_f32_16x16x32_bf16 v[44:47], v[164:167], v[196:199], v[44:47]
	v_mfma_f32_16x16x32_bf16 v[40:43], v[172:175], v[196:199], v[40:43]
	v_mfma_f32_16x16x32_bf16 v[36:39], v[164:167], v[204:207], v[36:39]
	v_mfma_f32_16x16x32_bf16 v[32:35], v[172:175], v[204:207], v[32:35]
	v_mfma_f32_16x16x32_bf16 v[60:63], v[168:171], v[184:187], v[60:63]
	v_mfma_f32_16x16x32_bf16 v[56:59], v[176:179], v[184:187], v[56:59]
	v_mfma_f32_16x16x32_bf16 v[52:55], v[168:171], v[192:195], v[52:55]
	v_mfma_f32_16x16x32_bf16 v[48:51], v[176:179], v[192:195], v[48:51]
	v_mfma_f32_16x16x32_bf16 v[44:47], v[168:171], v[200:203], v[44:47]
	v_mfma_f32_16x16x32_bf16 v[40:43], v[176:179], v[200:203], v[40:43]
	v_mfma_f32_16x16x32_bf16 v[36:39], v[168:171], v[208:211], v[36:39]
	v_mfma_f32_16x16x32_bf16 v[32:35], v[176:179], v[208:211], v[32:35]
	s_barrier
	s_add_i32 s65, s98, 0x4000
	v_lshl_add_u64 v[166:167], v[228:229], 0, s[26:27]
	s_mov_b32 m0, s65
	s_add_i32 s65, s98, 0x6000
	global_load_lds_dwordx4 v[166:167], off
	v_lshl_add_u64 v[166:167], v[228:229], 0, s[28:29]
	s_mov_b32 m0, s65
	s_nop 0
	global_load_lds_dwordx4 v[166:167], off
	ds_read_b128 v[164:167], v155
	ds_read_b128 v[168:171], v155 offset:1024
	ds_read_b128 v[172:175], v155 offset:2048
	ds_read_b128 v[176:179], v155 offset:3072
	s_waitcnt vmcnt(12)
	s_barrier
	v_mfma_f32_16x16x32_bf16 v[28:31], v[212:215], v[180:183], v[28:31]
	v_mfma_f32_16x16x32_bf16 v[24:27], v[220:223], v[180:183], v[24:27]
	v_mfma_f32_16x16x32_bf16 v[20:23], v[212:215], v[188:191], v[20:23]
	v_mfma_f32_16x16x32_bf16 v[16:19], v[220:223], v[188:191], v[16:19]
	v_mfma_f32_16x16x32_bf16 v[12:15], v[212:215], v[196:199], v[12:15]
	v_mfma_f32_16x16x32_bf16 v[8:11], v[220:223], v[196:199], v[8:11]
	v_mfma_f32_16x16x32_bf16 v[4:7], v[212:215], v[204:207], v[4:7]
	v_mfma_f32_16x16x32_bf16 v[0:3], v[220:223], v[204:207], v[0:3]
	v_mfma_f32_16x16x32_bf16 v[28:31], v[216:219], v[184:187], v[28:31]
	v_mfma_f32_16x16x32_bf16 v[24:27], v[224:227], v[184:187], v[24:27]
	v_mfma_f32_16x16x32_bf16 v[20:23], v[216:219], v[192:195], v[20:23]
	v_mfma_f32_16x16x32_bf16 v[16:19], v[224:227], v[192:195], v[16:19]
	v_mfma_f32_16x16x32_bf16 v[12:15], v[216:219], v[200:203], v[12:15]
	v_mfma_f32_16x16x32_bf16 v[8:11], v[224:227], v[200:203], v[8:11]
	v_mfma_f32_16x16x32_bf16 v[4:7], v[216:219], v[208:211], v[4:7]
	v_mfma_f32_16x16x32_bf16 v[0:3], v[224:227], v[208:211], v[0:3]
	s_barrier
	ds_read_b128 v[180:183], v153 offset:32768
	ds_read_b128 v[184:187], v153 offset:33792
	ds_read_b128 v[188:191], v152 offset:32768
	ds_read_b128 v[192:195], v152 offset:33792
	ds_read_b128 v[196:199], v151 offset:32768
	ds_read_b128 v[200:203], v151 offset:33792
	ds_read_b128 v[204:207], v150 offset:32768
	ds_read_b128 v[208:211], v150 offset:33792
	s_waitcnt lgkmcnt(8)
	s_waitcnt vmcnt(10)
	s_barrier
	s_waitcnt lgkmcnt(0)
	s_waitcnt lgkmcnt(0)
	v_mfma_f32_16x16x32_bf16 v[124:127], v[164:167], v[180:183], v[124:127]
	v_mfma_f32_16x16x32_bf16 v[120:123], v[172:175], v[180:183], v[120:123]
	v_mfma_f32_16x16x32_bf16 v[116:119], v[164:167], v[188:191], v[116:119]
	v_mfma_f32_16x16x32_bf16 v[112:115], v[172:175], v[188:191], v[112:115]
	v_mfma_f32_16x16x32_bf16 v[108:111], v[164:167], v[196:199], v[108:111]
	v_mfma_f32_16x16x32_bf16 v[104:107], v[172:175], v[196:199], v[104:107]
	v_mfma_f32_16x16x32_bf16 v[100:103], v[164:167], v[204:207], v[100:103]
	v_mfma_f32_16x16x32_bf16 v[96:99], v[172:175], v[204:207], v[96:99]
	v_mfma_f32_16x16x32_bf16 v[124:127], v[168:171], v[184:187], v[124:127]
	v_mfma_f32_16x16x32_bf16 v[120:123], v[176:179], v[184:187], v[120:123]
	v_mfma_f32_16x16x32_bf16 v[116:119], v[168:171], v[192:195], v[116:119]
	v_mfma_f32_16x16x32_bf16 v[112:115], v[176:179], v[192:195], v[112:115]
	v_mfma_f32_16x16x32_bf16 v[108:111], v[168:171], v[200:203], v[108:111]
	v_mfma_f32_16x16x32_bf16 v[104:107], v[176:179], v[200:203], v[104:107]
	v_mfma_f32_16x16x32_bf16 v[100:103], v[168:171], v[208:211], v[100:103]
	v_mfma_f32_16x16x32_bf16 v[96:99], v[176:179], v[208:211], v[96:99]
	s_barrier
	s_add_i32 s65, s98, 0x18000
	v_lshl_add_u64 v[232:233], v[230:231], 0, s[30:31]
	s_mov_b32 m0, s65
	s_add_i32 s65, s98, 0x1a000
	ds_read_b128 v[212:215], v154
	ds_read_b128 v[216:219], v154 offset:1024
	ds_read_b128 v[220:223], v154 offset:2048
	ds_read_b128 v[224:227], v154 offset:3072
	global_load_lds_dwordx4 v[232:233], off
	v_lshl_add_u64 v[232:233], v[230:231], 0, s[34:35]
	s_mov_b32 m0, s65
	s_nop 0
	global_load_lds_dwordx4 v[232:233], off
	s_add_i32 s65, s98, 0x8000
	v_lshl_add_u64 v[232:233], v[228:229], 0, s[40:41]
	s_mov_b32 m0, s65
	s_add_i32 s65, s98, 0xa000
	global_load_lds_dwordx4 v[232:233], off
	v_lshl_add_u64 v[228:229], v[228:229], 0, s[44:45]
	s_mov_b32 m0, s65
	s_nop 0
	global_load_lds_dwordx4 v[228:229], off
	s_waitcnt vmcnt(12)
	s_barrier
	s_waitcnt lgkmcnt(0)
	s_waitcnt lgkmcnt(0)
	v_mfma_f32_16x16x32_bf16 v[92:95], v[212:215], v[180:183], v[92:95]
	v_mfma_f32_16x16x32_bf16 v[88:91], v[220:223], v[180:183], v[88:91]
	v_mfma_f32_16x16x32_bf16 v[84:87], v[212:215], v[188:191], v[84:87]
	v_mfma_f32_16x16x32_bf16 v[80:83], v[220:223], v[188:191], v[80:83]
	v_mfma_f32_16x16x32_bf16 v[76:79], v[212:215], v[196:199], v[76:79]
	v_mfma_f32_16x16x32_bf16 v[72:75], v[220:223], v[196:199], v[72:75]
	v_mfma_f32_16x16x32_bf16 v[68:71], v[212:215], v[204:207], v[68:71]
	v_mfma_f32_16x16x32_bf16 v[64:67], v[220:223], v[204:207], v[64:67]
	v_mfma_f32_16x16x32_bf16 v[92:95], v[216:219], v[184:187], v[92:95]
	v_mfma_f32_16x16x32_bf16 v[88:91], v[224:227], v[184:187], v[88:91]
	v_mfma_f32_16x16x32_bf16 v[84:87], v[216:219], v[192:195], v[84:87]
	v_mfma_f32_16x16x32_bf16 v[80:83], v[224:227], v[192:195], v[80:83]
	v_mfma_f32_16x16x32_bf16 v[76:79], v[216:219], v[200:203], v[76:79]
	v_mfma_f32_16x16x32_bf16 v[72:75], v[224:227], v[200:203], v[72:75]
	v_mfma_f32_16x16x32_bf16 v[68:71], v[216:219], v[208:211], v[68:71]
	v_mfma_f32_16x16x32_bf16 v[64:67], v[224:227], v[208:211], v[64:67]
	s_barrier
	ds_read_b128 v[180:183], v153 offset:49152
	ds_read_b128 v[184:187], v153 offset:50176
	ds_read_b128 v[188:191], v152 offset:49152
	ds_read_b128 v[192:195], v152 offset:50176
	ds_read_b128 v[196:199], v151 offset:49152
	ds_read_b128 v[200:203], v151 offset:50176
	ds_read_b128 v[204:207], v150 offset:49152
	ds_read_b128 v[208:211], v150 offset:50176
	s_add_i32 s65, s98, 0x1c000
	v_lshl_add_u64 v[232:233], v[230:231], 0, s[46:47]
	s_mov_b32 m0, s65
	s_add_i32 s65, s98, 0x1e000
	global_load_lds_dwordx4 v[232:233], off
	v_lshl_add_u64 v[232:233], v[230:231], 0, s[56:57]
	s_mov_b32 m0, s65
	s_nop 0
	global_load_lds_dwordx4 v[232:233], off
	s_waitcnt vmcnt(12)
	s_barrier
	s_waitcnt lgkmcnt(0)
	s_waitcnt lgkmcnt(0)
	v_mfma_f32_16x16x32_bf16 v[60:63], v[164:167], v[180:183], v[60:63]
	v_mfma_f32_16x16x32_bf16 v[56:59], v[172:175], v[180:183], v[56:59]
	v_mfma_f32_16x16x32_bf16 v[52:55], v[164:167], v[188:191], v[52:55]
	v_mfma_f32_16x16x32_bf16 v[48:51], v[172:175], v[188:191], v[48:51]
	v_mfma_f32_16x16x32_bf16 v[44:47], v[164:167], v[196:199], v[44:47]
	v_mfma_f32_16x16x32_bf16 v[40:43], v[172:175], v[196:199], v[40:43]
	v_mfma_f32_16x16x32_bf16 v[36:39], v[164:167], v[204:207], v[36:39]
	v_mfma_f32_16x16x32_bf16 v[32:35], v[172:175], v[204:207], v[32:35]
	v_mfma_f32_16x16x32_bf16 v[60:63], v[168:171], v[184:187], v[60:63]
	v_mfma_f32_16x16x32_bf16 v[56:59], v[176:179], v[184:187], v[56:59]
	v_mfma_f32_16x16x32_bf16 v[52:55], v[168:171], v[192:195], v[52:55]
	v_mfma_f32_16x16x32_bf16 v[48:51], v[176:179], v[192:195], v[48:51]
	v_mfma_f32_16x16x32_bf16 v[44:47], v[168:171], v[200:203], v[44:47]
	v_mfma_f32_16x16x32_bf16 v[40:43], v[176:179], v[200:203], v[40:43]
	v_mfma_f32_16x16x32_bf16 v[36:39], v[168:171], v[208:211], v[36:39]
	v_mfma_f32_16x16x32_bf16 v[32:35], v[176:179], v[208:211], v[32:35]
	s_barrier
	v_lshl_add_u64 v[132:133], v[132:133], 0, s[58:59]
	v_lshl_add_u64 v[228:229], s[50:51], 0, v[132:133]
	s_mov_b64 s[66:67], 0xe080080
	s_add_i32 s65, s98, 0xc000
	v_lshl_add_u64 v[166:167], v[228:229], 0, s[66:67]
	s_mov_b32 m0, s65
	s_mov_b64 s[66:67], 0xe0c0080
	s_add_i32 s65, s98, 0xe000
	global_load_lds_dwordx4 v[166:167], off
	v_lshl_add_u64 v[166:167], v[228:229], 0, s[66:67]
	s_mov_b32 m0, s65
	s_nop 0
	global_load_lds_dwordx4 v[166:167], off
	ds_read_b128 v[164:167], v162
	ds_read_b128 v[168:171], v162 offset:1024
	ds_read_b128 v[172:175], v162 offset:2048
	ds_read_b128 v[176:179], v162 offset:3072
	s_waitcnt vmcnt(12)
	s_barrier
	v_mfma_f32_16x16x32_bf16 v[28:31], v[212:215], v[180:183], v[28:31]
	v_mfma_f32_16x16x32_bf16 v[24:27], v[220:223], v[180:183], v[24:27]
	v_mfma_f32_16x16x32_bf16 v[20:23], v[212:215], v[188:191], v[20:23]
	v_mfma_f32_16x16x32_bf16 v[16:19], v[220:223], v[188:191], v[16:19]
	v_mfma_f32_16x16x32_bf16 v[12:15], v[212:215], v[196:199], v[12:15]
	v_mfma_f32_16x16x32_bf16 v[8:11], v[220:223], v[196:199], v[8:11]
	v_mfma_f32_16x16x32_bf16 v[4:7], v[212:215], v[204:207], v[4:7]
	v_mfma_f32_16x16x32_bf16 v[0:3], v[220:223], v[204:207], v[0:3]
	v_mfma_f32_16x16x32_bf16 v[28:31], v[216:219], v[184:187], v[28:31]
	v_mfma_f32_16x16x32_bf16 v[24:27], v[224:227], v[184:187], v[24:27]
	v_mfma_f32_16x16x32_bf16 v[20:23], v[216:219], v[192:195], v[20:23]
	v_mfma_f32_16x16x32_bf16 v[16:19], v[224:227], v[192:195], v[16:19]
	v_mfma_f32_16x16x32_bf16 v[12:15], v[216:219], v[200:203], v[12:15]
	v_mfma_f32_16x16x32_bf16 v[8:11], v[224:227], v[200:203], v[8:11]
	v_mfma_f32_16x16x32_bf16 v[4:7], v[216:219], v[208:211], v[4:7]
	v_mfma_f32_16x16x32_bf16 v[0:3], v[224:227], v[208:211], v[0:3]
	s_add_i32 s24, s24, 2
	v_lshl_add_u64 v[130:131], v[130:131], 0, s[10:11]
	s_cmp_lt_u32 s24, 28
	s_barrier
	s_cbranch_scc1 .LBB0_178
	s_lshl_b32 s24, s85, 5
	s_lshl_b32 s65, s85, 8
	s_and_b32 s24, s24, 0x1800
	s_and_b32 s65, s65, 0x700
	s_or_b32 s24, s65, s24
	v_lshlrev_b32_e32 v128, 3, v156
	v_lshlrev_b32_e32 v130, 5, v156
	v_and_b32_e32 v128, 0xffff0, v128
	v_and_b32_e32 v130, 32, v130
	s_lshl_b32 s65, s24, 12
	v_add_u32_e32 v130, v130, v158
	v_add_lshl_u32 v128, v157, v128, 12
	s_add_u32 s66, s68, s65
	v_lshl_add_u32 v128, v130, 1, v128
	s_addc_u32 s67, s69, 0
	v_lshl_add_u64 v[156:157], s[66:67], 0, v[128:129]
	v_readfirstlane_b32 s65, v161
	ds_read_b128 v[130:133], v162
	ds_read_b128 v[164:167], v162 offset:1024
	ds_read_b128 v[168:171], v162 offset:2048
	ds_read_b128 v[172:175], v162 offset:3072
	ds_read_b128 v[176:179], v153
	ds_read_b128 v[180:183], v153 offset:1024
	ds_read_b128 v[184:187], v152
	ds_read_b128 v[188:191], v152 offset:1024
	ds_read_b128 v[192:195], v151
	ds_read_b128 v[196:199], v151 offset:1024
	ds_read_b128 v[200:203], v150
	ds_read_b128 v[204:207], v150 offset:1024
	v_lshl_add_u64 v[162:163], v[156:157], 0, s[60:61]
	s_mov_b32 m0, s65
	v_readfirstlane_b32 s65, v160
	global_load_lds_dwordx4 v[162:163], off
	v_lshl_add_u64 v[156:157], v[156:157], 0, s[62:63]
	s_mov_b32 m0, s65
	s_nop 0
	global_load_lds_dwordx4 v[156:157], off
	s_waitcnt vmcnt(10)
	s_barrier
	s_waitcnt lgkmcnt(0)
	s_setprio 1
	s_waitcnt lgkmcnt(0)
	v_mfma_f32_16x16x32_bf16 v[124:127], v[130:133], v[176:179], v[124:127]
	v_mfma_f32_16x16x32_bf16 v[120:123], v[168:171], v[176:179], v[120:123]
	v_mfma_f32_16x16x32_bf16 v[116:119], v[130:133], v[184:187], v[116:119]
	v_mfma_f32_16x16x32_bf16 v[112:115], v[168:171], v[184:187], v[112:115]
	v_mfma_f32_16x16x32_bf16 v[108:111], v[130:133], v[192:195], v[108:111]
	v_mfma_f32_16x16x32_bf16 v[104:107], v[168:171], v[192:195], v[104:107]
	v_mfma_f32_16x16x32_bf16 v[100:103], v[130:133], v[200:203], v[100:103]
	v_mfma_f32_16x16x32_bf16 v[96:99], v[168:171], v[200:203], v[96:99]
	v_mfma_f32_16x16x32_bf16 v[124:127], v[164:167], v[180:183], v[124:127]
	v_mfma_f32_16x16x32_bf16 v[120:123], v[172:175], v[180:183], v[120:123]
	v_mfma_f32_16x16x32_bf16 v[116:119], v[164:167], v[188:191], v[116:119]
	v_mfma_f32_16x16x32_bf16 v[112:115], v[172:175], v[188:191], v[112:115]
	v_mfma_f32_16x16x32_bf16 v[108:111], v[164:167], v[196:199], v[108:111]
	v_mfma_f32_16x16x32_bf16 v[104:107], v[172:175], v[196:199], v[104:107]
	v_mfma_f32_16x16x32_bf16 v[100:103], v[164:167], v[204:207], v[100:103]
	v_mfma_f32_16x16x32_bf16 v[96:99], v[172:175], v[204:207], v[96:99]
	s_setprio 0
	s_barrier
	ds_read_b128 v[160:163], v159
	ds_read_b128 v[208:211], v159 offset:1024
	ds_read_b128 v[212:215], v159 offset:2048
	ds_read_b128 v[156:159], v159 offset:3072
	s_barrier
	s_waitcnt lgkmcnt(0)
	s_setprio 1
	s_waitcnt lgkmcnt(0)
	v_mfma_f32_16x16x32_bf16 v[92:95], v[160:163], v[176:179], v[92:95]
	v_mfma_f32_16x16x32_bf16 v[88:91], v[212:215], v[176:179], v[88:91]
	v_mfma_f32_16x16x32_bf16 v[84:87], v[160:163], v[184:187], v[84:87]
	v_mfma_f32_16x16x32_bf16 v[80:83], v[212:215], v[184:187], v[80:83]
	v_mfma_f32_16x16x32_bf16 v[76:79], v[160:163], v[192:195], v[76:79]
	v_mfma_f32_16x16x32_bf16 v[72:75], v[212:215], v[192:195], v[72:75]
	v_mfma_f32_16x16x32_bf16 v[68:71], v[160:163], v[200:203], v[68:71]
	v_mfma_f32_16x16x32_bf16 v[64:67], v[212:215], v[200:203], v[64:67]
	v_mfma_f32_16x16x32_bf16 v[176:179], v[208:211], v[180:183], v[92:95]
	v_mfma_f32_16x16x32_bf16 v[180:183], v[156:159], v[180:183], v[88:91]
	v_mfma_f32_16x16x32_bf16 v[184:187], v[208:211], v[188:191], v[84:87]
	v_mfma_f32_16x16x32_bf16 v[188:191], v[156:159], v[188:191], v[80:83]
	v_mfma_f32_16x16x32_bf16 v[192:195], v[208:211], v[196:199], v[76:79]
	v_mfma_f32_16x16x32_bf16 v[196:199], v[156:159], v[196:199], v[72:75]
	v_mfma_f32_16x16x32_bf16 v[200:203], v[208:211], v[204:207], v[68:71]
	v_mfma_f32_16x16x32_bf16 v[204:207], v[156:159], v[204:207], v[64:67]
	s_setprio 0
	s_barrier
	s_nop 0
	ds_read_b128 v[64:67], v153 offset:16384
	ds_read_b128 v[68:71], v153 offset:17408
	ds_read_b128 v[72:75], v152 offset:16384
	ds_read_b128 v[76:79], v152 offset:17408
	ds_read_b128 v[80:83], v151 offset:16384
	ds_read_b128 v[84:87], v151 offset:17408
	ds_read_b128 v[88:91], v150 offset:16384
	ds_read_b128 v[92:95], v150 offset:17408
	s_waitcnt vmcnt(4)
	s_barrier
	s_waitcnt lgkmcnt(0)
	s_setprio 1
	s_waitcnt lgkmcnt(0)
	v_mfma_f32_16x16x32_bf16 v[60:63], v[130:133], v[64:67], v[60:63]
	v_mfma_f32_16x16x32_bf16 v[56:59], v[168:171], v[64:67], v[56:59]
	v_mfma_f32_16x16x32_bf16 v[52:55], v[130:133], v[72:75], v[52:55]
	v_mfma_f32_16x16x32_bf16 v[48:51], v[168:171], v[72:75], v[48:51]
	v_mfma_f32_16x16x32_bf16 v[216:219], v[130:133], v[80:83], v[44:47]
	v_mfma_f32_16x16x32_bf16 v[220:223], v[168:171], v[80:83], v[40:43]
	v_mfma_f32_16x16x32_bf16 v[130:133], v[130:133], v[88:91], v[36:39]
	v_mfma_f32_16x16x32_bf16 v[168:171], v[168:171], v[88:91], v[32:35]
	v_mfma_f32_16x16x32_bf16 v[32:35], v[164:167], v[68:71], v[60:63]
	v_mfma_f32_16x16x32_bf16 v[36:39], v[172:175], v[68:71], v[56:59]
	v_mfma_f32_16x16x32_bf16 v[40:43], v[164:167], v[76:79], v[52:55]
	v_mfma_f32_16x16x32_bf16 v[44:47], v[172:175], v[76:79], v[48:51]
	v_mfma_f32_16x16x32_bf16 v[48:51], v[164:167], v[84:87], v[216:219]
	v_mfma_f32_16x16x32_bf16 v[52:55], v[172:175], v[84:87], v[220:223]
	v_mfma_f32_16x16x32_bf16 v[56:59], v[164:167], v[92:95], v[130:133]
	v_mfma_f32_16x16x32_bf16 v[60:63], v[172:175], v[92:95], v[168:171]
	s_setprio 0
	s_setprio 1
	v_mfma_f32_16x16x32_bf16 v[28:31], v[160:163], v[64:67], v[28:31]
	v_mfma_f32_16x16x32_bf16 v[24:27], v[212:215], v[64:67], v[24:27]
	v_mfma_f32_16x16x32_bf16 v[20:23], v[160:163], v[72:75], v[20:23]
	v_mfma_f32_16x16x32_bf16 v[64:67], v[212:215], v[72:75], v[16:19]
	v_mfma_f32_16x16x32_bf16 v[72:75], v[160:163], v[80:83], v[12:15]
	v_mfma_f32_16x16x32_bf16 v[8:11], v[212:215], v[80:83], v[8:11]
	v_mfma_f32_16x16x32_bf16 v[80:83], v[160:163], v[88:91], v[4:7]
	v_mfma_f32_16x16x32_bf16 v[0:3], v[212:215], v[88:91], v[0:3]
	v_mfma_f32_16x16x32_bf16 v[4:7], v[208:211], v[68:71], v[28:31]
	v_mfma_f32_16x16x32_bf16 v[12:15], v[156:159], v[68:71], v[24:27]
	v_mfma_f32_16x16x32_bf16 v[16:19], v[208:211], v[76:79], v[20:23]
	v_mfma_f32_16x16x32_bf16 v[20:23], v[156:159], v[76:79], v[64:67]
	v_mfma_f32_16x16x32_bf16 v[24:27], v[208:211], v[84:87], v[72:75]
	v_mfma_f32_16x16x32_bf16 v[28:31], v[156:159], v[84:87], v[8:11]
	v_mfma_f32_16x16x32_bf16 v[64:67], v[208:211], v[92:95], v[80:83]
	v_mfma_f32_16x16x32_bf16 v[68:71], v[156:159], v[92:95], v[0:3]
	s_setprio 0
	s_barrier
	ds_read_b128 v[8:11], v155
	ds_read_b128 v[0:3], v155 offset:1024
	ds_read_b128 v[76:79], v155 offset:2048
	ds_read_b128 v[72:75], v155 offset:3072
	ds_read_b128 v[130:133], v153 offset:32768
	ds_read_b128 v[156:159], v153 offset:33792
	ds_read_b128 v[160:163], v152 offset:32768
	ds_read_b128 v[164:167], v152 offset:33792
	ds_read_b128 v[168:171], v151 offset:32768
	ds_read_b128 v[172:175], v151 offset:33792
	ds_read_b128 v[208:211], v150 offset:32768
	ds_read_b128 v[212:215], v150 offset:33792
	s_waitcnt vmcnt(2)
	s_barrier
	s_waitcnt lgkmcnt(0)
	s_setprio 1
	s_waitcnt lgkmcnt(0)
	v_mfma_f32_16x16x32_bf16 v[80:83], v[8:11], v[130:133], v[124:127]
	v_mfma_f32_16x16x32_bf16 v[84:87], v[76:79], v[130:133], v[120:123]
	v_mfma_f32_16x16x32_bf16 v[88:91], v[8:11], v[160:163], v[116:119]
	v_mfma_f32_16x16x32_bf16 v[92:95], v[76:79], v[160:163], v[112:115]
	v_mfma_f32_16x16x32_bf16 v[108:111], v[8:11], v[168:171], v[108:111]
	v_mfma_f32_16x16x32_bf16 v[104:107], v[76:79], v[168:171], v[104:107]
	v_mfma_f32_16x16x32_bf16 v[100:103], v[8:11], v[208:211], v[100:103]
	v_mfma_f32_16x16x32_bf16 v[96:99], v[76:79], v[208:211], v[96:99]
	v_mfma_f32_16x16x32_bf16 v[112:115], v[0:3], v[156:159], v[80:83]
	v_mfma_f32_16x16x32_bf16 v[116:119], v[72:75], v[156:159], v[84:87]
	v_mfma_f32_16x16x32_bf16 v[120:123], v[0:3], v[164:167], v[88:91]
	v_mfma_f32_16x16x32_bf16 v[124:127], v[72:75], v[164:167], v[92:95]
	v_mfma_f32_16x16x32_bf16 v[108:111], v[0:3], v[172:175], v[108:111]
	v_mfma_f32_16x16x32_bf16 v[104:107], v[72:75], v[172:175], v[104:107]
	v_mfma_f32_16x16x32_bf16 v[100:103], v[0:3], v[212:215], v[100:103]
	v_mfma_f32_16x16x32_bf16 v[96:99], v[72:75], v[212:215], v[96:99]
	s_setprio 0
	s_barrier
	ds_read_b128 v[88:91], v154
	ds_read_b128 v[80:83], v154 offset:1024
	ds_read_b128 v[92:95], v154 offset:2048
	ds_read_b128 v[84:87], v154 offset:3072
	s_waitcnt vmcnt(0)
	s_barrier
	s_waitcnt lgkmcnt(0)
	s_setprio 1
	s_waitcnt lgkmcnt(0)
	v_mfma_f32_16x16x32_bf16 v[176:179], v[88:91], v[130:133], v[176:179]
	v_mfma_f32_16x16x32_bf16 v[130:133], v[92:95], v[130:133], v[180:183]
	v_mfma_f32_16x16x32_bf16 v[180:183], v[88:91], v[160:163], v[184:187]
	v_mfma_f32_16x16x32_bf16 v[160:163], v[92:95], v[160:163], v[188:191]
	v_mfma_f32_16x16x32_bf16 v[184:187], v[88:91], v[168:171], v[192:195]
	v_mfma_f32_16x16x32_bf16 v[168:171], v[92:95], v[168:171], v[196:199]
	v_mfma_f32_16x16x32_bf16 v[188:191], v[88:91], v[208:211], v[200:203]
	v_mfma_f32_16x16x32_bf16 v[192:195], v[92:95], v[208:211], v[204:207]
	v_mfma_f32_16x16x32_bf16 v[176:179], v[80:83], v[156:159], v[176:179]
	v_mfma_f32_16x16x32_bf16 v[130:133], v[84:87], v[156:159], v[130:133]
	v_mfma_f32_16x16x32_bf16 v[154:157], v[80:83], v[164:167], v[180:183]
	v_mfma_f32_16x16x32_bf16 v[158:161], v[84:87], v[164:167], v[160:163]
	v_mfma_f32_16x16x32_bf16 v[162:165], v[80:83], v[172:175], v[184:187]
	v_mfma_f32_16x16x32_bf16 v[166:169], v[84:87], v[172:175], v[168:171]
	v_mfma_f32_16x16x32_bf16 v[170:173], v[80:83], v[212:215], v[188:191]
	v_mfma_f32_16x16x32_bf16 v[180:183], v[84:87], v[212:215], v[192:195]
	s_setprio 0
	s_barrier
	v_mbcnt_lo_u32_b32 v128, -1, 0
	v_mbcnt_hi_u32_b32 v128, -1, v128
	v_cvt_pk_bf16_f32 v112, v112, v113
	v_cvt_pk_bf16_f32 v113, v114, v115
	v_cvt_pk_bf16_f32 v114, v116, v117
	v_cvt_pk_bf16_f32 v115, v118, v119
	s_lshl_b32 s66, s64, 9
	v_add_u32_e32 v174, s72, v128
	v_ashrrev_i32_e32 v175, 6, v174
	v_and_b32_e32 v184, 15, v128
	v_and_b32_e32 v185, 48, v128
	v_mul_lo_u32 v186, v175, s77
	v_bfe_u32 v187, v128, 3, 3
	v_lshlrev_b32_e32 v128, 4, v128
	v_add_u32_e32 v186, 0x20000, v186
	v_lshrrev_b32_e32 v174, 2, v174
	v_and_b32_e32 v128, 0x70, v128
	v_mul_u32_u24_e32 v184, 0x90, v184
	v_and_b32_e32 v174, 64, v174
	v_add3_u32 v184, v186, v184, v185
	v_or_b32_e32 v185, v186, v128
	v_or3_b32 v174, s24, v174, v187
	v_mad_u32_u24 v185, v187, s78, v185
	ds_write_b128 v184, v[112:115]
	v_cvt_pk_bf16_f32 v112, v176, v177
	v_cvt_pk_bf16_f32 v113, v178, v179
	v_cvt_pk_bf16_f32 v114, v130, v131
	v_cvt_pk_bf16_f32 v115, v132, v133
	ds_write_b128 v184, v[112:115] offset:64
	v_lshlrev_b32_e32 v175, 7, v175
	ds_read_b128 v[112:115], v185
	v_lshlrev_b32_e32 v116, 12, v174
	v_and_or_b32 v116, v175, s79, v116
	v_or3_b32 v128, v116, s66, v128
	ds_read_b128 v[116:119], v185 offset:1152
	v_lshl_add_u64 v[130:131], s[0:1], 0, v[128:129]
	s_mov_b32 s64, 0x8000
	s_waitcnt lgkmcnt(0)
	global_store_dwordx4 v128, v[112:115], s[0:1]
	v_cvt_pk_bf16_f32 v108, v108, v109
	v_cvt_pk_bf16_f32 v109, v110, v111
	v_cvt_pk_bf16_f32 v110, v104, v105
	v_cvt_pk_bf16_f32 v111, v106, v107
	v_cvt_pk_bf16_f32 v104, v162, v163
	s_nop 1
	v_add_co_u32_e32 v112, vcc, s64, v130
	v_cvt_pk_bf16_f32 v114, v124, v125
	v_cvt_pk_bf16_f32 v115, v126, v127
	v_cvt_pk_bf16_f32 v105, v164, v165
	v_cvt_pk_bf16_f32 v106, v166, v167
	s_nop 1
	v_addc_co_u32_e32 v113, vcc, 0, v131, vcc
	global_store_dwordx4 v[112:113], v[116:119], off
	v_cvt_pk_bf16_f32 v112, v120, v121
	v_cvt_pk_bf16_f32 v113, v122, v123
	ds_write_b128 v184, v[112:115]
	v_cvt_pk_bf16_f32 v112, v154, v155
	v_cvt_pk_bf16_f32 v113, v156, v157
	v_cvt_pk_bf16_f32 v114, v158, v159
	v_cvt_pk_bf16_f32 v115, v160, v161
	ds_write_b128 v184, v[112:115] offset:64
	ds_read_b128 v[112:115], v185
	ds_read_b128 v[116:119], v185 offset:1152
	v_add_co_u32_e32 v120, vcc, s74, v130
	ds_write_b128 v184, v[108:111]
	v_cvt_pk_bf16_f32 v107, v168, v169
	ds_write_b128 v184, v[104:107] offset:64
	v_addc_co_u32_e32 v121, vcc, 0, v131, vcc
	ds_read_b128 v[104:107], v185
	ds_read_b128 v[108:111], v185 offset:1152
	s_waitcnt lgkmcnt(0)
	global_store_dwordx4 v[120:121], v[112:115], off
	v_cvt_pk_bf16_f32 v100, v100, v101
	v_cvt_pk_bf16_f32 v101, v102, v103
	v_cvt_pk_bf16_f32 v102, v96, v97
	v_cvt_pk_bf16_f32 v103, v98, v99
	ds_write_b128 v184, v[100:103]
	s_nop 0
	v_add_co_u32_e32 v112, vcc, s75, v130
	v_cvt_pk_bf16_f32 v96, v170, v171
	v_cvt_pk_bf16_f32 v97, v172, v173
	v_cvt_pk_bf16_f32 v98, v180, v181
	v_cvt_pk_bf16_f32 v99, v182, v183
	s_nop 1
	v_addc_co_u32_e32 v113, vcc, 0, v131, vcc
	global_store_dwordx4 v[112:113], v[116:119], off
	v_add_co_u32_e32 v112, vcc, s76, v130
	ds_write_b128 v184, v[96:99] offset:64
	s_nop 0
	v_addc_co_u32_e32 v113, vcc, 0, v131, vcc
	ds_read_b128 v[96:99], v185
	ds_read_b128 v[100:103], v185 offset:1152
	global_store_dwordx4 v[112:113], v[104:107], off
	s_nop 1
	v_add_co_u32_e32 v104, vcc, s80, v130
	s_nop 1
	v_addc_co_u32_e32 v105, vcc, 0, v131, vcc
	global_store_dwordx4 v[104:105], v[108:111], off
	v_add_co_u32_e32 v104, vcc, s81, v130
	s_nop 1
	v_addc_co_u32_e32 v105, vcc, 0, v131, vcc
	s_waitcnt lgkmcnt(0)
	global_store_dwordx4 v[104:105], v[96:99], off
	s_nop 1
	v_add_co_u32_e32 v96, vcc, s82, v130
	s_nop 1
	v_addc_co_u32_e32 v97, vcc, 0, v131, vcc
	global_store_dwordx4 v[96:97], v[100:103], off
	ds_read_b128 v[96:99], v153 offset:49152
	ds_read_b128 v[100:103], v153 offset:50176
	ds_read_b128 v[104:107], v152 offset:49152
	ds_read_b128 v[108:111], v152 offset:50176
	ds_read_b128 v[112:115], v151 offset:49152
	ds_read_b128 v[116:119], v151 offset:50176
	ds_read_b128 v[120:123], v150 offset:49152
	ds_read_b128 v[124:127], v150 offset:50176
	s_barrier
	s_waitcnt lgkmcnt(0)
	s_setprio 1
	s_waitcnt lgkmcnt(0)
	v_mfma_f32_16x16x32_bf16 v[32:35], v[8:11], v[96:99], v[32:35]
	v_mfma_f32_16x16x32_bf16 v[36:39], v[76:79], v[96:99], v[36:39]
	v_mfma_f32_16x16x32_bf16 v[40:43], v[8:11], v[104:107], v[40:43]
	v_mfma_f32_16x16x32_bf16 v[130:133], v[76:79], v[104:107], v[44:47]
	v_mfma_f32_16x16x32_bf16 v[150:153], v[8:11], v[112:115], v[48:51]
	v_mfma_f32_16x16x32_bf16 v[52:55], v[76:79], v[112:115], v[52:55]
	v_mfma_f32_16x16x32_bf16 v[8:11], v[8:11], v[120:123], v[56:59]
	v_mfma_f32_16x16x32_bf16 v[60:63], v[76:79], v[120:123], v[60:63]
	v_mfma_f32_16x16x32_bf16 v[56:59], v[0:3], v[100:103], v[32:35]
	v_mfma_f32_16x16x32_bf16 v[48:51], v[72:75], v[100:103], v[36:39]
	v_mfma_f32_16x16x32_bf16 v[44:47], v[0:3], v[108:111], v[40:43]
	v_mfma_f32_16x16x32_bf16 v[40:43], v[72:75], v[108:111], v[130:133]
	v_mfma_f32_16x16x32_bf16 v[36:39], v[0:3], v[116:119], v[150:153]
	v_mfma_f32_16x16x32_bf16 v[32:35], v[72:75], v[116:119], v[52:55]
	v_mfma_f32_16x16x32_bf16 v[8:11], v[0:3], v[124:127], v[8:11]
	v_mfma_f32_16x16x32_bf16 v[0:3], v[72:75], v[124:127], v[60:63]
	s_setprio 0
	s_setprio 1
	v_mfma_f32_16x16x32_bf16 v[4:7], v[88:91], v[96:99], v[4:7]
	v_mfma_f32_16x16x32_bf16 v[12:15], v[92:95], v[96:99], v[12:15]
	v_mfma_f32_16x16x32_bf16 v[16:19], v[88:91], v[104:107], v[16:19]
	v_mfma_f32_16x16x32_bf16 v[20:23], v[92:95], v[104:107], v[20:23]
	v_mfma_f32_16x16x32_bf16 v[72:75], v[88:91], v[112:115], v[24:27]
	v_mfma_f32_16x16x32_bf16 v[76:79], v[92:95], v[112:115], v[28:31]
	v_mfma_f32_16x16x32_bf16 v[64:67], v[88:91], v[120:123], v[64:67]
	v_mfma_f32_16x16x32_bf16 v[68:71], v[92:95], v[120:123], v[68:71]
	v_mfma_f32_16x16x32_bf16 v[60:63], v[80:83], v[100:103], v[4:7]
	v_mfma_f32_16x16x32_bf16 v[52:55], v[84:87], v[100:103], v[12:15]
	v_mfma_f32_16x16x32_bf16 v[28:31], v[80:83], v[108:111], v[16:19]
	v_mfma_f32_16x16x32_bf16 v[24:27], v[84:87], v[108:111], v[20:23]
	v_mfma_f32_16x16x32_bf16 v[20:23], v[80:83], v[116:119], v[72:75]
	v_mfma_f32_16x16x32_bf16 v[16:19], v[84:87], v[116:119], v[76:79]
	v_mfma_f32_16x16x32_bf16 v[12:15], v[80:83], v[124:127], v[64:67]
	v_mfma_f32_16x16x32_bf16 v[4:7], v[84:87], v[124:127], v[68:71]
	s_setprio 0
	v_cmp_gt_u32_e32 vcc, s83, v136
	s_barrier
	s_and_saveexec_b64 s[64:65], vcc
	s_cbranch_execz .LBB0_181
	s_barrier

.LBB0_233:
	v_bfe_i32 v5, v179, 27, 1
	v_lshlrev_b32_e32 v169, 4, v179
	v_lshrrev_b32_e32 v5, 22, v5
	v_add_u32_e32 v5, v169, v5
	v_and_b32_e32 v5, 0xfffffc00, v5
	v_sub_u32_e32 v5, v169, v5
	v_lshrrev_b32_e32 v6, 4, v5
	v_bitop3_b32 v5, v6, v5, 32 bitop3:0x6c
	v_ashrrev_i32_e32 v6, 31, v5
	v_lshrrev_b32_e32 v6, 26, v6
	v_ashrrev_i32_e32 v4, 31, v179
	v_add_u32_e32 v6, v5, v6
	s_lshl_b32 s56, s83, 3
	v_lshrrev_b32_e32 v4, 26, v4
	v_ashrrev_i32_e32 v133, 6, v6
	v_and_b32_e32 v6, 0xc0, v6
	s_ff1_i32_b32 s57, s56
	s_add_i32 s56, s56, -1
	v_and_b32_e32 v2, 15, v0
	v_and_b32_e32 v3, 48, v0
	v_add_u32_e32 v4, v179, v4
	v_sub_u32_e32 v5, v5, v6
	v_and_b32_e32 v6, 32, v0
	v_lshlrev_b32_e32 v10, 2, v0
	v_lshlrev_b32_e32 v0, 6, v0
	s_lshr_b32 s62, s85, s57
	s_and_b32 s56, s85, s56
	s_and_b32 s63, s85, 7
	v_ashrrev_i32_e32 v131, 6, v4
	v_lshlrev_b32_e32 v2, 6, v2
	v_and_b32_e32 v10, 32, v10
	v_and_b32_e32 v0, 0x3c0, v0
	s_lshr_b32 s80, s56, 3
	v_or_b32_e32 v9, v2, v3
	v_bitop3_b32 v2, v2, v10, v3 bitop3:0x36
	v_bitop3_b32 v3, v0, v10, v3 bitop3:0x36
	s_lshl_b32 s56, s62, 11
	s_lshl_b32 s57, s63, 8
	v_lshlrev_b32_e32 v0, 16, v131
	s_or_b32 s56, s56, s57
	s_mov_b32 s57, s15
	v_and_b32_e32 v0, 0xfffe0000, v0
	s_lshl_b32 s60, s80, 14
	v_ashrrev_i16_sdwa v5, v167, sext(v5) dst_sel:DWORD dst_unused:UNUSED_PAD src0_sel:DWORD src1_sel:BYTE_0
	s_lshl_b64 s[56:57], s[56:57], 13
	v_lshl_add_u32 v0, v133, 13, v0
	v_bfe_i32 v134, v5, 0, 16
	v_and_or_b32 v0, v4, 64, v0
	s_add_u32 s56, s40, s56
	v_lshl_add_u32 v164, v134, 1, v0
	s_addc_u32 s57, s41, s57
	v_lshlrev_b32_e32 v14, 13, v1
	v_lshl_add_u64 v[0:1], s[56:57], 0, v[164:165]
	s_mul_i32 s57, s14, 0x1800
	s_mul_hi_u32 s56, s14, 0x1800
	s_add_u32 s57, s57, s60
	s_addc_u32 s58, s56, 0
	s_add_u32 s56, s65, s57
	v_bfe_i32 v7, v179, 6, 1
	s_addc_u32 s57, s66, s58
	s_lshl_b64 s[58:59], s[14:15], 12
	v_and_b32_e32 v7, s14, v7
	v_lshrrev_b32_e32 v8, 7, v179
	s_add_u32 s14, s58, s60
	v_add_lshl_u32 v7, v7, v8, 10
	v_lshlrev_b32_e32 v8, 6, v179
	s_addc_u32 s61, s59, 0
	v_and_b32_e32 v5, 0x3f0, v169
	v_and_b32_e32 v8, 0x3000, v8
	v_bitop3_b32 v11, v9, s67, v10 bitop3:0xde
	v_bitop3_b32 v12, v9, s69, v10 bitop3:0xde
	v_bitop3_b32 v13, v9, s70, v10 bitop3:0xde
	v_bitop3_b32 v9, v9, s71, v10 bitop3:0xde
	v_or_b32_e32 v10, 0x800, v14
	v_or_b32_e32 v15, 0x1000, v14
	v_or_b32_e32 v16, 0x1800, v14
	v_lshl_add_u64 v[128:129], v[0:1], 0, s[16:17]
	s_add_u32 s60, s65, s14
	v_mov_b32_e32 v0, 0
	v_bitop3_b32 v164, v5, v7, v6 bitop3:0xde
	s_addc_u32 s61, s66, s61
	s_mov_b32 s14, -2
	v_add_u32_e32 v138, v11, v8
	v_add_u32_e32 v193, v2, v14
	v_add_u32_e32 v192, v3, v10
	v_add_u32_e32 v191, v3, v15
	v_add_u32_e32 v190, v3, v16
	v_add_u32_e32 v137, 0xc000, v169
	v_add_u32_e32 v136, 0xe000, v169
	v_add_u32_e32 v135, v12, v8
	v_add_u32_e32 v189, 0x10000, v169
	v_add_u32_e32 v188, 0x12000, v169
	v_add_u32_e32 v187, 0x2000, v169
	v_add_u32_e32 v186, 0x14000, v169
	v_add_u32_e32 v185, 0x16000, v169
	v_add_u32_e32 v130, v13, v8
	v_add_u32_e32 v184, 0x4000, v169
	v_add_u32_e32 v183, 0x6000, v169
	v_add_u32_e32 v132, v9, v8
	v_add_u32_e32 v182, 0x18000, v169
	v_add_u32_e32 v181, 0x1a000, v169
	v_add_u32_e32 v177, 0x8000, v169
	v_add_u32_e32 v175, 0xa000, v169
	v_add_u32_e32 v173, 0x1c000, v169
	v_add_u32_e32 v171, 0x1e000, v169
	v_mov_b32_e32 v1, v0
	v_mov_b32_e32 v2, v0
	v_mov_b32_e32 v3, v0
	v_mov_b32_e32 v4, v0
	v_mov_b32_e32 v5, v0
	v_mov_b32_e32 v6, v0
	v_mov_b32_e32 v7, v0
	v_mov_b32_e32 v8, v0
	v_mov_b32_e32 v9, v0
	v_mov_b32_e32 v10, v0
	v_mov_b32_e32 v11, v0
	v_mov_b32_e32 v12, v0
	v_mov_b32_e32 v13, v0
	v_mov_b32_e32 v14, v0
	v_mov_b32_e32 v15, v0
	v_mov_b32_e32 v16, v0
	v_mov_b32_e32 v17, v0
	v_mov_b32_e32 v18, v0
	v_mov_b32_e32 v19, v0
	v_mov_b32_e32 v20, v0
	v_mov_b32_e32 v21, v0
	v_mov_b32_e32 v22, v0
	v_mov_b32_e32 v23, v0
	v_mov_b32_e32 v24, v0
	v_mov_b32_e32 v25, v0
	v_mov_b32_e32 v26, v0
	v_mov_b32_e32 v27, v0
	v_mov_b32_e32 v28, v0
	v_mov_b32_e32 v29, v0
	v_mov_b32_e32 v30, v0
	v_mov_b32_e32 v31, v0
	v_mov_b32_e32 v32, v0
	v_mov_b32_e32 v33, v0
	v_mov_b32_e32 v34, v0
	v_mov_b32_e32 v35, v0
	v_mov_b32_e32 v36, v0
	v_mov_b32_e32 v37, v0
	v_mov_b32_e32 v38, v0
	v_mov_b32_e32 v39, v0
	v_mov_b32_e32 v40, v0
	v_mov_b32_e32 v41, v0
	v_mov_b32_e32 v42, v0
	v_mov_b32_e32 v43, v0
	v_mov_b32_e32 v44, v0
	v_mov_b32_e32 v45, v0
	v_mov_b32_e32 v46, v0
	v_mov_b32_e32 v47, v0
	v_mov_b32_e32 v48, v0
	v_mov_b32_e32 v49, v0
	v_mov_b32_e32 v50, v0
	v_mov_b32_e32 v51, v0
	v_mov_b32_e32 v52, v0
	v_mov_b32_e32 v53, v0
	v_mov_b32_e32 v54, v0
	v_mov_b32_e32 v55, v0
	v_mov_b32_e32 v56, v0
	v_mov_b32_e32 v57, v0
	v_mov_b32_e32 v58, v0
	v_mov_b32_e32 v59, v0
	v_mov_b32_e32 v60, v0
	v_mov_b32_e32 v61, v0
	v_mov_b32_e32 v62, v0
	v_mov_b32_e32 v63, v0
	v_mov_b32_e32 v64, v0
	v_mov_b32_e32 v65, v0
	v_mov_b32_e32 v66, v0
	v_mov_b32_e32 v67, v0
	v_mov_b32_e32 v68, v0
	v_mov_b32_e32 v69, v0
	v_mov_b32_e32 v70, v0
	v_mov_b32_e32 v71, v0
	v_mov_b32_e32 v72, v0
	v_mov_b32_e32 v73, v0
	v_mov_b32_e32 v74, v0
	v_mov_b32_e32 v75, v0
	v_mov_b32_e32 v76, v0
	v_mov_b32_e32 v77, v0
	v_mov_b32_e32 v78, v0
	v_mov_b32_e32 v79, v0
	v_mov_b32_e32 v80, v0
	v_mov_b32_e32 v81, v0
	v_mov_b32_e32 v82, v0
	v_mov_b32_e32 v83, v0
	v_mov_b32_e32 v84, v0
	v_mov_b32_e32 v85, v0
	v_mov_b32_e32 v86, v0
	v_mov_b32_e32 v87, v0
	v_mov_b32_e32 v88, v0
	v_mov_b32_e32 v89, v0
	v_mov_b32_e32 v90, v0
	v_mov_b32_e32 v91, v0
	v_mov_b32_e32 v92, v0
	v_mov_b32_e32 v93, v0
	v_mov_b32_e32 v94, v0
	v_mov_b32_e32 v95, v0
	v_mov_b32_e32 v96, v0
	v_mov_b32_e32 v97, v0
	v_mov_b32_e32 v98, v0
	v_mov_b32_e32 v99, v0
	v_mov_b32_e32 v100, v0
	v_mov_b32_e32 v101, v0
	v_mov_b32_e32 v102, v0
	v_mov_b32_e32 v103, v0
	v_mov_b32_e32 v104, v0
	v_mov_b32_e32 v105, v0
	v_mov_b32_e32 v106, v0
	v_mov_b32_e32 v107, v0
	v_mov_b32_e32 v108, v0
	v_mov_b32_e32 v109, v0
	v_mov_b32_e32 v110, v0
	v_mov_b32_e32 v111, v0
	v_mov_b32_e32 v112, v0
	v_mov_b32_e32 v113, v0
	v_mov_b32_e32 v114, v0
	v_mov_b32_e32 v115, v0
	v_mov_b32_e32 v116, v0
	v_mov_b32_e32 v117, v0
	v_mov_b32_e32 v118, v0
	v_mov_b32_e32 v119, v0
	v_mov_b32_e32 v120, v0
	v_mov_b32_e32 v121, v0
	v_mov_b32_e32 v122, v0
	v_mov_b32_e32 v123, v0
	v_mov_b32_e32 v124, v0
	v_mov_b32_e32 v125, v0
	v_mov_b32_e32 v126, v0
	v_mov_b32_e32 v127, v0
	s_barrier
	v_readlane_b32 s98, v242, 1
	s_lshl_b32 s98, s98, 10
	s_add_i32 s82, s98, 0xc000
	v_lshl_add_u64 v[142:143], v[128:129], 0, s[18:19]
	s_mov_b32 m0, s82
	s_add_i32 s82, s98, 0xe000
	global_load_lds_dwordx4 v[142:143], off
	v_lshl_add_u64 v[142:143], v[128:129], 0, s[20:21]
	s_mov_b32 m0, s82
	s_nop 0
	global_load_lds_dwordx4 v[142:143], off
	ds_read_b128 v[140:143], v138
	ds_read_b128 v[144:147], v138 offset:1024
	ds_read_b128 v[148:151], v138 offset:2048
	ds_read_b128 v[152:155], v138 offset:3072
.LBB0_234:
	ds_read_b128 v[156:159], v193
	ds_read_b128 v[160:163], v193 offset:1024
	ds_read_b128 v[194:197], v192
	ds_read_b128 v[198:201], v192 offset:1024
	ds_read_b128 v[202:205], v191
	ds_read_b128 v[206:209], v191 offset:1024
	ds_read_b128 v[210:213], v190
	ds_read_b128 v[214:217], v190 offset:1024
	s_waitcnt lgkmcnt(8)
	s_waitcnt vmcnt(10)
	s_barrier
	s_waitcnt lgkmcnt(0)
	s_waitcnt lgkmcnt(0)
	v_mfma_f32_16x16x32_bf16 v[124:127], v[140:143], v[156:159], v[124:127]
	v_mfma_f32_16x16x32_bf16 v[120:123], v[148:151], v[156:159], v[120:123]
	v_mfma_f32_16x16x32_bf16 v[116:119], v[140:143], v[194:197], v[116:119]
	v_mfma_f32_16x16x32_bf16 v[112:115], v[148:151], v[194:197], v[112:115]
	v_mfma_f32_16x16x32_bf16 v[108:111], v[140:143], v[202:205], v[108:111]
	v_mfma_f32_16x16x32_bf16 v[104:107], v[148:151], v[202:205], v[104:107]
	v_mfma_f32_16x16x32_bf16 v[100:103], v[140:143], v[210:213], v[100:103]
	v_mfma_f32_16x16x32_bf16 v[96:99], v[148:151], v[210:213], v[96:99]
	v_mfma_f32_16x16x32_bf16 v[124:127], v[144:147], v[160:163], v[124:127]
	v_mfma_f32_16x16x32_bf16 v[120:123], v[152:155], v[160:163], v[120:123]
	v_mfma_f32_16x16x32_bf16 v[116:119], v[144:147], v[198:201], v[116:119]
	v_mfma_f32_16x16x32_bf16 v[112:115], v[152:155], v[198:201], v[112:115]
	v_mfma_f32_16x16x32_bf16 v[108:111], v[144:147], v[206:209], v[108:111]
	v_mfma_f32_16x16x32_bf16 v[104:107], v[152:155], v[206:209], v[104:107]
	v_mfma_f32_16x16x32_bf16 v[100:103], v[144:147], v[214:217], v[100:103]
	v_mfma_f32_16x16x32_bf16 v[96:99], v[152:155], v[214:217], v[96:99]
	s_barrier
	s_add_i32 s82, s98, 0x10000
	v_lshl_add_u64 v[234:235], s[60:61], 0, v[164:165]
	s_mov_b32 m0, s82
	s_add_i32 s82, s98, 0x12000
	ds_read_b128 v[218:221], v135
	ds_read_b128 v[222:225], v135 offset:1024
	ds_read_b128 v[226:229], v135 offset:2048
	ds_read_b128 v[230:233], v135 offset:3072
	global_load_lds_dwordx4 v[234:235], off
	v_lshl_add_u64 v[236:237], v[234:235], 0, s[2:3]
	s_mov_b32 m0, s82
	s_nop 0
	global_load_lds_dwordx4 v[236:237], off
	s_mov_b32 s82, s98
	v_lshl_add_u64 v[236:237], v[128:129], 0, s[22:23]
	s_mov_b32 m0, s82
	s_add_i32 s82, s98, 0x2000
	global_load_lds_dwordx4 v[236:237], off
	v_lshl_add_u64 v[236:237], v[128:129], 0, s[24:25]
	s_mov_b32 m0, s82
	s_nop 0
	global_load_lds_dwordx4 v[236:237], off
	s_waitcnt vmcnt(12)
	s_barrier
	s_waitcnt lgkmcnt(0)
	s_waitcnt lgkmcnt(0)
	v_mfma_f32_16x16x32_bf16 v[92:95], v[218:221], v[156:159], v[92:95]
	v_mfma_f32_16x16x32_bf16 v[88:91], v[226:229], v[156:159], v[88:91]
	v_mfma_f32_16x16x32_bf16 v[84:87], v[218:221], v[194:197], v[84:87]
	v_mfma_f32_16x16x32_bf16 v[80:83], v[226:229], v[194:197], v[80:83]
	v_mfma_f32_16x16x32_bf16 v[76:79], v[218:221], v[202:205], v[76:79]
	v_mfma_f32_16x16x32_bf16 v[72:75], v[226:229], v[202:205], v[72:75]
	v_mfma_f32_16x16x32_bf16 v[68:71], v[218:221], v[210:213], v[68:71]
	v_mfma_f32_16x16x32_bf16 v[64:67], v[226:229], v[210:213], v[64:67]
	v_mfma_f32_16x16x32_bf16 v[92:95], v[222:225], v[160:163], v[92:95]
	v_mfma_f32_16x16x32_bf16 v[88:91], v[230:233], v[160:163], v[88:91]
	v_mfma_f32_16x16x32_bf16 v[84:87], v[222:225], v[198:201], v[84:87]
	v_mfma_f32_16x16x32_bf16 v[80:83], v[230:233], v[198:201], v[80:83]
	v_mfma_f32_16x16x32_bf16 v[76:79], v[222:225], v[206:209], v[76:79]
	v_mfma_f32_16x16x32_bf16 v[72:75], v[230:233], v[206:209], v[72:75]
	v_mfma_f32_16x16x32_bf16 v[68:71], v[222:225], v[214:217], v[68:71]
	v_mfma_f32_16x16x32_bf16 v[64:67], v[230:233], v[214:217], v[64:67]
	s_barrier
	ds_read_b128 v[156:159], v193 offset:16384
	ds_read_b128 v[160:163], v193 offset:17408
	ds_read_b128 v[194:197], v192 offset:16384
	ds_read_b128 v[198:201], v192 offset:17408
	ds_read_b128 v[202:205], v191 offset:16384
	ds_read_b128 v[206:209], v191 offset:17408
	ds_read_b128 v[210:213], v190 offset:16384
	ds_read_b128 v[214:217], v190 offset:17408
	s_add_i32 s82, s98, 0x14000
	v_lshl_add_u64 v[236:237], v[234:235], 0, s[6:7]
	s_mov_b32 m0, s82
	s_add_i32 s82, s98, 0x16000
	global_load_lds_dwordx4 v[236:237], off
	v_lshl_add_u64 v[236:237], v[234:235], 0, s[8:9]
	s_mov_b32 m0, s82
	s_nop 0
	global_load_lds_dwordx4 v[236:237], off
	s_waitcnt vmcnt(12)
	s_barrier
	s_waitcnt lgkmcnt(0)
	s_waitcnt lgkmcnt(0)
	v_mfma_f32_16x16x32_bf16 v[60:63], v[140:143], v[156:159], v[60:63]
	v_mfma_f32_16x16x32_bf16 v[56:59], v[148:151], v[156:159], v[56:59]
	v_mfma_f32_16x16x32_bf16 v[52:55], v[140:143], v[194:197], v[52:55]
	v_mfma_f32_16x16x32_bf16 v[48:51], v[148:151], v[194:197], v[48:51]
	v_mfma_f32_16x16x32_bf16 v[44:47], v[140:143], v[202:205], v[44:47]
	v_mfma_f32_16x16x32_bf16 v[40:43], v[148:151], v[202:205], v[40:43]
	v_mfma_f32_16x16x32_bf16 v[36:39], v[140:143], v[210:213], v[36:39]
	v_mfma_f32_16x16x32_bf16 v[32:35], v[148:151], v[210:213], v[32:35]
	v_mfma_f32_16x16x32_bf16 v[60:63], v[144:147], v[160:163], v[60:63]
	v_mfma_f32_16x16x32_bf16 v[56:59], v[152:155], v[160:163], v[56:59]
	v_mfma_f32_16x16x32_bf16 v[52:55], v[144:147], v[198:201], v[52:55]
	v_mfma_f32_16x16x32_bf16 v[48:51], v[152:155], v[198:201], v[48:51]
	v_mfma_f32_16x16x32_bf16 v[44:47], v[144:147], v[206:209], v[44:47]
	v_mfma_f32_16x16x32_bf16 v[40:43], v[152:155], v[206:209], v[40:43]
	v_mfma_f32_16x16x32_bf16 v[36:39], v[144:147], v[214:217], v[36:39]
	v_mfma_f32_16x16x32_bf16 v[32:35], v[152:155], v[214:217], v[32:35]
	s_barrier
	s_add_i32 s82, s98, 0x4000
	v_lshl_add_u64 v[142:143], v[128:129], 0, s[26:27]
	s_mov_b32 m0, s82
	s_add_i32 s82, s98, 0x6000
	global_load_lds_dwordx4 v[142:143], off
	s_mov_b32 m0, s82
	s_nop 0
	global_load_lds_dwordx4 v[128:129], off
	ds_read_b128 v[140:143], v130
	ds_read_b128 v[144:147], v130 offset:1024
	ds_read_b128 v[148:151], v130 offset:2048
	ds_read_b128 v[152:155], v130 offset:3072
	s_waitcnt vmcnt(12)
	s_barrier
	v_mfma_f32_16x16x32_bf16 v[28:31], v[218:221], v[156:159], v[28:31]
	v_mfma_f32_16x16x32_bf16 v[24:27], v[226:229], v[156:159], v[24:27]
	v_mfma_f32_16x16x32_bf16 v[20:23], v[218:221], v[194:197], v[20:23]
	v_mfma_f32_16x16x32_bf16 v[16:19], v[226:229], v[194:197], v[16:19]
	v_mfma_f32_16x16x32_bf16 v[12:15], v[218:221], v[202:205], v[12:15]
	v_mfma_f32_16x16x32_bf16 v[8:11], v[226:229], v[202:205], v[8:11]
	v_mfma_f32_16x16x32_bf16 v[4:7], v[218:221], v[210:213], v[4:7]
	v_mfma_f32_16x16x32_bf16 v[0:3], v[226:229], v[210:213], v[0:3]
	v_mfma_f32_16x16x32_bf16 v[28:31], v[222:225], v[160:163], v[28:31]
	v_mfma_f32_16x16x32_bf16 v[24:27], v[230:233], v[160:163], v[24:27]
	v_mfma_f32_16x16x32_bf16 v[20:23], v[222:225], v[198:201], v[20:23]
	v_mfma_f32_16x16x32_bf16 v[16:19], v[230:233], v[198:201], v[16:19]
	v_mfma_f32_16x16x32_bf16 v[12:15], v[222:225], v[206:209], v[12:15]
	v_mfma_f32_16x16x32_bf16 v[8:11], v[230:233], v[206:209], v[8:11]
	v_mfma_f32_16x16x32_bf16 v[4:7], v[222:225], v[214:217], v[4:7]
	v_mfma_f32_16x16x32_bf16 v[0:3], v[230:233], v[214:217], v[0:3]
	s_barrier
	ds_read_b128 v[156:159], v193 offset:32768
	ds_read_b128 v[160:163], v193 offset:33792
	ds_read_b128 v[194:197], v192 offset:32768
	ds_read_b128 v[198:201], v192 offset:33792
	ds_read_b128 v[202:205], v191 offset:32768
	ds_read_b128 v[206:209], v191 offset:33792
	ds_read_b128 v[210:213], v190 offset:32768
	ds_read_b128 v[214:217], v190 offset:33792
	s_waitcnt lgkmcnt(8)
	s_waitcnt vmcnt(10)
	s_barrier
	s_waitcnt lgkmcnt(0)
	s_waitcnt lgkmcnt(0)
	v_mfma_f32_16x16x32_bf16 v[124:127], v[140:143], v[156:159], v[124:127]
	v_mfma_f32_16x16x32_bf16 v[120:123], v[148:151], v[156:159], v[120:123]
	v_mfma_f32_16x16x32_bf16 v[116:119], v[140:143], v[194:197], v[116:119]
	v_mfma_f32_16x16x32_bf16 v[112:115], v[148:151], v[194:197], v[112:115]
	v_mfma_f32_16x16x32_bf16 v[108:111], v[140:143], v[202:205], v[108:111]
	v_mfma_f32_16x16x32_bf16 v[104:107], v[148:151], v[202:205], v[104:107]
	v_mfma_f32_16x16x32_bf16 v[100:103], v[140:143], v[210:213], v[100:103]
	v_mfma_f32_16x16x32_bf16 v[96:99], v[148:151], v[210:213], v[96:99]
	v_mfma_f32_16x16x32_bf16 v[124:127], v[144:147], v[160:163], v[124:127]
	v_mfma_f32_16x16x32_bf16 v[120:123], v[152:155], v[160:163], v[120:123]
	v_mfma_f32_16x16x32_bf16 v[116:119], v[144:147], v[198:201], v[116:119]
	v_mfma_f32_16x16x32_bf16 v[112:115], v[152:155], v[198:201], v[112:115]
	v_mfma_f32_16x16x32_bf16 v[108:111], v[144:147], v[206:209], v[108:111]
	v_mfma_f32_16x16x32_bf16 v[104:107], v[152:155], v[206:209], v[104:107]
	v_mfma_f32_16x16x32_bf16 v[100:103], v[144:147], v[214:217], v[100:103]
	v_mfma_f32_16x16x32_bf16 v[96:99], v[152:155], v[214:217], v[96:99]
	s_barrier
	s_add_i32 s82, s98, 0x18000
	v_lshl_add_u64 v[234:235], s[56:57], 0, v[164:165]
	s_mov_b32 m0, s82
	s_add_i32 s82, s98, 0x1a000
	ds_read_b128 v[218:221], v132
	ds_read_b128 v[222:225], v132 offset:1024
	ds_read_b128 v[226:229], v132 offset:2048
	ds_read_b128 v[230:233], v132 offset:3072
	global_load_lds_dwordx4 v[234:235], off
	v_lshl_add_u64 v[236:237], v[234:235], 0, s[2:3]
	s_mov_b32 m0, s82
	s_nop 0
	global_load_lds_dwordx4 v[236:237], off
	s_add_i32 s82, s98, 0x8000
	v_lshl_add_u64 v[236:237], v[128:129], 0, s[28:29]
	s_mov_b32 m0, s82
	s_add_i32 s82, s98, 0xa000
	global_load_lds_dwordx4 v[236:237], off
	v_lshl_add_u64 v[236:237], v[128:129], 0, s[30:31]
	s_mov_b32 m0, s82
	s_nop 0
	global_load_lds_dwordx4 v[236:237], off
	s_waitcnt vmcnt(12)
	s_barrier
	s_waitcnt lgkmcnt(0)
	s_waitcnt lgkmcnt(0)
	v_mfma_f32_16x16x32_bf16 v[92:95], v[218:221], v[156:159], v[92:95]
	v_mfma_f32_16x16x32_bf16 v[88:91], v[226:229], v[156:159], v[88:91]
	v_mfma_f32_16x16x32_bf16 v[84:87], v[218:221], v[194:197], v[84:87]
	v_mfma_f32_16x16x32_bf16 v[80:83], v[226:229], v[194:197], v[80:83]
	v_mfma_f32_16x16x32_bf16 v[76:79], v[218:221], v[202:205], v[76:79]
	v_mfma_f32_16x16x32_bf16 v[72:75], v[226:229], v[202:205], v[72:75]
	v_mfma_f32_16x16x32_bf16 v[68:71], v[218:221], v[210:213], v[68:71]
	v_mfma_f32_16x16x32_bf16 v[64:67], v[226:229], v[210:213], v[64:67]
	v_mfma_f32_16x16x32_bf16 v[92:95], v[222:225], v[160:163], v[92:95]
	v_mfma_f32_16x16x32_bf16 v[88:91], v[230:233], v[160:163], v[88:91]
	v_mfma_f32_16x16x32_bf16 v[84:87], v[222:225], v[198:201], v[84:87]
	v_mfma_f32_16x16x32_bf16 v[80:83], v[230:233], v[198:201], v[80:83]
	v_mfma_f32_16x16x32_bf16 v[76:79], v[222:225], v[206:209], v[76:79]
	v_mfma_f32_16x16x32_bf16 v[72:75], v[230:233], v[206:209], v[72:75]
	v_mfma_f32_16x16x32_bf16 v[68:71], v[222:225], v[214:217], v[68:71]
	v_mfma_f32_16x16x32_bf16 v[64:67], v[230:233], v[214:217], v[64:67]
	s_barrier
	ds_read_b128 v[156:159], v193 offset:49152
	ds_read_b128 v[160:163], v193 offset:50176
	ds_read_b128 v[194:197], v192 offset:49152
	ds_read_b128 v[198:201], v192 offset:50176
	ds_read_b128 v[202:205], v191 offset:49152
	ds_read_b128 v[206:209], v191 offset:50176
	ds_read_b128 v[210:213], v190 offset:49152
	ds_read_b128 v[214:217], v190 offset:50176
	s_add_i32 s82, s98, 0x1c000
	v_lshl_add_u64 v[236:237], v[234:235], 0, s[6:7]
	s_mov_b32 m0, s82
	s_add_i32 s82, s98, 0x1e000
	global_load_lds_dwordx4 v[236:237], off
	v_lshl_add_u64 v[236:237], v[234:235], 0, s[8:9]
	s_mov_b32 m0, s82
	s_nop 0
	global_load_lds_dwordx4 v[236:237], off
	s_waitcnt vmcnt(12)
	s_barrier
	s_waitcnt lgkmcnt(0)
	s_waitcnt lgkmcnt(0)
	v_mfma_f32_16x16x32_bf16 v[60:63], v[140:143], v[156:159], v[60:63]
	v_mfma_f32_16x16x32_bf16 v[56:59], v[148:151], v[156:159], v[56:59]
	v_mfma_f32_16x16x32_bf16 v[52:55], v[140:143], v[194:197], v[52:55]
	v_mfma_f32_16x16x32_bf16 v[48:51], v[148:151], v[194:197], v[48:51]
	v_mfma_f32_16x16x32_bf16 v[44:47], v[140:143], v[202:205], v[44:47]
	v_mfma_f32_16x16x32_bf16 v[40:43], v[148:151], v[202:205], v[40:43]
	v_mfma_f32_16x16x32_bf16 v[36:39], v[140:143], v[210:213], v[36:39]
	v_mfma_f32_16x16x32_bf16 v[32:35], v[148:151], v[210:213], v[32:35]
	v_mfma_f32_16x16x32_bf16 v[60:63], v[144:147], v[160:163], v[60:63]
	v_mfma_f32_16x16x32_bf16 v[56:59], v[152:155], v[160:163], v[56:59]
	v_mfma_f32_16x16x32_bf16 v[52:55], v[144:147], v[198:201], v[52:55]
	v_mfma_f32_16x16x32_bf16 v[48:51], v[152:155], v[198:201], v[48:51]
	v_mfma_f32_16x16x32_bf16 v[44:47], v[144:147], v[206:209], v[44:47]
	v_mfma_f32_16x16x32_bf16 v[40:43], v[152:155], v[206:209], v[40:43]
	v_mfma_f32_16x16x32_bf16 v[36:39], v[144:147], v[214:217], v[36:39]
	v_mfma_f32_16x16x32_bf16 v[32:35], v[152:155], v[214:217], v[32:35]
	s_barrier
	v_lshl_add_u64 v[128:129], v[128:129], 0, s[34:35]
	s_add_i32 s82, s98, 0xc000
	v_lshl_add_u64 v[142:143], v[128:129], 0, s[18:19]
	s_mov_b32 m0, s82
	s_add_i32 s82, s98, 0xe000
	global_load_lds_dwordx4 v[142:143], off
	v_lshl_add_u64 v[142:143], v[128:129], 0, s[20:21]
	s_mov_b32 m0, s82
	s_nop 0
	global_load_lds_dwordx4 v[142:143], off
	ds_read_b128 v[140:143], v138
	ds_read_b128 v[144:147], v138 offset:1024
	ds_read_b128 v[148:151], v138 offset:2048
	ds_read_b128 v[152:155], v138 offset:3072
	s_waitcnt vmcnt(12)
	s_barrier
	v_mfma_f32_16x16x32_bf16 v[28:31], v[218:221], v[156:159], v[28:31]
	v_mfma_f32_16x16x32_bf16 v[24:27], v[226:229], v[156:159], v[24:27]
	v_mfma_f32_16x16x32_bf16 v[20:23], v[218:221], v[194:197], v[20:23]
	v_mfma_f32_16x16x32_bf16 v[16:19], v[226:229], v[194:197], v[16:19]
	v_mfma_f32_16x16x32_bf16 v[12:15], v[218:221], v[202:205], v[12:15]
	v_mfma_f32_16x16x32_bf16 v[8:11], v[226:229], v[202:205], v[8:11]
	v_mfma_f32_16x16x32_bf16 v[4:7], v[218:221], v[210:213], v[4:7]
	v_mfma_f32_16x16x32_bf16 v[0:3], v[226:229], v[210:213], v[0:3]
	v_mfma_f32_16x16x32_bf16 v[28:31], v[222:225], v[160:163], v[28:31]
	v_mfma_f32_16x16x32_bf16 v[24:27], v[230:233], v[160:163], v[24:27]
	v_mfma_f32_16x16x32_bf16 v[20:23], v[222:225], v[198:201], v[20:23]
	v_mfma_f32_16x16x32_bf16 v[16:19], v[230:233], v[198:201], v[16:19]
	v_mfma_f32_16x16x32_bf16 v[12:15], v[222:225], v[206:209], v[12:15]
	v_mfma_f32_16x16x32_bf16 v[8:11], v[230:233], v[206:209], v[8:11]
	v_mfma_f32_16x16x32_bf16 v[4:7], v[222:225], v[214:217], v[4:7]
	v_mfma_f32_16x16x32_bf16 v[0:3], v[230:233], v[214:217], v[0:3]
	s_add_i32 s14, s14, 2
	s_add_u32 s56, s56, s58
	s_addc_u32 s57, s57, s59
	s_add_u32 s60, s60, s58
	s_addc_u32 s61, s61, s59
	s_cmp_lt_u32 s14, 28
	s_barrier
	s_cbranch_scc1 .LBB0_234
	s_lshl_b32 s14, s62, 3
	s_or_b32 s82, s63, s14
	s_lshl_b32 s56, s82, 8
	v_lshlrev_b32_e32 v128, 3, v131
	v_lshlrev_b32_e32 v129, 5, v131
	s_or_b32 s14, s56, 0x80
	v_and_b32_e32 v128, 0x7fff0, v128
	v_and_b32_e32 v129, 32, v129
	s_lshl_b64 s[58:59], s[14:15], 13
	v_add_u32_e32 v129, v129, v134
	v_add_lshl_u32 v128, v133, v128, 13
	s_add_u32 s58, s40, s58
	v_lshl_add_u32 v164, v129, 1, v128
	s_addc_u32 s59, s41, s59
	v_lshl_add_u64 v[128:129], s[58:59], 0, v[164:165]
	v_readfirstlane_b32 s14, v137
	ds_read_b128 v[140:143], v138
	ds_read_b128 v[144:147], v138 offset:1024
	ds_read_b128 v[148:151], v138 offset:2048
	ds_read_b128 v[152:155], v138 offset:3072
	ds_read_b128 v[156:159], v193
	ds_read_b128 v[160:163], v193 offset:1024
	ds_read_b128 v[194:197], v192
	ds_read_b128 v[198:201], v192 offset:1024
	ds_read_b128 v[202:205], v191
	ds_read_b128 v[206:209], v191 offset:1024
	ds_read_b128 v[210:213], v190
	ds_read_b128 v[214:217], v190 offset:1024
	v_lshl_add_u64 v[138:139], v[128:129], 0, s[44:45]
	s_mov_b32 m0, s14
	v_readfirstlane_b32 s14, v136
	global_load_lds_dwordx4 v[138:139], off
	v_lshl_add_u64 v[128:129], v[128:129], 0, s[46:47]
	s_mov_b32 m0, s14
	s_mov_b32 s57, s15
	global_load_lds_dwordx4 v[128:129], off
	s_mul_i32 s99, s78, s84
	s_add_i32 s99, s99, s33
	s_cmpk_lt_u32 s99, 0x400
	s_cbranch_scc1 .Lxt5_has
	s_mov_b32 s99, 0
	s_branch .Lxt5_set

.LBB0_273:
	v_and_b32_e32 v2, 15, v0
	s_bfe_u32 s64, s86, 0x30003
	v_and_b32_e32 v3, 48, v0
	v_lshlrev_b32_e32 v134, 4, v135
	v_and_b32_e32 v5, 32, v0
	s_movk_i32 s65, 0x3f0
	v_and_b32_e32 v6, 64, v135
	v_lshlrev_b32_e32 v2, 6, v2
	v_lshlrev_b32_e32 v9, 2, v0
	v_lshlrev_b32_e32 v0, 6, v0
	s_lshl_b32 s66, s64, 14
	v_and_b32_e32 v4, 0x3f0, v134
	v_bitop3_b32 v155, v134, v5, s65 bitop3:0x6c
	v_lshlrev_b32_e32 v156, 13, v6
	v_lshlrev_b32_e32 v7, 3, v135
	v_mul_i32_i24_e32 v6, 0xffffe800, v6
	s_add_i32 s65, s20, -2
	v_or_b32_e32 v8, v2, v3
	v_and_b32_e32 v9, 32, v9
	s_mov_b32 s67, 0x14000
	v_and_b32_e32 v0, 0x3c0, v0
	v_and_b32_e32 v157, 0xfffffc00, v7
	v_bitop3_b32 v2, v2, v9, v3 bitop3:0x36
	v_bitop3_b32 v11, v8, s67, v9 bitop3:0xde
	s_mov_b32 s67, 0x1c000
	v_bitop3_b32 v3, v0, v9, v3 bitop3:0x36
	v_bitop3_b32 v0, v6, v4, v5 bitop3:0xf6
	s_add_u32 s66, s70, s66
	v_bitop3_b32 v10, v8, s74, v9 bitop3:0xde
	v_bitop3_b32 v12, v8, s75, v9 bitop3:0xde
	v_bitop3_b32 v8, v8, s67, v9 bitop3:0xde
	v_add3_u32 v128, v0, v156, v157
	s_addc_u32 s67, s71, 0
	v_lshlrev_b32_e32 v13, 13, v1
	v_lshl_add_u64 v[0:1], s[66:67], 0, v[128:129]
	s_mov_b64 s[66:67], 0xc3000
	v_lshl_add_u64 v[130:131], v[0:1], 0, s[66:67]
	s_lshl_b32 s66, s86, 11
	s_and_b32 s67, s86, 7
	s_and_b32 s66, s66, 0x60000
	s_lshl_b32 s67, s67, 14
	s_or_b32 s66, s66, s67
	v_bitop3_b32 v0, v4, v156, v5 bitop3:0xde
	s_add_u32 s66, s68, s66
	v_add_u32_e32 v128, v0, v157
	s_addc_u32 s67, s69, 0
	v_lshlrev_b32_e32 v7, 6, v135
	v_lshl_add_u64 v[0:1], s[66:67], 0, v[128:129]
	s_mov_b64 s[66:67], 0x301000
	v_and_b32_e32 v7, 0x3000, v7
	v_or_b32_e32 v9, 0x800, v13
	v_or_b32_e32 v14, 0x1000, v13
	v_or_b32_e32 v15, 0x1800, v13
	v_lshl_add_u64 v[132:133], v[0:1], 0, s[66:67]
	v_mov_b32_e32 v0, 0
	s_mov_b32 s66, 0
	v_add_u32_e32 v161, v10, v7
	v_add_u32_e32 v152, v2, v13
	v_add_u32_e32 v151, v3, v9
	v_add_u32_e32 v150, v3, v14
	v_add_u32_e32 v149, v3, v15
	v_add_u32_e32 v160, 0xc000, v134
	v_add_u32_e32 v159, 0xe000, v134
	v_add_u32_e32 v158, v11, v7
	v_add_u32_e32 v148, 0x10000, v134
	v_add_u32_e32 v147, 0x12000, v134
	v_add_u32_e32 v146, 0x2000, v134
	v_add_u32_e32 v145, 0x14000, v134
	v_add_u32_e32 v144, 0x16000, v134
	v_add_u32_e32 v154, v12, v7
	v_add_u32_e32 v143, 0x4000, v134
	v_add_u32_e32 v142, 0x6000, v134
	v_add_u32_e32 v153, v8, v7
	v_add_u32_e32 v141, 0x18000, v134
	v_add_u32_e32 v140, 0x1a000, v134
	v_add_u32_e32 v139, 0x8000, v134
	v_add_u32_e32 v138, 0xa000, v134
	v_add_u32_e32 v137, 0x1c000, v134
	v_add_u32_e32 v136, 0x1e000, v134
	v_mov_b32_e32 v1, v0
	v_mov_b32_e32 v2, v0
	v_mov_b32_e32 v3, v0
	v_mov_b32_e32 v4, v0
	v_mov_b32_e32 v5, v0
	v_mov_b32_e32 v6, v0
	v_mov_b32_e32 v7, v0
	v_mov_b32_e32 v8, v0
	v_mov_b32_e32 v9, v0
	v_mov_b32_e32 v10, v0
	v_mov_b32_e32 v11, v0
	v_mov_b32_e32 v12, v0
	v_mov_b32_e32 v13, v0
	v_mov_b32_e32 v14, v0
	v_mov_b32_e32 v15, v0
	v_mov_b32_e32 v16, v0
	v_mov_b32_e32 v17, v0
	v_mov_b32_e32 v18, v0
	v_mov_b32_e32 v19, v0
	v_mov_b32_e32 v20, v0
	v_mov_b32_e32 v21, v0
	v_mov_b32_e32 v22, v0
	v_mov_b32_e32 v23, v0
	v_mov_b32_e32 v24, v0
	v_mov_b32_e32 v25, v0
	v_mov_b32_e32 v26, v0
	v_mov_b32_e32 v27, v0
	v_mov_b32_e32 v28, v0
	v_mov_b32_e32 v29, v0
	v_mov_b32_e32 v30, v0
	v_mov_b32_e32 v31, v0
	v_mov_b32_e32 v32, v0
	v_mov_b32_e32 v33, v0
	v_mov_b32_e32 v34, v0
	v_mov_b32_e32 v35, v0
	v_mov_b32_e32 v36, v0
	v_mov_b32_e32 v37, v0
	v_mov_b32_e32 v38, v0
	v_mov_b32_e32 v39, v0
	v_mov_b32_e32 v40, v0
	v_mov_b32_e32 v41, v0
	v_mov_b32_e32 v42, v0
	v_mov_b32_e32 v43, v0
	v_mov_b32_e32 v44, v0
	v_mov_b32_e32 v45, v0
	v_mov_b32_e32 v46, v0
	v_mov_b32_e32 v47, v0
	v_mov_b32_e32 v48, v0
	v_mov_b32_e32 v49, v0
	v_mov_b32_e32 v50, v0
	v_mov_b32_e32 v51, v0
	v_mov_b32_e32 v52, v0
	v_mov_b32_e32 v53, v0
	v_mov_b32_e32 v54, v0
	v_mov_b32_e32 v55, v0
	v_mov_b32_e32 v56, v0
	v_mov_b32_e32 v57, v0
	v_mov_b32_e32 v58, v0
	v_mov_b32_e32 v59, v0
	v_mov_b32_e32 v60, v0
	v_mov_b32_e32 v61, v0
	v_mov_b32_e32 v62, v0
	v_mov_b32_e32 v63, v0
	v_mov_b32_e32 v64, v0
	v_mov_b32_e32 v65, v0
	v_mov_b32_e32 v66, v0
	v_mov_b32_e32 v67, v0
	v_mov_b32_e32 v68, v0
	v_mov_b32_e32 v69, v0
	v_mov_b32_e32 v70, v0
	v_mov_b32_e32 v71, v0
	v_mov_b32_e32 v72, v0
	v_mov_b32_e32 v73, v0
	v_mov_b32_e32 v74, v0
	v_mov_b32_e32 v75, v0
	v_mov_b32_e32 v76, v0
	v_mov_b32_e32 v77, v0
	v_mov_b32_e32 v78, v0
	v_mov_b32_e32 v79, v0
	v_mov_b32_e32 v80, v0
	v_mov_b32_e32 v81, v0
	v_mov_b32_e32 v82, v0
	v_mov_b32_e32 v83, v0
	v_mov_b32_e32 v84, v0
	v_mov_b32_e32 v85, v0
	v_mov_b32_e32 v86, v0
	v_mov_b32_e32 v87, v0
	v_mov_b32_e32 v88, v0
	v_mov_b32_e32 v89, v0
	v_mov_b32_e32 v90, v0
	v_mov_b32_e32 v91, v0
	v_mov_b32_e32 v92, v0
	v_mov_b32_e32 v93, v0
	v_mov_b32_e32 v94, v0
	v_mov_b32_e32 v95, v0
	v_mov_b32_e32 v96, v0
	v_mov_b32_e32 v97, v0
	v_mov_b32_e32 v98, v0
	v_mov_b32_e32 v99, v0
	v_mov_b32_e32 v100, v0
	v_mov_b32_e32 v101, v0
	v_mov_b32_e32 v102, v0
	v_mov_b32_e32 v103, v0
	v_mov_b32_e32 v104, v0
	v_mov_b32_e32 v105, v0
	v_mov_b32_e32 v106, v0
	v_mov_b32_e32 v107, v0
	v_mov_b32_e32 v108, v0
	v_mov_b32_e32 v109, v0
	v_mov_b32_e32 v110, v0
	v_mov_b32_e32 v111, v0
	v_mov_b32_e32 v112, v0
	v_mov_b32_e32 v113, v0
	v_mov_b32_e32 v114, v0
	v_mov_b32_e32 v115, v0
	v_mov_b32_e32 v116, v0
	v_mov_b32_e32 v117, v0
	v_mov_b32_e32 v118, v0
	v_mov_b32_e32 v119, v0
	v_mov_b32_e32 v120, v0
	v_mov_b32_e32 v121, v0
	v_mov_b32_e32 v122, v0
	v_mov_b32_e32 v123, v0
	v_mov_b32_e32 v124, v0
	v_mov_b32_e32 v125, v0
	v_mov_b32_e32 v126, v0
	v_mov_b32_e32 v127, v0
	s_barrier
	v_readlane_b32 s98, v242, 1
	s_lshl_b32 s98, s98, 10
	s_mov_b32 vcc_lo, 0xffe01000
	s_mov_b32 vcc_hi, -1
	v_lshl_add_u64 v[164:165], v[132:133], 0, vcc
	s_add_i32 s67, s98, 0xc000
	s_mov_b32 vcc_lo, 0xffe02000
	s_mov_b32 m0, s67
	s_mov_b32 vcc_hi, -1
	s_add_i32 s67, s98, 0xe000
	global_load_lds_dwordx4 v[164:165], off
	v_lshl_add_u64 v[164:165], v[132:133], 0, vcc
	s_mov_b32 m0, s67
	s_nop 0
	global_load_lds_dwordx4 v[164:165], off
	ds_read_b128 v[162:165], v161
	ds_read_b128 v[166:169], v161 offset:1024
	ds_read_b128 v[170:173], v161 offset:2048
	ds_read_b128 v[174:177], v161 offset:3072
.LBB0_274:
	ds_read_b128 v[178:181], v152
	ds_read_b128 v[182:185], v152 offset:1024
	ds_read_b128 v[186:189], v151
	ds_read_b128 v[190:193], v151 offset:1024
	ds_read_b128 v[194:197], v150
	ds_read_b128 v[198:201], v150 offset:1024
	ds_read_b128 v[202:205], v149
	ds_read_b128 v[206:209], v149 offset:1024
	s_waitcnt lgkmcnt(8)
	s_waitcnt vmcnt(10)
	s_barrier
	s_waitcnt lgkmcnt(0)
	s_waitcnt lgkmcnt(0)
	v_mfma_f32_16x16x32_bf16 v[124:127], v[162:165], v[178:181], v[124:127]
	v_mfma_f32_16x16x32_bf16 v[120:123], v[170:173], v[178:181], v[120:123]
	v_mfma_f32_16x16x32_bf16 v[116:119], v[162:165], v[186:189], v[116:119]
	v_mfma_f32_16x16x32_bf16 v[112:115], v[170:173], v[186:189], v[112:115]
	v_mfma_f32_16x16x32_bf16 v[108:111], v[162:165], v[194:197], v[108:111]
	v_mfma_f32_16x16x32_bf16 v[104:107], v[170:173], v[194:197], v[104:107]
	v_mfma_f32_16x16x32_bf16 v[100:103], v[162:165], v[202:205], v[100:103]
	v_mfma_f32_16x16x32_bf16 v[96:99], v[170:173], v[202:205], v[96:99]
	v_mfma_f32_16x16x32_bf16 v[124:127], v[166:169], v[182:185], v[124:127]
	v_mfma_f32_16x16x32_bf16 v[120:123], v[174:177], v[182:185], v[120:123]
	v_mfma_f32_16x16x32_bf16 v[116:119], v[166:169], v[190:193], v[116:119]
	v_mfma_f32_16x16x32_bf16 v[112:115], v[174:177], v[190:193], v[112:115]
	v_mfma_f32_16x16x32_bf16 v[108:111], v[166:169], v[198:201], v[108:111]
	v_mfma_f32_16x16x32_bf16 v[104:107], v[174:177], v[198:201], v[104:107]
	v_mfma_f32_16x16x32_bf16 v[100:103], v[166:169], v[206:209], v[100:103]
	v_mfma_f32_16x16x32_bf16 v[96:99], v[174:177], v[206:209], v[96:99]
	s_barrier
	s_mov_b32 vcc_lo, 0xfffbd000
	s_mov_b32 vcc_hi, -1
	s_add_i32 s67, s98, 0x10000
	v_lshl_add_u64 v[226:227], v[130:131], 0, vcc
	s_mov_b32 m0, s67
	s_add_i32 s67, s98, 0x12000
	ds_read_b128 v[210:213], v158
	ds_read_b128 v[214:217], v158 offset:1024
	ds_read_b128 v[218:221], v158 offset:2048
	ds_read_b128 v[222:225], v158 offset:3072
	global_load_lds_dwordx4 v[226:227], off
	v_lshl_add_u64 v[226:227], v[130:131], 0, s[22:23]
	s_mov_b32 m0, s67
	s_add_i32 s66, s66, 2
	global_load_lds_dwordx4 v[226:227], off
	s_mov_b32 s67, s98
	v_lshl_add_u64 v[226:227], v[132:133], 0, s[24:25]
	s_mov_b32 m0, s67
	s_add_i32 s67, s98, 0x2000
	global_load_lds_dwordx4 v[226:227], off
	v_lshl_add_u64 v[226:227], v[132:133], 0, s[26:27]
	s_mov_b32 m0, s67
	s_nop 0
	global_load_lds_dwordx4 v[226:227], off
	s_waitcnt vmcnt(12)
	s_barrier
	s_waitcnt lgkmcnt(0)
	s_waitcnt lgkmcnt(0)
	v_mfma_f32_16x16x32_bf16 v[92:95], v[210:213], v[178:181], v[92:95]
	v_mfma_f32_16x16x32_bf16 v[88:91], v[218:221], v[178:181], v[88:91]
	v_mfma_f32_16x16x32_bf16 v[84:87], v[210:213], v[186:189], v[84:87]
	v_mfma_f32_16x16x32_bf16 v[80:83], v[218:221], v[186:189], v[80:83]
	v_mfma_f32_16x16x32_bf16 v[76:79], v[210:213], v[194:197], v[76:79]
	v_mfma_f32_16x16x32_bf16 v[72:75], v[218:221], v[194:197], v[72:75]
	v_mfma_f32_16x16x32_bf16 v[68:71], v[210:213], v[202:205], v[68:71]
	v_mfma_f32_16x16x32_bf16 v[64:67], v[218:221], v[202:205], v[64:67]
	v_mfma_f32_16x16x32_bf16 v[92:95], v[214:217], v[182:185], v[92:95]
	v_mfma_f32_16x16x32_bf16 v[88:91], v[222:225], v[182:185], v[88:91]
	v_mfma_f32_16x16x32_bf16 v[84:87], v[214:217], v[190:193], v[84:87]
	v_mfma_f32_16x16x32_bf16 v[80:83], v[222:225], v[190:193], v[80:83]
	v_mfma_f32_16x16x32_bf16 v[76:79], v[214:217], v[198:201], v[76:79]
	v_mfma_f32_16x16x32_bf16 v[72:75], v[222:225], v[198:201], v[72:75]
	v_mfma_f32_16x16x32_bf16 v[68:71], v[214:217], v[206:209], v[68:71]
	v_mfma_f32_16x16x32_bf16 v[64:67], v[222:225], v[206:209], v[64:67]
	s_barrier
	ds_read_b128 v[178:181], v152 offset:16384
	ds_read_b128 v[182:185], v152 offset:17408
	ds_read_b128 v[186:189], v151 offset:16384
	ds_read_b128 v[190:193], v151 offset:17408
	ds_read_b128 v[194:197], v150 offset:16384
	ds_read_b128 v[198:201], v150 offset:17408
	ds_read_b128 v[202:205], v149 offset:16384
	ds_read_b128 v[206:209], v149 offset:17408
	s_add_i32 s67, s98, 0x14000
	v_lshl_add_u64 v[226:227], v[130:131], 0, s[28:29]
	s_mov_b32 m0, s67
	s_add_i32 s67, s98, 0x16000
	global_load_lds_dwordx4 v[226:227], off
	v_lshl_add_u64 v[226:227], v[130:131], 0, s[30:31]
	s_mov_b32 m0, s67
	s_nop 0
	global_load_lds_dwordx4 v[226:227], off
	s_waitcnt vmcnt(12)
	s_barrier
	s_waitcnt lgkmcnt(0)
	s_waitcnt lgkmcnt(0)
	v_mfma_f32_16x16x32_bf16 v[60:63], v[162:165], v[178:181], v[60:63]
	v_mfma_f32_16x16x32_bf16 v[56:59], v[170:173], v[178:181], v[56:59]
	v_mfma_f32_16x16x32_bf16 v[52:55], v[162:165], v[186:189], v[52:55]
	v_mfma_f32_16x16x32_bf16 v[48:51], v[170:173], v[186:189], v[48:51]
	v_mfma_f32_16x16x32_bf16 v[44:47], v[162:165], v[194:197], v[44:47]
	v_mfma_f32_16x16x32_bf16 v[40:43], v[170:173], v[194:197], v[40:43]
	v_mfma_f32_16x16x32_bf16 v[36:39], v[162:165], v[202:205], v[36:39]
	v_mfma_f32_16x16x32_bf16 v[32:35], v[170:173], v[202:205], v[32:35]
	v_mfma_f32_16x16x32_bf16 v[60:63], v[166:169], v[182:185], v[60:63]
	v_mfma_f32_16x16x32_bf16 v[56:59], v[174:177], v[182:185], v[56:59]
	v_mfma_f32_16x16x32_bf16 v[52:55], v[166:169], v[190:193], v[52:55]
	v_mfma_f32_16x16x32_bf16 v[48:51], v[174:177], v[190:193], v[48:51]
	v_mfma_f32_16x16x32_bf16 v[44:47], v[166:169], v[198:201], v[44:47]
	v_mfma_f32_16x16x32_bf16 v[40:43], v[174:177], v[198:201], v[40:43]
	v_mfma_f32_16x16x32_bf16 v[36:39], v[166:169], v[206:209], v[36:39]
	v_mfma_f32_16x16x32_bf16 v[32:35], v[174:177], v[206:209], v[32:35]
	s_barrier
	s_add_i32 s67, s98, 0x4000
	v_lshl_add_u64 v[164:165], v[132:133], 0, s[34:35]
	s_mov_b32 m0, s67
	s_add_i32 s67, s98, 0x6000
	global_load_lds_dwordx4 v[164:165], off
	v_lshl_add_u64 v[164:165], v[132:133], 0, s[44:45]
	s_mov_b32 m0, s67
	s_nop 0
	global_load_lds_dwordx4 v[164:165], off
	ds_read_b128 v[162:165], v154
	ds_read_b128 v[166:169], v154 offset:1024
	ds_read_b128 v[170:173], v154 offset:2048
	ds_read_b128 v[174:177], v154 offset:3072
	s_waitcnt vmcnt(12)
	s_barrier
	v_mfma_f32_16x16x32_bf16 v[28:31], v[210:213], v[178:181], v[28:31]
	v_mfma_f32_16x16x32_bf16 v[24:27], v[218:221], v[178:181], v[24:27]
	v_mfma_f32_16x16x32_bf16 v[20:23], v[210:213], v[186:189], v[20:23]
	v_mfma_f32_16x16x32_bf16 v[16:19], v[218:221], v[186:189], v[16:19]
	v_mfma_f32_16x16x32_bf16 v[12:15], v[210:213], v[194:197], v[12:15]
	v_mfma_f32_16x16x32_bf16 v[8:11], v[218:221], v[194:197], v[8:11]
	v_mfma_f32_16x16x32_bf16 v[4:7], v[210:213], v[202:205], v[4:7]
	v_mfma_f32_16x16x32_bf16 v[0:3], v[218:221], v[202:205], v[0:3]
	v_mfma_f32_16x16x32_bf16 v[28:31], v[214:217], v[182:185], v[28:31]
	v_mfma_f32_16x16x32_bf16 v[24:27], v[222:225], v[182:185], v[24:27]
	v_mfma_f32_16x16x32_bf16 v[20:23], v[214:217], v[190:193], v[20:23]
	v_mfma_f32_16x16x32_bf16 v[16:19], v[222:225], v[190:193], v[16:19]
	v_mfma_f32_16x16x32_bf16 v[12:15], v[214:217], v[198:201], v[12:15]
	v_mfma_f32_16x16x32_bf16 v[8:11], v[222:225], v[198:201], v[8:11]
	v_mfma_f32_16x16x32_bf16 v[4:7], v[214:217], v[206:209], v[4:7]
	v_mfma_f32_16x16x32_bf16 v[0:3], v[222:225], v[206:209], v[0:3]
	s_barrier
	ds_read_b128 v[178:181], v152 offset:32768
	ds_read_b128 v[182:185], v152 offset:33792
	ds_read_b128 v[186:189], v151 offset:32768
	ds_read_b128 v[190:193], v151 offset:33792
	ds_read_b128 v[194:197], v150 offset:32768
	ds_read_b128 v[198:201], v150 offset:33792
	ds_read_b128 v[202:205], v149 offset:32768
	ds_read_b128 v[206:209], v149 offset:33792
	s_waitcnt lgkmcnt(8)
	s_waitcnt vmcnt(10)
	s_barrier
	s_waitcnt lgkmcnt(0)
	s_waitcnt lgkmcnt(0)
	v_mfma_f32_16x16x32_bf16 v[124:127], v[162:165], v[178:181], v[124:127]
	v_mfma_f32_16x16x32_bf16 v[120:123], v[170:173], v[178:181], v[120:123]
	v_mfma_f32_16x16x32_bf16 v[116:119], v[162:165], v[186:189], v[116:119]
	v_mfma_f32_16x16x32_bf16 v[112:115], v[170:173], v[186:189], v[112:115]
	v_mfma_f32_16x16x32_bf16 v[108:111], v[162:165], v[194:197], v[108:111]
	v_mfma_f32_16x16x32_bf16 v[104:107], v[170:173], v[194:197], v[104:107]
	v_mfma_f32_16x16x32_bf16 v[100:103], v[162:165], v[202:205], v[100:103]
	v_mfma_f32_16x16x32_bf16 v[96:99], v[170:173], v[202:205], v[96:99]
	v_mfma_f32_16x16x32_bf16 v[124:127], v[166:169], v[182:185], v[124:127]
	v_mfma_f32_16x16x32_bf16 v[120:123], v[174:177], v[182:185], v[120:123]
	v_mfma_f32_16x16x32_bf16 v[116:119], v[166:169], v[190:193], v[116:119]
	v_mfma_f32_16x16x32_bf16 v[112:115], v[174:177], v[190:193], v[112:115]
	v_mfma_f32_16x16x32_bf16 v[108:111], v[166:169], v[198:201], v[108:111]
	v_mfma_f32_16x16x32_bf16 v[104:107], v[174:177], v[198:201], v[104:107]
	v_mfma_f32_16x16x32_bf16 v[100:103], v[166:169], v[206:209], v[100:103]
	v_mfma_f32_16x16x32_bf16 v[96:99], v[174:177], v[206:209], v[96:99]
	s_barrier
	s_add_i32 s67, s98, 0x18000
	v_lshl_add_u64 v[226:227], v[130:131], 0, s[46:47]
	s_mov_b32 m0, s67
	s_add_i32 s67, s98, 0x1a000
	ds_read_b128 v[210:213], v153
	ds_read_b128 v[214:217], v153 offset:1024
	ds_read_b128 v[218:221], v153 offset:2048
	ds_read_b128 v[222:225], v153 offset:3072
	global_load_lds_dwordx4 v[226:227], off
	v_lshl_add_u64 v[226:227], v[130:131], 0, s[56:57]
	s_mov_b32 m0, s67
	s_nop 0
	global_load_lds_dwordx4 v[226:227], off
	s_add_i32 s67, s98, 0x8000
	v_lshl_add_u64 v[226:227], v[132:133], 0, s[58:59]
	s_mov_b32 m0, s67
	s_add_i32 s67, s98, 0xa000
	global_load_lds_dwordx4 v[226:227], off
	s_mov_b32 m0, s67
	s_nop 0
	global_load_lds_dwordx4 v[132:133], off
	s_waitcnt vmcnt(12)
	s_barrier
	s_waitcnt lgkmcnt(0)
	s_waitcnt lgkmcnt(0)
	v_mfma_f32_16x16x32_bf16 v[92:95], v[210:213], v[178:181], v[92:95]
	v_mfma_f32_16x16x32_bf16 v[88:91], v[218:221], v[178:181], v[88:91]
	v_mfma_f32_16x16x32_bf16 v[84:87], v[210:213], v[186:189], v[84:87]
	v_mfma_f32_16x16x32_bf16 v[80:83], v[218:221], v[186:189], v[80:83]
	v_mfma_f32_16x16x32_bf16 v[76:79], v[210:213], v[194:197], v[76:79]
	v_mfma_f32_16x16x32_bf16 v[72:75], v[218:221], v[194:197], v[72:75]
	v_mfma_f32_16x16x32_bf16 v[68:71], v[210:213], v[202:205], v[68:71]
	v_mfma_f32_16x16x32_bf16 v[64:67], v[218:221], v[202:205], v[64:67]
	v_mfma_f32_16x16x32_bf16 v[92:95], v[214:217], v[182:185], v[92:95]
	v_mfma_f32_16x16x32_bf16 v[88:91], v[222:225], v[182:185], v[88:91]
	v_mfma_f32_16x16x32_bf16 v[84:87], v[214:217], v[190:193], v[84:87]
	v_mfma_f32_16x16x32_bf16 v[80:83], v[222:225], v[190:193], v[80:83]
	v_mfma_f32_16x16x32_bf16 v[76:79], v[214:217], v[198:201], v[76:79]
	v_mfma_f32_16x16x32_bf16 v[72:75], v[222:225], v[198:201], v[72:75]
	v_mfma_f32_16x16x32_bf16 v[68:71], v[214:217], v[206:209], v[68:71]
	v_mfma_f32_16x16x32_bf16 v[64:67], v[222:225], v[206:209], v[64:67]
	s_barrier
	ds_read_b128 v[178:181], v152 offset:49152
	ds_read_b128 v[182:185], v152 offset:50176
	ds_read_b128 v[186:189], v151 offset:49152
	ds_read_b128 v[190:193], v151 offset:50176
	ds_read_b128 v[194:197], v150 offset:49152
	ds_read_b128 v[198:201], v150 offset:50176
	ds_read_b128 v[202:205], v149 offset:49152
	ds_read_b128 v[206:209], v149 offset:50176
	s_add_i32 s67, s98, 0x1c000
	v_lshl_add_u64 v[226:227], v[130:131], 0, s[58:59]
	s_mov_b32 m0, s67
	s_add_i32 s67, s98, 0x1e000
	global_load_lds_dwordx4 v[226:227], off
	s_mov_b32 m0, s67
	s_nop 0
	global_load_lds_dwordx4 v[130:131], off
	s_waitcnt vmcnt(12)
	s_barrier
	s_waitcnt lgkmcnt(0)
	s_waitcnt lgkmcnt(0)
	v_mfma_f32_16x16x32_bf16 v[60:63], v[162:165], v[178:181], v[60:63]
	v_mfma_f32_16x16x32_bf16 v[56:59], v[170:173], v[178:181], v[56:59]
	v_mfma_f32_16x16x32_bf16 v[52:55], v[162:165], v[186:189], v[52:55]
	v_mfma_f32_16x16x32_bf16 v[48:51], v[170:173], v[186:189], v[48:51]
	v_mfma_f32_16x16x32_bf16 v[44:47], v[162:165], v[194:197], v[44:47]
	v_mfma_f32_16x16x32_bf16 v[40:43], v[170:173], v[194:197], v[40:43]
	v_mfma_f32_16x16x32_bf16 v[36:39], v[162:165], v[202:205], v[36:39]
	v_mfma_f32_16x16x32_bf16 v[32:35], v[170:173], v[202:205], v[32:35]
	v_mfma_f32_16x16x32_bf16 v[60:63], v[166:169], v[182:185], v[60:63]
	v_mfma_f32_16x16x32_bf16 v[56:59], v[174:177], v[182:185], v[56:59]
	v_mfma_f32_16x16x32_bf16 v[52:55], v[166:169], v[190:193], v[52:55]
	v_mfma_f32_16x16x32_bf16 v[48:51], v[174:177], v[190:193], v[48:51]
	v_mfma_f32_16x16x32_bf16 v[44:47], v[166:169], v[198:201], v[44:47]
	v_mfma_f32_16x16x32_bf16 v[40:43], v[174:177], v[198:201], v[40:43]
	v_mfma_f32_16x16x32_bf16 v[36:39], v[166:169], v[206:209], v[36:39]
	v_mfma_f32_16x16x32_bf16 v[32:35], v[174:177], v[206:209], v[32:35]
	s_barrier
	v_lshl_add_u64 v[132:133], v[132:133], 0, s[62:63]
	s_mov_b32 vcc_lo, 0xffe01000
	s_mov_b32 vcc_hi, -1
	v_lshl_add_u64 v[164:165], v[132:133], 0, vcc
	s_add_i32 s67, s98, 0xc000
	s_mov_b32 vcc_lo, 0xffe02000
	s_mov_b32 m0, s67
	s_mov_b32 vcc_hi, -1
	s_add_i32 s67, s98, 0xe000
	global_load_lds_dwordx4 v[164:165], off
	v_lshl_add_u64 v[164:165], v[132:133], 0, vcc
	s_mov_b32 m0, s67
	s_nop 0
	global_load_lds_dwordx4 v[164:165], off
	ds_read_b128 v[162:165], v161
	ds_read_b128 v[166:169], v161 offset:1024
	ds_read_b128 v[170:173], v161 offset:2048
	ds_read_b128 v[174:177], v161 offset:3072
	s_waitcnt vmcnt(12)
	s_barrier
	v_mfma_f32_16x16x32_bf16 v[28:31], v[210:213], v[178:181], v[28:31]
	v_mfma_f32_16x16x32_bf16 v[24:27], v[218:221], v[178:181], v[24:27]
	v_mfma_f32_16x16x32_bf16 v[20:23], v[210:213], v[186:189], v[20:23]
	v_mfma_f32_16x16x32_bf16 v[16:19], v[218:221], v[186:189], v[16:19]
	v_mfma_f32_16x16x32_bf16 v[12:15], v[210:213], v[194:197], v[12:15]
	v_mfma_f32_16x16x32_bf16 v[8:11], v[218:221], v[194:197], v[8:11]
	v_mfma_f32_16x16x32_bf16 v[4:7], v[210:213], v[202:205], v[4:7]
	v_mfma_f32_16x16x32_bf16 v[0:3], v[218:221], v[202:205], v[0:3]
	v_mfma_f32_16x16x32_bf16 v[28:31], v[214:217], v[182:185], v[28:31]
	v_mfma_f32_16x16x32_bf16 v[24:27], v[222:225], v[182:185], v[24:27]
	v_mfma_f32_16x16x32_bf16 v[20:23], v[214:217], v[190:193], v[20:23]
	v_mfma_f32_16x16x32_bf16 v[16:19], v[222:225], v[190:193], v[16:19]
	v_mfma_f32_16x16x32_bf16 v[12:15], v[214:217], v[198:201], v[12:15]
	v_mfma_f32_16x16x32_bf16 v[8:11], v[222:225], v[198:201], v[8:11]
	v_mfma_f32_16x16x32_bf16 v[4:7], v[214:217], v[206:209], v[4:7]
	v_mfma_f32_16x16x32_bf16 v[0:3], v[222:225], v[206:209], v[0:3]
	v_lshl_add_u64 v[130:131], v[130:131], 0, s[60:61]
	s_cmp_lt_u32 s66, s65
	s_barrier
	s_cbranch_scc1 .LBB0_274
	s_lshl_b32 s65, s86, 5
	s_lshl_b32 s66, s86, 8
	s_and_b32 s65, s65, 0x1800
	s_and_b32 s66, s66, 0x700
	s_or_b32 s97, s66, s65
	s_lshl_b32 s65, s97, 6
	s_add_u32 s65, s68, s65
	s_addc_u32 s86, s69, 0
	s_add_i32 s20, s20, -1
	s_lshl_b64 s[66:67], s[20:21], 20
	v_add_u32_e32 v128, v156, v157
	s_add_u32 s66, s65, s66
	v_or_b32_e32 v128, v128, v155
	s_addc_u32 s67, s86, s67
	v_lshl_add_u64 v[156:157], s[66:67], 0, v[128:129]
	v_readfirstlane_b32 s20, v160
	v_lshl_add_u64 v[206:207], v[156:157], 0, s[4:5]
	s_mov_b32 m0, s20
	v_readfirstlane_b32 s20, v159
	ds_read_b128 v[130:133], v161
	ds_read_b128 v[162:165], v161 offset:1024
	ds_read_b128 v[166:169], v161 offset:2048
	ds_read_b128 v[170:173], v161 offset:3072
	ds_read_b128 v[174:177], v152
	ds_read_b128 v[178:181], v152 offset:1024
	ds_read_b128 v[182:185], v151
	ds_read_b128 v[186:189], v151 offset:1024
	ds_read_b128 v[190:193], v150
	ds_read_b128 v[194:197], v150 offset:1024
	ds_read_b128 v[198:201], v149
	ds_read_b128 v[202:205], v149 offset:1024
	global_load_lds_dwordx4 v[206:207], off
	v_lshl_add_u64 v[156:157], v[156:157], 0, s[6:7]
	s_mov_b32 m0, s20
	s_nop 0
	global_load_lds_dwordx4 v[156:157], off
	s_waitcnt vmcnt(10)
	s_barrier
	s_waitcnt lgkmcnt(0)
	s_setprio 1
	s_waitcnt lgkmcnt(0)
	v_mfma_f32_16x16x32_bf16 v[124:127], v[130:133], v[174:177], v[124:127]
	v_mfma_f32_16x16x32_bf16 v[120:123], v[166:169], v[174:177], v[120:123]
	v_mfma_f32_16x16x32_bf16 v[116:119], v[130:133], v[182:185], v[116:119]
	v_mfma_f32_16x16x32_bf16 v[112:115], v[166:169], v[182:185], v[112:115]
	v_mfma_f32_16x16x32_bf16 v[108:111], v[130:133], v[190:193], v[108:111]
	v_mfma_f32_16x16x32_bf16 v[104:107], v[166:169], v[190:193], v[104:107]
	v_mfma_f32_16x16x32_bf16 v[100:103], v[130:133], v[198:201], v[100:103]
	v_mfma_f32_16x16x32_bf16 v[96:99], v[166:169], v[198:201], v[96:99]
	v_mfma_f32_16x16x32_bf16 v[124:127], v[162:165], v[178:181], v[124:127]
	v_mfma_f32_16x16x32_bf16 v[120:123], v[170:173], v[178:181], v[120:123]
	v_mfma_f32_16x16x32_bf16 v[116:119], v[162:165], v[186:189], v[116:119]
	v_mfma_f32_16x16x32_bf16 v[112:115], v[170:173], v[186:189], v[112:115]
	v_mfma_f32_16x16x32_bf16 v[108:111], v[162:165], v[194:197], v[108:111]
	v_mfma_f32_16x16x32_bf16 v[104:107], v[170:173], v[194:197], v[104:107]
	v_mfma_f32_16x16x32_bf16 v[100:103], v[162:165], v[202:205], v[100:103]
	v_mfma_f32_16x16x32_bf16 v[96:99], v[170:173], v[202:205], v[96:99]
	s_setprio 0
	s_barrier
	ds_read_b128 v[206:209], v158
	ds_read_b128 v[210:213], v158 offset:1024
	ds_read_b128 v[214:217], v158 offset:2048
	ds_read_b128 v[156:159], v158 offset:3072
	s_barrier
	s_waitcnt lgkmcnt(0)
	s_setprio 1
	s_waitcnt lgkmcnt(0)
	v_mfma_f32_16x16x32_bf16 v[92:95], v[206:209], v[174:177], v[92:95]
	v_mfma_f32_16x16x32_bf16 v[88:91], v[214:217], v[174:177], v[88:91]
	v_mfma_f32_16x16x32_bf16 v[84:87], v[206:209], v[182:185], v[84:87]
	v_mfma_f32_16x16x32_bf16 v[80:83], v[214:217], v[182:185], v[80:83]
	v_mfma_f32_16x16x32_bf16 v[76:79], v[206:209], v[190:193], v[76:79]
	v_mfma_f32_16x16x32_bf16 v[72:75], v[214:217], v[190:193], v[72:75]
	v_mfma_f32_16x16x32_bf16 v[68:71], v[206:209], v[198:201], v[68:71]
	v_mfma_f32_16x16x32_bf16 v[64:67], v[214:217], v[198:201], v[64:67]
	v_mfma_f32_16x16x32_bf16 v[174:177], v[210:213], v[178:181], v[92:95]
	v_mfma_f32_16x16x32_bf16 v[178:181], v[156:159], v[178:181], v[88:91]
	v_mfma_f32_16x16x32_bf16 v[182:185], v[210:213], v[186:189], v[84:87]
	v_mfma_f32_16x16x32_bf16 v[186:189], v[156:159], v[186:189], v[80:83]
	v_mfma_f32_16x16x32_bf16 v[190:193], v[210:213], v[194:197], v[76:79]
	v_mfma_f32_16x16x32_bf16 v[194:197], v[156:159], v[194:197], v[72:75]
	v_mfma_f32_16x16x32_bf16 v[198:201], v[210:213], v[202:205], v[68:71]
	v_mfma_f32_16x16x32_bf16 v[202:205], v[156:159], v[202:205], v[64:67]
	s_setprio 0
	s_barrier
	s_nop 0
	ds_read_b128 v[64:67], v152 offset:16384
	ds_read_b128 v[68:71], v152 offset:17408
	ds_read_b128 v[72:75], v151 offset:16384
	ds_read_b128 v[76:79], v151 offset:17408
	ds_read_b128 v[80:83], v150 offset:16384
	ds_read_b128 v[84:87], v150 offset:17408
	ds_read_b128 v[88:91], v149 offset:16384
	ds_read_b128 v[92:95], v149 offset:17408
	s_waitcnt vmcnt(4)
	s_barrier
	s_waitcnt lgkmcnt(0)
	s_setprio 1
	s_waitcnt lgkmcnt(0)
	v_mfma_f32_16x16x32_bf16 v[60:63], v[130:133], v[64:67], v[60:63]
	v_mfma_f32_16x16x32_bf16 v[56:59], v[166:169], v[64:67], v[56:59]
	v_mfma_f32_16x16x32_bf16 v[52:55], v[130:133], v[72:75], v[52:55]
	v_mfma_f32_16x16x32_bf16 v[48:51], v[166:169], v[72:75], v[48:51]
	v_mfma_f32_16x16x32_bf16 v[218:221], v[130:133], v[80:83], v[44:47]
	v_mfma_f32_16x16x32_bf16 v[222:225], v[166:169], v[80:83], v[40:43]
	v_mfma_f32_16x16x32_bf16 v[130:133], v[130:133], v[88:91], v[36:39]
	v_mfma_f32_16x16x32_bf16 v[166:169], v[166:169], v[88:91], v[32:35]
	v_mfma_f32_16x16x32_bf16 v[32:35], v[162:165], v[68:71], v[60:63]
	v_mfma_f32_16x16x32_bf16 v[36:39], v[170:173], v[68:71], v[56:59]
	v_mfma_f32_16x16x32_bf16 v[40:43], v[162:165], v[76:79], v[52:55]
	v_mfma_f32_16x16x32_bf16 v[44:47], v[170:173], v[76:79], v[48:51]
	v_mfma_f32_16x16x32_bf16 v[48:51], v[162:165], v[84:87], v[218:221]
	v_mfma_f32_16x16x32_bf16 v[52:55], v[170:173], v[84:87], v[222:225]
	v_mfma_f32_16x16x32_bf16 v[56:59], v[162:165], v[92:95], v[130:133]
	v_mfma_f32_16x16x32_bf16 v[60:63], v[170:173], v[92:95], v[166:169]
	s_setprio 0
	s_setprio 1
	v_mfma_f32_16x16x32_bf16 v[28:31], v[206:209], v[64:67], v[28:31]
	v_mfma_f32_16x16x32_bf16 v[24:27], v[214:217], v[64:67], v[24:27]
	v_mfma_f32_16x16x32_bf16 v[20:23], v[206:209], v[72:75], v[20:23]
	v_mfma_f32_16x16x32_bf16 v[64:67], v[214:217], v[72:75], v[16:19]
	v_mfma_f32_16x16x32_bf16 v[72:75], v[206:209], v[80:83], v[12:15]
	v_mfma_f32_16x16x32_bf16 v[8:11], v[214:217], v[80:83], v[8:11]
	v_mfma_f32_16x16x32_bf16 v[80:83], v[206:209], v[88:91], v[4:7]
	v_mfma_f32_16x16x32_bf16 v[0:3], v[214:217], v[88:91], v[0:3]
	v_mfma_f32_16x16x32_bf16 v[4:7], v[210:213], v[68:71], v[28:31]
	v_mfma_f32_16x16x32_bf16 v[12:15], v[156:159], v[68:71], v[24:27]
	v_mfma_f32_16x16x32_bf16 v[16:19], v[210:213], v[76:79], v[20:23]
	v_mfma_f32_16x16x32_bf16 v[20:23], v[156:159], v[76:79], v[64:67]
	v_mfma_f32_16x16x32_bf16 v[24:27], v[210:213], v[84:87], v[72:75]
	v_mfma_f32_16x16x32_bf16 v[28:31], v[156:159], v[84:87], v[8:11]
	v_mfma_f32_16x16x32_bf16 v[64:67], v[210:213], v[92:95], v[80:83]
	v_mfma_f32_16x16x32_bf16 v[68:71], v[156:159], v[92:95], v[0:3]
	s_setprio 0
	s_barrier
	ds_read_b128 v[8:11], v154
	ds_read_b128 v[0:3], v154 offset:1024
	ds_read_b128 v[76:79], v154 offset:2048
	ds_read_b128 v[72:75], v154 offset:3072
	ds_read_b128 v[130:133], v152 offset:32768
	ds_read_b128 v[154:157], v152 offset:33792
	ds_read_b128 v[158:161], v151 offset:32768
	ds_read_b128 v[162:165], v151 offset:33792
	ds_read_b128 v[166:169], v150 offset:32768
	ds_read_b128 v[170:173], v150 offset:33792
	ds_read_b128 v[206:209], v149 offset:32768
	ds_read_b128 v[210:213], v149 offset:33792
	s_waitcnt vmcnt(2)
	s_barrier
	s_waitcnt lgkmcnt(0)
	s_setprio 1
	s_waitcnt lgkmcnt(0)
	v_mfma_f32_16x16x32_bf16 v[80:83], v[8:11], v[130:133], v[124:127]
	v_mfma_f32_16x16x32_bf16 v[84:87], v[76:79], v[130:133], v[120:123]
	v_mfma_f32_16x16x32_bf16 v[88:91], v[8:11], v[158:161], v[116:119]
	v_mfma_f32_16x16x32_bf16 v[92:95], v[76:79], v[158:161], v[112:115]
	v_mfma_f32_16x16x32_bf16 v[108:111], v[8:11], v[166:169], v[108:111]
	v_mfma_f32_16x16x32_bf16 v[104:107], v[76:79], v[166:169], v[104:107]
	v_mfma_f32_16x16x32_bf16 v[100:103], v[8:11], v[206:209], v[100:103]
	v_mfma_f32_16x16x32_bf16 v[96:99], v[76:79], v[206:209], v[96:99]
	v_mfma_f32_16x16x32_bf16 v[112:115], v[0:3], v[154:157], v[80:83]
	v_mfma_f32_16x16x32_bf16 v[116:119], v[72:75], v[154:157], v[84:87]
	v_mfma_f32_16x16x32_bf16 v[120:123], v[0:3], v[162:165], v[88:91]
	v_mfma_f32_16x16x32_bf16 v[124:127], v[72:75], v[162:165], v[92:95]
	v_mfma_f32_16x16x32_bf16 v[108:111], v[0:3], v[170:173], v[108:111]
	v_mfma_f32_16x16x32_bf16 v[104:107], v[72:75], v[170:173], v[104:107]
	v_mfma_f32_16x16x32_bf16 v[100:103], v[0:3], v[210:213], v[100:103]
	v_mfma_f32_16x16x32_bf16 v[96:99], v[72:75], v[210:213], v[96:99]
	s_setprio 0
	s_barrier
	ds_read_b128 v[88:91], v153
	ds_read_b128 v[80:83], v153 offset:1024
	ds_read_b128 v[92:95], v153 offset:2048
	ds_read_b128 v[84:87], v153 offset:3072
	s_waitcnt vmcnt(0)
	s_barrier
	s_waitcnt lgkmcnt(0)
	s_setprio 1
	s_waitcnt lgkmcnt(0)
	v_mfma_f32_16x16x32_bf16 v[174:177], v[88:91], v[130:133], v[174:177]
	v_mfma_f32_16x16x32_bf16 v[130:133], v[92:95], v[130:133], v[178:181]
	v_mfma_f32_16x16x32_bf16 v[178:181], v[88:91], v[158:161], v[182:185]
	v_mfma_f32_16x16x32_bf16 v[158:161], v[92:95], v[158:161], v[186:189]
	v_mfma_f32_16x16x32_bf16 v[182:185], v[88:91], v[166:169], v[190:193]
	v_mfma_f32_16x16x32_bf16 v[166:169], v[92:95], v[166:169], v[194:197]
	v_mfma_f32_16x16x32_bf16 v[186:189], v[88:91], v[206:209], v[198:201]
	v_mfma_f32_16x16x32_bf16 v[190:193], v[92:95], v[206:209], v[202:205]
	v_mfma_f32_16x16x32_bf16 v[174:177], v[80:83], v[154:157], v[174:177]
	v_mfma_f32_16x16x32_bf16 v[130:133], v[84:87], v[154:157], v[130:133]
	v_mfma_f32_16x16x32_bf16 v[154:157], v[80:83], v[162:165], v[178:181]
	v_mfma_f32_16x16x32_bf16 v[158:161], v[84:87], v[162:165], v[158:161]
	v_mfma_f32_16x16x32_bf16 v[162:165], v[80:83], v[170:173], v[182:185]
	v_mfma_f32_16x16x32_bf16 v[166:169], v[84:87], v[170:173], v[166:169]
	v_mfma_f32_16x16x32_bf16 v[170:173], v[80:83], v[210:213], v[186:189]
	v_mfma_f32_16x16x32_bf16 v[178:181], v[84:87], v[210:213], v[190:193]
	s_setprio 0
	s_barrier
	v_mbcnt_lo_u32_b32 v128, -1, 0
	v_mbcnt_hi_u32_b32 v128, -1, v128
	v_cvt_pk_bf16_f32 v112, v112, v113
	v_cvt_pk_bf16_f32 v113, v114, v115
	v_cvt_pk_bf16_f32 v114, v116, v117
	v_cvt_pk_bf16_f32 v115, v118, v119
	s_lshl_b32 s89, s64, 9
	v_add_u32_e32 v153, s72, v128
	v_ashrrev_i32_e32 v182, 6, v153
	v_and_b32_e32 v183, 15, v128
	v_and_b32_e32 v184, 48, v128
	v_mul_lo_u32 v185, v182, s77
	v_bfe_u32 v186, v128, 3, 3
	v_lshlrev_b32_e32 v128, 4, v128
	v_add_u32_e32 v185, 0x20000, v185
	v_lshrrev_b32_e32 v153, 2, v153
	v_and_b32_e32 v128, 0x70, v128
	v_mul_u32_u24_e32 v183, 0x90, v183
	v_and_b32_e32 v153, 64, v153
	v_add3_u32 v183, v185, v183, v184
	v_or_b32_e32 v184, v185, v128
	v_or3_b32 v153, s97, v153, v186
	v_mad_u32_u24 v184, v186, s79, v184
	ds_write_b128 v183, v[112:115]
	v_cvt_pk_bf16_f32 v112, v174, v175
	v_cvt_pk_bf16_f32 v113, v176, v177
	v_cvt_pk_bf16_f32 v114, v130, v131
	v_cvt_pk_bf16_f32 v115, v132, v133
	ds_write_b128 v183, v[112:115] offset:64
	v_lshlrev_b32_e32 v182, 7, v182
	ds_read_b128 v[112:115], v184
	v_lshlrev_b32_e32 v116, 12, v153
	v_and_or_b32 v116, v182, s80, v116
	v_or3_b32 v128, v116, s89, v128
	ds_read_b128 v[116:119], v184 offset:1152
	v_lshl_add_u64 v[130:131], s[0:1], 0, v[128:129]
	s_mov_b32 s20, 0x8000
	s_waitcnt lgkmcnt(0)
	global_store_dwordx4 v128, v[112:115], s[0:1]
	v_cvt_pk_bf16_f32 v108, v108, v109
	v_cvt_pk_bf16_f32 v109, v110, v111
	v_cvt_pk_bf16_f32 v110, v104, v105
	v_cvt_pk_bf16_f32 v111, v106, v107
	v_cvt_pk_bf16_f32 v104, v162, v163
	s_nop 1
	v_add_co_u32_e32 v112, vcc, s20, v130
	v_cvt_pk_bf16_f32 v114, v124, v125
	v_cvt_pk_bf16_f32 v115, v126, v127
	v_cvt_pk_bf16_f32 v105, v164, v165
	v_cvt_pk_bf16_f32 v106, v166, v167
	s_nop 1
	v_addc_co_u32_e32 v113, vcc, 0, v131, vcc
	global_store_dwordx4 v[112:113], v[116:119], off
	v_cvt_pk_bf16_f32 v112, v120, v121
	v_cvt_pk_bf16_f32 v113, v122, v123
	ds_write_b128 v183, v[112:115]
	v_cvt_pk_bf16_f32 v112, v154, v155
	v_cvt_pk_bf16_f32 v113, v156, v157
	v_cvt_pk_bf16_f32 v114, v158, v159
	v_cvt_pk_bf16_f32 v115, v160, v161
	ds_write_b128 v183, v[112:115] offset:64
	ds_read_b128 v[112:115], v184
	ds_read_b128 v[116:119], v184 offset:1152
	v_add_co_u32_e32 v120, vcc, s74, v130
	ds_write_b128 v183, v[108:111]
	v_cvt_pk_bf16_f32 v107, v168, v169
	ds_write_b128 v183, v[104:107] offset:64
	v_addc_co_u32_e32 v121, vcc, 0, v131, vcc
	ds_read_b128 v[104:107], v184
	ds_read_b128 v[108:111], v184 offset:1152
	s_waitcnt lgkmcnt(0)
	global_store_dwordx4 v[120:121], v[112:115], off
	v_cvt_pk_bf16_f32 v100, v100, v101
	v_cvt_pk_bf16_f32 v101, v102, v103
	v_cvt_pk_bf16_f32 v102, v96, v97
	v_cvt_pk_bf16_f32 v103, v98, v99
	ds_write_b128 v183, v[100:103]
	s_nop 0
	v_add_co_u32_e32 v112, vcc, s75, v130
	v_cvt_pk_bf16_f32 v96, v170, v171
	v_cvt_pk_bf16_f32 v97, v172, v173
	v_cvt_pk_bf16_f32 v98, v178, v179
	v_cvt_pk_bf16_f32 v99, v180, v181
	s_nop 1
	v_addc_co_u32_e32 v113, vcc, 0, v131, vcc
	global_store_dwordx4 v[112:113], v[116:119], off
	v_add_co_u32_e32 v112, vcc, s78, v130
	ds_write_b128 v183, v[96:99] offset:64
	s_nop 0
	v_addc_co_u32_e32 v113, vcc, 0, v131, vcc
	ds_read_b128 v[96:99], v184
	ds_read_b128 v[100:103], v184 offset:1152
	global_store_dwordx4 v[112:113], v[104:107], off
	s_nop 1
	v_add_co_u32_e32 v104, vcc, s81, v130
	s_nop 1
	v_addc_co_u32_e32 v105, vcc, 0, v131, vcc
	global_store_dwordx4 v[104:105], v[108:111], off
	v_add_co_u32_e32 v104, vcc, s82, v130
	s_nop 1
	v_addc_co_u32_e32 v105, vcc, 0, v131, vcc
	s_waitcnt lgkmcnt(0)
	global_store_dwordx4 v[104:105], v[96:99], off
	s_nop 1
	v_add_co_u32_e32 v96, vcc, s83, v130
	s_nop 1
	v_addc_co_u32_e32 v97, vcc, 0, v131, vcc
	global_store_dwordx4 v[96:97], v[100:103], off
	ds_read_b128 v[96:99], v152 offset:49152
	ds_read_b128 v[100:103], v152 offset:50176
	ds_read_b128 v[104:107], v151 offset:49152
	ds_read_b128 v[108:111], v151 offset:50176
	ds_read_b128 v[112:115], v150 offset:49152
	ds_read_b128 v[116:119], v150 offset:50176
	ds_read_b128 v[120:123], v149 offset:49152
	ds_read_b128 v[124:127], v149 offset:50176
	s_barrier
	s_waitcnt lgkmcnt(0)
	s_setprio 1
	s_waitcnt lgkmcnt(0)
	v_mfma_f32_16x16x32_bf16 v[32:35], v[8:11], v[96:99], v[32:35]
	v_mfma_f32_16x16x32_bf16 v[36:39], v[76:79], v[96:99], v[36:39]
	v_mfma_f32_16x16x32_bf16 v[40:43], v[8:11], v[104:107], v[40:43]
	v_mfma_f32_16x16x32_bf16 v[130:133], v[76:79], v[104:107], v[44:47]
	v_mfma_f32_16x16x32_bf16 v[150:153], v[8:11], v[112:115], v[48:51]
	v_mfma_f32_16x16x32_bf16 v[52:55], v[76:79], v[112:115], v[52:55]
	v_mfma_f32_16x16x32_bf16 v[8:11], v[8:11], v[120:123], v[56:59]
	v_mfma_f32_16x16x32_bf16 v[60:63], v[76:79], v[120:123], v[60:63]
	v_mfma_f32_16x16x32_bf16 v[56:59], v[0:3], v[100:103], v[32:35]
	v_mfma_f32_16x16x32_bf16 v[48:51], v[72:75], v[100:103], v[36:39]
	v_mfma_f32_16x16x32_bf16 v[44:47], v[0:3], v[108:111], v[40:43]
	v_mfma_f32_16x16x32_bf16 v[40:43], v[72:75], v[108:111], v[130:133]
	v_mfma_f32_16x16x32_bf16 v[36:39], v[0:3], v[116:119], v[150:153]
	v_mfma_f32_16x16x32_bf16 v[32:35], v[72:75], v[116:119], v[52:55]
	v_mfma_f32_16x16x32_bf16 v[8:11], v[0:3], v[124:127], v[8:11]
	v_mfma_f32_16x16x32_bf16 v[0:3], v[72:75], v[124:127], v[60:63]
	s_setprio 0
	s_setprio 1
	v_mfma_f32_16x16x32_bf16 v[4:7], v[88:91], v[96:99], v[4:7]
	v_mfma_f32_16x16x32_bf16 v[12:15], v[92:95], v[96:99], v[12:15]
	v_mfma_f32_16x16x32_bf16 v[16:19], v[88:91], v[104:107], v[16:19]
	v_mfma_f32_16x16x32_bf16 v[20:23], v[92:95], v[104:107], v[20:23]
	v_mfma_f32_16x16x32_bf16 v[72:75], v[88:91], v[112:115], v[24:27]
	v_mfma_f32_16x16x32_bf16 v[76:79], v[92:95], v[112:115], v[28:31]
	v_mfma_f32_16x16x32_bf16 v[64:67], v[88:91], v[120:123], v[64:67]
	v_mfma_f32_16x16x32_bf16 v[68:71], v[92:95], v[120:123], v[68:71]
	v_mfma_f32_16x16x32_bf16 v[60:63], v[80:83], v[100:103], v[4:7]
	v_mfma_f32_16x16x32_bf16 v[52:55], v[84:87], v[100:103], v[12:15]
	v_mfma_f32_16x16x32_bf16 v[28:31], v[80:83], v[108:111], v[16:19]
	v_mfma_f32_16x16x32_bf16 v[24:27], v[84:87], v[108:111], v[20:23]
	v_mfma_f32_16x16x32_bf16 v[20:23], v[80:83], v[116:119], v[72:75]
	v_mfma_f32_16x16x32_bf16 v[16:19], v[84:87], v[116:119], v[76:79]
	v_mfma_f32_16x16x32_bf16 v[12:15], v[80:83], v[124:127], v[64:67]
	v_mfma_f32_16x16x32_bf16 v[4:7], v[84:87], v[124:127], v[68:71]
	s_setprio 0
	v_cmp_gt_u32_e32 vcc, s85, v135
	s_barrier
	s_and_saveexec_b64 s[64:65], vcc
	s_cbranch_execz .LBB0_277
	s_barrier

.LBB0_355:
	s_lshl_b32 s14, s70, 3
	v_cvt_f32_u32_e32 v2, s14
	s_sub_i32 s17, 0, s14
	s_abs_i32 s16, s69
	s_ashr_i32 s15, s69, 31
	v_rcp_iflag_f32_e32 v2, v2
	v_and_b32_e32 v3, 15, v0
	v_lshlrev_b32_e32 v3, 6, v3
	v_lshlrev_b32_e32 v6, 2, v0
	v_mul_f32_e32 v2, 0x4f7ffffe, v2
	v_cvt_u32_f32_e32 v2, v2
	v_lshlrev_b32_e32 v4, 6, v183
	v_and_b32_e32 v6, 32, v6
	v_lshlrev_b32_e32 v1, 13, v1
	v_readfirstlane_b32 s24, v2
	s_mul_i32 s17, s17, s24
	s_mul_hi_u32 s17, s24, s17
	s_add_i32 s24, s24, s17
	s_mul_hi_u32 s17, s16, s24
	s_mul_i32 s24, s17, s14
	s_sub_i32 s16, s16, s24
	s_add_i32 s25, s17, 1
	s_sub_i32 s24, s16, s14
	s_cmp_ge_u32 s16, s14
	s_cselect_b32 s17, s25, s17
	s_cselect_b32 s16, s24, s16
	s_add_i32 s24, s17, 1
	s_cmp_ge_u32 s16, s14
	s_cselect_b32 s16, s24, s17
	s_xor_b32 s16, s16, s15
	s_sub_i32 s67, s16, s15
	s_mul_i32 s14, s67, s14
	s_sub_i32 s14, s69, s14
	s_lshl_b32 s15, s67, 3
	s_and_b32 s16, s14, 7
	s_ashr_i32 s66, s14, 3
	s_or_b32 s68, s16, s15
	s_lshl_b32 s16, s66, 8
	s_lshl_b32 s14, s68, 8
	s_and_b64 s[24:25], s[22:23], exec
	s_cselect_b32 s24, s45, 0x40000
	s_cselect_b32 s36, 32, 0x80
	s_cselect_b32 s25, s46, 0x1000
	s_or_b32 s26, s14, 0x80
	s_ashr_i32 s27, s26, 31
	s_and_b64 s[28:29], s[22:23], exec
	s_cselect_b32 s37, 6, 12
	s_lshl_b64 s[26:27], s[26:27], s37
	s_add_u32 s26, s18, s26
	s_addc_u32 s27, s19, s27
	s_and_b64 s[28:29], s[22:23], exec
	s_cselect_b32 s28, 18, 7
	s_ashr_i32 s17, s16, 31
	s_and_b64 s[30:31], s[22:23], exec
	s_cselect_b32 s69, 12, 6
	s_lshl_b64 s[30:31], s[16:17], s69
	s_add_u32 s17, s20, s30
	s_addc_u32 s29, s21, s31
	s_ashr_i32 s15, s14, 31
	s_lshl_b64 s[30:31], s[14:15], s37
	s_add_u32 s15, s18, s30
	s_addc_u32 s30, s19, s31
	s_or_b32 s18, s16, s36
	s_ashr_i32 s19, s18, 31
	s_lshl_b64 s[18:19], s[18:19], s69
	v_and_b32_e32 v2, 48, v0
	s_add_u32 s20, s20, s18
	v_lshlrev_b32_e32 v0, 6, v0
	v_or_b32_e32 v5, v3, v2
	s_addc_u32 s21, s21, s19
	v_and_b32_e32 v0, 0x3c0, v0
	v_and_b32_e32 v4, 0x3000, v4
	v_bitop3_b32 v3, v3, v6, v2 bitop3:0x36
	v_bitop3_b32 v7, v5, s56, v6 bitop3:0xde
	v_bitop3_b32 v8, v5, s57, v6 bitop3:0xde
	v_bitop3_b32 v9, v5, s58, v6 bitop3:0xde
	v_bitop3_b32 v5, v5, s59, v6 bitop3:0xde
	v_bitop3_b32 v2, v0, v6, v2 bitop3:0x36
	v_or_b32_e32 v6, 0x800, v1
	v_or_b32_e32 v10, 0x1000, v1
	v_or_b32_e32 v11, 0x1800, v1
	s_and_b64 s[18:19], s[22:23], exec
	v_mov_b32_e32 v0, 0
	v_mov_b32_e32 v129, v165
	s_cselect_b32 s22, 7, 18
	s_mov_b64 s[18:19], 1
	v_add_u32_e32 v134, v7, v4
	v_add_u32_e32 v187, v3, v1
	v_add_u32_e32 v186, v2, v6
	v_add_u32_e32 v185, v2, v10
	v_add_u32_e32 v184, v2, v11
	v_add_u32_e32 v133, 0xc000, v169
	v_add_u32_e32 v132, 0xe000, v169
	v_add_u32_e32 v131, v8, v4
	v_add_u32_e32 v182, 0x10000, v169
	v_add_u32_e32 v181, 0x12000, v169
	v_add_u32_e32 v180, 0x2000, v169
	v_add_u32_e32 v179, 0x14000, v169
	v_add_u32_e32 v178, 0x16000, v169
	v_add_u32_e32 v130, v9, v4
	v_add_u32_e32 v177, 0x4000, v169
	v_add_u32_e32 v176, 0x6000, v169
	v_add_u32_e32 v136, v5, v4
	v_add_u32_e32 v175, 0x18000, v169
	v_add_u32_e32 v174, 0x1a000, v169
	v_add_u32_e32 v173, 0x8000, v169
	v_add_u32_e32 v172, 0xa000, v169
	v_add_u32_e32 v171, 0x1c000, v169
	v_add_u32_e32 v170, 0x1e000, v169
	v_mov_b32_e32 v1, v0
	v_mov_b32_e32 v2, v0
	v_mov_b32_e32 v3, v0
	v_mov_b32_e32 v4, v0
	v_mov_b32_e32 v5, v0
	v_mov_b32_e32 v6, v0
	v_mov_b32_e32 v7, v0
	v_mov_b32_e32 v8, v0
	v_mov_b32_e32 v9, v0
	v_mov_b32_e32 v10, v0
	v_mov_b32_e32 v11, v0
	v_mov_b32_e32 v12, v0
	v_mov_b32_e32 v13, v0
	v_mov_b32_e32 v14, v0
	v_mov_b32_e32 v15, v0
	v_mov_b32_e32 v16, v0
	v_mov_b32_e32 v17, v0
	v_mov_b32_e32 v18, v0
	v_mov_b32_e32 v19, v0
	v_mov_b32_e32 v20, v0
	v_mov_b32_e32 v21, v0
	v_mov_b32_e32 v22, v0
	v_mov_b32_e32 v23, v0
	v_mov_b32_e32 v24, v0
	v_mov_b32_e32 v25, v0
	v_mov_b32_e32 v26, v0
	v_mov_b32_e32 v27, v0
	v_mov_b32_e32 v28, v0
	v_mov_b32_e32 v29, v0
	v_mov_b32_e32 v30, v0
	v_mov_b32_e32 v31, v0
	v_mov_b32_e32 v32, v0
	v_mov_b32_e32 v33, v0
	v_mov_b32_e32 v34, v0
	v_mov_b32_e32 v35, v0
	v_mov_b32_e32 v36, v0
	v_mov_b32_e32 v37, v0
	v_mov_b32_e32 v38, v0
	v_mov_b32_e32 v39, v0
	v_mov_b32_e32 v40, v0
	v_mov_b32_e32 v41, v0
	v_mov_b32_e32 v42, v0
	v_mov_b32_e32 v43, v0
	v_mov_b32_e32 v44, v0
	v_mov_b32_e32 v45, v0
	v_mov_b32_e32 v46, v0
	v_mov_b32_e32 v47, v0
	v_mov_b32_e32 v48, v0
	v_mov_b32_e32 v49, v0
	v_mov_b32_e32 v50, v0
	v_mov_b32_e32 v51, v0
	v_mov_b32_e32 v52, v0
	v_mov_b32_e32 v53, v0
	v_mov_b32_e32 v54, v0
	v_mov_b32_e32 v55, v0
	v_mov_b32_e32 v56, v0
	v_mov_b32_e32 v57, v0
	v_mov_b32_e32 v58, v0
	v_mov_b32_e32 v59, v0
	v_mov_b32_e32 v60, v0
	v_mov_b32_e32 v61, v0
	v_mov_b32_e32 v62, v0
	v_mov_b32_e32 v63, v0
	v_mov_b32_e32 v64, v0
	v_mov_b32_e32 v65, v0
	v_mov_b32_e32 v66, v0
	v_mov_b32_e32 v67, v0
	v_mov_b32_e32 v68, v0
	v_mov_b32_e32 v69, v0
	v_mov_b32_e32 v70, v0
	v_mov_b32_e32 v71, v0
	v_mov_b32_e32 v72, v0
	v_mov_b32_e32 v73, v0
	v_mov_b32_e32 v74, v0
	v_mov_b32_e32 v75, v0
	v_mov_b32_e32 v76, v0
	v_mov_b32_e32 v77, v0
	v_mov_b32_e32 v78, v0
	v_mov_b32_e32 v79, v0
	v_mov_b32_e32 v80, v0
	v_mov_b32_e32 v81, v0
	v_mov_b32_e32 v82, v0
	v_mov_b32_e32 v83, v0
	v_mov_b32_e32 v84, v0
	v_mov_b32_e32 v85, v0
	v_mov_b32_e32 v86, v0
	v_mov_b32_e32 v87, v0
	v_mov_b32_e32 v88, v0
	v_mov_b32_e32 v89, v0
	v_mov_b32_e32 v90, v0
	v_mov_b32_e32 v91, v0
	v_mov_b32_e32 v92, v0
	v_mov_b32_e32 v93, v0
	v_mov_b32_e32 v94, v0
	v_mov_b32_e32 v95, v0
	v_mov_b32_e32 v96, v0
	v_mov_b32_e32 v97, v0
	v_mov_b32_e32 v98, v0
	v_mov_b32_e32 v99, v0
	v_mov_b32_e32 v100, v0
	v_mov_b32_e32 v101, v0
	v_mov_b32_e32 v102, v0
	v_mov_b32_e32 v103, v0
	v_mov_b32_e32 v104, v0
	v_mov_b32_e32 v105, v0
	v_mov_b32_e32 v106, v0
	v_mov_b32_e32 v107, v0
	v_mov_b32_e32 v108, v0
	v_mov_b32_e32 v109, v0
	v_mov_b32_e32 v110, v0
	v_mov_b32_e32 v111, v0
	v_mov_b32_e32 v112, v0
	v_mov_b32_e32 v113, v0
	v_mov_b32_e32 v114, v0
	v_mov_b32_e32 v115, v0
	v_mov_b32_e32 v116, v0
	v_mov_b32_e32 v117, v0
	v_mov_b32_e32 v118, v0
	v_mov_b32_e32 v119, v0
	v_mov_b32_e32 v120, v0
	v_mov_b32_e32 v121, v0
	v_mov_b32_e32 v122, v0
	v_mov_b32_e32 v123, v0
	v_mov_b32_e32 v124, v0
	v_mov_b32_e32 v125, v0
	v_mov_b32_e32 v126, v0
	v_mov_b32_e32 v127, v0
	s_barrier
	v_readlane_b32 s98, v242, 1
	s_lshl_b32 s98, s98, 10
	s_lshl_b64 s[70:71], s[18:19], s28
	s_add_u32 s70, s26, s70
	s_addc_u32 s71, s27, s71
	v_lshl_add_u64 v[162:163], s[70:71], 0, v[164:165]
	s_add_i32 s23, s98, 0xc000
	s_add_u32 s70, s70, s24
	s_mov_b32 m0, s23
	s_addc_u32 s71, s71, 0
	s_add_i32 s23, s98, 0xe000
	global_load_lds_dwordx4 v[162:163], off
	v_lshl_add_u64 v[162:163], s[70:71], 0, v[164:165]
	s_mov_b32 m0, s23
	s_nop 0
	global_load_lds_dwordx4 v[162:163], off
	ds_read_b128 v[138:141], v134
	ds_read_b128 v[142:145], v134 offset:1024
	ds_read_b128 v[146:149], v134 offset:2048
	ds_read_b128 v[150:153], v134 offset:3072
.LBB0_356:
	ds_read_b128 v[154:157], v187
	ds_read_b128 v[158:161], v187 offset:1024
	ds_read_b128 v[188:191], v186
	ds_read_b128 v[192:195], v186 offset:1024
	ds_read_b128 v[196:199], v185
	ds_read_b128 v[200:203], v185 offset:1024
	ds_read_b128 v[204:207], v184
	ds_read_b128 v[208:211], v184 offset:1024
	s_waitcnt lgkmcnt(8)
	s_waitcnt vmcnt(10)
	s_barrier
	s_waitcnt lgkmcnt(0)
	s_waitcnt lgkmcnt(0)
	v_mfma_f32_16x16x32_bf16 v[124:127], v[138:141], v[154:157], v[124:127]
	v_mfma_f32_16x16x32_bf16 v[120:123], v[146:149], v[154:157], v[120:123]
	v_mfma_f32_16x16x32_bf16 v[116:119], v[138:141], v[188:191], v[116:119]
	v_mfma_f32_16x16x32_bf16 v[112:115], v[146:149], v[188:191], v[112:115]
	v_mfma_f32_16x16x32_bf16 v[108:111], v[138:141], v[196:199], v[108:111]
	v_mfma_f32_16x16x32_bf16 v[104:107], v[146:149], v[196:199], v[104:107]
	v_mfma_f32_16x16x32_bf16 v[100:103], v[138:141], v[204:207], v[100:103]
	v_mfma_f32_16x16x32_bf16 v[96:99], v[146:149], v[204:207], v[96:99]
	v_mfma_f32_16x16x32_bf16 v[124:127], v[142:145], v[158:161], v[124:127]
	v_mfma_f32_16x16x32_bf16 v[120:123], v[150:153], v[158:161], v[120:123]
	v_mfma_f32_16x16x32_bf16 v[116:119], v[142:145], v[192:195], v[116:119]
	v_mfma_f32_16x16x32_bf16 v[112:115], v[150:153], v[192:195], v[112:115]
	v_mfma_f32_16x16x32_bf16 v[108:111], v[142:145], v[200:203], v[108:111]
	v_mfma_f32_16x16x32_bf16 v[104:107], v[150:153], v[200:203], v[104:107]
	v_mfma_f32_16x16x32_bf16 v[100:103], v[142:145], v[208:211], v[100:103]
	v_mfma_f32_16x16x32_bf16 v[96:99], v[150:153], v[208:211], v[96:99]
	s_barrier
	s_add_u32 s70, s18, 1
	s_addc_u32 s71, s19, 0
	s_lshl_b64 s[72:73], s[70:71], s22
	s_add_u32 s74, s17, s72
	s_addc_u32 s75, s29, s73
	v_lshl_add_u64 v[162:163], s[74:75], 0, v[128:129]
	s_add_i32 s23, s98, 0x10000
	s_add_u32 s74, s74, s25
	s_mov_b32 m0, s23
	s_addc_u32 s75, s75, 0
	s_add_i32 s23, s98, 0x12000
	ds_read_b128 v[212:215], v131
	ds_read_b128 v[216:219], v131 offset:1024
	ds_read_b128 v[220:223], v131 offset:2048
	ds_read_b128 v[224:227], v131 offset:3072
	global_load_lds_dwordx4 v[162:163], off
	v_lshl_add_u64 v[162:163], s[74:75], 0, v[128:129]
	s_mov_b32 m0, s23
	s_nop 0
	global_load_lds_dwordx4 v[162:163], off
	s_lshl_b64 s[70:71], s[70:71], s28
	s_add_u32 s74, s15, s70
	s_addc_u32 s75, s30, s71
	v_lshl_add_u64 v[162:163], s[74:75], 0, v[164:165]
	s_mov_b32 s23, s98
	s_add_u32 s74, s74, s24
	s_mov_b32 m0, s23
	s_addc_u32 s75, s75, 0
	s_add_i32 s23, s98, 0x2000
	global_load_lds_dwordx4 v[162:163], off
	v_lshl_add_u64 v[162:163], s[74:75], 0, v[164:165]
	s_mov_b32 m0, s23
	s_nop 0
	global_load_lds_dwordx4 v[162:163], off
	s_waitcnt vmcnt(12)
	s_barrier
	s_waitcnt lgkmcnt(0)
	s_waitcnt lgkmcnt(0)
	v_mfma_f32_16x16x32_bf16 v[92:95], v[212:215], v[154:157], v[92:95]
	v_mfma_f32_16x16x32_bf16 v[88:91], v[220:223], v[154:157], v[88:91]
	v_mfma_f32_16x16x32_bf16 v[84:87], v[212:215], v[188:191], v[84:87]
	v_mfma_f32_16x16x32_bf16 v[80:83], v[220:223], v[188:191], v[80:83]
	v_mfma_f32_16x16x32_bf16 v[76:79], v[212:215], v[196:199], v[76:79]
	v_mfma_f32_16x16x32_bf16 v[72:75], v[220:223], v[196:199], v[72:75]
	v_mfma_f32_16x16x32_bf16 v[68:71], v[212:215], v[204:207], v[68:71]
	v_mfma_f32_16x16x32_bf16 v[64:67], v[220:223], v[204:207], v[64:67]
	v_mfma_f32_16x16x32_bf16 v[92:95], v[216:219], v[158:161], v[92:95]
	v_mfma_f32_16x16x32_bf16 v[88:91], v[224:227], v[158:161], v[88:91]
	v_mfma_f32_16x16x32_bf16 v[84:87], v[216:219], v[192:195], v[84:87]
	v_mfma_f32_16x16x32_bf16 v[80:83], v[224:227], v[192:195], v[80:83]
	v_mfma_f32_16x16x32_bf16 v[76:79], v[216:219], v[200:203], v[76:79]
	v_mfma_f32_16x16x32_bf16 v[72:75], v[224:227], v[200:203], v[72:75]
	v_mfma_f32_16x16x32_bf16 v[68:71], v[216:219], v[208:211], v[68:71]
	v_mfma_f32_16x16x32_bf16 v[64:67], v[224:227], v[208:211], v[64:67]
	s_barrier
	ds_read_b128 v[154:157], v187 offset:16384
	ds_read_b128 v[158:161], v187 offset:17408
	ds_read_b128 v[188:191], v186 offset:16384
	ds_read_b128 v[192:195], v186 offset:17408
	ds_read_b128 v[196:199], v185 offset:16384
	ds_read_b128 v[200:203], v185 offset:17408
	ds_read_b128 v[204:207], v184 offset:16384
	ds_read_b128 v[208:211], v184 offset:17408
	s_add_u32 s72, s20, s72
	s_addc_u32 s73, s21, s73
	v_lshl_add_u64 v[162:163], s[72:73], 0, v[128:129]
	s_add_i32 s23, s98, 0x14000
	s_add_u32 s72, s72, s25
	s_mov_b32 m0, s23
	s_addc_u32 s73, s73, 0
	s_add_i32 s23, s98, 0x16000
	global_load_lds_dwordx4 v[162:163], off
	v_lshl_add_u64 v[162:163], s[72:73], 0, v[128:129]
	s_mov_b32 m0, s23
	s_nop 0
	global_load_lds_dwordx4 v[162:163], off
	s_waitcnt vmcnt(12)
	s_barrier
	s_waitcnt lgkmcnt(0)
	s_waitcnt lgkmcnt(0)
	v_mfma_f32_16x16x32_bf16 v[60:63], v[138:141], v[154:157], v[60:63]
	v_mfma_f32_16x16x32_bf16 v[56:59], v[146:149], v[154:157], v[56:59]
	v_mfma_f32_16x16x32_bf16 v[52:55], v[138:141], v[188:191], v[52:55]
	v_mfma_f32_16x16x32_bf16 v[48:51], v[146:149], v[188:191], v[48:51]
	v_mfma_f32_16x16x32_bf16 v[44:47], v[138:141], v[196:199], v[44:47]
	v_mfma_f32_16x16x32_bf16 v[40:43], v[146:149], v[196:199], v[40:43]
	v_mfma_f32_16x16x32_bf16 v[36:39], v[138:141], v[204:207], v[36:39]
	v_mfma_f32_16x16x32_bf16 v[32:35], v[146:149], v[204:207], v[32:35]
	v_mfma_f32_16x16x32_bf16 v[60:63], v[142:145], v[158:161], v[60:63]
	v_mfma_f32_16x16x32_bf16 v[56:59], v[150:153], v[158:161], v[56:59]
	v_mfma_f32_16x16x32_bf16 v[52:55], v[142:145], v[192:195], v[52:55]
	v_mfma_f32_16x16x32_bf16 v[48:51], v[150:153], v[192:195], v[48:51]
	v_mfma_f32_16x16x32_bf16 v[44:47], v[142:145], v[200:203], v[44:47]
	v_mfma_f32_16x16x32_bf16 v[40:43], v[150:153], v[200:203], v[40:43]
	v_mfma_f32_16x16x32_bf16 v[36:39], v[142:145], v[208:211], v[36:39]
	v_mfma_f32_16x16x32_bf16 v[32:35], v[150:153], v[208:211], v[32:35]
	s_barrier
	s_add_u32 s70, s26, s70
	s_addc_u32 s71, s27, s71
	v_lshl_add_u64 v[162:163], s[70:71], 0, v[164:165]
	s_add_i32 s23, s98, 0x4000
	s_add_u32 s70, s70, s24
	s_mov_b32 m0, s23
	s_addc_u32 s71, s71, 0
	s_add_i32 s23, s98, 0x6000
	global_load_lds_dwordx4 v[162:163], off
	v_lshl_add_u64 v[162:163], s[70:71], 0, v[164:165]
	s_mov_b32 m0, s23
	s_nop 0
	global_load_lds_dwordx4 v[162:163], off
	ds_read_b128 v[138:141], v130
	ds_read_b128 v[142:145], v130 offset:1024
	ds_read_b128 v[146:149], v130 offset:2048
	ds_read_b128 v[150:153], v130 offset:3072
	s_waitcnt vmcnt(12)
	s_barrier
	v_mfma_f32_16x16x32_bf16 v[28:31], v[212:215], v[154:157], v[28:31]
	v_mfma_f32_16x16x32_bf16 v[24:27], v[220:223], v[154:157], v[24:27]
	v_mfma_f32_16x16x32_bf16 v[20:23], v[212:215], v[188:191], v[20:23]
	v_mfma_f32_16x16x32_bf16 v[16:19], v[220:223], v[188:191], v[16:19]
	v_mfma_f32_16x16x32_bf16 v[12:15], v[212:215], v[196:199], v[12:15]
	v_mfma_f32_16x16x32_bf16 v[8:11], v[220:223], v[196:199], v[8:11]
	v_mfma_f32_16x16x32_bf16 v[4:7], v[212:215], v[204:207], v[4:7]
	v_mfma_f32_16x16x32_bf16 v[0:3], v[220:223], v[204:207], v[0:3]
	v_mfma_f32_16x16x32_bf16 v[28:31], v[216:219], v[158:161], v[28:31]
	v_mfma_f32_16x16x32_bf16 v[24:27], v[224:227], v[158:161], v[24:27]
	v_mfma_f32_16x16x32_bf16 v[20:23], v[216:219], v[192:195], v[20:23]
	v_mfma_f32_16x16x32_bf16 v[16:19], v[224:227], v[192:195], v[16:19]
	v_mfma_f32_16x16x32_bf16 v[12:15], v[216:219], v[200:203], v[12:15]
	v_mfma_f32_16x16x32_bf16 v[8:11], v[224:227], v[200:203], v[8:11]
	v_mfma_f32_16x16x32_bf16 v[4:7], v[216:219], v[208:211], v[4:7]
	v_mfma_f32_16x16x32_bf16 v[0:3], v[224:227], v[208:211], v[0:3]
	s_barrier
	ds_read_b128 v[154:157], v187 offset:32768
	ds_read_b128 v[158:161], v187 offset:33792
	ds_read_b128 v[188:191], v186 offset:32768
	ds_read_b128 v[192:195], v186 offset:33792
	ds_read_b128 v[196:199], v185 offset:32768
	ds_read_b128 v[200:203], v185 offset:33792
	ds_read_b128 v[204:207], v184 offset:32768
	ds_read_b128 v[208:211], v184 offset:33792
	s_waitcnt lgkmcnt(8)
	s_waitcnt vmcnt(10)
	s_barrier
	s_waitcnt lgkmcnt(0)
	s_waitcnt lgkmcnt(0)
	v_mfma_f32_16x16x32_bf16 v[124:127], v[138:141], v[154:157], v[124:127]
	v_mfma_f32_16x16x32_bf16 v[120:123], v[146:149], v[154:157], v[120:123]
	v_mfma_f32_16x16x32_bf16 v[116:119], v[138:141], v[188:191], v[116:119]
	v_mfma_f32_16x16x32_bf16 v[112:115], v[146:149], v[188:191], v[112:115]
	v_mfma_f32_16x16x32_bf16 v[108:111], v[138:141], v[196:199], v[108:111]
	v_mfma_f32_16x16x32_bf16 v[104:107], v[146:149], v[196:199], v[104:107]
	v_mfma_f32_16x16x32_bf16 v[100:103], v[138:141], v[204:207], v[100:103]
	v_mfma_f32_16x16x32_bf16 v[96:99], v[146:149], v[204:207], v[96:99]
	v_mfma_f32_16x16x32_bf16 v[124:127], v[142:145], v[158:161], v[124:127]
	v_mfma_f32_16x16x32_bf16 v[120:123], v[150:153], v[158:161], v[120:123]
	v_mfma_f32_16x16x32_bf16 v[116:119], v[142:145], v[192:195], v[116:119]
	v_mfma_f32_16x16x32_bf16 v[112:115], v[150:153], v[192:195], v[112:115]
	v_mfma_f32_16x16x32_bf16 v[108:111], v[142:145], v[200:203], v[108:111]
	v_mfma_f32_16x16x32_bf16 v[104:107], v[150:153], v[200:203], v[104:107]
	v_mfma_f32_16x16x32_bf16 v[100:103], v[142:145], v[208:211], v[100:103]
	v_mfma_f32_16x16x32_bf16 v[96:99], v[150:153], v[208:211], v[96:99]
	s_barrier
	s_add_u32 s18, s18, 2
	s_addc_u32 s19, s19, 0
	s_lshl_b64 s[70:71], s[18:19], s22
	s_add_u32 s72, s17, s70
	s_addc_u32 s73, s29, s71
	v_lshl_add_u64 v[162:163], s[72:73], 0, v[128:129]
	s_add_i32 s23, s98, 0x18000
	s_add_u32 s72, s72, s25
	s_mov_b32 m0, s23
	s_addc_u32 s73, s73, 0
	s_add_i32 s23, s98, 0x1a000
	ds_read_b128 v[212:215], v136
	ds_read_b128 v[216:219], v136 offset:1024
	ds_read_b128 v[220:223], v136 offset:2048
	ds_read_b128 v[224:227], v136 offset:3072
	global_load_lds_dwordx4 v[162:163], off
	v_lshl_add_u64 v[162:163], s[72:73], 0, v[128:129]
	s_mov_b32 m0, s23
	s_nop 0
	global_load_lds_dwordx4 v[162:163], off
	s_lshl_b64 s[72:73], s[18:19], s28
	s_add_u32 s72, s15, s72
	s_addc_u32 s73, s30, s73
	v_lshl_add_u64 v[162:163], s[72:73], 0, v[164:165]
	s_add_i32 s23, s98, 0x8000
	s_add_u32 s72, s72, s24
	s_mov_b32 m0, s23
	s_addc_u32 s73, s73, 0
	s_add_i32 s23, s98, 0xa000
	global_load_lds_dwordx4 v[162:163], off
	v_lshl_add_u64 v[162:163], s[72:73], 0, v[164:165]
	s_mov_b32 m0, s23
	s_nop 0
	global_load_lds_dwordx4 v[162:163], off
	s_waitcnt vmcnt(12)
	s_barrier
	s_waitcnt lgkmcnt(0)
	s_waitcnt lgkmcnt(0)
	v_mfma_f32_16x16x32_bf16 v[92:95], v[212:215], v[154:157], v[92:95]
	v_mfma_f32_16x16x32_bf16 v[88:91], v[220:223], v[154:157], v[88:91]
	v_mfma_f32_16x16x32_bf16 v[84:87], v[212:215], v[188:191], v[84:87]
	v_mfma_f32_16x16x32_bf16 v[80:83], v[220:223], v[188:191], v[80:83]
	v_mfma_f32_16x16x32_bf16 v[76:79], v[212:215], v[196:199], v[76:79]
	v_mfma_f32_16x16x32_bf16 v[72:75], v[220:223], v[196:199], v[72:75]
	v_mfma_f32_16x16x32_bf16 v[68:71], v[212:215], v[204:207], v[68:71]
	v_mfma_f32_16x16x32_bf16 v[64:67], v[220:223], v[204:207], v[64:67]
	v_mfma_f32_16x16x32_bf16 v[92:95], v[216:219], v[158:161], v[92:95]
	v_mfma_f32_16x16x32_bf16 v[88:91], v[224:227], v[158:161], v[88:91]
	v_mfma_f32_16x16x32_bf16 v[84:87], v[216:219], v[192:195], v[84:87]
	v_mfma_f32_16x16x32_bf16 v[80:83], v[224:227], v[192:195], v[80:83]
	v_mfma_f32_16x16x32_bf16 v[76:79], v[216:219], v[200:203], v[76:79]
	v_mfma_f32_16x16x32_bf16 v[72:75], v[224:227], v[200:203], v[72:75]
	v_mfma_f32_16x16x32_bf16 v[68:71], v[216:219], v[208:211], v[68:71]
	v_mfma_f32_16x16x32_bf16 v[64:67], v[224:227], v[208:211], v[64:67]
	s_barrier
	ds_read_b128 v[154:157], v187 offset:49152
	ds_read_b128 v[158:161], v187 offset:50176
	ds_read_b128 v[188:191], v186 offset:49152
	ds_read_b128 v[192:195], v186 offset:50176
	ds_read_b128 v[196:199], v185 offset:49152
	ds_read_b128 v[200:203], v185 offset:50176
	ds_read_b128 v[204:207], v184 offset:49152
	ds_read_b128 v[208:211], v184 offset:50176
	s_add_u32 s70, s20, s70
	s_addc_u32 s71, s21, s71
	v_lshl_add_u64 v[162:163], s[70:71], 0, v[128:129]
	s_add_i32 s23, s98, 0x1c000
	s_add_u32 s70, s70, s25
	s_mov_b32 m0, s23
	s_addc_u32 s71, s71, 0
	s_add_i32 s23, s98, 0x1e000
	global_load_lds_dwordx4 v[162:163], off
	v_lshl_add_u64 v[162:163], s[70:71], 0, v[128:129]
	s_mov_b32 m0, s23
	s_nop 0
	global_load_lds_dwordx4 v[162:163], off
	s_waitcnt vmcnt(12)
	s_barrier
	s_waitcnt lgkmcnt(0)
	s_waitcnt lgkmcnt(0)
	v_mfma_f32_16x16x32_bf16 v[60:63], v[138:141], v[154:157], v[60:63]
	v_mfma_f32_16x16x32_bf16 v[56:59], v[146:149], v[154:157], v[56:59]
	v_mfma_f32_16x16x32_bf16 v[52:55], v[138:141], v[188:191], v[52:55]
	v_mfma_f32_16x16x32_bf16 v[48:51], v[146:149], v[188:191], v[48:51]
	v_mfma_f32_16x16x32_bf16 v[44:47], v[138:141], v[196:199], v[44:47]
	v_mfma_f32_16x16x32_bf16 v[40:43], v[146:149], v[196:199], v[40:43]
	v_mfma_f32_16x16x32_bf16 v[36:39], v[138:141], v[204:207], v[36:39]
	v_mfma_f32_16x16x32_bf16 v[32:35], v[146:149], v[204:207], v[32:35]
	v_mfma_f32_16x16x32_bf16 v[60:63], v[142:145], v[158:161], v[60:63]
	v_mfma_f32_16x16x32_bf16 v[56:59], v[150:153], v[158:161], v[56:59]
	v_mfma_f32_16x16x32_bf16 v[52:55], v[142:145], v[192:195], v[52:55]
	v_mfma_f32_16x16x32_bf16 v[48:51], v[150:153], v[192:195], v[48:51]
	v_mfma_f32_16x16x32_bf16 v[44:47], v[142:145], v[200:203], v[44:47]
	v_mfma_f32_16x16x32_bf16 v[40:43], v[150:153], v[200:203], v[40:43]
	v_mfma_f32_16x16x32_bf16 v[36:39], v[142:145], v[208:211], v[36:39]
	v_mfma_f32_16x16x32_bf16 v[32:35], v[150:153], v[208:211], v[32:35]
	s_barrier
	s_lshl_b64 s[70:71], s[18:19], s28
	s_add_u32 s70, s26, s70
	s_addc_u32 s71, s27, s71
	v_lshl_add_u64 v[162:163], s[70:71], 0, v[164:165]
	s_add_i32 s23, s98, 0xc000
	s_add_u32 s70, s70, s24
	s_mov_b32 m0, s23
	s_addc_u32 s71, s71, 0
	s_add_i32 s23, s98, 0xe000
	global_load_lds_dwordx4 v[162:163], off
	v_lshl_add_u64 v[162:163], s[70:71], 0, v[164:165]
	s_mov_b32 m0, s23
	s_nop 0
	global_load_lds_dwordx4 v[162:163], off
	ds_read_b128 v[138:141], v134
	ds_read_b128 v[142:145], v134 offset:1024
	ds_read_b128 v[146:149], v134 offset:2048
	ds_read_b128 v[150:153], v134 offset:3072
	s_waitcnt vmcnt(12)
	s_barrier
	v_mfma_f32_16x16x32_bf16 v[28:31], v[212:215], v[154:157], v[28:31]
	v_mfma_f32_16x16x32_bf16 v[24:27], v[220:223], v[154:157], v[24:27]
	v_mfma_f32_16x16x32_bf16 v[20:23], v[212:215], v[188:191], v[20:23]
	v_mfma_f32_16x16x32_bf16 v[16:19], v[220:223], v[188:191], v[16:19]
	v_mfma_f32_16x16x32_bf16 v[12:15], v[212:215], v[196:199], v[12:15]
	v_mfma_f32_16x16x32_bf16 v[8:11], v[220:223], v[196:199], v[8:11]
	v_mfma_f32_16x16x32_bf16 v[4:7], v[212:215], v[204:207], v[4:7]
	v_mfma_f32_16x16x32_bf16 v[0:3], v[220:223], v[204:207], v[0:3]
	v_mfma_f32_16x16x32_bf16 v[28:31], v[216:219], v[158:161], v[28:31]
	v_mfma_f32_16x16x32_bf16 v[24:27], v[224:227], v[158:161], v[24:27]
	v_mfma_f32_16x16x32_bf16 v[20:23], v[216:219], v[192:195], v[20:23]
	v_mfma_f32_16x16x32_bf16 v[16:19], v[224:227], v[192:195], v[16:19]
	v_mfma_f32_16x16x32_bf16 v[12:15], v[216:219], v[200:203], v[12:15]
	v_mfma_f32_16x16x32_bf16 v[8:11], v[224:227], v[200:203], v[8:11]
	v_mfma_f32_16x16x32_bf16 v[4:7], v[216:219], v[208:211], v[4:7]
	v_mfma_f32_16x16x32_bf16 v[0:3], v[224:227], v[208:211], v[0:3]
	s_add_i32 s23, s18, -3
	s_cmp_lt_u32 s23, 28
	s_barrier
	s_cbranch_scc1 .LBB0_356
	s_lshl_b64 s[18:19], 31, s28
	s_add_u32 s18, s26, s18
	s_addc_u32 s19, s27, s19
	v_lshl_add_u64 v[128:129], s[18:19], 0, v[164:165]
	v_readfirstlane_b32 s15, v133
	s_add_u32 s18, s18, s24
	s_mov_b32 m0, s15
	s_addc_u32 s19, s19, 0
	v_readfirstlane_b32 s15, v132
	ds_read_b128 v[138:141], v134
	ds_read_b128 v[142:145], v134 offset:1024
	ds_read_b128 v[146:149], v134 offset:2048
	ds_read_b128 v[150:153], v134 offset:3072
	ds_read_b128 v[154:157], v187
	ds_read_b128 v[158:161], v187 offset:1024
	ds_read_b128 v[188:191], v186
	ds_read_b128 v[192:195], v186 offset:1024
	ds_read_b128 v[196:199], v185
	ds_read_b128 v[200:203], v185 offset:1024
	ds_read_b128 v[204:207], v184
	ds_read_b128 v[208:211], v184 offset:1024
	global_load_lds_dwordx4 v[128:129], off
	v_lshl_add_u64 v[128:129], s[18:19], 0, v[164:165]
	s_mov_b32 m0, s15
	s_nop 0
	global_load_lds_dwordx4 v[128:129], off
	s_waitcnt vmcnt(10)
	s_barrier
	s_waitcnt lgkmcnt(0)
	s_setprio 1
	s_waitcnt lgkmcnt(0)
	v_mfma_f32_16x16x32_bf16 v[124:127], v[138:141], v[154:157], v[124:127]
	v_mfma_f32_16x16x32_bf16 v[120:123], v[146:149], v[154:157], v[120:123]
	v_mfma_f32_16x16x32_bf16 v[116:119], v[138:141], v[188:191], v[116:119]
	v_mfma_f32_16x16x32_bf16 v[112:115], v[146:149], v[188:191], v[112:115]
	v_mfma_f32_16x16x32_bf16 v[108:111], v[138:141], v[196:199], v[108:111]
	v_mfma_f32_16x16x32_bf16 v[104:107], v[146:149], v[196:199], v[104:107]
	v_mfma_f32_16x16x32_bf16 v[100:103], v[138:141], v[204:207], v[100:103]
	v_mfma_f32_16x16x32_bf16 v[96:99], v[146:149], v[204:207], v[96:99]
	v_mfma_f32_16x16x32_bf16 v[124:127], v[142:145], v[158:161], v[124:127]
	v_mfma_f32_16x16x32_bf16 v[120:123], v[150:153], v[158:161], v[120:123]
	v_mfma_f32_16x16x32_bf16 v[116:119], v[142:145], v[192:195], v[116:119]
	v_mfma_f32_16x16x32_bf16 v[112:115], v[150:153], v[192:195], v[112:115]
	v_mfma_f32_16x16x32_bf16 v[108:111], v[142:145], v[200:203], v[108:111]
	v_mfma_f32_16x16x32_bf16 v[104:107], v[150:153], v[200:203], v[104:107]
	v_mfma_f32_16x16x32_bf16 v[100:103], v[142:145], v[208:211], v[100:103]
	v_mfma_f32_16x16x32_bf16 v[96:99], v[150:153], v[208:211], v[96:99]
	s_setprio 0
	s_barrier
	ds_read_b128 v[132:135], v131
	ds_read_b128 v[212:215], v131 offset:1024
	ds_read_b128 v[216:219], v131 offset:2048
	ds_read_b128 v[220:223], v131 offset:3072
	s_barrier
	s_waitcnt lgkmcnt(0)
	s_setprio 1
	s_waitcnt lgkmcnt(0)
	v_mfma_f32_16x16x32_bf16 v[92:95], v[132:135], v[154:157], v[92:95]
	v_mfma_f32_16x16x32_bf16 v[88:91], v[216:219], v[154:157], v[88:91]
	v_mfma_f32_16x16x32_bf16 v[84:87], v[132:135], v[188:191], v[84:87]
	v_mfma_f32_16x16x32_bf16 v[80:83], v[216:219], v[188:191], v[80:83]
	v_mfma_f32_16x16x32_bf16 v[76:79], v[132:135], v[196:199], v[76:79]
	v_mfma_f32_16x16x32_bf16 v[72:75], v[216:219], v[196:199], v[72:75]
	v_mfma_f32_16x16x32_bf16 v[68:71], v[132:135], v[204:207], v[68:71]
	v_mfma_f32_16x16x32_bf16 v[64:67], v[216:219], v[204:207], v[64:67]
	v_mfma_f32_16x16x32_bf16 v[154:157], v[212:215], v[158:161], v[92:95]
	v_mfma_f32_16x16x32_bf16 v[158:161], v[220:223], v[158:161], v[88:91]
	v_mfma_f32_16x16x32_bf16 v[188:191], v[212:215], v[192:195], v[84:87]
	v_mfma_f32_16x16x32_bf16 v[192:195], v[220:223], v[192:195], v[80:83]
	v_mfma_f32_16x16x32_bf16 v[196:199], v[212:215], v[200:203], v[76:79]
	v_mfma_f32_16x16x32_bf16 v[200:203], v[220:223], v[200:203], v[72:75]
	v_mfma_f32_16x16x32_bf16 v[204:207], v[212:215], v[208:211], v[68:71]
	v_mfma_f32_16x16x32_bf16 v[208:211], v[220:223], v[208:211], v[64:67]
	s_setprio 0
	s_barrier
	s_nop 0
	ds_read_b128 v[64:67], v187 offset:16384
	ds_read_b128 v[68:71], v187 offset:17408
	ds_read_b128 v[72:75], v186 offset:16384
	ds_read_b128 v[76:79], v186 offset:17408
	ds_read_b128 v[80:83], v185 offset:16384
	ds_read_b128 v[84:87], v185 offset:17408
	ds_read_b128 v[88:91], v184 offset:16384
	ds_read_b128 v[92:95], v184 offset:17408
	s_waitcnt vmcnt(4)
	s_barrier
	s_waitcnt lgkmcnt(0)
	s_setprio 1
	s_waitcnt lgkmcnt(0)
	v_mfma_f32_16x16x32_bf16 v[60:63], v[138:141], v[64:67], v[60:63]
	v_mfma_f32_16x16x32_bf16 v[56:59], v[146:149], v[64:67], v[56:59]
	v_mfma_f32_16x16x32_bf16 v[52:55], v[138:141], v[72:75], v[52:55]
	v_mfma_f32_16x16x32_bf16 v[48:51], v[146:149], v[72:75], v[48:51]
	v_mfma_f32_16x16x32_bf16 v[224:227], v[138:141], v[80:83], v[44:47]
	v_mfma_f32_16x16x32_bf16 v[228:231], v[146:149], v[80:83], v[40:43]
	v_mfma_f32_16x16x32_bf16 v[138:141], v[138:141], v[88:91], v[36:39]
	v_mfma_f32_16x16x32_bf16 v[146:149], v[146:149], v[88:91], v[32:35]
	v_mfma_f32_16x16x32_bf16 v[32:35], v[142:145], v[68:71], v[60:63]
	v_mfma_f32_16x16x32_bf16 v[36:39], v[150:153], v[68:71], v[56:59]
	v_mfma_f32_16x16x32_bf16 v[40:43], v[142:145], v[76:79], v[52:55]
	v_mfma_f32_16x16x32_bf16 v[44:47], v[150:153], v[76:79], v[48:51]
	v_mfma_f32_16x16x32_bf16 v[48:51], v[142:145], v[84:87], v[224:227]
	v_mfma_f32_16x16x32_bf16 v[52:55], v[150:153], v[84:87], v[228:231]
	v_mfma_f32_16x16x32_bf16 v[56:59], v[142:145], v[92:95], v[138:141]
	v_mfma_f32_16x16x32_bf16 v[60:63], v[150:153], v[92:95], v[146:149]
	s_setprio 0
	s_setprio 1
	v_mfma_f32_16x16x32_bf16 v[28:31], v[132:135], v[64:67], v[28:31]
	v_mfma_f32_16x16x32_bf16 v[24:27], v[216:219], v[64:67], v[24:27]
	v_mfma_f32_16x16x32_bf16 v[20:23], v[132:135], v[72:75], v[20:23]
	v_mfma_f32_16x16x32_bf16 v[16:19], v[216:219], v[72:75], v[16:19]
	v_mfma_f32_16x16x32_bf16 v[64:67], v[132:135], v[80:83], v[12:15]
	v_mfma_f32_16x16x32_bf16 v[8:11], v[216:219], v[80:83], v[8:11]
	v_mfma_f32_16x16x32_bf16 v[72:75], v[132:135], v[88:91], v[4:7]
	v_mfma_f32_16x16x32_bf16 v[0:3], v[216:219], v[88:91], v[0:3]
	v_mfma_f32_16x16x32_bf16 v[4:7], v[212:215], v[68:71], v[28:31]
	v_mfma_f32_16x16x32_bf16 v[12:15], v[220:223], v[68:71], v[24:27]
	v_mfma_f32_16x16x32_bf16 v[20:23], v[212:215], v[76:79], v[20:23]
	v_mfma_f32_16x16x32_bf16 v[28:31], v[220:223], v[76:79], v[16:19]
	v_mfma_f32_16x16x32_bf16 v[64:67], v[212:215], v[84:87], v[64:67]
	v_mfma_f32_16x16x32_bf16 v[68:71], v[220:223], v[84:87], v[8:11]
	v_mfma_f32_16x16x32_bf16 v[72:75], v[212:215], v[92:95], v[72:75]
	v_mfma_f32_16x16x32_bf16 v[76:79], v[220:223], v[92:95], v[0:3]
	s_setprio 0
	s_barrier
	ds_read_b128 v[8:11], v130
	ds_read_b128 v[0:3], v130 offset:1024
	ds_read_b128 v[16:19], v130 offset:2048
	ds_read_b128 v[80:83], v130 offset:3072
	ds_read_b128 v[138:141], v187 offset:32768
	ds_read_b128 v[212:215], v187 offset:33792
	ds_read_b128 v[216:219], v186 offset:32768
	ds_read_b128 v[220:223], v186 offset:33792
	ds_read_b128 v[224:227], v185 offset:32768
	ds_read_b128 v[228:231], v185 offset:33792
	ds_read_b128 v[232:235], v184 offset:32768
	ds_read_b128 v[236:239], v184 offset:33792
	s_waitcnt vmcnt(2)
	s_barrier
	s_waitcnt lgkmcnt(0)
	s_setprio 1
	s_waitcnt lgkmcnt(0)
	v_mfma_f32_16x16x32_bf16 v[24:27], v[8:11], v[138:141], v[124:127]
	v_mfma_f32_16x16x32_bf16 v[84:87], v[16:19], v[138:141], v[120:123]
	v_mfma_f32_16x16x32_bf16 v[88:91], v[8:11], v[216:219], v[116:119]
	v_mfma_f32_16x16x32_bf16 v[92:95], v[16:19], v[216:219], v[112:115]
	v_mfma_f32_16x16x32_bf16 v[108:111], v[8:11], v[224:227], v[108:111]
	v_mfma_f32_16x16x32_bf16 v[104:107], v[16:19], v[224:227], v[104:107]
	v_mfma_f32_16x16x32_bf16 v[100:103], v[8:11], v[232:235], v[100:103]
	v_mfma_f32_16x16x32_bf16 v[96:99], v[16:19], v[232:235], v[96:99]
	v_mfma_f32_16x16x32_bf16 v[148:151], v[0:3], v[212:215], v[24:27]
	v_mfma_f32_16x16x32_bf16 v[144:147], v[80:83], v[212:215], v[84:87]
	v_mfma_f32_16x16x32_bf16 v[132:135], v[0:3], v[220:223], v[88:91]
	v_mfma_f32_16x16x32_bf16 v[128:131], v[80:83], v[220:223], v[92:95]
	v_mfma_f32_16x16x32_bf16 v[116:119], v[0:3], v[228:231], v[108:111]
	v_mfma_f32_16x16x32_bf16 v[112:115], v[80:83], v[228:231], v[104:107]
	v_mfma_f32_16x16x32_bf16 v[100:103], v[0:3], v[236:239], v[100:103]
	v_mfma_f32_16x16x32_bf16 v[24:27], v[80:83], v[236:239], v[96:99]
	s_setprio 0
	s_barrier
	ds_read_b128 v[92:95], v136
	ds_read_b128 v[84:87], v136 offset:1024
	ds_read_b128 v[96:99], v136 offset:2048
	ds_read_b128 v[88:91], v136 offset:3072
	s_waitcnt vmcnt(0)
	s_barrier
	s_waitcnt lgkmcnt(0)
	s_setprio 1
	s_waitcnt lgkmcnt(0)
	v_mfma_f32_16x16x32_bf16 v[104:107], v[92:95], v[138:141], v[154:157]
	v_mfma_f32_16x16x32_bf16 v[108:111], v[96:99], v[138:141], v[158:161]
	v_mfma_f32_16x16x32_bf16 v[120:123], v[92:95], v[216:219], v[188:191]
	v_mfma_f32_16x16x32_bf16 v[124:127], v[96:99], v[216:219], v[192:195]
	v_mfma_f32_16x16x32_bf16 v[160:163], v[92:95], v[224:227], v[196:199]
	v_mfma_f32_16x16x32_bf16 v[188:191], v[96:99], v[224:227], v[200:203]
	v_mfma_f32_16x16x32_bf16 v[192:195], v[92:95], v[232:235], v[204:207]
	v_mfma_f32_16x16x32_bf16 v[196:199], v[96:99], v[232:235], v[208:211]
	v_mfma_f32_16x16x32_bf16 v[156:159], v[84:87], v[212:215], v[104:107]
	v_mfma_f32_16x16x32_bf16 v[152:155], v[88:91], v[212:215], v[108:111]
	v_mfma_f32_16x16x32_bf16 v[140:143], v[84:87], v[220:223], v[120:123]
	v_mfma_f32_16x16x32_bf16 v[136:139], v[88:91], v[220:223], v[124:127]
	v_mfma_f32_16x16x32_bf16 v[124:127], v[84:87], v[228:231], v[160:163]
	v_mfma_f32_16x16x32_bf16 v[120:123], v[88:91], v[228:231], v[188:191]
	v_mfma_f32_16x16x32_bf16 v[108:111], v[84:87], v[236:239], v[192:195]
	v_mfma_f32_16x16x32_bf16 v[104:107], v[88:91], v[236:239], v[196:199]
	s_setprio 0
	s_barrier
	v_mbcnt_lo_u32_b32 v164, -1, 0
	v_mbcnt_hi_u32_b32 v164, -1, v164
	s_cmp_lt_i32 s64, 3
	v_add_u32_e32 v160, s34, v164
	v_ashrrev_i32_e32 v192, 6, v160
	v_bfe_u32 v190, v160, 8, 1
	v_and_b32_e32 v191, 3, v192
	v_and_b32_e32 v188, 15, v164
	v_bfe_u32 v189, v160, 4, 2
	s_mov_b64 s[18:19], 0
	s_cbranch_scc1 .LBB0_362
	v_lshrrev_b32_e32 v160, 4, v160
	v_lshlrev_b32_e32 v162, 9, v189
	v_lshlrev_b32_e32 v163, 9, v160
	s_mov_b64 s[20:21], -1
	s_cmp_gt_i32 s64, 3
	v_lshlrev_b32_e32 v161, 4, v188
	v_and_b32_e32 v160, 0x400, v162
	v_and_b32_e32 v162, 0x200, v163
	s_cbranch_scc0 .LBB0_360
	s_lshl_b32 s15, s66, 20
	s_lshl_b32 s20, s66, 16
	s_and_b32 s15, s15, 0xff000000
	s_and_b32 s20, s20, 0xf0000
	s_lshl_b32 s17, s68, 21
	s_or_b32 s15, s20, s15
	v_lshlrev_b32_e32 v163, 14, v191
	s_add_i32 s15, s15, s17
	v_lshlrev_b32_e32 v166, 12, v190
	v_or3_b32 v163, s15, v161, v163
	v_or3_b32 v163, v163, v166, v162
	v_add_u32_e32 v166, v163, v160
	s_mov_b64 s[20:21], 0

.LBB0_464:
	v_bfe_i32 v5, v136, 27, 1
	v_lshlrev_b32_e32 v135, 4, v136
	v_lshrrev_b32_e32 v5, 22, v5
	v_add_u32_e32 v5, v135, v5
	v_and_b32_e32 v5, 0xfffffc00, v5
	v_sub_u32_e32 v5, v135, v5
	v_lshrrev_b32_e32 v6, 4, v5
	v_bitop3_b32 v5, v6, v5, 32 bitop3:0x6c
	v_ashrrev_i32_e32 v6, 31, v5
	v_lshrrev_b32_e32 v6, 26, v6
	v_add_u32_e32 v6, v5, v6
	v_ashrrev_i32_e32 v157, 6, v6
	v_and_b32_e32 v6, 0xc0, v6
	v_sub_u32_e32 v5, v5, v6
	v_ashrrev_i16_sdwa v5, v134, sext(v5) dst_sel:DWORD dst_unused:UNUSED_PAD src0_sel:DWORD src1_sel:BYTE_0
	v_and_b32_e32 v2, 15, v0
	v_and_b32_e32 v3, 48, v0
	v_bfe_i32 v158, v5, 0, 16
	v_and_b32_e32 v5, 32, v0
	v_lshlrev_b32_e32 v8, 2, v0
	v_lshlrev_b32_e32 v0, 6, v0
	s_movk_i32 s36, 0x3f0
	v_lshlrev_b32_e32 v2, 6, v2
	v_and_b32_e32 v8, 32, v8
	v_and_b32_e32 v0, 0x3c0, v0
	v_ashrrev_i32_e32 v4, 31, v136
	v_bitop3_b32 v5, v135, v5, s36 bitop3:0x6c
	v_or_b32_e32 v7, v2, v3
	v_bitop3_b32 v2, v2, v8, v3 bitop3:0x36
	v_bitop3_b32 v3, v0, v8, v3 bitop3:0x36
	v_lshlrev_b32_e32 v0, 11, v136
	v_lshrrev_b32_e32 v4, 26, v4
	v_and_or_b32 v0, v0, s78, v5
	v_lshlrev_b32_e32 v5, 3, v136
	s_bfe_u32 s66, s86, 0x30003
	v_add_u32_e32 v4, v136, v4
	s_mov_b32 s36, 0x14000
	v_and_b32_e32 v5, 0xfffffc00, v5
	s_lshl_b32 s24, s66, 14
	v_ashrrev_i32_e32 v156, 6, v4
	v_bitop3_b32 v10, v7, s36, v8 bitop3:0xde
	s_mov_b32 s36, 0x1c000
	v_add_u32_e32 v128, v0, v5
	v_bitop3_b32 v9, v7, s76, v8 bitop3:0xde
	v_bitop3_b32 v11, v7, s77, v8 bitop3:0xde
	v_bitop3_b32 v7, v7, s36, v8 bitop3:0xde
	v_lshl_add_u64 v[130:131], s[24:25], 0, v[128:129]
	v_lshlrev_b32_e32 v0, 15, v156
	s_lshl_b32 s24, s86, 17
	s_and_b32 s36, s86, 7
	v_and_b32_e32 v0, 0xffff0000, v0
	s_and_b32 s24, s24, 0x1800000
	s_lshl_b32 s36, s36, 20
	v_lshl_add_u32 v0, v157, 12, v0
	s_or_b32 s24, s24, s36
	v_lshlrev_b32_e32 v6, 6, v136
	v_lshlrev_b32_e32 v1, 13, v1
	v_and_or_b32 v0, v4, 64, v0
	s_add_u32 s68, s24, s90
	v_and_b32_e32 v6, 0x3000, v6
	v_or_b32_e32 v8, 0x800, v1
	v_or_b32_e32 v12, 0x1000, v1
	v_or_b32_e32 v13, 0x1800, v1
	v_lshl_add_u32 v128, v158, 1, v0
	s_addc_u32 s69, 0, 0
	v_mov_b32_e32 v0, 0
	v_lshl_add_u64 v[132:133], s[68:69], 0, v[128:129]
	s_mov_b32 s24, -2
	v_add_u32_e32 v162, v9, v6
	v_add_u32_e32 v153, v2, v1
	v_add_u32_e32 v152, v3, v8
	v_add_u32_e32 v151, v3, v12
	v_add_u32_e32 v150, v3, v13
	v_add_u32_e32 v161, 0xc000, v135
	v_add_u32_e32 v160, 0xe000, v135
	v_add_u32_e32 v159, v10, v6
	v_add_u32_e32 v149, 0x10000, v135
	v_add_u32_e32 v148, 0x12000, v135
	v_add_u32_e32 v147, 0x2000, v135
	v_add_u32_e32 v146, 0x14000, v135
	v_add_u32_e32 v145, 0x16000, v135
	v_add_u32_e32 v155, v11, v6
	v_add_u32_e32 v144, 0x4000, v135
	v_add_u32_e32 v143, 0x6000, v135
	v_add_u32_e32 v154, v7, v6
	v_add_u32_e32 v142, 0x18000, v135
	v_add_u32_e32 v141, 0x1a000, v135
	v_add_u32_e32 v140, 0x8000, v135
	v_add_u32_e32 v139, 0xa000, v135
	v_add_u32_e32 v138, 0x1c000, v135
	v_add_u32_e32 v137, 0x1e000, v135
	v_mov_b32_e32 v1, v0
	v_mov_b32_e32 v2, v0
	v_mov_b32_e32 v3, v0
	v_mov_b32_e32 v4, v0
	v_mov_b32_e32 v5, v0
	v_mov_b32_e32 v6, v0
	v_mov_b32_e32 v7, v0
	v_mov_b32_e32 v8, v0
	v_mov_b32_e32 v9, v0
	v_mov_b32_e32 v10, v0
	v_mov_b32_e32 v11, v0
	v_mov_b32_e32 v12, v0
	v_mov_b32_e32 v13, v0
	v_mov_b32_e32 v14, v0
	v_mov_b32_e32 v15, v0
	v_mov_b32_e32 v16, v0
	v_mov_b32_e32 v17, v0
	v_mov_b32_e32 v18, v0
	v_mov_b32_e32 v19, v0
	v_mov_b32_e32 v20, v0
	v_mov_b32_e32 v21, v0
	v_mov_b32_e32 v22, v0
	v_mov_b32_e32 v23, v0
	v_mov_b32_e32 v24, v0
	v_mov_b32_e32 v25, v0
	v_mov_b32_e32 v26, v0
	v_mov_b32_e32 v27, v0
	v_mov_b32_e32 v28, v0
	v_mov_b32_e32 v29, v0
	v_mov_b32_e32 v30, v0
	v_mov_b32_e32 v31, v0
	v_mov_b32_e32 v32, v0
	v_mov_b32_e32 v33, v0
	v_mov_b32_e32 v34, v0
	v_mov_b32_e32 v35, v0
	v_mov_b32_e32 v36, v0
	v_mov_b32_e32 v37, v0
	v_mov_b32_e32 v38, v0
	v_mov_b32_e32 v39, v0
	v_mov_b32_e32 v40, v0
	v_mov_b32_e32 v41, v0
	v_mov_b32_e32 v42, v0
	v_mov_b32_e32 v43, v0
	v_mov_b32_e32 v44, v0
	v_mov_b32_e32 v45, v0
	v_mov_b32_e32 v46, v0
	v_mov_b32_e32 v47, v0
	v_mov_b32_e32 v48, v0
	v_mov_b32_e32 v49, v0
	v_mov_b32_e32 v50, v0
	v_mov_b32_e32 v51, v0
	v_mov_b32_e32 v52, v0
	v_mov_b32_e32 v53, v0
	v_mov_b32_e32 v54, v0
	v_mov_b32_e32 v55, v0
	v_mov_b32_e32 v56, v0
	v_mov_b32_e32 v57, v0
	v_mov_b32_e32 v58, v0
	v_mov_b32_e32 v59, v0
	v_mov_b32_e32 v60, v0
	v_mov_b32_e32 v61, v0
	v_mov_b32_e32 v62, v0
	v_mov_b32_e32 v63, v0
	v_mov_b32_e32 v64, v0
	v_mov_b32_e32 v65, v0
	v_mov_b32_e32 v66, v0
	v_mov_b32_e32 v67, v0
	v_mov_b32_e32 v68, v0
	v_mov_b32_e32 v69, v0
	v_mov_b32_e32 v70, v0
	v_mov_b32_e32 v71, v0
	v_mov_b32_e32 v72, v0
	v_mov_b32_e32 v73, v0
	v_mov_b32_e32 v74, v0
	v_mov_b32_e32 v75, v0
	v_mov_b32_e32 v76, v0
	v_mov_b32_e32 v77, v0
	v_mov_b32_e32 v78, v0
	v_mov_b32_e32 v79, v0
	v_mov_b32_e32 v80, v0
	v_mov_b32_e32 v81, v0
	v_mov_b32_e32 v82, v0
	v_mov_b32_e32 v83, v0
	v_mov_b32_e32 v84, v0
	v_mov_b32_e32 v85, v0
	v_mov_b32_e32 v86, v0
	v_mov_b32_e32 v87, v0
	v_mov_b32_e32 v88, v0
	v_mov_b32_e32 v89, v0
	v_mov_b32_e32 v90, v0
	v_mov_b32_e32 v91, v0
	v_mov_b32_e32 v92, v0
	v_mov_b32_e32 v93, v0
	v_mov_b32_e32 v94, v0
	v_mov_b32_e32 v95, v0
	v_mov_b32_e32 v96, v0
	v_mov_b32_e32 v97, v0
	v_mov_b32_e32 v98, v0
	v_mov_b32_e32 v99, v0
	v_mov_b32_e32 v100, v0
	v_mov_b32_e32 v101, v0
	v_mov_b32_e32 v102, v0
	v_mov_b32_e32 v103, v0
	v_mov_b32_e32 v104, v0
	v_mov_b32_e32 v105, v0
	v_mov_b32_e32 v106, v0
	v_mov_b32_e32 v107, v0
	v_mov_b32_e32 v108, v0
	v_mov_b32_e32 v109, v0
	v_mov_b32_e32 v110, v0
	v_mov_b32_e32 v111, v0
	v_mov_b32_e32 v112, v0
	v_mov_b32_e32 v113, v0
	v_mov_b32_e32 v114, v0
	v_mov_b32_e32 v115, v0
	v_mov_b32_e32 v116, v0
	v_mov_b32_e32 v117, v0
	v_mov_b32_e32 v118, v0
	v_mov_b32_e32 v119, v0
	v_mov_b32_e32 v120, v0
	v_mov_b32_e32 v121, v0
	v_mov_b32_e32 v122, v0
	v_mov_b32_e32 v123, v0
	v_mov_b32_e32 v124, v0
	v_mov_b32_e32 v125, v0
	v_mov_b32_e32 v126, v0
	v_mov_b32_e32 v127, v0
	s_barrier
	v_readlane_b32 s98, v242, 1
	s_lshl_b32 s98, s98, 10
	v_lshl_add_u64 v[228:229], s[50:51], 0, v[132:133]
	s_mov_b64 s[68:69], 0xe080080
	s_add_i32 s36, s98, 0xc000
	v_lshl_add_u64 v[166:167], v[228:229], 0, s[68:69]
	s_mov_b32 m0, s36
	s_mov_b64 s[68:69], 0xe0c0080
	s_add_i32 s36, s98, 0xe000
	global_load_lds_dwordx4 v[166:167], off
	v_lshl_add_u64 v[166:167], v[228:229], 0, s[68:69]
	s_mov_b32 m0, s36
	s_nop 0
	global_load_lds_dwordx4 v[166:167], off
	ds_read_b128 v[164:167], v162
	ds_read_b128 v[168:171], v162 offset:1024
	ds_read_b128 v[172:175], v162 offset:2048
	ds_read_b128 v[176:179], v162 offset:3072
.LBB0_465:
	ds_read_b128 v[180:183], v153
	ds_read_b128 v[184:187], v153 offset:1024
	ds_read_b128 v[188:191], v152
	ds_read_b128 v[192:195], v152 offset:1024
	ds_read_b128 v[196:199], v151
	ds_read_b128 v[200:203], v151 offset:1024
	ds_read_b128 v[204:207], v150
	ds_read_b128 v[208:211], v150 offset:1024
	s_waitcnt lgkmcnt(8)
	s_waitcnt vmcnt(10)
	s_barrier
	s_waitcnt lgkmcnt(0)
	s_waitcnt lgkmcnt(0)
	v_mfma_f32_16x16x32_bf16 v[124:127], v[164:167], v[180:183], v[124:127]
	v_mfma_f32_16x16x32_bf16 v[120:123], v[172:175], v[180:183], v[120:123]
	v_mfma_f32_16x16x32_bf16 v[116:119], v[164:167], v[188:191], v[116:119]
	v_mfma_f32_16x16x32_bf16 v[112:115], v[172:175], v[188:191], v[112:115]
	v_mfma_f32_16x16x32_bf16 v[108:111], v[164:167], v[196:199], v[108:111]
	v_mfma_f32_16x16x32_bf16 v[104:107], v[172:175], v[196:199], v[104:107]
	v_mfma_f32_16x16x32_bf16 v[100:103], v[164:167], v[204:207], v[100:103]
	v_mfma_f32_16x16x32_bf16 v[96:99], v[172:175], v[204:207], v[96:99]
	v_mfma_f32_16x16x32_bf16 v[124:127], v[168:171], v[184:187], v[124:127]
	v_mfma_f32_16x16x32_bf16 v[120:123], v[176:179], v[184:187], v[120:123]
	v_mfma_f32_16x16x32_bf16 v[116:119], v[168:171], v[192:195], v[116:119]
	v_mfma_f32_16x16x32_bf16 v[112:115], v[176:179], v[192:195], v[112:115]
	v_mfma_f32_16x16x32_bf16 v[108:111], v[168:171], v[200:203], v[108:111]
	v_mfma_f32_16x16x32_bf16 v[104:107], v[176:179], v[200:203], v[104:107]
	v_mfma_f32_16x16x32_bf16 v[100:103], v[168:171], v[208:211], v[100:103]
	v_mfma_f32_16x16x32_bf16 v[96:99], v[176:179], v[208:211], v[96:99]
	s_barrier
	v_lshl_add_u64 v[230:231], s[50:51], 0, v[130:131]
	s_mov_b64 s[68:69], 0x3880000
	s_add_i32 s36, s98, 0x10000
	v_lshl_add_u64 v[232:233], v[230:231], 0, s[68:69]
	s_mov_b32 m0, s36
	s_mov_b64 s[68:69], 0x3881000
	s_add_i32 s36, s98, 0x12000
	ds_read_b128 v[212:215], v159
	ds_read_b128 v[216:219], v159 offset:1024
	ds_read_b128 v[220:223], v159 offset:2048
	ds_read_b128 v[224:227], v159 offset:3072
	global_load_lds_dwordx4 v[232:233], off
	v_lshl_add_u64 v[232:233], v[230:231], 0, s[68:69]
	s_mov_b32 m0, s36
	s_nop 0
	global_load_lds_dwordx4 v[232:233], off
	s_mov_b64 s[68:69], 0xe000100
	s_mov_b32 s36, s98
	v_lshl_add_u64 v[232:233], v[228:229], 0, s[68:69]
	s_mov_b32 m0, s36
	s_mov_b64 s[68:69], 0xe040100
	s_add_i32 s36, s98, 0x2000
	global_load_lds_dwordx4 v[232:233], off
	v_lshl_add_u64 v[232:233], v[228:229], 0, s[68:69]
	s_mov_b32 m0, s36
	s_nop 0
	global_load_lds_dwordx4 v[232:233], off
	s_waitcnt vmcnt(12)
	s_barrier
	s_waitcnt lgkmcnt(0)
	s_waitcnt lgkmcnt(0)
	v_mfma_f32_16x16x32_bf16 v[92:95], v[212:215], v[180:183], v[92:95]
	v_mfma_f32_16x16x32_bf16 v[88:91], v[220:223], v[180:183], v[88:91]
	v_mfma_f32_16x16x32_bf16 v[84:87], v[212:215], v[188:191], v[84:87]
	v_mfma_f32_16x16x32_bf16 v[80:83], v[220:223], v[188:191], v[80:83]
	v_mfma_f32_16x16x32_bf16 v[76:79], v[212:215], v[196:199], v[76:79]
	v_mfma_f32_16x16x32_bf16 v[72:75], v[220:223], v[196:199], v[72:75]
	v_mfma_f32_16x16x32_bf16 v[68:71], v[212:215], v[204:207], v[68:71]
	v_mfma_f32_16x16x32_bf16 v[64:67], v[220:223], v[204:207], v[64:67]
	v_mfma_f32_16x16x32_bf16 v[92:95], v[216:219], v[184:187], v[92:95]
	v_mfma_f32_16x16x32_bf16 v[88:91], v[224:227], v[184:187], v[88:91]
	v_mfma_f32_16x16x32_bf16 v[84:87], v[216:219], v[192:195], v[84:87]
	v_mfma_f32_16x16x32_bf16 v[80:83], v[224:227], v[192:195], v[80:83]
	v_mfma_f32_16x16x32_bf16 v[76:79], v[216:219], v[200:203], v[76:79]
	v_mfma_f32_16x16x32_bf16 v[72:75], v[224:227], v[200:203], v[72:75]
	v_mfma_f32_16x16x32_bf16 v[68:71], v[216:219], v[208:211], v[68:71]
	v_mfma_f32_16x16x32_bf16 v[64:67], v[224:227], v[208:211], v[64:67]
	s_barrier
	ds_read_b128 v[180:183], v153 offset:16384
	ds_read_b128 v[184:187], v153 offset:17408
	ds_read_b128 v[188:191], v152 offset:16384
	ds_read_b128 v[192:195], v152 offset:17408
	ds_read_b128 v[196:199], v151 offset:16384
	ds_read_b128 v[200:203], v151 offset:17408
	ds_read_b128 v[204:207], v150 offset:16384
	ds_read_b128 v[208:211], v150 offset:17408
	s_mov_b64 s[68:69], 0x3882000
	s_add_i32 s36, s98, 0x14000
	v_lshl_add_u64 v[232:233], v[230:231], 0, s[68:69]
	s_mov_b32 m0, s36
	s_mov_b64 s[68:69], 0x3883000
	s_add_i32 s36, s98, 0x16000
	global_load_lds_dwordx4 v[232:233], off
	v_lshl_add_u64 v[232:233], v[230:231], 0, s[68:69]
	s_mov_b32 m0, s36
	s_nop 0
	global_load_lds_dwordx4 v[232:233], off
	s_waitcnt vmcnt(12)
	s_barrier
	s_waitcnt lgkmcnt(0)
	s_waitcnt lgkmcnt(0)
	v_mfma_f32_16x16x32_bf16 v[60:63], v[164:167], v[180:183], v[60:63]
	v_mfma_f32_16x16x32_bf16 v[56:59], v[172:175], v[180:183], v[56:59]
	v_mfma_f32_16x16x32_bf16 v[52:55], v[164:167], v[188:191], v[52:55]
	v_mfma_f32_16x16x32_bf16 v[48:51], v[172:175], v[188:191], v[48:51]
	v_mfma_f32_16x16x32_bf16 v[44:47], v[164:167], v[196:199], v[44:47]
	v_mfma_f32_16x16x32_bf16 v[40:43], v[172:175], v[196:199], v[40:43]
	v_mfma_f32_16x16x32_bf16 v[36:39], v[164:167], v[204:207], v[36:39]
	v_mfma_f32_16x16x32_bf16 v[32:35], v[172:175], v[204:207], v[32:35]
	v_mfma_f32_16x16x32_bf16 v[60:63], v[168:171], v[184:187], v[60:63]
	v_mfma_f32_16x16x32_bf16 v[56:59], v[176:179], v[184:187], v[56:59]
	v_mfma_f32_16x16x32_bf16 v[52:55], v[168:171], v[192:195], v[52:55]
	v_mfma_f32_16x16x32_bf16 v[48:51], v[176:179], v[192:195], v[48:51]
	v_mfma_f32_16x16x32_bf16 v[44:47], v[168:171], v[200:203], v[44:47]
	v_mfma_f32_16x16x32_bf16 v[40:43], v[176:179], v[200:203], v[40:43]
	v_mfma_f32_16x16x32_bf16 v[36:39], v[168:171], v[208:211], v[36:39]
	v_mfma_f32_16x16x32_bf16 v[32:35], v[176:179], v[208:211], v[32:35]
	s_barrier
	s_add_i32 s36, s98, 0x4000
	v_lshl_add_u64 v[166:167], v[228:229], 0, s[26:27]
	s_mov_b32 m0, s36
	s_add_i32 s36, s98, 0x6000
	global_load_lds_dwordx4 v[166:167], off
	v_lshl_add_u64 v[166:167], v[228:229], 0, s[28:29]
	s_mov_b32 m0, s36
	s_nop 0
	global_load_lds_dwordx4 v[166:167], off
	ds_read_b128 v[164:167], v155
	ds_read_b128 v[168:171], v155 offset:1024
	ds_read_b128 v[172:175], v155 offset:2048
	ds_read_b128 v[176:179], v155 offset:3072
	s_waitcnt vmcnt(12)
	s_barrier
	v_mfma_f32_16x16x32_bf16 v[28:31], v[212:215], v[180:183], v[28:31]
	v_mfma_f32_16x16x32_bf16 v[24:27], v[220:223], v[180:183], v[24:27]
	v_mfma_f32_16x16x32_bf16 v[20:23], v[212:215], v[188:191], v[20:23]
	v_mfma_f32_16x16x32_bf16 v[16:19], v[220:223], v[188:191], v[16:19]
	v_mfma_f32_16x16x32_bf16 v[12:15], v[212:215], v[196:199], v[12:15]
	v_mfma_f32_16x16x32_bf16 v[8:11], v[220:223], v[196:199], v[8:11]
	v_mfma_f32_16x16x32_bf16 v[4:7], v[212:215], v[204:207], v[4:7]
	v_mfma_f32_16x16x32_bf16 v[0:3], v[220:223], v[204:207], v[0:3]
	v_mfma_f32_16x16x32_bf16 v[28:31], v[216:219], v[184:187], v[28:31]
	v_mfma_f32_16x16x32_bf16 v[24:27], v[224:227], v[184:187], v[24:27]
	v_mfma_f32_16x16x32_bf16 v[20:23], v[216:219], v[192:195], v[20:23]
	v_mfma_f32_16x16x32_bf16 v[16:19], v[224:227], v[192:195], v[16:19]
	v_mfma_f32_16x16x32_bf16 v[12:15], v[216:219], v[200:203], v[12:15]
	v_mfma_f32_16x16x32_bf16 v[8:11], v[224:227], v[200:203], v[8:11]
	v_mfma_f32_16x16x32_bf16 v[4:7], v[216:219], v[208:211], v[4:7]
	v_mfma_f32_16x16x32_bf16 v[0:3], v[224:227], v[208:211], v[0:3]
	s_barrier
	ds_read_b128 v[180:183], v153 offset:32768
	ds_read_b128 v[184:187], v153 offset:33792
	ds_read_b128 v[188:191], v152 offset:32768
	ds_read_b128 v[192:195], v152 offset:33792
	ds_read_b128 v[196:199], v151 offset:32768
	ds_read_b128 v[200:203], v151 offset:33792
	ds_read_b128 v[204:207], v150 offset:32768
	ds_read_b128 v[208:211], v150 offset:33792
	s_waitcnt lgkmcnt(8)
	s_waitcnt vmcnt(10)
	s_barrier
	s_waitcnt lgkmcnt(0)
	s_waitcnt lgkmcnt(0)
	v_mfma_f32_16x16x32_bf16 v[124:127], v[164:167], v[180:183], v[124:127]
	v_mfma_f32_16x16x32_bf16 v[120:123], v[172:175], v[180:183], v[120:123]
	v_mfma_f32_16x16x32_bf16 v[116:119], v[164:167], v[188:191], v[116:119]
	v_mfma_f32_16x16x32_bf16 v[112:115], v[172:175], v[188:191], v[112:115]
	v_mfma_f32_16x16x32_bf16 v[108:111], v[164:167], v[196:199], v[108:111]
	v_mfma_f32_16x16x32_bf16 v[104:107], v[172:175], v[196:199], v[104:107]
	v_mfma_f32_16x16x32_bf16 v[100:103], v[164:167], v[204:207], v[100:103]
	v_mfma_f32_16x16x32_bf16 v[96:99], v[172:175], v[204:207], v[96:99]
	v_mfma_f32_16x16x32_bf16 v[124:127], v[168:171], v[184:187], v[124:127]
	v_mfma_f32_16x16x32_bf16 v[120:123], v[176:179], v[184:187], v[120:123]
	v_mfma_f32_16x16x32_bf16 v[116:119], v[168:171], v[192:195], v[116:119]
	v_mfma_f32_16x16x32_bf16 v[112:115], v[176:179], v[192:195], v[112:115]
	v_mfma_f32_16x16x32_bf16 v[108:111], v[168:171], v[200:203], v[108:111]
	v_mfma_f32_16x16x32_bf16 v[104:107], v[176:179], v[200:203], v[104:107]
	v_mfma_f32_16x16x32_bf16 v[100:103], v[168:171], v[208:211], v[100:103]
	v_mfma_f32_16x16x32_bf16 v[96:99], v[176:179], v[208:211], v[96:99]
	s_barrier
	s_add_i32 s36, s98, 0x18000
	v_lshl_add_u64 v[232:233], v[230:231], 0, s[30:31]
	s_mov_b32 m0, s36
	s_add_i32 s36, s98, 0x1a000
	ds_read_b128 v[212:215], v154
	ds_read_b128 v[216:219], v154 offset:1024
	ds_read_b128 v[220:223], v154 offset:2048
	ds_read_b128 v[224:227], v154 offset:3072
	global_load_lds_dwordx4 v[232:233], off
	v_lshl_add_u64 v[232:233], v[230:231], 0, s[34:35]
	s_mov_b32 m0, s36
	s_nop 0
	global_load_lds_dwordx4 v[232:233], off
	s_add_i32 s36, s98, 0x8000
	v_lshl_add_u64 v[232:233], v[228:229], 0, s[44:45]
	s_mov_b32 m0, s36
	s_add_i32 s36, s98, 0xa000
	global_load_lds_dwordx4 v[232:233], off
	v_lshl_add_u64 v[228:229], v[228:229], 0, s[46:47]
	s_mov_b32 m0, s36
	s_nop 0
	global_load_lds_dwordx4 v[228:229], off
	s_waitcnt vmcnt(12)
	s_barrier
	s_waitcnt lgkmcnt(0)
	s_waitcnt lgkmcnt(0)
	v_mfma_f32_16x16x32_bf16 v[92:95], v[212:215], v[180:183], v[92:95]
	v_mfma_f32_16x16x32_bf16 v[88:91], v[220:223], v[180:183], v[88:91]
	v_mfma_f32_16x16x32_bf16 v[84:87], v[212:215], v[188:191], v[84:87]
	v_mfma_f32_16x16x32_bf16 v[80:83], v[220:223], v[188:191], v[80:83]
	v_mfma_f32_16x16x32_bf16 v[76:79], v[212:215], v[196:199], v[76:79]
	v_mfma_f32_16x16x32_bf16 v[72:75], v[220:223], v[196:199], v[72:75]
	v_mfma_f32_16x16x32_bf16 v[68:71], v[212:215], v[204:207], v[68:71]
	v_mfma_f32_16x16x32_bf16 v[64:67], v[220:223], v[204:207], v[64:67]
	v_mfma_f32_16x16x32_bf16 v[92:95], v[216:219], v[184:187], v[92:95]
	v_mfma_f32_16x16x32_bf16 v[88:91], v[224:227], v[184:187], v[88:91]
	v_mfma_f32_16x16x32_bf16 v[84:87], v[216:219], v[192:195], v[84:87]
	v_mfma_f32_16x16x32_bf16 v[80:83], v[224:227], v[192:195], v[80:83]
	v_mfma_f32_16x16x32_bf16 v[76:79], v[216:219], v[200:203], v[76:79]
	v_mfma_f32_16x16x32_bf16 v[72:75], v[224:227], v[200:203], v[72:75]
	v_mfma_f32_16x16x32_bf16 v[68:71], v[216:219], v[208:211], v[68:71]
	v_mfma_f32_16x16x32_bf16 v[64:67], v[224:227], v[208:211], v[64:67]
	s_barrier
	ds_read_b128 v[180:183], v153 offset:49152
	ds_read_b128 v[184:187], v153 offset:50176
	ds_read_b128 v[188:191], v152 offset:49152
	ds_read_b128 v[192:195], v152 offset:50176
	ds_read_b128 v[196:199], v151 offset:49152
	ds_read_b128 v[200:203], v151 offset:50176
	ds_read_b128 v[204:207], v150 offset:49152
	ds_read_b128 v[208:211], v150 offset:50176
	s_add_i32 s36, s98, 0x1c000
	v_lshl_add_u64 v[232:233], v[230:231], 0, s[56:57]
	s_mov_b32 m0, s36
	s_add_i32 s36, s98, 0x1e000
	global_load_lds_dwordx4 v[232:233], off
	v_lshl_add_u64 v[232:233], v[230:231], 0, s[58:59]
	s_mov_b32 m0, s36
	s_nop 0
	global_load_lds_dwordx4 v[232:233], off
	s_waitcnt vmcnt(12)
	s_barrier
	s_waitcnt lgkmcnt(0)
	s_waitcnt lgkmcnt(0)
	v_mfma_f32_16x16x32_bf16 v[60:63], v[164:167], v[180:183], v[60:63]
	v_mfma_f32_16x16x32_bf16 v[56:59], v[172:175], v[180:183], v[56:59]
	v_mfma_f32_16x16x32_bf16 v[52:55], v[164:167], v[188:191], v[52:55]
	v_mfma_f32_16x16x32_bf16 v[48:51], v[172:175], v[188:191], v[48:51]
	v_mfma_f32_16x16x32_bf16 v[44:47], v[164:167], v[196:199], v[44:47]
	v_mfma_f32_16x16x32_bf16 v[40:43], v[172:175], v[196:199], v[40:43]
	v_mfma_f32_16x16x32_bf16 v[36:39], v[164:167], v[204:207], v[36:39]
	v_mfma_f32_16x16x32_bf16 v[32:35], v[172:175], v[204:207], v[32:35]
	v_mfma_f32_16x16x32_bf16 v[60:63], v[168:171], v[184:187], v[60:63]
	v_mfma_f32_16x16x32_bf16 v[56:59], v[176:179], v[184:187], v[56:59]
	v_mfma_f32_16x16x32_bf16 v[52:55], v[168:171], v[192:195], v[52:55]
	v_mfma_f32_16x16x32_bf16 v[48:51], v[176:179], v[192:195], v[48:51]
	v_mfma_f32_16x16x32_bf16 v[44:47], v[168:171], v[200:203], v[44:47]
	v_mfma_f32_16x16x32_bf16 v[40:43], v[176:179], v[200:203], v[40:43]
	v_mfma_f32_16x16x32_bf16 v[36:39], v[168:171], v[208:211], v[36:39]
	v_mfma_f32_16x16x32_bf16 v[32:35], v[176:179], v[208:211], v[32:35]
	s_barrier
	v_lshl_add_u64 v[132:133], v[132:133], 0, s[60:61]
	v_lshl_add_u64 v[228:229], s[50:51], 0, v[132:133]
	s_mov_b64 s[68:69], 0xe080080
	s_add_i32 s36, s98, 0xc000
	v_lshl_add_u64 v[166:167], v[228:229], 0, s[68:69]
	s_mov_b32 m0, s36
	s_mov_b64 s[68:69], 0xe0c0080
	s_add_i32 s36, s98, 0xe000
	global_load_lds_dwordx4 v[166:167], off
	v_lshl_add_u64 v[166:167], v[228:229], 0, s[68:69]
	s_mov_b32 m0, s36
	s_nop 0
	global_load_lds_dwordx4 v[166:167], off
	ds_read_b128 v[164:167], v162
	ds_read_b128 v[168:171], v162 offset:1024
	ds_read_b128 v[172:175], v162 offset:2048
	ds_read_b128 v[176:179], v162 offset:3072
	s_waitcnt vmcnt(12)
	s_barrier
	v_mfma_f32_16x16x32_bf16 v[28:31], v[212:215], v[180:183], v[28:31]
	v_mfma_f32_16x16x32_bf16 v[24:27], v[220:223], v[180:183], v[24:27]
	v_mfma_f32_16x16x32_bf16 v[20:23], v[212:215], v[188:191], v[20:23]
	v_mfma_f32_16x16x32_bf16 v[16:19], v[220:223], v[188:191], v[16:19]
	v_mfma_f32_16x16x32_bf16 v[12:15], v[212:215], v[196:199], v[12:15]
	v_mfma_f32_16x16x32_bf16 v[8:11], v[220:223], v[196:199], v[8:11]
	v_mfma_f32_16x16x32_bf16 v[4:7], v[212:215], v[204:207], v[4:7]
	v_mfma_f32_16x16x32_bf16 v[0:3], v[220:223], v[204:207], v[0:3]
	v_mfma_f32_16x16x32_bf16 v[28:31], v[216:219], v[184:187], v[28:31]
	v_mfma_f32_16x16x32_bf16 v[24:27], v[224:227], v[184:187], v[24:27]
	v_mfma_f32_16x16x32_bf16 v[20:23], v[216:219], v[192:195], v[20:23]
	v_mfma_f32_16x16x32_bf16 v[16:19], v[224:227], v[192:195], v[16:19]
	v_mfma_f32_16x16x32_bf16 v[12:15], v[216:219], v[200:203], v[12:15]
	v_mfma_f32_16x16x32_bf16 v[8:11], v[224:227], v[200:203], v[8:11]
	v_mfma_f32_16x16x32_bf16 v[4:7], v[216:219], v[208:211], v[4:7]
	v_mfma_f32_16x16x32_bf16 v[0:3], v[224:227], v[208:211], v[0:3]
	s_add_i32 s24, s24, 2
	v_lshl_add_u64 v[130:131], v[130:131], 0, s[10:11]
	s_cmp_lt_u32 s24, 28
	s_barrier
	s_cbranch_scc1 .LBB0_465
	s_lshl_b32 s24, s86, 5
	s_lshl_b32 s36, s86, 8
	s_and_b32 s24, s24, 0x1800
	s_and_b32 s36, s36, 0x700
	s_or_b32 s24, s36, s24
	v_lshlrev_b32_e32 v128, 3, v156
	v_lshlrev_b32_e32 v130, 5, v156
	v_and_b32_e32 v128, 0xffff0, v128
	v_and_b32_e32 v130, 32, v130
	s_lshl_b32 s36, s24, 12
	v_add_u32_e32 v130, v130, v158
	v_add_lshl_u32 v128, v157, v128, 12
	s_add_u32 s68, s70, s36
	v_lshl_add_u32 v128, v130, 1, v128
	s_addc_u32 s69, s71, 0
	v_lshl_add_u64 v[156:157], s[68:69], 0, v[128:129]
	v_readfirstlane_b32 s36, v161
	ds_read_b128 v[130:133], v162
	ds_read_b128 v[164:167], v162 offset:1024
	ds_read_b128 v[168:171], v162 offset:2048
	ds_read_b128 v[172:175], v162 offset:3072
	ds_read_b128 v[176:179], v153
	ds_read_b128 v[180:183], v153 offset:1024
	ds_read_b128 v[184:187], v152
	ds_read_b128 v[188:191], v152 offset:1024
	ds_read_b128 v[192:195], v151
	ds_read_b128 v[196:199], v151 offset:1024
	ds_read_b128 v[200:203], v150
	ds_read_b128 v[204:207], v150 offset:1024
	v_lshl_add_u64 v[162:163], v[156:157], 0, s[62:63]
	s_mov_b32 m0, s36
	v_readfirstlane_b32 s36, v160
	global_load_lds_dwordx4 v[162:163], off
	v_lshl_add_u64 v[156:157], v[156:157], 0, s[64:65]
	s_mov_b32 m0, s36
	s_nop 0
	global_load_lds_dwordx4 v[156:157], off
	s_waitcnt vmcnt(10)
	s_barrier
	s_waitcnt lgkmcnt(0)
	s_setprio 1
	s_waitcnt lgkmcnt(0)
	v_mfma_f32_16x16x32_bf16 v[124:127], v[130:133], v[176:179], v[124:127]
	v_mfma_f32_16x16x32_bf16 v[120:123], v[168:171], v[176:179], v[120:123]
	v_mfma_f32_16x16x32_bf16 v[116:119], v[130:133], v[184:187], v[116:119]
	v_mfma_f32_16x16x32_bf16 v[112:115], v[168:171], v[184:187], v[112:115]
	v_mfma_f32_16x16x32_bf16 v[108:111], v[130:133], v[192:195], v[108:111]
	v_mfma_f32_16x16x32_bf16 v[104:107], v[168:171], v[192:195], v[104:107]
	v_mfma_f32_16x16x32_bf16 v[100:103], v[130:133], v[200:203], v[100:103]
	v_mfma_f32_16x16x32_bf16 v[96:99], v[168:171], v[200:203], v[96:99]
	v_mfma_f32_16x16x32_bf16 v[124:127], v[164:167], v[180:183], v[124:127]
	v_mfma_f32_16x16x32_bf16 v[120:123], v[172:175], v[180:183], v[120:123]
	v_mfma_f32_16x16x32_bf16 v[116:119], v[164:167], v[188:191], v[116:119]
	v_mfma_f32_16x16x32_bf16 v[112:115], v[172:175], v[188:191], v[112:115]
	v_mfma_f32_16x16x32_bf16 v[108:111], v[164:167], v[196:199], v[108:111]
	v_mfma_f32_16x16x32_bf16 v[104:107], v[172:175], v[196:199], v[104:107]
	v_mfma_f32_16x16x32_bf16 v[100:103], v[164:167], v[204:207], v[100:103]
	v_mfma_f32_16x16x32_bf16 v[96:99], v[172:175], v[204:207], v[96:99]
	s_setprio 0
	s_barrier
	ds_read_b128 v[160:163], v159
	ds_read_b128 v[208:211], v159 offset:1024
	ds_read_b128 v[212:215], v159 offset:2048
	ds_read_b128 v[156:159], v159 offset:3072
	s_barrier
	s_waitcnt lgkmcnt(0)
	s_setprio 1
	s_waitcnt lgkmcnt(0)
	v_mfma_f32_16x16x32_bf16 v[92:95], v[160:163], v[176:179], v[92:95]
	v_mfma_f32_16x16x32_bf16 v[88:91], v[212:215], v[176:179], v[88:91]
	v_mfma_f32_16x16x32_bf16 v[84:87], v[160:163], v[184:187], v[84:87]
	v_mfma_f32_16x16x32_bf16 v[80:83], v[212:215], v[184:187], v[80:83]
	v_mfma_f32_16x16x32_bf16 v[76:79], v[160:163], v[192:195], v[76:79]
	v_mfma_f32_16x16x32_bf16 v[72:75], v[212:215], v[192:195], v[72:75]
	v_mfma_f32_16x16x32_bf16 v[68:71], v[160:163], v[200:203], v[68:71]
	v_mfma_f32_16x16x32_bf16 v[64:67], v[212:215], v[200:203], v[64:67]
	v_mfma_f32_16x16x32_bf16 v[176:179], v[208:211], v[180:183], v[92:95]
	v_mfma_f32_16x16x32_bf16 v[180:183], v[156:159], v[180:183], v[88:91]
	v_mfma_f32_16x16x32_bf16 v[184:187], v[208:211], v[188:191], v[84:87]
	v_mfma_f32_16x16x32_bf16 v[188:191], v[156:159], v[188:191], v[80:83]
	v_mfma_f32_16x16x32_bf16 v[192:195], v[208:211], v[196:199], v[76:79]
	v_mfma_f32_16x16x32_bf16 v[196:199], v[156:159], v[196:199], v[72:75]
	v_mfma_f32_16x16x32_bf16 v[200:203], v[208:211], v[204:207], v[68:71]
	v_mfma_f32_16x16x32_bf16 v[204:207], v[156:159], v[204:207], v[64:67]
	s_setprio 0
	s_barrier
	s_nop 0
	ds_read_b128 v[64:67], v153 offset:16384
	ds_read_b128 v[68:71], v153 offset:17408
	ds_read_b128 v[72:75], v152 offset:16384
	ds_read_b128 v[76:79], v152 offset:17408
	ds_read_b128 v[80:83], v151 offset:16384
	ds_read_b128 v[84:87], v151 offset:17408
	ds_read_b128 v[88:91], v150 offset:16384
	ds_read_b128 v[92:95], v150 offset:17408
	s_waitcnt vmcnt(4)
	s_barrier
	s_waitcnt lgkmcnt(0)
	s_setprio 1
	s_waitcnt lgkmcnt(0)
	v_mfma_f32_16x16x32_bf16 v[60:63], v[130:133], v[64:67], v[60:63]
	v_mfma_f32_16x16x32_bf16 v[56:59], v[168:171], v[64:67], v[56:59]
	v_mfma_f32_16x16x32_bf16 v[52:55], v[130:133], v[72:75], v[52:55]
	v_mfma_f32_16x16x32_bf16 v[48:51], v[168:171], v[72:75], v[48:51]
	v_mfma_f32_16x16x32_bf16 v[216:219], v[130:133], v[80:83], v[44:47]
	v_mfma_f32_16x16x32_bf16 v[220:223], v[168:171], v[80:83], v[40:43]
	v_mfma_f32_16x16x32_bf16 v[130:133], v[130:133], v[88:91], v[36:39]
	v_mfma_f32_16x16x32_bf16 v[168:171], v[168:171], v[88:91], v[32:35]
	v_mfma_f32_16x16x32_bf16 v[32:35], v[164:167], v[68:71], v[60:63]
	v_mfma_f32_16x16x32_bf16 v[36:39], v[172:175], v[68:71], v[56:59]
	v_mfma_f32_16x16x32_bf16 v[40:43], v[164:167], v[76:79], v[52:55]
	v_mfma_f32_16x16x32_bf16 v[44:47], v[172:175], v[76:79], v[48:51]
	v_mfma_f32_16x16x32_bf16 v[48:51], v[164:167], v[84:87], v[216:219]
	v_mfma_f32_16x16x32_bf16 v[52:55], v[172:175], v[84:87], v[220:223]
	v_mfma_f32_16x16x32_bf16 v[56:59], v[164:167], v[92:95], v[130:133]
	v_mfma_f32_16x16x32_bf16 v[60:63], v[172:175], v[92:95], v[168:171]
	s_setprio 0
	s_setprio 1
	v_mfma_f32_16x16x32_bf16 v[28:31], v[160:163], v[64:67], v[28:31]
	v_mfma_f32_16x16x32_bf16 v[24:27], v[212:215], v[64:67], v[24:27]
	v_mfma_f32_16x16x32_bf16 v[20:23], v[160:163], v[72:75], v[20:23]
	v_mfma_f32_16x16x32_bf16 v[64:67], v[212:215], v[72:75], v[16:19]
	v_mfma_f32_16x16x32_bf16 v[72:75], v[160:163], v[80:83], v[12:15]
	v_mfma_f32_16x16x32_bf16 v[8:11], v[212:215], v[80:83], v[8:11]
	v_mfma_f32_16x16x32_bf16 v[80:83], v[160:163], v[88:91], v[4:7]
	v_mfma_f32_16x16x32_bf16 v[0:3], v[212:215], v[88:91], v[0:3]
	v_mfma_f32_16x16x32_bf16 v[4:7], v[208:211], v[68:71], v[28:31]
	v_mfma_f32_16x16x32_bf16 v[12:15], v[156:159], v[68:71], v[24:27]
	v_mfma_f32_16x16x32_bf16 v[16:19], v[208:211], v[76:79], v[20:23]
	v_mfma_f32_16x16x32_bf16 v[20:23], v[156:159], v[76:79], v[64:67]
	v_mfma_f32_16x16x32_bf16 v[24:27], v[208:211], v[84:87], v[72:75]
	v_mfma_f32_16x16x32_bf16 v[28:31], v[156:159], v[84:87], v[8:11]
	v_mfma_f32_16x16x32_bf16 v[64:67], v[208:211], v[92:95], v[80:83]
	v_mfma_f32_16x16x32_bf16 v[68:71], v[156:159], v[92:95], v[0:3]
	s_setprio 0
	s_barrier
	ds_read_b128 v[8:11], v155
	ds_read_b128 v[0:3], v155 offset:1024
	ds_read_b128 v[76:79], v155 offset:2048
	ds_read_b128 v[72:75], v155 offset:3072
	ds_read_b128 v[130:133], v153 offset:32768
	ds_read_b128 v[156:159], v153 offset:33792
	ds_read_b128 v[160:163], v152 offset:32768
	ds_read_b128 v[164:167], v152 offset:33792
	ds_read_b128 v[168:171], v151 offset:32768
	ds_read_b128 v[172:175], v151 offset:33792
	ds_read_b128 v[208:211], v150 offset:32768
	ds_read_b128 v[212:215], v150 offset:33792
	s_waitcnt vmcnt(2)
	s_barrier
	s_waitcnt lgkmcnt(0)
	s_setprio 1
	s_waitcnt lgkmcnt(0)
	v_mfma_f32_16x16x32_bf16 v[80:83], v[8:11], v[130:133], v[124:127]
	v_mfma_f32_16x16x32_bf16 v[84:87], v[76:79], v[130:133], v[120:123]
	v_mfma_f32_16x16x32_bf16 v[88:91], v[8:11], v[160:163], v[116:119]
	v_mfma_f32_16x16x32_bf16 v[92:95], v[76:79], v[160:163], v[112:115]
	v_mfma_f32_16x16x32_bf16 v[108:111], v[8:11], v[168:171], v[108:111]
	v_mfma_f32_16x16x32_bf16 v[104:107], v[76:79], v[168:171], v[104:107]
	v_mfma_f32_16x16x32_bf16 v[100:103], v[8:11], v[208:211], v[100:103]
	v_mfma_f32_16x16x32_bf16 v[96:99], v[76:79], v[208:211], v[96:99]
	v_mfma_f32_16x16x32_bf16 v[112:115], v[0:3], v[156:159], v[80:83]
	v_mfma_f32_16x16x32_bf16 v[116:119], v[72:75], v[156:159], v[84:87]
	v_mfma_f32_16x16x32_bf16 v[120:123], v[0:3], v[164:167], v[88:91]
	v_mfma_f32_16x16x32_bf16 v[124:127], v[72:75], v[164:167], v[92:95]
	v_mfma_f32_16x16x32_bf16 v[108:111], v[0:3], v[172:175], v[108:111]
	v_mfma_f32_16x16x32_bf16 v[104:107], v[72:75], v[172:175], v[104:107]
	v_mfma_f32_16x16x32_bf16 v[100:103], v[0:3], v[212:215], v[100:103]
	v_mfma_f32_16x16x32_bf16 v[96:99], v[72:75], v[212:215], v[96:99]
	s_setprio 0
	s_barrier
	ds_read_b128 v[88:91], v154
	ds_read_b128 v[80:83], v154 offset:1024
	ds_read_b128 v[92:95], v154 offset:2048
	ds_read_b128 v[84:87], v154 offset:3072
	s_waitcnt vmcnt(0)
	s_barrier
	s_waitcnt lgkmcnt(0)
	s_setprio 1
	s_waitcnt lgkmcnt(0)
	v_mfma_f32_16x16x32_bf16 v[176:179], v[88:91], v[130:133], v[176:179]
	v_mfma_f32_16x16x32_bf16 v[130:133], v[92:95], v[130:133], v[180:183]
	v_mfma_f32_16x16x32_bf16 v[180:183], v[88:91], v[160:163], v[184:187]
	v_mfma_f32_16x16x32_bf16 v[160:163], v[92:95], v[160:163], v[188:191]
	v_mfma_f32_16x16x32_bf16 v[184:187], v[88:91], v[168:171], v[192:195]
	v_mfma_f32_16x16x32_bf16 v[168:171], v[92:95], v[168:171], v[196:199]
	v_mfma_f32_16x16x32_bf16 v[188:191], v[88:91], v[208:211], v[200:203]
	v_mfma_f32_16x16x32_bf16 v[192:195], v[92:95], v[208:211], v[204:207]
	v_mfma_f32_16x16x32_bf16 v[176:179], v[80:83], v[156:159], v[176:179]
	v_mfma_f32_16x16x32_bf16 v[130:133], v[84:87], v[156:159], v[130:133]
	v_mfma_f32_16x16x32_bf16 v[154:157], v[80:83], v[164:167], v[180:183]
	v_mfma_f32_16x16x32_bf16 v[158:161], v[84:87], v[164:167], v[160:163]
	v_mfma_f32_16x16x32_bf16 v[162:165], v[80:83], v[172:175], v[184:187]
	v_mfma_f32_16x16x32_bf16 v[166:169], v[84:87], v[172:175], v[168:171]
	v_mfma_f32_16x16x32_bf16 v[170:173], v[80:83], v[212:215], v[188:191]
	v_mfma_f32_16x16x32_bf16 v[180:183], v[84:87], v[212:215], v[192:195]
	s_setprio 0
	s_barrier
	v_mbcnt_lo_u32_b32 v128, -1, 0
	v_mbcnt_hi_u32_b32 v128, -1, v128
	v_cvt_pk_bf16_f32 v112, v112, v113
	v_cvt_pk_bf16_f32 v113, v114, v115
	v_cvt_pk_bf16_f32 v114, v116, v117
	v_cvt_pk_bf16_f32 v115, v118, v119
	s_lshl_b32 s68, s66, 9
	v_add_u32_e32 v174, s74, v128
	v_ashrrev_i32_e32 v175, 6, v174
	v_and_b32_e32 v184, 15, v128
	v_and_b32_e32 v185, 48, v128
	v_mul_lo_u32 v186, v175, s79
	v_bfe_u32 v187, v128, 3, 3
	v_lshlrev_b32_e32 v128, 4, v128
	v_add_u32_e32 v186, 0x20000, v186
	v_lshrrev_b32_e32 v174, 2, v174
	v_and_b32_e32 v128, 0x70, v128
	v_mul_u32_u24_e32 v184, 0x90, v184
	v_and_b32_e32 v174, 64, v174
	v_add3_u32 v184, v186, v184, v185
	v_or_b32_e32 v185, v186, v128
	v_or3_b32 v174, s24, v174, v187
	v_mad_u32_u24 v185, v187, s80, v185
	ds_write_b128 v184, v[112:115]
	v_cvt_pk_bf16_f32 v112, v176, v177
	v_cvt_pk_bf16_f32 v113, v178, v179
	v_cvt_pk_bf16_f32 v114, v130, v131
	v_cvt_pk_bf16_f32 v115, v132, v133
	ds_write_b128 v184, v[112:115] offset:64
	v_lshlrev_b32_e32 v175, 7, v175
	ds_read_b128 v[112:115], v185
	v_lshlrev_b32_e32 v116, 12, v174
	v_and_or_b32 v116, v175, s81, v116
	v_or3_b32 v128, v116, s68, v128
	ds_read_b128 v[116:119], v185 offset:1152
	v_lshl_add_u64 v[130:131], s[0:1], 0, v[128:129]
	s_mov_b32 s36, 0x8000
	s_waitcnt lgkmcnt(0)
	global_store_dwordx4 v128, v[112:115], s[0:1]
	v_cvt_pk_bf16_f32 v108, v108, v109
	v_cvt_pk_bf16_f32 v109, v110, v111
	v_cvt_pk_bf16_f32 v110, v104, v105
	v_cvt_pk_bf16_f32 v111, v106, v107
	v_cvt_pk_bf16_f32 v104, v162, v163
	s_nop 1
	v_add_co_u32_e32 v112, vcc, s36, v130
	v_cvt_pk_bf16_f32 v114, v124, v125
	v_cvt_pk_bf16_f32 v115, v126, v127
	v_cvt_pk_bf16_f32 v105, v164, v165
	v_cvt_pk_bf16_f32 v106, v166, v167
	s_nop 1
	v_addc_co_u32_e32 v113, vcc, 0, v131, vcc
	global_store_dwordx4 v[112:113], v[116:119], off
	v_cvt_pk_bf16_f32 v112, v120, v121
	v_cvt_pk_bf16_f32 v113, v122, v123
	ds_write_b128 v184, v[112:115]
	v_cvt_pk_bf16_f32 v112, v154, v155
	v_cvt_pk_bf16_f32 v113, v156, v157
	v_cvt_pk_bf16_f32 v114, v158, v159
	v_cvt_pk_bf16_f32 v115, v160, v161
	ds_write_b128 v184, v[112:115] offset:64
	ds_read_b128 v[112:115], v185
	ds_read_b128 v[116:119], v185 offset:1152
	v_add_co_u32_e32 v120, vcc, s76, v130
	ds_write_b128 v184, v[108:111]
	v_cvt_pk_bf16_f32 v107, v168, v169
	ds_write_b128 v184, v[104:107] offset:64
	v_addc_co_u32_e32 v121, vcc, 0, v131, vcc
	ds_read_b128 v[104:107], v185
	ds_read_b128 v[108:111], v185 offset:1152
	s_waitcnt lgkmcnt(0)
	global_store_dwordx4 v[120:121], v[112:115], off
	v_cvt_pk_bf16_f32 v100, v100, v101
	v_cvt_pk_bf16_f32 v101, v102, v103
	v_cvt_pk_bf16_f32 v102, v96, v97
	v_cvt_pk_bf16_f32 v103, v98, v99
	ds_write_b128 v184, v[100:103]
	s_nop 0
	v_add_co_u32_e32 v112, vcc, s77, v130
	v_cvt_pk_bf16_f32 v96, v170, v171
	v_cvt_pk_bf16_f32 v97, v172, v173
	v_cvt_pk_bf16_f32 v98, v180, v181
	v_cvt_pk_bf16_f32 v99, v182, v183
	s_nop 1
	v_addc_co_u32_e32 v113, vcc, 0, v131, vcc
	global_store_dwordx4 v[112:113], v[116:119], off
	v_add_co_u32_e32 v112, vcc, s78, v130
	ds_write_b128 v184, v[96:99] offset:64
	s_nop 0
	v_addc_co_u32_e32 v113, vcc, 0, v131, vcc
	ds_read_b128 v[96:99], v185
	ds_read_b128 v[100:103], v185 offset:1152
	global_store_dwordx4 v[112:113], v[104:107], off
	s_nop 1
	v_add_co_u32_e32 v104, vcc, s82, v130
	s_nop 1
	v_addc_co_u32_e32 v105, vcc, 0, v131, vcc
	global_store_dwordx4 v[104:105], v[108:111], off
	v_add_co_u32_e32 v104, vcc, s83, v130
	s_nop 1
	v_addc_co_u32_e32 v105, vcc, 0, v131, vcc
	s_waitcnt lgkmcnt(0)
	global_store_dwordx4 v[104:105], v[96:99], off
	s_nop 1
	v_add_co_u32_e32 v96, vcc, s91, v130
	s_nop 1
	v_addc_co_u32_e32 v97, vcc, 0, v131, vcc
	global_store_dwordx4 v[96:97], v[100:103], off
	ds_read_b128 v[96:99], v153 offset:49152
	ds_read_b128 v[100:103], v153 offset:50176
	ds_read_b128 v[104:107], v152 offset:49152
	ds_read_b128 v[108:111], v152 offset:50176
	ds_read_b128 v[112:115], v151 offset:49152
	ds_read_b128 v[116:119], v151 offset:50176
	ds_read_b128 v[120:123], v150 offset:49152
	ds_read_b128 v[124:127], v150 offset:50176
	s_barrier
	s_waitcnt lgkmcnt(0)
	s_setprio 1
	s_waitcnt lgkmcnt(0)
	v_mfma_f32_16x16x32_bf16 v[32:35], v[8:11], v[96:99], v[32:35]
	v_mfma_f32_16x16x32_bf16 v[36:39], v[76:79], v[96:99], v[36:39]
	v_mfma_f32_16x16x32_bf16 v[40:43], v[8:11], v[104:107], v[40:43]
	v_mfma_f32_16x16x32_bf16 v[130:133], v[76:79], v[104:107], v[44:47]
	v_mfma_f32_16x16x32_bf16 v[150:153], v[8:11], v[112:115], v[48:51]
	v_mfma_f32_16x16x32_bf16 v[52:55], v[76:79], v[112:115], v[52:55]
	v_mfma_f32_16x16x32_bf16 v[8:11], v[8:11], v[120:123], v[56:59]
	v_mfma_f32_16x16x32_bf16 v[60:63], v[76:79], v[120:123], v[60:63]
	v_mfma_f32_16x16x32_bf16 v[56:59], v[0:3], v[100:103], v[32:35]
	v_mfma_f32_16x16x32_bf16 v[48:51], v[72:75], v[100:103], v[36:39]
	v_mfma_f32_16x16x32_bf16 v[44:47], v[0:3], v[108:111], v[40:43]
	v_mfma_f32_16x16x32_bf16 v[40:43], v[72:75], v[108:111], v[130:133]
	v_mfma_f32_16x16x32_bf16 v[36:39], v[0:3], v[116:119], v[150:153]
	v_mfma_f32_16x16x32_bf16 v[32:35], v[72:75], v[116:119], v[52:55]
	v_mfma_f32_16x16x32_bf16 v[8:11], v[0:3], v[124:127], v[8:11]
	v_mfma_f32_16x16x32_bf16 v[0:3], v[72:75], v[124:127], v[60:63]
	s_setprio 0
	s_setprio 1
	v_mfma_f32_16x16x32_bf16 v[4:7], v[88:91], v[96:99], v[4:7]
	v_mfma_f32_16x16x32_bf16 v[12:15], v[92:95], v[96:99], v[12:15]
	v_mfma_f32_16x16x32_bf16 v[16:19], v[88:91], v[104:107], v[16:19]
	v_mfma_f32_16x16x32_bf16 v[20:23], v[92:95], v[104:107], v[20:23]
	v_mfma_f32_16x16x32_bf16 v[72:75], v[88:91], v[112:115], v[24:27]
	v_mfma_f32_16x16x32_bf16 v[76:79], v[92:95], v[112:115], v[28:31]
	v_mfma_f32_16x16x32_bf16 v[64:67], v[88:91], v[120:123], v[64:67]
	v_mfma_f32_16x16x32_bf16 v[68:71], v[92:95], v[120:123], v[68:71]
	v_mfma_f32_16x16x32_bf16 v[60:63], v[80:83], v[100:103], v[4:7]
	v_mfma_f32_16x16x32_bf16 v[52:55], v[84:87], v[100:103], v[12:15]
	v_mfma_f32_16x16x32_bf16 v[28:31], v[80:83], v[108:111], v[16:19]
	v_mfma_f32_16x16x32_bf16 v[24:27], v[84:87], v[108:111], v[20:23]
	v_mfma_f32_16x16x32_bf16 v[20:23], v[80:83], v[116:119], v[72:75]
	v_mfma_f32_16x16x32_bf16 v[16:19], v[84:87], v[116:119], v[76:79]
	v_mfma_f32_16x16x32_bf16 v[12:15], v[80:83], v[124:127], v[64:67]
	v_mfma_f32_16x16x32_bf16 v[4:7], v[84:87], v[124:127], v[68:71]
	s_setprio 0
	v_cmp_gt_u32_e32 vcc, s92, v136
	s_barrier
	s_and_saveexec_b64 s[66:67], vcc
	s_cbranch_execz .LBB0_468
	s_barrier

.LBB0_520:
	v_bfe_i32 v5, v179, 27, 1
	v_lshlrev_b32_e32 v169, 4, v179
	v_lshrrev_b32_e32 v5, 22, v5
	v_add_u32_e32 v5, v169, v5
	v_and_b32_e32 v5, 0xfffffc00, v5
	v_sub_u32_e32 v5, v169, v5
	v_lshrrev_b32_e32 v6, 4, v5
	v_bitop3_b32 v5, v6, v5, 32 bitop3:0x6c
	v_ashrrev_i32_e32 v6, 31, v5
	v_lshrrev_b32_e32 v6, 26, v6
	v_ashrrev_i32_e32 v4, 31, v179
	v_add_u32_e32 v6, v5, v6
	s_lshl_b32 s36, s81, 3
	v_lshrrev_b32_e32 v4, 26, v4
	v_ashrrev_i32_e32 v133, 6, v6
	v_and_b32_e32 v6, 0xc0, v6
	s_ff1_i32_b32 s37, s36
	v_and_b32_e32 v2, 15, v0
	v_and_b32_e32 v3, 48, v0
	v_add_u32_e32 v4, v179, v4
	v_sub_u32_e32 v5, v5, v6
	v_and_b32_e32 v6, 32, v0
	v_lshlrev_b32_e32 v10, 2, v0
	v_lshlrev_b32_e32 v0, 6, v0
	s_lshr_b32 s60, s82, s37
	s_add_i32 s36, s36, -1
	s_and_b32 s61, s82, 7
	v_ashrrev_i32_e32 v131, 6, v4
	v_lshlrev_b32_e32 v2, 6, v2
	v_and_b32_e32 v10, 32, v10
	v_and_b32_e32 v0, 0x3c0, v0
	s_and_b32 s36, s82, s36
	v_or_b32_e32 v9, v2, v3
	v_bitop3_b32 v2, v2, v10, v3 bitop3:0x36
	v_bitop3_b32 v3, v0, v10, v3 bitop3:0x36
	s_lshl_b32 s37, s60, 11
	s_lshl_b32 s46, s61, 8
	v_lshlrev_b32_e32 v0, 16, v131
	s_lshr_b32 s78, s36, 3
	s_or_b32 s46, s37, s46
	s_mov_b32 s47, s15
	v_and_b32_e32 v0, 0xfffe0000, v0
	s_lshl_b32 s36, s78, 14
	v_ashrrev_i16_sdwa v5, v167, sext(v5) dst_sel:DWORD dst_unused:UNUSED_PAD src0_sel:DWORD src1_sel:BYTE_0
	s_lshl_b64 s[46:47], s[46:47], 13
	v_lshl_add_u32 v0, v133, 13, v0
	v_bfe_i32 v134, v5, 0, 16
	v_and_or_b32 v0, v4, 64, v0
	s_add_u32 s46, s40, s46
	v_lshl_add_u32 v164, v134, 1, v0
	s_addc_u32 s47, s41, s47
	v_lshlrev_b32_e32 v14, 13, v1
	v_lshl_add_u64 v[0:1], s[46:47], 0, v[164:165]
	s_mul_i32 s46, s14, 0x1800
	s_mul_hi_u32 s37, s14, 0x1800
	s_add_u32 s46, s46, s36
	s_addc_u32 s37, s37, 0
	s_add_u32 s46, s62, s46
	v_bfe_i32 v7, v179, 6, 1
	s_addc_u32 s47, s63, s37
	s_lshl_b64 s[56:57], s[14:15], 12
	v_and_b32_e32 v7, s14, v7
	v_lshrrev_b32_e32 v8, 7, v179
	s_add_u32 s14, s56, s36
	v_add_lshl_u32 v7, v7, v8, 10
	v_lshlrev_b32_e32 v8, 6, v179
	s_addc_u32 s36, s57, 0
	v_and_b32_e32 v5, 0x3f0, v169
	v_and_b32_e32 v8, 0x3000, v8
	v_bitop3_b32 v11, v9, s65, v10 bitop3:0xde
	v_bitop3_b32 v12, v9, s67, v10 bitop3:0xde
	v_bitop3_b32 v13, v9, s68, v10 bitop3:0xde
	v_bitop3_b32 v9, v9, s69, v10 bitop3:0xde
	v_or_b32_e32 v10, 0x800, v14
	v_or_b32_e32 v15, 0x1000, v14
	v_or_b32_e32 v16, 0x1800, v14
	v_lshl_add_u64 v[128:129], v[0:1], 0, s[16:17]
	s_add_u32 s58, s62, s14
	v_mov_b32_e32 v0, 0
	v_bitop3_b32 v164, v5, v7, v6 bitop3:0xde
	s_addc_u32 s59, s63, s36
	s_mov_b32 s14, -2
	v_add_u32_e32 v138, v11, v8
	v_add_u32_e32 v193, v2, v14
	v_add_u32_e32 v192, v3, v10
	v_add_u32_e32 v191, v3, v15
	v_add_u32_e32 v190, v3, v16
	v_add_u32_e32 v137, 0xc000, v169
	v_add_u32_e32 v136, 0xe000, v169
	v_add_u32_e32 v135, v12, v8
	v_add_u32_e32 v189, 0x10000, v169
	v_add_u32_e32 v188, 0x12000, v169
	v_add_u32_e32 v187, 0x2000, v169
	v_add_u32_e32 v186, 0x14000, v169
	v_add_u32_e32 v185, 0x16000, v169
	v_add_u32_e32 v130, v13, v8
	v_add_u32_e32 v184, 0x4000, v169
	v_add_u32_e32 v183, 0x6000, v169
	v_add_u32_e32 v132, v9, v8
	v_add_u32_e32 v182, 0x18000, v169
	v_add_u32_e32 v181, 0x1a000, v169
	v_add_u32_e32 v177, 0x8000, v169
	v_add_u32_e32 v175, 0xa000, v169
	v_add_u32_e32 v173, 0x1c000, v169
	v_add_u32_e32 v171, 0x1e000, v169
	v_mov_b32_e32 v1, v0
	v_mov_b32_e32 v2, v0
	v_mov_b32_e32 v3, v0
	v_mov_b32_e32 v4, v0
	v_mov_b32_e32 v5, v0
	v_mov_b32_e32 v6, v0
	v_mov_b32_e32 v7, v0
	v_mov_b32_e32 v8, v0
	v_mov_b32_e32 v9, v0
	v_mov_b32_e32 v10, v0
	v_mov_b32_e32 v11, v0
	v_mov_b32_e32 v12, v0
	v_mov_b32_e32 v13, v0
	v_mov_b32_e32 v14, v0
	v_mov_b32_e32 v15, v0
	v_mov_b32_e32 v16, v0
	v_mov_b32_e32 v17, v0
	v_mov_b32_e32 v18, v0
	v_mov_b32_e32 v19, v0
	v_mov_b32_e32 v20, v0
	v_mov_b32_e32 v21, v0
	v_mov_b32_e32 v22, v0
	v_mov_b32_e32 v23, v0
	v_mov_b32_e32 v24, v0
	v_mov_b32_e32 v25, v0
	v_mov_b32_e32 v26, v0
	v_mov_b32_e32 v27, v0
	v_mov_b32_e32 v28, v0
	v_mov_b32_e32 v29, v0
	v_mov_b32_e32 v30, v0
	v_mov_b32_e32 v31, v0
	v_mov_b32_e32 v32, v0
	v_mov_b32_e32 v33, v0
	v_mov_b32_e32 v34, v0
	v_mov_b32_e32 v35, v0
	v_mov_b32_e32 v36, v0
	v_mov_b32_e32 v37, v0
	v_mov_b32_e32 v38, v0
	v_mov_b32_e32 v39, v0
	v_mov_b32_e32 v40, v0
	v_mov_b32_e32 v41, v0
	v_mov_b32_e32 v42, v0
	v_mov_b32_e32 v43, v0
	v_mov_b32_e32 v44, v0
	v_mov_b32_e32 v45, v0
	v_mov_b32_e32 v46, v0
	v_mov_b32_e32 v47, v0
	v_mov_b32_e32 v48, v0
	v_mov_b32_e32 v49, v0
	v_mov_b32_e32 v50, v0
	v_mov_b32_e32 v51, v0
	v_mov_b32_e32 v52, v0
	v_mov_b32_e32 v53, v0
	v_mov_b32_e32 v54, v0
	v_mov_b32_e32 v55, v0
	v_mov_b32_e32 v56, v0
	v_mov_b32_e32 v57, v0
	v_mov_b32_e32 v58, v0
	v_mov_b32_e32 v59, v0
	v_mov_b32_e32 v60, v0
	v_mov_b32_e32 v61, v0
	v_mov_b32_e32 v62, v0
	v_mov_b32_e32 v63, v0
	v_mov_b32_e32 v64, v0
	v_mov_b32_e32 v65, v0
	v_mov_b32_e32 v66, v0
	v_mov_b32_e32 v67, v0
	v_mov_b32_e32 v68, v0
	v_mov_b32_e32 v69, v0
	v_mov_b32_e32 v70, v0
	v_mov_b32_e32 v71, v0
	v_mov_b32_e32 v72, v0
	v_mov_b32_e32 v73, v0
	v_mov_b32_e32 v74, v0
	v_mov_b32_e32 v75, v0
	v_mov_b32_e32 v76, v0
	v_mov_b32_e32 v77, v0
	v_mov_b32_e32 v78, v0
	v_mov_b32_e32 v79, v0
	v_mov_b32_e32 v80, v0
	v_mov_b32_e32 v81, v0
	v_mov_b32_e32 v82, v0
	v_mov_b32_e32 v83, v0
	v_mov_b32_e32 v84, v0
	v_mov_b32_e32 v85, v0
	v_mov_b32_e32 v86, v0
	v_mov_b32_e32 v87, v0
	v_mov_b32_e32 v88, v0
	v_mov_b32_e32 v89, v0
	v_mov_b32_e32 v90, v0
	v_mov_b32_e32 v91, v0
	v_mov_b32_e32 v92, v0
	v_mov_b32_e32 v93, v0
	v_mov_b32_e32 v94, v0
	v_mov_b32_e32 v95, v0
	v_mov_b32_e32 v96, v0
	v_mov_b32_e32 v97, v0
	v_mov_b32_e32 v98, v0
	v_mov_b32_e32 v99, v0
	v_mov_b32_e32 v100, v0
	v_mov_b32_e32 v101, v0
	v_mov_b32_e32 v102, v0
	v_mov_b32_e32 v103, v0
	v_mov_b32_e32 v104, v0
	v_mov_b32_e32 v105, v0
	v_mov_b32_e32 v106, v0
	v_mov_b32_e32 v107, v0
	v_mov_b32_e32 v108, v0
	v_mov_b32_e32 v109, v0
	v_mov_b32_e32 v110, v0
	v_mov_b32_e32 v111, v0
	v_mov_b32_e32 v112, v0
	v_mov_b32_e32 v113, v0
	v_mov_b32_e32 v114, v0
	v_mov_b32_e32 v115, v0
	v_mov_b32_e32 v116, v0
	v_mov_b32_e32 v117, v0
	v_mov_b32_e32 v118, v0
	v_mov_b32_e32 v119, v0
	v_mov_b32_e32 v120, v0
	v_mov_b32_e32 v121, v0
	v_mov_b32_e32 v122, v0
	v_mov_b32_e32 v123, v0
	v_mov_b32_e32 v124, v0
	v_mov_b32_e32 v125, v0
	v_mov_b32_e32 v126, v0
	v_mov_b32_e32 v127, v0
	s_barrier
	v_readlane_b32 s98, v242, 1
	s_lshl_b32 s98, s98, 10
	s_add_i32 s36, s98, 0xc000
	v_lshl_add_u64 v[142:143], v[128:129], 0, s[18:19]
	s_mov_b32 m0, s36
	s_add_i32 s36, s98, 0xe000
	global_load_lds_dwordx4 v[142:143], off
	v_lshl_add_u64 v[142:143], v[128:129], 0, s[20:21]
	s_mov_b32 m0, s36
	s_nop 0
	global_load_lds_dwordx4 v[142:143], off
	ds_read_b128 v[140:143], v138
	ds_read_b128 v[144:147], v138 offset:1024
	ds_read_b128 v[148:151], v138 offset:2048
	ds_read_b128 v[152:155], v138 offset:3072
.LBB0_521:
	ds_read_b128 v[156:159], v193
	ds_read_b128 v[160:163], v193 offset:1024
	ds_read_b128 v[194:197], v192
	ds_read_b128 v[198:201], v192 offset:1024
	ds_read_b128 v[202:205], v191
	ds_read_b128 v[206:209], v191 offset:1024
	ds_read_b128 v[210:213], v190
	ds_read_b128 v[214:217], v190 offset:1024
	s_waitcnt lgkmcnt(8)
	s_waitcnt vmcnt(10)
	s_barrier
	s_waitcnt lgkmcnt(0)
	s_waitcnt lgkmcnt(0)
	v_mfma_f32_16x16x32_bf16 v[124:127], v[140:143], v[156:159], v[124:127]
	v_mfma_f32_16x16x32_bf16 v[120:123], v[148:151], v[156:159], v[120:123]
	v_mfma_f32_16x16x32_bf16 v[116:119], v[140:143], v[194:197], v[116:119]
	v_mfma_f32_16x16x32_bf16 v[112:115], v[148:151], v[194:197], v[112:115]
	v_mfma_f32_16x16x32_bf16 v[108:111], v[140:143], v[202:205], v[108:111]
	v_mfma_f32_16x16x32_bf16 v[104:107], v[148:151], v[202:205], v[104:107]
	v_mfma_f32_16x16x32_bf16 v[100:103], v[140:143], v[210:213], v[100:103]
	v_mfma_f32_16x16x32_bf16 v[96:99], v[148:151], v[210:213], v[96:99]
	v_mfma_f32_16x16x32_bf16 v[124:127], v[144:147], v[160:163], v[124:127]
	v_mfma_f32_16x16x32_bf16 v[120:123], v[152:155], v[160:163], v[120:123]
	v_mfma_f32_16x16x32_bf16 v[116:119], v[144:147], v[198:201], v[116:119]
	v_mfma_f32_16x16x32_bf16 v[112:115], v[152:155], v[198:201], v[112:115]
	v_mfma_f32_16x16x32_bf16 v[108:111], v[144:147], v[206:209], v[108:111]
	v_mfma_f32_16x16x32_bf16 v[104:107], v[152:155], v[206:209], v[104:107]
	v_mfma_f32_16x16x32_bf16 v[100:103], v[144:147], v[214:217], v[100:103]
	v_mfma_f32_16x16x32_bf16 v[96:99], v[152:155], v[214:217], v[96:99]
	s_barrier
	s_add_i32 s36, s98, 0x10000
	v_lshl_add_u64 v[234:235], s[58:59], 0, v[164:165]
	s_mov_b32 m0, s36
	s_add_i32 s36, s98, 0x12000
	ds_read_b128 v[218:221], v135
	ds_read_b128 v[222:225], v135 offset:1024
	ds_read_b128 v[226:229], v135 offset:2048
	ds_read_b128 v[230:233], v135 offset:3072
	global_load_lds_dwordx4 v[234:235], off
	v_lshl_add_u64 v[236:237], v[234:235], 0, s[2:3]
	s_mov_b32 m0, s36
	s_nop 0
	global_load_lds_dwordx4 v[236:237], off
	s_mov_b32 s36, s98
	v_lshl_add_u64 v[236:237], v[128:129], 0, s[22:23]
	s_mov_b32 m0, s36
	s_add_i32 s36, s98, 0x2000
	global_load_lds_dwordx4 v[236:237], off
	v_lshl_add_u64 v[236:237], v[128:129], 0, s[24:25]
	s_mov_b32 m0, s36
	s_nop 0
	global_load_lds_dwordx4 v[236:237], off
	s_waitcnt vmcnt(12)
	s_barrier
	s_waitcnt lgkmcnt(0)
	s_waitcnt lgkmcnt(0)
	v_mfma_f32_16x16x32_bf16 v[92:95], v[218:221], v[156:159], v[92:95]
	v_mfma_f32_16x16x32_bf16 v[88:91], v[226:229], v[156:159], v[88:91]
	v_mfma_f32_16x16x32_bf16 v[84:87], v[218:221], v[194:197], v[84:87]
	v_mfma_f32_16x16x32_bf16 v[80:83], v[226:229], v[194:197], v[80:83]
	v_mfma_f32_16x16x32_bf16 v[76:79], v[218:221], v[202:205], v[76:79]
	v_mfma_f32_16x16x32_bf16 v[72:75], v[226:229], v[202:205], v[72:75]
	v_mfma_f32_16x16x32_bf16 v[68:71], v[218:221], v[210:213], v[68:71]
	v_mfma_f32_16x16x32_bf16 v[64:67], v[226:229], v[210:213], v[64:67]
	v_mfma_f32_16x16x32_bf16 v[92:95], v[222:225], v[160:163], v[92:95]
	v_mfma_f32_16x16x32_bf16 v[88:91], v[230:233], v[160:163], v[88:91]
	v_mfma_f32_16x16x32_bf16 v[84:87], v[222:225], v[198:201], v[84:87]
	v_mfma_f32_16x16x32_bf16 v[80:83], v[230:233], v[198:201], v[80:83]
	v_mfma_f32_16x16x32_bf16 v[76:79], v[222:225], v[206:209], v[76:79]
	v_mfma_f32_16x16x32_bf16 v[72:75], v[230:233], v[206:209], v[72:75]
	v_mfma_f32_16x16x32_bf16 v[68:71], v[222:225], v[214:217], v[68:71]
	v_mfma_f32_16x16x32_bf16 v[64:67], v[230:233], v[214:217], v[64:67]
	s_barrier
	ds_read_b128 v[156:159], v193 offset:16384
	ds_read_b128 v[160:163], v193 offset:17408
	ds_read_b128 v[194:197], v192 offset:16384
	ds_read_b128 v[198:201], v192 offset:17408
	ds_read_b128 v[202:205], v191 offset:16384
	ds_read_b128 v[206:209], v191 offset:17408
	ds_read_b128 v[210:213], v190 offset:16384
	ds_read_b128 v[214:217], v190 offset:17408
	s_add_i32 s36, s98, 0x14000
	v_lshl_add_u64 v[236:237], v[234:235], 0, s[6:7]
	s_mov_b32 m0, s36
	s_add_i32 s36, s98, 0x16000
	global_load_lds_dwordx4 v[236:237], off
	v_lshl_add_u64 v[236:237], v[234:235], 0, s[8:9]
	s_mov_b32 m0, s36
	s_nop 0
	global_load_lds_dwordx4 v[236:237], off
	s_waitcnt vmcnt(12)
	s_barrier
	s_waitcnt lgkmcnt(0)
	s_waitcnt lgkmcnt(0)
	v_mfma_f32_16x16x32_bf16 v[60:63], v[140:143], v[156:159], v[60:63]
	v_mfma_f32_16x16x32_bf16 v[56:59], v[148:151], v[156:159], v[56:59]
	v_mfma_f32_16x16x32_bf16 v[52:55], v[140:143], v[194:197], v[52:55]
	v_mfma_f32_16x16x32_bf16 v[48:51], v[148:151], v[194:197], v[48:51]
	v_mfma_f32_16x16x32_bf16 v[44:47], v[140:143], v[202:205], v[44:47]
	v_mfma_f32_16x16x32_bf16 v[40:43], v[148:151], v[202:205], v[40:43]
	v_mfma_f32_16x16x32_bf16 v[36:39], v[140:143], v[210:213], v[36:39]
	v_mfma_f32_16x16x32_bf16 v[32:35], v[148:151], v[210:213], v[32:35]
	v_mfma_f32_16x16x32_bf16 v[60:63], v[144:147], v[160:163], v[60:63]
	v_mfma_f32_16x16x32_bf16 v[56:59], v[152:155], v[160:163], v[56:59]
	v_mfma_f32_16x16x32_bf16 v[52:55], v[144:147], v[198:201], v[52:55]
	v_mfma_f32_16x16x32_bf16 v[48:51], v[152:155], v[198:201], v[48:51]
	v_mfma_f32_16x16x32_bf16 v[44:47], v[144:147], v[206:209], v[44:47]
	v_mfma_f32_16x16x32_bf16 v[40:43], v[152:155], v[206:209], v[40:43]
	v_mfma_f32_16x16x32_bf16 v[36:39], v[144:147], v[214:217], v[36:39]
	v_mfma_f32_16x16x32_bf16 v[32:35], v[152:155], v[214:217], v[32:35]
	s_barrier
	s_add_i32 s36, s98, 0x4000
	v_lshl_add_u64 v[142:143], v[128:129], 0, s[26:27]
	s_mov_b32 m0, s36
	s_add_i32 s36, s98, 0x6000
	global_load_lds_dwordx4 v[142:143], off
	s_mov_b32 m0, s36
	s_nop 0
	global_load_lds_dwordx4 v[128:129], off
	ds_read_b128 v[140:143], v130
	ds_read_b128 v[144:147], v130 offset:1024
	ds_read_b128 v[148:151], v130 offset:2048
	ds_read_b128 v[152:155], v130 offset:3072
	s_waitcnt vmcnt(12)
	s_barrier
	v_mfma_f32_16x16x32_bf16 v[28:31], v[218:221], v[156:159], v[28:31]
	v_mfma_f32_16x16x32_bf16 v[24:27], v[226:229], v[156:159], v[24:27]
	v_mfma_f32_16x16x32_bf16 v[20:23], v[218:221], v[194:197], v[20:23]
	v_mfma_f32_16x16x32_bf16 v[16:19], v[226:229], v[194:197], v[16:19]
	v_mfma_f32_16x16x32_bf16 v[12:15], v[218:221], v[202:205], v[12:15]
	v_mfma_f32_16x16x32_bf16 v[8:11], v[226:229], v[202:205], v[8:11]
	v_mfma_f32_16x16x32_bf16 v[4:7], v[218:221], v[210:213], v[4:7]
	v_mfma_f32_16x16x32_bf16 v[0:3], v[226:229], v[210:213], v[0:3]
	v_mfma_f32_16x16x32_bf16 v[28:31], v[222:225], v[160:163], v[28:31]
	v_mfma_f32_16x16x32_bf16 v[24:27], v[230:233], v[160:163], v[24:27]
	v_mfma_f32_16x16x32_bf16 v[20:23], v[222:225], v[198:201], v[20:23]
	v_mfma_f32_16x16x32_bf16 v[16:19], v[230:233], v[198:201], v[16:19]
	v_mfma_f32_16x16x32_bf16 v[12:15], v[222:225], v[206:209], v[12:15]
	v_mfma_f32_16x16x32_bf16 v[8:11], v[230:233], v[206:209], v[8:11]
	v_mfma_f32_16x16x32_bf16 v[4:7], v[222:225], v[214:217], v[4:7]
	v_mfma_f32_16x16x32_bf16 v[0:3], v[230:233], v[214:217], v[0:3]
	s_barrier
	ds_read_b128 v[156:159], v193 offset:32768
	ds_read_b128 v[160:163], v193 offset:33792
	ds_read_b128 v[194:197], v192 offset:32768
	ds_read_b128 v[198:201], v192 offset:33792
	ds_read_b128 v[202:205], v191 offset:32768
	ds_read_b128 v[206:209], v191 offset:33792
	ds_read_b128 v[210:213], v190 offset:32768
	ds_read_b128 v[214:217], v190 offset:33792
	s_waitcnt lgkmcnt(8)
	s_waitcnt vmcnt(10)
	s_barrier
	s_waitcnt lgkmcnt(0)
	s_waitcnt lgkmcnt(0)
	v_mfma_f32_16x16x32_bf16 v[124:127], v[140:143], v[156:159], v[124:127]
	v_mfma_f32_16x16x32_bf16 v[120:123], v[148:151], v[156:159], v[120:123]
	v_mfma_f32_16x16x32_bf16 v[116:119], v[140:143], v[194:197], v[116:119]
	v_mfma_f32_16x16x32_bf16 v[112:115], v[148:151], v[194:197], v[112:115]
	v_mfma_f32_16x16x32_bf16 v[108:111], v[140:143], v[202:205], v[108:111]
	v_mfma_f32_16x16x32_bf16 v[104:107], v[148:151], v[202:205], v[104:107]
	v_mfma_f32_16x16x32_bf16 v[100:103], v[140:143], v[210:213], v[100:103]
	v_mfma_f32_16x16x32_bf16 v[96:99], v[148:151], v[210:213], v[96:99]
	v_mfma_f32_16x16x32_bf16 v[124:127], v[144:147], v[160:163], v[124:127]
	v_mfma_f32_16x16x32_bf16 v[120:123], v[152:155], v[160:163], v[120:123]
	v_mfma_f32_16x16x32_bf16 v[116:119], v[144:147], v[198:201], v[116:119]
	v_mfma_f32_16x16x32_bf16 v[112:115], v[152:155], v[198:201], v[112:115]
	v_mfma_f32_16x16x32_bf16 v[108:111], v[144:147], v[206:209], v[108:111]
	v_mfma_f32_16x16x32_bf16 v[104:107], v[152:155], v[206:209], v[104:107]
	v_mfma_f32_16x16x32_bf16 v[100:103], v[144:147], v[214:217], v[100:103]
	v_mfma_f32_16x16x32_bf16 v[96:99], v[152:155], v[214:217], v[96:99]
	s_barrier
	s_add_i32 s36, s98, 0x18000
	v_lshl_add_u64 v[234:235], s[46:47], 0, v[164:165]
	s_mov_b32 m0, s36
	s_add_i32 s36, s98, 0x1a000
	ds_read_b128 v[218:221], v132
	ds_read_b128 v[222:225], v132 offset:1024
	ds_read_b128 v[226:229], v132 offset:2048
	ds_read_b128 v[230:233], v132 offset:3072
	global_load_lds_dwordx4 v[234:235], off
	v_lshl_add_u64 v[236:237], v[234:235], 0, s[2:3]
	s_mov_b32 m0, s36
	s_nop 0
	global_load_lds_dwordx4 v[236:237], off
	s_add_i32 s36, s98, 0x8000
	v_lshl_add_u64 v[236:237], v[128:129], 0, s[28:29]
	s_mov_b32 m0, s36
	s_add_i32 s36, s98, 0xa000
	global_load_lds_dwordx4 v[236:237], off
	v_lshl_add_u64 v[236:237], v[128:129], 0, s[30:31]
	s_mov_b32 m0, s36
	s_nop 0
	global_load_lds_dwordx4 v[236:237], off
	s_waitcnt vmcnt(12)
	s_barrier
	s_waitcnt lgkmcnt(0)
	s_waitcnt lgkmcnt(0)
	v_mfma_f32_16x16x32_bf16 v[92:95], v[218:221], v[156:159], v[92:95]
	v_mfma_f32_16x16x32_bf16 v[88:91], v[226:229], v[156:159], v[88:91]
	v_mfma_f32_16x16x32_bf16 v[84:87], v[218:221], v[194:197], v[84:87]
	v_mfma_f32_16x16x32_bf16 v[80:83], v[226:229], v[194:197], v[80:83]
	v_mfma_f32_16x16x32_bf16 v[76:79], v[218:221], v[202:205], v[76:79]
	v_mfma_f32_16x16x32_bf16 v[72:75], v[226:229], v[202:205], v[72:75]
	v_mfma_f32_16x16x32_bf16 v[68:71], v[218:221], v[210:213], v[68:71]
	v_mfma_f32_16x16x32_bf16 v[64:67], v[226:229], v[210:213], v[64:67]
	v_mfma_f32_16x16x32_bf16 v[92:95], v[222:225], v[160:163], v[92:95]
	v_mfma_f32_16x16x32_bf16 v[88:91], v[230:233], v[160:163], v[88:91]
	v_mfma_f32_16x16x32_bf16 v[84:87], v[222:225], v[198:201], v[84:87]
	v_mfma_f32_16x16x32_bf16 v[80:83], v[230:233], v[198:201], v[80:83]
	v_mfma_f32_16x16x32_bf16 v[76:79], v[222:225], v[206:209], v[76:79]
	v_mfma_f32_16x16x32_bf16 v[72:75], v[230:233], v[206:209], v[72:75]
	v_mfma_f32_16x16x32_bf16 v[68:71], v[222:225], v[214:217], v[68:71]
	v_mfma_f32_16x16x32_bf16 v[64:67], v[230:233], v[214:217], v[64:67]
	s_barrier
	ds_read_b128 v[156:159], v193 offset:49152
	ds_read_b128 v[160:163], v193 offset:50176
	ds_read_b128 v[194:197], v192 offset:49152
	ds_read_b128 v[198:201], v192 offset:50176
	ds_read_b128 v[202:205], v191 offset:49152
	ds_read_b128 v[206:209], v191 offset:50176
	ds_read_b128 v[210:213], v190 offset:49152
	ds_read_b128 v[214:217], v190 offset:50176
	s_add_i32 s36, s98, 0x1c000
	v_lshl_add_u64 v[236:237], v[234:235], 0, s[6:7]
	s_mov_b32 m0, s36
	s_add_i32 s36, s98, 0x1e000
	global_load_lds_dwordx4 v[236:237], off
	v_lshl_add_u64 v[236:237], v[234:235], 0, s[8:9]
	s_mov_b32 m0, s36
	s_nop 0
	global_load_lds_dwordx4 v[236:237], off
	s_waitcnt vmcnt(12)
	s_barrier
	s_waitcnt lgkmcnt(0)
	s_waitcnt lgkmcnt(0)
	v_mfma_f32_16x16x32_bf16 v[60:63], v[140:143], v[156:159], v[60:63]
	v_mfma_f32_16x16x32_bf16 v[56:59], v[148:151], v[156:159], v[56:59]
	v_mfma_f32_16x16x32_bf16 v[52:55], v[140:143], v[194:197], v[52:55]
	v_mfma_f32_16x16x32_bf16 v[48:51], v[148:151], v[194:197], v[48:51]
	v_mfma_f32_16x16x32_bf16 v[44:47], v[140:143], v[202:205], v[44:47]
	v_mfma_f32_16x16x32_bf16 v[40:43], v[148:151], v[202:205], v[40:43]
	v_mfma_f32_16x16x32_bf16 v[36:39], v[140:143], v[210:213], v[36:39]
	v_mfma_f32_16x16x32_bf16 v[32:35], v[148:151], v[210:213], v[32:35]
	v_mfma_f32_16x16x32_bf16 v[60:63], v[144:147], v[160:163], v[60:63]
	v_mfma_f32_16x16x32_bf16 v[56:59], v[152:155], v[160:163], v[56:59]
	v_mfma_f32_16x16x32_bf16 v[52:55], v[144:147], v[198:201], v[52:55]
	v_mfma_f32_16x16x32_bf16 v[48:51], v[152:155], v[198:201], v[48:51]
	v_mfma_f32_16x16x32_bf16 v[44:47], v[144:147], v[206:209], v[44:47]
	v_mfma_f32_16x16x32_bf16 v[40:43], v[152:155], v[206:209], v[40:43]
	v_mfma_f32_16x16x32_bf16 v[36:39], v[144:147], v[214:217], v[36:39]
	v_mfma_f32_16x16x32_bf16 v[32:35], v[152:155], v[214:217], v[32:35]
	s_barrier
	v_lshl_add_u64 v[128:129], v[128:129], 0, s[34:35]
	s_add_i32 s36, s98, 0xc000
	v_lshl_add_u64 v[142:143], v[128:129], 0, s[18:19]
	s_mov_b32 m0, s36
	s_add_i32 s36, s98, 0xe000
	global_load_lds_dwordx4 v[142:143], off
	v_lshl_add_u64 v[142:143], v[128:129], 0, s[20:21]
	s_mov_b32 m0, s36
	s_nop 0
	global_load_lds_dwordx4 v[142:143], off
	ds_read_b128 v[140:143], v138
	ds_read_b128 v[144:147], v138 offset:1024
	ds_read_b128 v[148:151], v138 offset:2048
	ds_read_b128 v[152:155], v138 offset:3072
	s_waitcnt vmcnt(12)
	s_barrier
	v_mfma_f32_16x16x32_bf16 v[28:31], v[218:221], v[156:159], v[28:31]
	v_mfma_f32_16x16x32_bf16 v[24:27], v[226:229], v[156:159], v[24:27]
	v_mfma_f32_16x16x32_bf16 v[20:23], v[218:221], v[194:197], v[20:23]
	v_mfma_f32_16x16x32_bf16 v[16:19], v[226:229], v[194:197], v[16:19]
	v_mfma_f32_16x16x32_bf16 v[12:15], v[218:221], v[202:205], v[12:15]
	v_mfma_f32_16x16x32_bf16 v[8:11], v[226:229], v[202:205], v[8:11]
	v_mfma_f32_16x16x32_bf16 v[4:7], v[218:221], v[210:213], v[4:7]
	v_mfma_f32_16x16x32_bf16 v[0:3], v[226:229], v[210:213], v[0:3]
	v_mfma_f32_16x16x32_bf16 v[28:31], v[222:225], v[160:163], v[28:31]
	v_mfma_f32_16x16x32_bf16 v[24:27], v[230:233], v[160:163], v[24:27]
	v_mfma_f32_16x16x32_bf16 v[20:23], v[222:225], v[198:201], v[20:23]
	v_mfma_f32_16x16x32_bf16 v[16:19], v[230:233], v[198:201], v[16:19]
	v_mfma_f32_16x16x32_bf16 v[12:15], v[222:225], v[206:209], v[12:15]
	v_mfma_f32_16x16x32_bf16 v[8:11], v[230:233], v[206:209], v[8:11]
	v_mfma_f32_16x16x32_bf16 v[4:7], v[222:225], v[214:217], v[4:7]
	v_mfma_f32_16x16x32_bf16 v[0:3], v[230:233], v[214:217], v[0:3]
	s_add_i32 s14, s14, 2
	s_add_u32 s46, s46, s56
	s_addc_u32 s47, s47, s57
	s_add_u32 s58, s58, s56
	s_addc_u32 s59, s59, s57
	s_cmp_lt_u32 s14, 28
	s_barrier
	s_cbranch_scc1 .LBB0_521
	s_lshl_b32 s14, s60, 3
	s_or_b32 s80, s61, s14
	s_lshl_b32 s46, s80, 8
	v_lshlrev_b32_e32 v128, 3, v131
	v_lshlrev_b32_e32 v129, 5, v131
	s_or_b32 s14, s46, 0x80
	v_and_b32_e32 v128, 0x7fff0, v128
	v_and_b32_e32 v129, 32, v129
	s_lshl_b64 s[56:57], s[14:15], 13
	v_add_u32_e32 v129, v129, v134
	v_add_lshl_u32 v128, v133, v128, 13
	s_add_u32 s56, s40, s56
	v_lshl_add_u32 v164, v129, 1, v128
	s_addc_u32 s57, s41, s57
	v_lshl_add_u64 v[128:129], s[56:57], 0, v[164:165]
	v_readfirstlane_b32 s14, v137
	ds_read_b128 v[140:143], v138
	ds_read_b128 v[144:147], v138 offset:1024
	ds_read_b128 v[148:151], v138 offset:2048
	ds_read_b128 v[152:155], v138 offset:3072
	ds_read_b128 v[156:159], v193
	ds_read_b128 v[160:163], v193 offset:1024
	ds_read_b128 v[194:197], v192
	ds_read_b128 v[198:201], v192 offset:1024
	ds_read_b128 v[202:205], v191
	ds_read_b128 v[206:209], v191 offset:1024
	ds_read_b128 v[210:213], v190
	ds_read_b128 v[214:217], v190 offset:1024
	v_lshl_add_u64 v[138:139], v[128:129], 0, s[38:39]
	s_mov_b32 m0, s14
	v_readfirstlane_b32 s14, v136
	global_load_lds_dwordx4 v[138:139], off
	v_lshl_add_u64 v[128:129], v[128:129], 0, s[44:45]
	s_mov_b32 m0, s14
	s_mov_b32 s47, s15
	global_load_lds_dwordx4 v[128:129], off
	s_mul_i32 s99, s76, s84
	s_add_i32 s99, s99, s33
	s_cmpk_lt_u32 s99, 0x400
	s_cbranch_scc1 .Lxt12_has
	s_mov_b32 s99, 0
	s_branch .Lxt12_set

.LBB0_560:
	v_and_b32_e32 v2, 15, v0
	s_bfe_u32 s66, s86, 0x30003
	v_and_b32_e32 v3, 48, v0
	v_lshlrev_b32_e32 v134, 4, v135
	v_and_b32_e32 v5, 32, v0
	s_movk_i32 s37, 0x3f0
	v_lshlrev_b32_e32 v2, 6, v2
	v_lshlrev_b32_e32 v9, 2, v0
	s_lshl_b32 s36, s66, 14
	v_bitop3_b32 v155, v134, v5, s37 bitop3:0x6c
	v_and_b32_e32 v6, 64, v135
	s_add_i32 s67, s20, -2
	v_or_b32_e32 v8, v2, v3
	v_and_b32_e32 v9, 32, v9
	s_mov_b32 s37, 0x14000
	v_lshlrev_b32_e32 v0, 6, v0
	v_and_b32_e32 v4, 0x3f0, v134
	v_lshlrev_b32_e32 v156, 13, v6
	v_lshlrev_b32_e32 v7, 3, v135
	v_mul_i32_i24_e32 v6, 0xffffe800, v6
	v_bitop3_b32 v11, v8, s37, v9 bitop3:0xde
	s_mov_b32 s37, 0x1c000
	v_and_b32_e32 v0, 0x3c0, v0
	s_add_u32 s68, s72, s36
	v_and_b32_e32 v157, 0xfffffc00, v7
	v_bitop3_b32 v2, v2, v9, v3 bitop3:0x36
	v_bitop3_b32 v10, v8, s76, v9 bitop3:0xde
	v_bitop3_b32 v12, v8, s77, v9 bitop3:0xde
	v_bitop3_b32 v8, v8, s37, v9 bitop3:0xde
	v_bitop3_b32 v3, v0, v9, v3 bitop3:0x36
	v_bitop3_b32 v0, v6, v4, v5 bitop3:0xf6
	s_addc_u32 s69, s73, 0
	s_lshl_b32 s36, s86, 11
	s_and_b32 s37, s86, 7
	v_add3_u32 v128, v0, v156, v157
	s_and_b32 s36, s36, 0x60000
	s_lshl_b32 s37, s37, 14
	v_lshlrev_b32_e32 v13, 13, v1
	v_lshl_add_u64 v[0:1], s[68:69], 0, v[128:129]
	s_mov_b64 s[68:69], 0xc3000
	s_or_b32 s36, s36, s37
	v_lshl_add_u64 v[130:131], v[0:1], 0, s[68:69]
	v_bitop3_b32 v0, v4, v156, v5 bitop3:0xde
	s_add_u32 s68, s70, s36
	v_add_u32_e32 v128, v0, v157
	s_addc_u32 s69, s71, 0
	v_lshlrev_b32_e32 v7, 6, v135
	v_lshl_add_u64 v[0:1], s[68:69], 0, v[128:129]
	s_mov_b64 s[68:69], 0x301000
	v_and_b32_e32 v7, 0x3000, v7
	v_or_b32_e32 v9, 0x800, v13
	v_or_b32_e32 v14, 0x1000, v13
	v_or_b32_e32 v15, 0x1800, v13
	v_lshl_add_u64 v[132:133], v[0:1], 0, s[68:69]
	v_mov_b32_e32 v0, 0
	s_mov_b32 s68, 0
	v_add_u32_e32 v161, v10, v7
	v_add_u32_e32 v152, v2, v13
	v_add_u32_e32 v151, v3, v9
	v_add_u32_e32 v150, v3, v14
	v_add_u32_e32 v149, v3, v15
	v_add_u32_e32 v160, 0xc000, v134
	v_add_u32_e32 v159, 0xe000, v134
	v_add_u32_e32 v158, v11, v7
	v_add_u32_e32 v148, 0x10000, v134
	v_add_u32_e32 v147, 0x12000, v134
	v_add_u32_e32 v146, 0x2000, v134
	v_add_u32_e32 v145, 0x14000, v134
	v_add_u32_e32 v144, 0x16000, v134
	v_add_u32_e32 v154, v12, v7
	v_add_u32_e32 v143, 0x4000, v134
	v_add_u32_e32 v142, 0x6000, v134
	v_add_u32_e32 v153, v8, v7
	v_add_u32_e32 v141, 0x18000, v134
	v_add_u32_e32 v140, 0x1a000, v134
	v_add_u32_e32 v139, 0x8000, v134
	v_add_u32_e32 v138, 0xa000, v134
	v_add_u32_e32 v137, 0x1c000, v134
	v_add_u32_e32 v136, 0x1e000, v134
	v_mov_b32_e32 v1, v0
	v_mov_b32_e32 v2, v0
	v_mov_b32_e32 v3, v0
	v_mov_b32_e32 v4, v0
	v_mov_b32_e32 v5, v0
	v_mov_b32_e32 v6, v0
	v_mov_b32_e32 v7, v0
	v_mov_b32_e32 v8, v0
	v_mov_b32_e32 v9, v0
	v_mov_b32_e32 v10, v0
	v_mov_b32_e32 v11, v0
	v_mov_b32_e32 v12, v0
	v_mov_b32_e32 v13, v0
	v_mov_b32_e32 v14, v0
	v_mov_b32_e32 v15, v0
	v_mov_b32_e32 v16, v0
	v_mov_b32_e32 v17, v0
	v_mov_b32_e32 v18, v0
	v_mov_b32_e32 v19, v0
	v_mov_b32_e32 v20, v0
	v_mov_b32_e32 v21, v0
	v_mov_b32_e32 v22, v0
	v_mov_b32_e32 v23, v0
	v_mov_b32_e32 v24, v0
	v_mov_b32_e32 v25, v0
	v_mov_b32_e32 v26, v0
	v_mov_b32_e32 v27, v0
	v_mov_b32_e32 v28, v0
	v_mov_b32_e32 v29, v0
	v_mov_b32_e32 v30, v0
	v_mov_b32_e32 v31, v0
	v_mov_b32_e32 v32, v0
	v_mov_b32_e32 v33, v0
	v_mov_b32_e32 v34, v0
	v_mov_b32_e32 v35, v0
	v_mov_b32_e32 v36, v0
	v_mov_b32_e32 v37, v0
	v_mov_b32_e32 v38, v0
	v_mov_b32_e32 v39, v0
	v_mov_b32_e32 v40, v0
	v_mov_b32_e32 v41, v0
	v_mov_b32_e32 v42, v0
	v_mov_b32_e32 v43, v0
	v_mov_b32_e32 v44, v0
	v_mov_b32_e32 v45, v0
	v_mov_b32_e32 v46, v0
	v_mov_b32_e32 v47, v0
	v_mov_b32_e32 v48, v0
	v_mov_b32_e32 v49, v0
	v_mov_b32_e32 v50, v0
	v_mov_b32_e32 v51, v0
	v_mov_b32_e32 v52, v0
	v_mov_b32_e32 v53, v0
	v_mov_b32_e32 v54, v0
	v_mov_b32_e32 v55, v0
	v_mov_b32_e32 v56, v0
	v_mov_b32_e32 v57, v0
	v_mov_b32_e32 v58, v0
	v_mov_b32_e32 v59, v0
	v_mov_b32_e32 v60, v0
	v_mov_b32_e32 v61, v0
	v_mov_b32_e32 v62, v0
	v_mov_b32_e32 v63, v0
	v_mov_b32_e32 v64, v0
	v_mov_b32_e32 v65, v0
	v_mov_b32_e32 v66, v0
	v_mov_b32_e32 v67, v0
	v_mov_b32_e32 v68, v0
	v_mov_b32_e32 v69, v0
	v_mov_b32_e32 v70, v0
	v_mov_b32_e32 v71, v0
	v_mov_b32_e32 v72, v0
	v_mov_b32_e32 v73, v0
	v_mov_b32_e32 v74, v0
	v_mov_b32_e32 v75, v0
	v_mov_b32_e32 v76, v0
	v_mov_b32_e32 v77, v0
	v_mov_b32_e32 v78, v0
	v_mov_b32_e32 v79, v0
	v_mov_b32_e32 v80, v0
	v_mov_b32_e32 v81, v0
	v_mov_b32_e32 v82, v0
	v_mov_b32_e32 v83, v0
	v_mov_b32_e32 v84, v0
	v_mov_b32_e32 v85, v0
	v_mov_b32_e32 v86, v0
	v_mov_b32_e32 v87, v0
	v_mov_b32_e32 v88, v0
	v_mov_b32_e32 v89, v0
	v_mov_b32_e32 v90, v0
	v_mov_b32_e32 v91, v0
	v_mov_b32_e32 v92, v0
	v_mov_b32_e32 v93, v0
	v_mov_b32_e32 v94, v0
	v_mov_b32_e32 v95, v0
	v_mov_b32_e32 v96, v0
	v_mov_b32_e32 v97, v0
	v_mov_b32_e32 v98, v0
	v_mov_b32_e32 v99, v0
	v_mov_b32_e32 v100, v0
	v_mov_b32_e32 v101, v0
	v_mov_b32_e32 v102, v0
	v_mov_b32_e32 v103, v0
	v_mov_b32_e32 v104, v0
	v_mov_b32_e32 v105, v0
	v_mov_b32_e32 v106, v0
	v_mov_b32_e32 v107, v0
	v_mov_b32_e32 v108, v0
	v_mov_b32_e32 v109, v0
	v_mov_b32_e32 v110, v0
	v_mov_b32_e32 v111, v0
	v_mov_b32_e32 v112, v0
	v_mov_b32_e32 v113, v0
	v_mov_b32_e32 v114, v0
	v_mov_b32_e32 v115, v0
	v_mov_b32_e32 v116, v0
	v_mov_b32_e32 v117, v0
	v_mov_b32_e32 v118, v0
	v_mov_b32_e32 v119, v0
	v_mov_b32_e32 v120, v0
	v_mov_b32_e32 v121, v0
	v_mov_b32_e32 v122, v0
	v_mov_b32_e32 v123, v0
	v_mov_b32_e32 v124, v0
	v_mov_b32_e32 v125, v0
	v_mov_b32_e32 v126, v0
	v_mov_b32_e32 v127, v0
	s_barrier
	v_readlane_b32 s98, v242, 1
	s_lshl_b32 s98, s98, 10
	s_add_i32 s36, s98, 0xc000
	v_lshl_add_u64 v[164:165], v[132:133], 0, s[22:23]
	s_mov_b32 m0, s36
	s_add_i32 s36, s98, 0xe000
	global_load_lds_dwordx4 v[164:165], off
	v_lshl_add_u64 v[164:165], v[132:133], 0, s[24:25]
	s_mov_b32 m0, s36
	s_nop 0
	global_load_lds_dwordx4 v[164:165], off
	ds_read_b128 v[162:165], v161
	ds_read_b128 v[166:169], v161 offset:1024
	ds_read_b128 v[170:173], v161 offset:2048
	ds_read_b128 v[174:177], v161 offset:3072
.LBB0_561:
	ds_read_b128 v[178:181], v152
	ds_read_b128 v[182:185], v152 offset:1024
	ds_read_b128 v[186:189], v151
	ds_read_b128 v[190:193], v151 offset:1024
	ds_read_b128 v[194:197], v150
	ds_read_b128 v[198:201], v150 offset:1024
	ds_read_b128 v[202:205], v149
	ds_read_b128 v[206:209], v149 offset:1024
	s_waitcnt lgkmcnt(8)
	s_waitcnt vmcnt(10)
	s_barrier
	s_waitcnt lgkmcnt(0)
	s_waitcnt lgkmcnt(0)
	v_mfma_f32_16x16x32_bf16 v[124:127], v[162:165], v[178:181], v[124:127]
	v_mfma_f32_16x16x32_bf16 v[120:123], v[170:173], v[178:181], v[120:123]
	v_mfma_f32_16x16x32_bf16 v[116:119], v[162:165], v[186:189], v[116:119]
	v_mfma_f32_16x16x32_bf16 v[112:115], v[170:173], v[186:189], v[112:115]
	v_mfma_f32_16x16x32_bf16 v[108:111], v[162:165], v[194:197], v[108:111]
	v_mfma_f32_16x16x32_bf16 v[104:107], v[170:173], v[194:197], v[104:107]
	v_mfma_f32_16x16x32_bf16 v[100:103], v[162:165], v[202:205], v[100:103]
	v_mfma_f32_16x16x32_bf16 v[96:99], v[170:173], v[202:205], v[96:99]
	v_mfma_f32_16x16x32_bf16 v[124:127], v[166:169], v[182:185], v[124:127]
	v_mfma_f32_16x16x32_bf16 v[120:123], v[174:177], v[182:185], v[120:123]
	v_mfma_f32_16x16x32_bf16 v[116:119], v[166:169], v[190:193], v[116:119]
	v_mfma_f32_16x16x32_bf16 v[112:115], v[174:177], v[190:193], v[112:115]
	v_mfma_f32_16x16x32_bf16 v[108:111], v[166:169], v[198:201], v[108:111]
	v_mfma_f32_16x16x32_bf16 v[104:107], v[174:177], v[198:201], v[104:107]
	v_mfma_f32_16x16x32_bf16 v[100:103], v[166:169], v[206:209], v[100:103]
	v_mfma_f32_16x16x32_bf16 v[96:99], v[174:177], v[206:209], v[96:99]
	s_barrier
	s_add_i32 s36, s98, 0x10000
	v_lshl_add_u64 v[226:227], v[130:131], 0, s[26:27]
	s_mov_b32 m0, s36
	s_add_i32 s36, s98, 0x12000
	ds_read_b128 v[210:213], v158
	ds_read_b128 v[214:217], v158 offset:1024
	ds_read_b128 v[218:221], v158 offset:2048
	ds_read_b128 v[222:225], v158 offset:3072
	global_load_lds_dwordx4 v[226:227], off
	v_lshl_add_u64 v[226:227], v[130:131], 0, s[28:29]
	s_mov_b32 m0, s36
	s_add_i32 s68, s68, 2
	global_load_lds_dwordx4 v[226:227], off
	s_mov_b32 s36, s98
	v_lshl_add_u64 v[226:227], v[132:133], 0, s[30:31]
	s_mov_b32 m0, s36
	s_add_i32 s36, s98, 0x2000
	global_load_lds_dwordx4 v[226:227], off
	v_lshl_add_u64 v[226:227], v[132:133], 0, s[34:35]
	s_mov_b32 m0, s36
	s_nop 0
	global_load_lds_dwordx4 v[226:227], off
	s_waitcnt vmcnt(12)
	s_barrier
	s_waitcnt lgkmcnt(0)
	s_waitcnt lgkmcnt(0)
	v_mfma_f32_16x16x32_bf16 v[92:95], v[210:213], v[178:181], v[92:95]
	v_mfma_f32_16x16x32_bf16 v[88:91], v[218:221], v[178:181], v[88:91]
	v_mfma_f32_16x16x32_bf16 v[84:87], v[210:213], v[186:189], v[84:87]
	v_mfma_f32_16x16x32_bf16 v[80:83], v[218:221], v[186:189], v[80:83]
	v_mfma_f32_16x16x32_bf16 v[76:79], v[210:213], v[194:197], v[76:79]
	v_mfma_f32_16x16x32_bf16 v[72:75], v[218:221], v[194:197], v[72:75]
	v_mfma_f32_16x16x32_bf16 v[68:71], v[210:213], v[202:205], v[68:71]
	v_mfma_f32_16x16x32_bf16 v[64:67], v[218:221], v[202:205], v[64:67]
	v_mfma_f32_16x16x32_bf16 v[92:95], v[214:217], v[182:185], v[92:95]
	v_mfma_f32_16x16x32_bf16 v[88:91], v[222:225], v[182:185], v[88:91]
	v_mfma_f32_16x16x32_bf16 v[84:87], v[214:217], v[190:193], v[84:87]
	v_mfma_f32_16x16x32_bf16 v[80:83], v[222:225], v[190:193], v[80:83]
	v_mfma_f32_16x16x32_bf16 v[76:79], v[214:217], v[198:201], v[76:79]
	v_mfma_f32_16x16x32_bf16 v[72:75], v[222:225], v[198:201], v[72:75]
	v_mfma_f32_16x16x32_bf16 v[68:71], v[214:217], v[206:209], v[68:71]
	v_mfma_f32_16x16x32_bf16 v[64:67], v[222:225], v[206:209], v[64:67]
	s_barrier
	ds_read_b128 v[178:181], v152 offset:16384
	ds_read_b128 v[182:185], v152 offset:17408
	ds_read_b128 v[186:189], v151 offset:16384
	ds_read_b128 v[190:193], v151 offset:17408
	ds_read_b128 v[194:197], v150 offset:16384
	ds_read_b128 v[198:201], v150 offset:17408
	ds_read_b128 v[202:205], v149 offset:16384
	ds_read_b128 v[206:209], v149 offset:17408
	s_add_i32 s36, s98, 0x14000
	v_lshl_add_u64 v[226:227], v[130:131], 0, s[38:39]
	s_mov_b32 m0, s36
	s_add_i32 s36, s98, 0x16000
	global_load_lds_dwordx4 v[226:227], off
	v_lshl_add_u64 v[226:227], v[130:131], 0, s[44:45]
	s_mov_b32 m0, s36
	s_nop 0
	global_load_lds_dwordx4 v[226:227], off
	s_waitcnt vmcnt(12)
	s_barrier
	s_waitcnt lgkmcnt(0)
	s_waitcnt lgkmcnt(0)
	v_mfma_f32_16x16x32_bf16 v[60:63], v[162:165], v[178:181], v[60:63]
	v_mfma_f32_16x16x32_bf16 v[56:59], v[170:173], v[178:181], v[56:59]
	v_mfma_f32_16x16x32_bf16 v[52:55], v[162:165], v[186:189], v[52:55]
	v_mfma_f32_16x16x32_bf16 v[48:51], v[170:173], v[186:189], v[48:51]
	v_mfma_f32_16x16x32_bf16 v[44:47], v[162:165], v[194:197], v[44:47]
	v_mfma_f32_16x16x32_bf16 v[40:43], v[170:173], v[194:197], v[40:43]
	v_mfma_f32_16x16x32_bf16 v[36:39], v[162:165], v[202:205], v[36:39]
	v_mfma_f32_16x16x32_bf16 v[32:35], v[170:173], v[202:205], v[32:35]
	v_mfma_f32_16x16x32_bf16 v[60:63], v[166:169], v[182:185], v[60:63]
	v_mfma_f32_16x16x32_bf16 v[56:59], v[174:177], v[182:185], v[56:59]
	v_mfma_f32_16x16x32_bf16 v[52:55], v[166:169], v[190:193], v[52:55]
	v_mfma_f32_16x16x32_bf16 v[48:51], v[174:177], v[190:193], v[48:51]
	v_mfma_f32_16x16x32_bf16 v[44:47], v[166:169], v[198:201], v[44:47]
	v_mfma_f32_16x16x32_bf16 v[40:43], v[174:177], v[198:201], v[40:43]
	v_mfma_f32_16x16x32_bf16 v[36:39], v[166:169], v[206:209], v[36:39]
	v_mfma_f32_16x16x32_bf16 v[32:35], v[174:177], v[206:209], v[32:35]
	s_barrier
	s_add_i32 s36, s98, 0x4000
	v_lshl_add_u64 v[164:165], v[132:133], 0, s[46:47]
	s_mov_b32 m0, s36
	s_add_i32 s36, s98, 0x6000
	global_load_lds_dwordx4 v[164:165], off
	v_lshl_add_u64 v[164:165], v[132:133], 0, s[50:51]
	s_mov_b32 m0, s36
	s_nop 0
	global_load_lds_dwordx4 v[164:165], off
	ds_read_b128 v[162:165], v154
	ds_read_b128 v[166:169], v154 offset:1024
	ds_read_b128 v[170:173], v154 offset:2048
	ds_read_b128 v[174:177], v154 offset:3072
	s_waitcnt vmcnt(12)
	s_barrier
	v_mfma_f32_16x16x32_bf16 v[28:31], v[210:213], v[178:181], v[28:31]
	v_mfma_f32_16x16x32_bf16 v[24:27], v[218:221], v[178:181], v[24:27]
	v_mfma_f32_16x16x32_bf16 v[20:23], v[210:213], v[186:189], v[20:23]
	v_mfma_f32_16x16x32_bf16 v[16:19], v[218:221], v[186:189], v[16:19]
	v_mfma_f32_16x16x32_bf16 v[12:15], v[210:213], v[194:197], v[12:15]
	v_mfma_f32_16x16x32_bf16 v[8:11], v[218:221], v[194:197], v[8:11]
	v_mfma_f32_16x16x32_bf16 v[4:7], v[210:213], v[202:205], v[4:7]
	v_mfma_f32_16x16x32_bf16 v[0:3], v[218:221], v[202:205], v[0:3]
	v_mfma_f32_16x16x32_bf16 v[28:31], v[214:217], v[182:185], v[28:31]
	v_mfma_f32_16x16x32_bf16 v[24:27], v[222:225], v[182:185], v[24:27]
	v_mfma_f32_16x16x32_bf16 v[20:23], v[214:217], v[190:193], v[20:23]
	v_mfma_f32_16x16x32_bf16 v[16:19], v[222:225], v[190:193], v[16:19]
	v_mfma_f32_16x16x32_bf16 v[12:15], v[214:217], v[198:201], v[12:15]
	v_mfma_f32_16x16x32_bf16 v[8:11], v[222:225], v[198:201], v[8:11]
	v_mfma_f32_16x16x32_bf16 v[4:7], v[214:217], v[206:209], v[4:7]
	v_mfma_f32_16x16x32_bf16 v[0:3], v[222:225], v[206:209], v[0:3]
	s_barrier
	ds_read_b128 v[178:181], v152 offset:32768
	ds_read_b128 v[182:185], v152 offset:33792
	ds_read_b128 v[186:189], v151 offset:32768
	ds_read_b128 v[190:193], v151 offset:33792
	ds_read_b128 v[194:197], v150 offset:32768
	ds_read_b128 v[198:201], v150 offset:33792
	ds_read_b128 v[202:205], v149 offset:32768
	ds_read_b128 v[206:209], v149 offset:33792
	s_waitcnt lgkmcnt(8)
	s_waitcnt vmcnt(10)
	s_barrier
	s_waitcnt lgkmcnt(0)
	s_waitcnt lgkmcnt(0)
	v_mfma_f32_16x16x32_bf16 v[124:127], v[162:165], v[178:181], v[124:127]
	v_mfma_f32_16x16x32_bf16 v[120:123], v[170:173], v[178:181], v[120:123]
	v_mfma_f32_16x16x32_bf16 v[116:119], v[162:165], v[186:189], v[116:119]
	v_mfma_f32_16x16x32_bf16 v[112:115], v[170:173], v[186:189], v[112:115]
	v_mfma_f32_16x16x32_bf16 v[108:111], v[162:165], v[194:197], v[108:111]
	v_mfma_f32_16x16x32_bf16 v[104:107], v[170:173], v[194:197], v[104:107]
	v_mfma_f32_16x16x32_bf16 v[100:103], v[162:165], v[202:205], v[100:103]
	v_mfma_f32_16x16x32_bf16 v[96:99], v[170:173], v[202:205], v[96:99]
	v_mfma_f32_16x16x32_bf16 v[124:127], v[166:169], v[182:185], v[124:127]
	v_mfma_f32_16x16x32_bf16 v[120:123], v[174:177], v[182:185], v[120:123]
	v_mfma_f32_16x16x32_bf16 v[116:119], v[166:169], v[190:193], v[116:119]
	v_mfma_f32_16x16x32_bf16 v[112:115], v[174:177], v[190:193], v[112:115]
	v_mfma_f32_16x16x32_bf16 v[108:111], v[166:169], v[198:201], v[108:111]
	v_mfma_f32_16x16x32_bf16 v[104:107], v[174:177], v[198:201], v[104:107]
	v_mfma_f32_16x16x32_bf16 v[100:103], v[166:169], v[206:209], v[100:103]
	v_mfma_f32_16x16x32_bf16 v[96:99], v[174:177], v[206:209], v[96:99]
	s_barrier
	s_add_i32 s36, s98, 0x18000
	v_lshl_add_u64 v[226:227], v[130:131], 0, s[56:57]
	s_mov_b32 m0, s36
	s_add_i32 s36, s98, 0x1a000
	ds_read_b128 v[210:213], v153
	ds_read_b128 v[214:217], v153 offset:1024
	ds_read_b128 v[218:221], v153 offset:2048
	ds_read_b128 v[222:225], v153 offset:3072
	global_load_lds_dwordx4 v[226:227], off
	v_lshl_add_u64 v[226:227], v[130:131], 0, s[58:59]
	s_mov_b32 m0, s36
	s_nop 0
	global_load_lds_dwordx4 v[226:227], off
	s_add_i32 s36, s98, 0x8000
	v_lshl_add_u64 v[226:227], v[132:133], 0, s[60:61]
	s_mov_b32 m0, s36
	s_add_i32 s36, s98, 0xa000
	global_load_lds_dwordx4 v[226:227], off
	s_mov_b32 m0, s36
	s_nop 0
	global_load_lds_dwordx4 v[132:133], off
	s_waitcnt vmcnt(12)
	s_barrier
	s_waitcnt lgkmcnt(0)
	s_waitcnt lgkmcnt(0)
	v_mfma_f32_16x16x32_bf16 v[92:95], v[210:213], v[178:181], v[92:95]
	v_mfma_f32_16x16x32_bf16 v[88:91], v[218:221], v[178:181], v[88:91]
	v_mfma_f32_16x16x32_bf16 v[84:87], v[210:213], v[186:189], v[84:87]
	v_mfma_f32_16x16x32_bf16 v[80:83], v[218:221], v[186:189], v[80:83]
	v_mfma_f32_16x16x32_bf16 v[76:79], v[210:213], v[194:197], v[76:79]
	v_mfma_f32_16x16x32_bf16 v[72:75], v[218:221], v[194:197], v[72:75]
	v_mfma_f32_16x16x32_bf16 v[68:71], v[210:213], v[202:205], v[68:71]
	v_mfma_f32_16x16x32_bf16 v[64:67], v[218:221], v[202:205], v[64:67]
	v_mfma_f32_16x16x32_bf16 v[92:95], v[214:217], v[182:185], v[92:95]
	v_mfma_f32_16x16x32_bf16 v[88:91], v[222:225], v[182:185], v[88:91]
	v_mfma_f32_16x16x32_bf16 v[84:87], v[214:217], v[190:193], v[84:87]
	v_mfma_f32_16x16x32_bf16 v[80:83], v[222:225], v[190:193], v[80:83]
	v_mfma_f32_16x16x32_bf16 v[76:79], v[214:217], v[198:201], v[76:79]
	v_mfma_f32_16x16x32_bf16 v[72:75], v[222:225], v[198:201], v[72:75]
	v_mfma_f32_16x16x32_bf16 v[68:71], v[214:217], v[206:209], v[68:71]
	v_mfma_f32_16x16x32_bf16 v[64:67], v[222:225], v[206:209], v[64:67]
	s_barrier
	ds_read_b128 v[178:181], v152 offset:49152
	ds_read_b128 v[182:185], v152 offset:50176
	ds_read_b128 v[186:189], v151 offset:49152
	ds_read_b128 v[190:193], v151 offset:50176
	ds_read_b128 v[194:197], v150 offset:49152
	ds_read_b128 v[198:201], v150 offset:50176
	ds_read_b128 v[202:205], v149 offset:49152
	ds_read_b128 v[206:209], v149 offset:50176
	s_add_i32 s36, s98, 0x1c000
	v_lshl_add_u64 v[226:227], v[130:131], 0, s[60:61]
	s_mov_b32 m0, s36
	s_add_i32 s36, s98, 0x1e000
	global_load_lds_dwordx4 v[226:227], off
	s_mov_b32 m0, s36
	s_nop 0
	global_load_lds_dwordx4 v[130:131], off
	s_waitcnt vmcnt(12)
	s_barrier
	s_waitcnt lgkmcnt(0)
	s_waitcnt lgkmcnt(0)
	v_mfma_f32_16x16x32_bf16 v[60:63], v[162:165], v[178:181], v[60:63]
	v_mfma_f32_16x16x32_bf16 v[56:59], v[170:173], v[178:181], v[56:59]
	v_mfma_f32_16x16x32_bf16 v[52:55], v[162:165], v[186:189], v[52:55]
	v_mfma_f32_16x16x32_bf16 v[48:51], v[170:173], v[186:189], v[48:51]
	v_mfma_f32_16x16x32_bf16 v[44:47], v[162:165], v[194:197], v[44:47]
	v_mfma_f32_16x16x32_bf16 v[40:43], v[170:173], v[194:197], v[40:43]
	v_mfma_f32_16x16x32_bf16 v[36:39], v[162:165], v[202:205], v[36:39]
	v_mfma_f32_16x16x32_bf16 v[32:35], v[170:173], v[202:205], v[32:35]
	v_mfma_f32_16x16x32_bf16 v[60:63], v[166:169], v[182:185], v[60:63]
	v_mfma_f32_16x16x32_bf16 v[56:59], v[174:177], v[182:185], v[56:59]
	v_mfma_f32_16x16x32_bf16 v[52:55], v[166:169], v[190:193], v[52:55]
	v_mfma_f32_16x16x32_bf16 v[48:51], v[174:177], v[190:193], v[48:51]
	v_mfma_f32_16x16x32_bf16 v[44:47], v[166:169], v[198:201], v[44:47]
	v_mfma_f32_16x16x32_bf16 v[40:43], v[174:177], v[198:201], v[40:43]
	v_mfma_f32_16x16x32_bf16 v[36:39], v[166:169], v[206:209], v[36:39]
	v_mfma_f32_16x16x32_bf16 v[32:35], v[174:177], v[206:209], v[32:35]
	s_barrier
	v_lshl_add_u64 v[132:133], v[132:133], 0, s[64:65]
	s_add_i32 s36, s98, 0xc000
	v_lshl_add_u64 v[164:165], v[132:133], 0, s[22:23]
	s_mov_b32 m0, s36
	s_add_i32 s36, s98, 0xe000
	global_load_lds_dwordx4 v[164:165], off
	v_lshl_add_u64 v[164:165], v[132:133], 0, s[24:25]
	s_mov_b32 m0, s36
	s_nop 0
	global_load_lds_dwordx4 v[164:165], off
	ds_read_b128 v[162:165], v161
	ds_read_b128 v[166:169], v161 offset:1024
	ds_read_b128 v[170:173], v161 offset:2048
	ds_read_b128 v[174:177], v161 offset:3072
	s_waitcnt vmcnt(12)
	s_barrier
	v_mfma_f32_16x16x32_bf16 v[28:31], v[210:213], v[178:181], v[28:31]
	v_mfma_f32_16x16x32_bf16 v[24:27], v[218:221], v[178:181], v[24:27]
	v_mfma_f32_16x16x32_bf16 v[20:23], v[210:213], v[186:189], v[20:23]
	v_mfma_f32_16x16x32_bf16 v[16:19], v[218:221], v[186:189], v[16:19]
	v_mfma_f32_16x16x32_bf16 v[12:15], v[210:213], v[194:197], v[12:15]
	v_mfma_f32_16x16x32_bf16 v[8:11], v[218:221], v[194:197], v[8:11]
	v_mfma_f32_16x16x32_bf16 v[4:7], v[210:213], v[202:205], v[4:7]
	v_mfma_f32_16x16x32_bf16 v[0:3], v[218:221], v[202:205], v[0:3]
	v_mfma_f32_16x16x32_bf16 v[28:31], v[214:217], v[182:185], v[28:31]
	v_mfma_f32_16x16x32_bf16 v[24:27], v[222:225], v[182:185], v[24:27]
	v_mfma_f32_16x16x32_bf16 v[20:23], v[214:217], v[190:193], v[20:23]
	v_mfma_f32_16x16x32_bf16 v[16:19], v[222:225], v[190:193], v[16:19]
	v_mfma_f32_16x16x32_bf16 v[12:15], v[214:217], v[198:201], v[12:15]
	v_mfma_f32_16x16x32_bf16 v[8:11], v[222:225], v[198:201], v[8:11]
	v_mfma_f32_16x16x32_bf16 v[4:7], v[214:217], v[206:209], v[4:7]
	v_mfma_f32_16x16x32_bf16 v[0:3], v[222:225], v[206:209], v[0:3]
	v_lshl_add_u64 v[130:131], v[130:131], 0, s[62:63]
	s_cmp_lt_u32 s68, s67
	s_barrier
	s_cbranch_scc1 .LBB0_561
	s_lshl_b32 s36, s86, 5
	s_lshl_b32 s37, s86, 8
	s_and_b32 s36, s36, 0x1800
	s_and_b32 s37, s37, 0x700
	s_or_b32 s96, s37, s36
	s_lshl_b32 s36, s96, 6
	s_add_u32 s36, s70, s36
	s_addc_u32 s37, s71, 0
	s_add_i32 s20, s20, -1
	s_lshl_b64 s[68:69], s[20:21], 20
	v_add_u32_e32 v128, v156, v157
	s_add_u32 s68, s36, s68
	v_or_b32_e32 v128, v128, v155
	s_addc_u32 s69, s37, s69
	v_lshl_add_u64 v[156:157], s[68:69], 0, v[128:129]
	v_readfirstlane_b32 s20, v160
	v_lshl_add_u64 v[206:207], v[156:157], 0, s[4:5]
	s_mov_b32 m0, s20
	v_readfirstlane_b32 s20, v159
	ds_read_b128 v[130:133], v161
	ds_read_b128 v[162:165], v161 offset:1024
	ds_read_b128 v[166:169], v161 offset:2048
	ds_read_b128 v[170:173], v161 offset:3072
	ds_read_b128 v[174:177], v152
	ds_read_b128 v[178:181], v152 offset:1024
	ds_read_b128 v[182:185], v151
	ds_read_b128 v[186:189], v151 offset:1024
	ds_read_b128 v[190:193], v150
	ds_read_b128 v[194:197], v150 offset:1024
	ds_read_b128 v[198:201], v149
	ds_read_b128 v[202:205], v149 offset:1024
	global_load_lds_dwordx4 v[206:207], off
	v_lshl_add_u64 v[156:157], v[156:157], 0, s[6:7]
	s_mov_b32 m0, s20
	s_nop 0
	global_load_lds_dwordx4 v[156:157], off
	s_waitcnt vmcnt(10)
	s_barrier
	s_waitcnt lgkmcnt(0)
	s_setprio 1
	s_waitcnt lgkmcnt(0)
	v_mfma_f32_16x16x32_bf16 v[124:127], v[130:133], v[174:177], v[124:127]
	v_mfma_f32_16x16x32_bf16 v[120:123], v[166:169], v[174:177], v[120:123]
	v_mfma_f32_16x16x32_bf16 v[116:119], v[130:133], v[182:185], v[116:119]
	v_mfma_f32_16x16x32_bf16 v[112:115], v[166:169], v[182:185], v[112:115]
	v_mfma_f32_16x16x32_bf16 v[108:111], v[130:133], v[190:193], v[108:111]
	v_mfma_f32_16x16x32_bf16 v[104:107], v[166:169], v[190:193], v[104:107]
	v_mfma_f32_16x16x32_bf16 v[100:103], v[130:133], v[198:201], v[100:103]
	v_mfma_f32_16x16x32_bf16 v[96:99], v[166:169], v[198:201], v[96:99]
	v_mfma_f32_16x16x32_bf16 v[124:127], v[162:165], v[178:181], v[124:127]
	v_mfma_f32_16x16x32_bf16 v[120:123], v[170:173], v[178:181], v[120:123]
	v_mfma_f32_16x16x32_bf16 v[116:119], v[162:165], v[186:189], v[116:119]
	v_mfma_f32_16x16x32_bf16 v[112:115], v[170:173], v[186:189], v[112:115]
	v_mfma_f32_16x16x32_bf16 v[108:111], v[162:165], v[194:197], v[108:111]
	v_mfma_f32_16x16x32_bf16 v[104:107], v[170:173], v[194:197], v[104:107]
	v_mfma_f32_16x16x32_bf16 v[100:103], v[162:165], v[202:205], v[100:103]
	v_mfma_f32_16x16x32_bf16 v[96:99], v[170:173], v[202:205], v[96:99]
	s_setprio 0
	s_barrier
	ds_read_b128 v[206:209], v158
	ds_read_b128 v[210:213], v158 offset:1024
	ds_read_b128 v[214:217], v158 offset:2048
	ds_read_b128 v[156:159], v158 offset:3072
	s_barrier
	s_waitcnt lgkmcnt(0)
	s_setprio 1
	s_waitcnt lgkmcnt(0)
	v_mfma_f32_16x16x32_bf16 v[92:95], v[206:209], v[174:177], v[92:95]
	v_mfma_f32_16x16x32_bf16 v[88:91], v[214:217], v[174:177], v[88:91]
	v_mfma_f32_16x16x32_bf16 v[84:87], v[206:209], v[182:185], v[84:87]
	v_mfma_f32_16x16x32_bf16 v[80:83], v[214:217], v[182:185], v[80:83]
	v_mfma_f32_16x16x32_bf16 v[76:79], v[206:209], v[190:193], v[76:79]
	v_mfma_f32_16x16x32_bf16 v[72:75], v[214:217], v[190:193], v[72:75]
	v_mfma_f32_16x16x32_bf16 v[68:71], v[206:209], v[198:201], v[68:71]
	v_mfma_f32_16x16x32_bf16 v[64:67], v[214:217], v[198:201], v[64:67]
	v_mfma_f32_16x16x32_bf16 v[174:177], v[210:213], v[178:181], v[92:95]
	v_mfma_f32_16x16x32_bf16 v[178:181], v[156:159], v[178:181], v[88:91]
	v_mfma_f32_16x16x32_bf16 v[182:185], v[210:213], v[186:189], v[84:87]
	v_mfma_f32_16x16x32_bf16 v[186:189], v[156:159], v[186:189], v[80:83]
	v_mfma_f32_16x16x32_bf16 v[190:193], v[210:213], v[194:197], v[76:79]
	v_mfma_f32_16x16x32_bf16 v[194:197], v[156:159], v[194:197], v[72:75]
	v_mfma_f32_16x16x32_bf16 v[198:201], v[210:213], v[202:205], v[68:71]
	v_mfma_f32_16x16x32_bf16 v[202:205], v[156:159], v[202:205], v[64:67]
	s_setprio 0
	s_barrier
	s_nop 0
	ds_read_b128 v[64:67], v152 offset:16384
	ds_read_b128 v[68:71], v152 offset:17408
	ds_read_b128 v[72:75], v151 offset:16384
	ds_read_b128 v[76:79], v151 offset:17408
	ds_read_b128 v[80:83], v150 offset:16384
	ds_read_b128 v[84:87], v150 offset:17408
	ds_read_b128 v[88:91], v149 offset:16384
	ds_read_b128 v[92:95], v149 offset:17408
	s_waitcnt vmcnt(4)
	s_barrier
	s_waitcnt lgkmcnt(0)
	s_setprio 1
	s_waitcnt lgkmcnt(0)
	v_mfma_f32_16x16x32_bf16 v[60:63], v[130:133], v[64:67], v[60:63]
	v_mfma_f32_16x16x32_bf16 v[56:59], v[166:169], v[64:67], v[56:59]
	v_mfma_f32_16x16x32_bf16 v[52:55], v[130:133], v[72:75], v[52:55]
	v_mfma_f32_16x16x32_bf16 v[48:51], v[166:169], v[72:75], v[48:51]
	v_mfma_f32_16x16x32_bf16 v[218:221], v[130:133], v[80:83], v[44:47]
	v_mfma_f32_16x16x32_bf16 v[222:225], v[166:169], v[80:83], v[40:43]
	v_mfma_f32_16x16x32_bf16 v[130:133], v[130:133], v[88:91], v[36:39]
	v_mfma_f32_16x16x32_bf16 v[166:169], v[166:169], v[88:91], v[32:35]
	v_mfma_f32_16x16x32_bf16 v[32:35], v[162:165], v[68:71], v[60:63]
	v_mfma_f32_16x16x32_bf16 v[36:39], v[170:173], v[68:71], v[56:59]
	v_mfma_f32_16x16x32_bf16 v[40:43], v[162:165], v[76:79], v[52:55]
	v_mfma_f32_16x16x32_bf16 v[44:47], v[170:173], v[76:79], v[48:51]
	v_mfma_f32_16x16x32_bf16 v[48:51], v[162:165], v[84:87], v[218:221]
	v_mfma_f32_16x16x32_bf16 v[52:55], v[170:173], v[84:87], v[222:225]
	v_mfma_f32_16x16x32_bf16 v[56:59], v[162:165], v[92:95], v[130:133]
	v_mfma_f32_16x16x32_bf16 v[60:63], v[170:173], v[92:95], v[166:169]
	s_setprio 0
	s_setprio 1
	v_mfma_f32_16x16x32_bf16 v[28:31], v[206:209], v[64:67], v[28:31]
	v_mfma_f32_16x16x32_bf16 v[24:27], v[214:217], v[64:67], v[24:27]
	v_mfma_f32_16x16x32_bf16 v[20:23], v[206:209], v[72:75], v[20:23]
	v_mfma_f32_16x16x32_bf16 v[64:67], v[214:217], v[72:75], v[16:19]
	v_mfma_f32_16x16x32_bf16 v[72:75], v[206:209], v[80:83], v[12:15]
	v_mfma_f32_16x16x32_bf16 v[8:11], v[214:217], v[80:83], v[8:11]
	v_mfma_f32_16x16x32_bf16 v[80:83], v[206:209], v[88:91], v[4:7]
	v_mfma_f32_16x16x32_bf16 v[0:3], v[214:217], v[88:91], v[0:3]
	v_mfma_f32_16x16x32_bf16 v[4:7], v[210:213], v[68:71], v[28:31]
	v_mfma_f32_16x16x32_bf16 v[12:15], v[156:159], v[68:71], v[24:27]
	v_mfma_f32_16x16x32_bf16 v[16:19], v[210:213], v[76:79], v[20:23]
	v_mfma_f32_16x16x32_bf16 v[20:23], v[156:159], v[76:79], v[64:67]
	v_mfma_f32_16x16x32_bf16 v[24:27], v[210:213], v[84:87], v[72:75]
	v_mfma_f32_16x16x32_bf16 v[28:31], v[156:159], v[84:87], v[8:11]
	v_mfma_f32_16x16x32_bf16 v[64:67], v[210:213], v[92:95], v[80:83]
	v_mfma_f32_16x16x32_bf16 v[68:71], v[156:159], v[92:95], v[0:3]
	s_setprio 0
	s_barrier
	ds_read_b128 v[8:11], v154
	ds_read_b128 v[0:3], v154 offset:1024
	ds_read_b128 v[76:79], v154 offset:2048
	ds_read_b128 v[72:75], v154 offset:3072
	ds_read_b128 v[130:133], v152 offset:32768
	ds_read_b128 v[154:157], v152 offset:33792
	ds_read_b128 v[158:161], v151 offset:32768
	ds_read_b128 v[162:165], v151 offset:33792
	ds_read_b128 v[166:169], v150 offset:32768
	ds_read_b128 v[170:173], v150 offset:33792
	ds_read_b128 v[206:209], v149 offset:32768
	ds_read_b128 v[210:213], v149 offset:33792
	s_waitcnt vmcnt(2)
	s_barrier
	s_waitcnt lgkmcnt(0)
	s_setprio 1
	s_waitcnt lgkmcnt(0)
	v_mfma_f32_16x16x32_bf16 v[80:83], v[8:11], v[130:133], v[124:127]
	v_mfma_f32_16x16x32_bf16 v[84:87], v[76:79], v[130:133], v[120:123]
	v_mfma_f32_16x16x32_bf16 v[88:91], v[8:11], v[158:161], v[116:119]
	v_mfma_f32_16x16x32_bf16 v[92:95], v[76:79], v[158:161], v[112:115]
	v_mfma_f32_16x16x32_bf16 v[108:111], v[8:11], v[166:169], v[108:111]
	v_mfma_f32_16x16x32_bf16 v[104:107], v[76:79], v[166:169], v[104:107]
	v_mfma_f32_16x16x32_bf16 v[100:103], v[8:11], v[206:209], v[100:103]
	v_mfma_f32_16x16x32_bf16 v[96:99], v[76:79], v[206:209], v[96:99]
	v_mfma_f32_16x16x32_bf16 v[112:115], v[0:3], v[154:157], v[80:83]
	v_mfma_f32_16x16x32_bf16 v[116:119], v[72:75], v[154:157], v[84:87]
	v_mfma_f32_16x16x32_bf16 v[120:123], v[0:3], v[162:165], v[88:91]
	v_mfma_f32_16x16x32_bf16 v[124:127], v[72:75], v[162:165], v[92:95]
	v_mfma_f32_16x16x32_bf16 v[108:111], v[0:3], v[170:173], v[108:111]
	v_mfma_f32_16x16x32_bf16 v[104:107], v[72:75], v[170:173], v[104:107]
	v_mfma_f32_16x16x32_bf16 v[100:103], v[0:3], v[210:213], v[100:103]
	v_mfma_f32_16x16x32_bf16 v[96:99], v[72:75], v[210:213], v[96:99]
	s_setprio 0
	s_barrier
	ds_read_b128 v[88:91], v153
	ds_read_b128 v[80:83], v153 offset:1024
	ds_read_b128 v[92:95], v153 offset:2048
	ds_read_b128 v[84:87], v153 offset:3072
	s_waitcnt vmcnt(0)
	s_barrier
	s_waitcnt lgkmcnt(0)
	s_setprio 1
	s_waitcnt lgkmcnt(0)
	v_mfma_f32_16x16x32_bf16 v[174:177], v[88:91], v[130:133], v[174:177]
	v_mfma_f32_16x16x32_bf16 v[130:133], v[92:95], v[130:133], v[178:181]
	v_mfma_f32_16x16x32_bf16 v[178:181], v[88:91], v[158:161], v[182:185]
	v_mfma_f32_16x16x32_bf16 v[158:161], v[92:95], v[158:161], v[186:189]
	v_mfma_f32_16x16x32_bf16 v[182:185], v[88:91], v[166:169], v[190:193]
	v_mfma_f32_16x16x32_bf16 v[166:169], v[92:95], v[166:169], v[194:197]
	v_mfma_f32_16x16x32_bf16 v[186:189], v[88:91], v[206:209], v[198:201]
	v_mfma_f32_16x16x32_bf16 v[190:193], v[92:95], v[206:209], v[202:205]
	v_mfma_f32_16x16x32_bf16 v[174:177], v[80:83], v[154:157], v[174:177]
	v_mfma_f32_16x16x32_bf16 v[130:133], v[84:87], v[154:157], v[130:133]
	v_mfma_f32_16x16x32_bf16 v[154:157], v[80:83], v[162:165], v[178:181]
	v_mfma_f32_16x16x32_bf16 v[158:161], v[84:87], v[162:165], v[158:161]
	v_mfma_f32_16x16x32_bf16 v[162:165], v[80:83], v[170:173], v[182:185]
	v_mfma_f32_16x16x32_bf16 v[166:169], v[84:87], v[170:173], v[166:169]
	v_mfma_f32_16x16x32_bf16 v[170:173], v[80:83], v[210:213], v[186:189]
	v_mfma_f32_16x16x32_bf16 v[178:181], v[84:87], v[210:213], v[190:193]
	s_setprio 0
	s_barrier
	v_mbcnt_lo_u32_b32 v128, -1, 0
	v_mbcnt_hi_u32_b32 v128, -1, v128
	v_cvt_pk_bf16_f32 v112, v112, v113
	v_cvt_pk_bf16_f32 v113, v114, v115
	v_cvt_pk_bf16_f32 v114, v116, v117
	v_cvt_pk_bf16_f32 v115, v118, v119
	s_lshl_b32 s89, s66, 9
	v_add_u32_e32 v153, s74, v128
	v_ashrrev_i32_e32 v182, 6, v153
	v_and_b32_e32 v183, 15, v128
	v_and_b32_e32 v184, 48, v128
	v_mul_lo_u32 v185, v182, s79
	v_bfe_u32 v186, v128, 3, 3
	v_lshlrev_b32_e32 v128, 4, v128
	v_add_u32_e32 v185, 0x20000, v185
	v_lshrrev_b32_e32 v153, 2, v153
	v_and_b32_e32 v128, 0x70, v128
	v_mul_u32_u24_e32 v183, 0x90, v183
	v_and_b32_e32 v153, 64, v153
	v_add3_u32 v183, v185, v183, v184
	v_or_b32_e32 v184, v185, v128
	v_or3_b32 v153, s96, v153, v186
	v_mad_u32_u24 v184, v186, s81, v184
	ds_write_b128 v183, v[112:115]
	v_cvt_pk_bf16_f32 v112, v174, v175
	v_cvt_pk_bf16_f32 v113, v176, v177
	v_cvt_pk_bf16_f32 v114, v130, v131
	v_cvt_pk_bf16_f32 v115, v132, v133
	ds_write_b128 v183, v[112:115] offset:64
	v_lshlrev_b32_e32 v182, 7, v182
	ds_read_b128 v[112:115], v184
	v_lshlrev_b32_e32 v116, 12, v153
	v_and_or_b32 v116, v182, s82, v116
	v_or3_b32 v128, v116, s89, v128
	ds_read_b128 v[116:119], v184 offset:1152
	v_lshl_add_u64 v[130:131], s[0:1], 0, v[128:129]
	s_mov_b32 s20, 0x8000
	s_waitcnt lgkmcnt(0)
	global_store_dwordx4 v128, v[112:115], s[0:1]
	v_cvt_pk_bf16_f32 v108, v108, v109
	v_cvt_pk_bf16_f32 v109, v110, v111
	v_cvt_pk_bf16_f32 v110, v104, v105
	v_cvt_pk_bf16_f32 v111, v106, v107
	v_cvt_pk_bf16_f32 v104, v162, v163
	s_nop 1
	v_add_co_u32_e32 v112, vcc, s20, v130
	v_cvt_pk_bf16_f32 v114, v124, v125
	v_cvt_pk_bf16_f32 v115, v126, v127
	v_cvt_pk_bf16_f32 v105, v164, v165
	v_cvt_pk_bf16_f32 v106, v166, v167
	s_nop 1
	v_addc_co_u32_e32 v113, vcc, 0, v131, vcc
	global_store_dwordx4 v[112:113], v[116:119], off
	v_cvt_pk_bf16_f32 v112, v120, v121
	v_cvt_pk_bf16_f32 v113, v122, v123
	ds_write_b128 v183, v[112:115]
	v_cvt_pk_bf16_f32 v112, v154, v155
	v_cvt_pk_bf16_f32 v113, v156, v157
	v_cvt_pk_bf16_f32 v114, v158, v159
	v_cvt_pk_bf16_f32 v115, v160, v161
	ds_write_b128 v183, v[112:115] offset:64
	ds_read_b128 v[112:115], v184
	ds_read_b128 v[116:119], v184 offset:1152
	v_add_co_u32_e32 v120, vcc, s76, v130
	ds_write_b128 v183, v[108:111]
	v_cvt_pk_bf16_f32 v107, v168, v169
	ds_write_b128 v183, v[104:107] offset:64
	v_addc_co_u32_e32 v121, vcc, 0, v131, vcc
	ds_read_b128 v[104:107], v184
	ds_read_b128 v[108:111], v184 offset:1152
	s_waitcnt lgkmcnt(0)
	global_store_dwordx4 v[120:121], v[112:115], off
	v_cvt_pk_bf16_f32 v100, v100, v101
	v_cvt_pk_bf16_f32 v101, v102, v103
	v_cvt_pk_bf16_f32 v102, v96, v97
	v_cvt_pk_bf16_f32 v103, v98, v99
	ds_write_b128 v183, v[100:103]
	s_nop 0
	v_add_co_u32_e32 v112, vcc, s77, v130
	v_cvt_pk_bf16_f32 v96, v170, v171
	v_cvt_pk_bf16_f32 v97, v172, v173
	v_cvt_pk_bf16_f32 v98, v178, v179
	v_cvt_pk_bf16_f32 v99, v180, v181
	s_nop 1
	v_addc_co_u32_e32 v113, vcc, 0, v131, vcc
	global_store_dwordx4 v[112:113], v[116:119], off
	v_add_co_u32_e32 v112, vcc, s80, v130
	ds_write_b128 v183, v[96:99] offset:64
	s_nop 0
	v_addc_co_u32_e32 v113, vcc, 0, v131, vcc
	ds_read_b128 v[96:99], v184
	ds_read_b128 v[100:103], v184 offset:1152
	global_store_dwordx4 v[112:113], v[104:107], off
	s_nop 1
	v_add_co_u32_e32 v104, vcc, s83, v130
	s_nop 1
	v_addc_co_u32_e32 v105, vcc, 0, v131, vcc
	global_store_dwordx4 v[104:105], v[108:111], off
	v_add_co_u32_e32 v104, vcc, s85, v130
	s_nop 1
	v_addc_co_u32_e32 v105, vcc, 0, v131, vcc
	s_waitcnt lgkmcnt(0)
	global_store_dwordx4 v[104:105], v[96:99], off
	s_nop 1
	v_add_co_u32_e32 v96, vcc, s87, v130
	s_nop 1
	v_addc_co_u32_e32 v97, vcc, 0, v131, vcc
	global_store_dwordx4 v[96:97], v[100:103], off
	ds_read_b128 v[96:99], v152 offset:49152
	ds_read_b128 v[100:103], v152 offset:50176
	ds_read_b128 v[104:107], v151 offset:49152
	ds_read_b128 v[108:111], v151 offset:50176
	ds_read_b128 v[112:115], v150 offset:49152
	ds_read_b128 v[116:119], v150 offset:50176
	ds_read_b128 v[120:123], v149 offset:49152
	ds_read_b128 v[124:127], v149 offset:50176
	s_barrier
	s_waitcnt lgkmcnt(0)
	s_setprio 1
	s_waitcnt lgkmcnt(0)
	v_mfma_f32_16x16x32_bf16 v[32:35], v[8:11], v[96:99], v[32:35]
	v_mfma_f32_16x16x32_bf16 v[36:39], v[76:79], v[96:99], v[36:39]
	v_mfma_f32_16x16x32_bf16 v[40:43], v[8:11], v[104:107], v[40:43]
	v_mfma_f32_16x16x32_bf16 v[130:133], v[76:79], v[104:107], v[44:47]
	v_mfma_f32_16x16x32_bf16 v[150:153], v[8:11], v[112:115], v[48:51]
	v_mfma_f32_16x16x32_bf16 v[52:55], v[76:79], v[112:115], v[52:55]
	v_mfma_f32_16x16x32_bf16 v[8:11], v[8:11], v[120:123], v[56:59]
	v_mfma_f32_16x16x32_bf16 v[60:63], v[76:79], v[120:123], v[60:63]
	v_mfma_f32_16x16x32_bf16 v[56:59], v[0:3], v[100:103], v[32:35]
	v_mfma_f32_16x16x32_bf16 v[48:51], v[72:75], v[100:103], v[36:39]
	v_mfma_f32_16x16x32_bf16 v[44:47], v[0:3], v[108:111], v[40:43]
	v_mfma_f32_16x16x32_bf16 v[40:43], v[72:75], v[108:111], v[130:133]
	v_mfma_f32_16x16x32_bf16 v[36:39], v[0:3], v[116:119], v[150:153]
	v_mfma_f32_16x16x32_bf16 v[32:35], v[72:75], v[116:119], v[52:55]
	v_mfma_f32_16x16x32_bf16 v[8:11], v[0:3], v[124:127], v[8:11]
	v_mfma_f32_16x16x32_bf16 v[0:3], v[72:75], v[124:127], v[60:63]
	s_setprio 0
	s_setprio 1
	v_mfma_f32_16x16x32_bf16 v[4:7], v[88:91], v[96:99], v[4:7]
	v_mfma_f32_16x16x32_bf16 v[12:15], v[92:95], v[96:99], v[12:15]
	v_mfma_f32_16x16x32_bf16 v[16:19], v[88:91], v[104:107], v[16:19]
	v_mfma_f32_16x16x32_bf16 v[20:23], v[92:95], v[104:107], v[20:23]
	v_mfma_f32_16x16x32_bf16 v[72:75], v[88:91], v[112:115], v[24:27]
	v_mfma_f32_16x16x32_bf16 v[76:79], v[92:95], v[112:115], v[28:31]
	v_mfma_f32_16x16x32_bf16 v[64:67], v[88:91], v[120:123], v[64:67]
	v_mfma_f32_16x16x32_bf16 v[68:71], v[92:95], v[120:123], v[68:71]
	v_mfma_f32_16x16x32_bf16 v[60:63], v[80:83], v[100:103], v[4:7]
	v_mfma_f32_16x16x32_bf16 v[52:55], v[84:87], v[100:103], v[12:15]
	v_mfma_f32_16x16x32_bf16 v[28:31], v[80:83], v[108:111], v[16:19]
	v_mfma_f32_16x16x32_bf16 v[24:27], v[84:87], v[108:111], v[20:23]
	v_mfma_f32_16x16x32_bf16 v[20:23], v[80:83], v[116:119], v[72:75]
	v_mfma_f32_16x16x32_bf16 v[16:19], v[84:87], v[116:119], v[76:79]
	v_mfma_f32_16x16x32_bf16 v[12:15], v[80:83], v[124:127], v[64:67]
	v_mfma_f32_16x16x32_bf16 v[4:7], v[84:87], v[124:127], v[68:71]
	s_setprio 0
	v_cmp_gt_u32_e32 vcc, s88, v135
	s_barrier
	s_and_saveexec_b64 s[66:67], vcc
	s_cbranch_execz .LBB0_564
	s_barrier
